# resid_rows passes hand-written: rolling 4-row software pipeline per wave (saddr addressing, DPP wave-sum), layer-0 resid2 halves fused
# speedup vs baseline: 1.0075x; 1.0075x over previous
; __device__ __forceinline__ float bflo(unsigned w) { return __uint_as_float(w << 16); }
; __device__ __forceinline__ void resid_rows(bf16_t* R, const bf16_t* Y, const float* ssqY, const float* g, float* rstd_out, float* outf, bool wf32, int row_lo, int row_hi, int yoff, int gw, int NGW, int lane) {
;     constexpr int RP = 4;
;     f32x4 gv[2][2];
; #pragma unroll
;     for (int j = 0; j < 2; ++j) { gv[j][0] = *(const f32x4*)(g + 8 * lane + 512 * j); gv[j][1] = *(const f32x4*)(g + 8 * lane + 512 * j + 4); }
;     for (int row0 = row_lo + gw; row0 < row_hi; row0 += RP * NGW) {
;         u32x4 rr[RP][2], oo[RP][2]; float ssv[RP];
; #pragma unroll
;         for (int k = 0; k < RP; ++k) { const int row = row0 + k * NGW; const bool ok = row < row_hi; const int rw = ok ? row : row0;
;             ssv[k] = ssqY[rw];
; #pragma unroll
;             for (int j = 0; j < 2; ++j) { const int c = 8 * lane + 512 * j; rr[k][j] = *(const u32x4*)(R + (size_t)rw * DM + c); oo[k][j] = *(const u32x4*)(Y + (size_t)(rw - yoff) * DM + c); } }
; #pragma unroll
;         for (int k = 0; k < RP; ++k) { const int row = row0 + k * NGW; if (row < row_hi) {
;             const float rs = __builtin_amdgcn_rsqf(ssv[k] * (1.0f / DM) + RMS_EPS); float s = 0.f;
; #pragma unroll
;             for (int j = 0; j < 2; ++j) { const int c = 8 * lane + 512 * j; const u32x4 r = rr[k][j], o = oo[k][j]; const f32x4 ga = gv[j][0], gb = gv[j][1];
;                 f32x4 ya, yb; ya[0] = bflo(r.x) + bflo(o.x) * rs * ga[0]; ya[1] = bfhi(r.x) + bfhi(o.x) * rs * ga[1]; ya[2] = bflo(r.y) + bflo(o.y) * rs * ga[2]; ya[3] = bfhi(r.y) + bfhi(o.y) * rs * ga[3];
;                 yb[0] = bflo(r.z) + bflo(o.z) * rs * gb[0]; yb[1] = bfhi(r.z) + bfhi(o.z) * rs * gb[1]; yb[2] = bflo(r.w) + bflo(o.w) * rs * gb[2]; yb[3] = bfhi(r.w) + bfhi(o.w) * rs * gb[3];
;                 if (wf32) { *(f32x4*)(outf + (size_t)row * DM + c) = ya; *(f32x4*)(outf + (size_t)row * DM + c + 4) = yb; }
;                 s += (ya[0] * ya[0] + ya[1] * ya[1]) + (ya[2] * ya[2] + ya[3] * ya[3]) + (yb[0] * yb[0] + yb[1] * yb[1]) + (yb[2] * yb[2] + yb[3] * yb[3]);
;                 u32x4 w; w.x = pk2(ya[0], ya[1]); w.y = pk2(ya[2], ya[3]); w.z = pk2(yb[0], yb[1]); w.w = pk2(yb[2], yb[3]); *(u32x4*)(R + (size_t)row * DM + c) = w; }
;             s = wave_sum(s); if (lane == 0) rstd_out[row] = __builtin_amdgcn_rsqf(s * (1.0f / DM) + RMS_EPS); } }
.LBB0_497:
	s_andn2_b64 vcc, exec, s[4:5]
	s_cbranch_vccnz .LBB0_566
	v_mov_b32_e32 v2, v0
	v_mov_b32_e32 v3, v0
	v_readlane_b32 s4, v255, 4
	v_ashrrev_i32_e32 v3, 6, v3
	s_mov_b64 s[6:7], s[0:1]
	v_add_u32_e32 v92, s4, v3
	s_mov_b64 s[4:5], s[0:1]
	s_mov_b64 s[8:9], s[0:1]
	s_mov_b64 s[14:15], s[0:1]
	v_cmp_gt_i32_e32 vcc, s45, v92
	s_and_saveexec_b64 s[12:13], vcc
	v_readlane_b32 s22, v255, 37
	v_readlane_b32 s23, v255, 38
	v_readlane_b32 s23, v255, 45
	s_cbranch_execz .LBB0_512
	v_lshrrev_b32_e32 v114, 6, v0
	v_readlane_b32 s14, v255, 49
	v_readlane_b32 s15, v255, 4
	v_readfirstlane_b32 s16, v114
	s_load_dwordx2 s[4:5], s[0:1], 0x98
	s_load_dwordx2 s[8:9], s[0:1], 0x20
	s_add_i32 s15, s15, s16
	v_and_b32_e32 v115, 63, v0
	v_lshlrev_b32_e32 v114, 4, v115
	v_lshlrev_b32_e32 v115, 5, v115
	s_lshl_b32 s16, s14, 12
	s_lshl_b32 s17, s14, 18
	s_bfm_b64 s[6:7], 1, 63
	s_waitcnt lgkmcnt(0)
	s_add_u32 s8, s8, s16
	s_addc_u32 s9, s9, 0
	global_load_dwordx4 v[2:5], v115, s[8:9] offset:2048
	global_load_dwordx4 v[6:9], v115, s[8:9] offset:2064
	global_load_dwordx4 v[10:13], v115, s[8:9]
	global_load_dwordx4 v[14:17], v115, s[8:9] offset:16
	s_lshl_b32 s16, s15, 11
	v_add_u32_e32 v18, s16, v114
	v_mov_b32_e32 v19, v18
	v_mov_b32_e32 v20, v18
	s_lshl_b32 s16, s15, 2
	v_mov_b32_e32 v22, s16
	s_add_i32 s16, s16, s17
	v_mov_b32_e32 v21, s16
	v_add_u32_e32 v18, 0x3001000, v18
	v_add_u32_e32 v20, 0x7800000, v20
	v_add_u32_e32 v21, 0x2d40000, v21
	global_load_dwordx4 v[24:27], v18, s[4:5]
	global_load_dwordx4 v[32:35], v20, s[4:5]
	global_load_dwordx4 v[28:31], v18, s[4:5] offset:1024
	global_load_dwordx4 v[36:39], v20, s[4:5] offset:1024
	global_load_dword v40, v21, s[4:5]
	v_add_u32_e32 v18, 0x400000, v18
	v_add_u32_e32 v20, 0x400000, v20
	v_add_u32_e32 v21, 0x2000, v21
	global_load_dwordx4 v[42:45], v18, s[4:5]
	global_load_dwordx4 v[50:53], v20, s[4:5]
	global_load_dwordx4 v[46:49], v18, s[4:5] offset:1024
	global_load_dwordx4 v[54:57], v20, s[4:5] offset:1024
	global_load_dword v58, v21, s[4:5]
	v_add_u32_e32 v18, 0x400000, v18
	v_add_u32_e32 v20, 0x400000, v20
	v_add_u32_e32 v21, 0x2000, v21
	global_load_dwordx4 v[60:63], v18, s[4:5]
	global_load_dwordx4 v[68:71], v20, s[4:5]
	global_load_dwordx4 v[64:67], v18, s[4:5] offset:1024
	global_load_dwordx4 v[72:75], v20, s[4:5] offset:1024
	global_load_dword v76, v21, s[4:5]
	v_add_u32_e32 v18, 0x400000, v18
	v_add_u32_e32 v20, 0x400000, v20
	v_add_u32_e32 v21, 0x2000, v21
	global_load_dwordx4 v[78:81], v18, s[4:5]
	global_load_dwordx4 v[86:89], v20, s[4:5]
	global_load_dwordx4 v[82:85], v18, s[4:5] offset:1024
	global_load_dwordx4 v[90:93], v20, s[4:5] offset:1024
	global_load_dword v94, v21, s[4:5]
	s_waitcnt vmcnt(15)
	v_fmamk_f32 v96, v40, 0x3a800000, v244
	v_rsq_f32_e32 v96, v96
	v_add_u32_e32 v19, 0x3001000, v19
	v_lshlrev_b32_e32 v106, 16, v32
	v_and_b32_e32 v107, 0xffff0000, v32
	v_lshlrev_b32_e32 v108, 16, v24
	v_and_b32_e32 v109, 0xffff0000, v24
	v_pk_mul_f32 v[106:107], v[96:97], v[106:107] op_sel_hi:[0,1]
	v_pk_fma_f32 v[98:99], v[10:11], v[106:107], v[108:109]
	v_lshlrev_b32_e32 v106, 16, v33
	v_and_b32_e32 v107, 0xffff0000, v33
	v_lshlrev_b32_e32 v108, 16, v25
	v_and_b32_e32 v109, 0xffff0000, v25
	v_pk_mul_f32 v[106:107], v[96:97], v[106:107] op_sel_hi:[0,1]
	v_pk_fma_f32 v[100:101], v[12:13], v[106:107], v[108:109]
	v_lshlrev_b32_e32 v106, 16, v34
	v_and_b32_e32 v107, 0xffff0000, v34
	v_lshlrev_b32_e32 v108, 16, v26
	v_and_b32_e32 v109, 0xffff0000, v26
	v_pk_mul_f32 v[106:107], v[96:97], v[106:107] op_sel_hi:[0,1]
	v_pk_fma_f32 v[102:103], v[14:15], v[106:107], v[108:109]
	v_lshlrev_b32_e32 v106, 16, v35
	v_and_b32_e32 v107, 0xffff0000, v35
	v_lshlrev_b32_e32 v108, 16, v27
	v_and_b32_e32 v109, 0xffff0000, v27
	v_pk_mul_f32 v[106:107], v[96:97], v[106:107] op_sel_hi:[0,1]
	v_pk_fma_f32 v[104:105], v[16:17], v[106:107], v[108:109]
	v_pk_mul_f32 v[110:111], v[98:99], v[98:99]
	v_pk_fma_f32 v[110:111], v[100:101], v[100:101], v[110:111]
	v_pk_fma_f32 v[110:111], v[102:103], v[102:103], v[110:111]
	v_pk_fma_f32 v[110:111], v[104:105], v[104:105], v[110:111]
	v_cvt_pk_bf16_f32 v24, v98, v99
	v_cvt_pk_bf16_f32 v25, v100, v101
	v_cvt_pk_bf16_f32 v26, v102, v103
	v_cvt_pk_bf16_f32 v27, v104, v105
	global_store_dwordx4 v19, v[24:27], s[4:5]
	v_lshlrev_b32_e32 v106, 16, v36
	v_and_b32_e32 v107, 0xffff0000, v36
	v_lshlrev_b32_e32 v108, 16, v28
	v_and_b32_e32 v109, 0xffff0000, v28
	v_pk_mul_f32 v[106:107], v[96:97], v[106:107] op_sel_hi:[0,1]
	v_pk_fma_f32 v[98:99], v[2:3], v[106:107], v[108:109]
	v_lshlrev_b32_e32 v106, 16, v37
	v_and_b32_e32 v107, 0xffff0000, v37
	v_lshlrev_b32_e32 v108, 16, v29
	v_and_b32_e32 v109, 0xffff0000, v29
	v_pk_mul_f32 v[106:107], v[96:97], v[106:107] op_sel_hi:[0,1]
	v_pk_fma_f32 v[100:101], v[4:5], v[106:107], v[108:109]
	v_lshlrev_b32_e32 v106, 16, v38
	v_and_b32_e32 v107, 0xffff0000, v38
	v_lshlrev_b32_e32 v108, 16, v30
	v_and_b32_e32 v109, 0xffff0000, v30
	v_pk_mul_f32 v[106:107], v[96:97], v[106:107] op_sel_hi:[0,1]
	v_pk_fma_f32 v[102:103], v[6:7], v[106:107], v[108:109]
	v_lshlrev_b32_e32 v106, 16, v39
	v_and_b32_e32 v107, 0xffff0000, v39
	v_lshlrev_b32_e32 v108, 16, v31
	v_and_b32_e32 v109, 0xffff0000, v31
	v_pk_mul_f32 v[106:107], v[96:97], v[106:107] op_sel_hi:[0,1]
	v_pk_fma_f32 v[104:105], v[8:9], v[106:107], v[108:109]
	v_pk_fma_f32 v[110:111], v[98:99], v[98:99], v[110:111]
	v_pk_fma_f32 v[110:111], v[100:101], v[100:101], v[110:111]
	v_pk_fma_f32 v[110:111], v[102:103], v[102:103], v[110:111]
	v_pk_fma_f32 v[110:111], v[104:105], v[104:105], v[110:111]
	v_cvt_pk_bf16_f32 v28, v98, v99
	v_cvt_pk_bf16_f32 v29, v100, v101
	v_cvt_pk_bf16_f32 v30, v102, v103
	v_cvt_pk_bf16_f32 v31, v104, v105
	global_store_dwordx4 v19, v[28:31], s[4:5] offset:1024
	v_add_f32_e32 v112, v110, v111
	v_add_u32_e32 v22, 0x2d20000, v22
	s_nop 1
	v_add_f32_dpp v112, v112, v112 quad_perm:[1,0,3,2] row_mask:0xf bank_mask:0xf
	s_nop 1
	v_add_f32_dpp v112, v112, v112 quad_perm:[2,3,0,1] row_mask:0xf bank_mask:0xf
	s_nop 1
	v_add_f32_dpp v112, v112, v112 row_half_mirror row_mask:0xf bank_mask:0xf
	s_nop 1
	v_add_f32_dpp v112, v112, v112 row_mirror row_mask:0xf bank_mask:0xf
	s_nop 1
	v_add_f32_dpp v112, v112, v112 row_bcast:15 row_mask:0xa bank_mask:0xf
	s_nop 1
	v_add_f32_dpp v112, v112, v112 row_bcast:31 row_mask:0xc bank_mask:0xf
	v_fmamk_f32 v113, v112, 0x3a800000, v244
	v_rsq_f32_e32 v113, v113
	s_mov_b64 exec, s[6:7]
	global_store_dword v22, v113, s[4:5]
	s_mov_b64 exec, -1
	v_add_u32_e32 v18, 0x400000, v18
	v_add_u32_e32 v20, 0x400000, v20
	v_add_u32_e32 v21, 0x2000, v21
	global_load_dwordx4 v[24:27], v18, s[4:5]
	global_load_dwordx4 v[32:35], v20, s[4:5]
	global_load_dwordx4 v[28:31], v18, s[4:5] offset:1024
	global_load_dwordx4 v[36:39], v20, s[4:5] offset:1024
	global_load_dword v40, v21, s[4:5]
	s_waitcnt vmcnt(18)
; __device__ __forceinline__ float bflo(unsigned w) { return __uint_as_float(w << 16); }
; __device__ __forceinline__ float bfhi(unsigned w) { return __uint_as_float(w & 0xffff0000u); }
; __device__ __forceinline__ void resid_rows(bf16_t* R, const bf16_t* Y, const float* ssqY, const float* g, float* rstd_out, float* outf, bool wf32, int row_lo, int row_hi, int yoff, int gw, int NGW, int lane) {
;     ...
;         for (int k = 0; k < RP; ++k) { const int row = row0 + k * NGW; if (row < row_hi) {
;             const float rs = __builtin_amdgcn_rsqf(ssv[k] * (1.0f / DM) + RMS_EPS); float s = 0.f;
; #pragma unroll
;             for (int j = 0; j < 2; ++j) { const int c = 8 * lane + 512 * j; const u32x4 r = rr[k][j], o = oo[k][j]; const f32x4 ga = gv[j][0], gb = gv[j][1];
;                 f32x4 ya, yb; ya[0] = bflo(r.x) + bflo(o.x) * rs * ga[0]; ya[1] = bfhi(r.x) + bfhi(o.x) * rs * ga[1]; ya[2] = bflo(r.y) + bflo(o.y) * rs * ga[2]; ya[3] = bfhi(r.y) + bfhi(o.y) * rs * ga[3];
;                 yb[0] = bflo(r.z) + bflo(o.z) * rs * gb[0]; yb[1] = bfhi(r.z) + bfhi(o.z) * rs * gb[1]; yb[2] = bflo(r.w) + bflo(o.w) * rs * gb[2]; yb[3] = bfhi(r.w) + bfhi(o.w) * rs * gb[3];
;                 if (wf32) { *(f32x4*)(outf + (size_t)row * DM + c) = ya; *(f32x4*)(outf + (size_t)row * DM + c + 4) = yb; }
;                 s += (ya[0] * ya[0] + ya[1] * ya[1]) + (ya[2] * ya[2] + ya[3] * ya[3]) + (yb[0] * yb[0] + yb[1] * yb[1]) + (yb[2] * yb[2] + yb[3] * yb[3]);
;                 u32x4 w; w.x = pk2(ya[0], ya[1]); w.y = pk2(ya[2], ya[3]); w.z = pk2(yb[0], yb[1]); w.w = pk2(yb[2], yb[3]); *(u32x4*)(R + (size_t)row * DM + c) = w; }
;             s = wave_sum(s); if (lane == 0) rstd_out[row] = __builtin_amdgcn_rsqf(s * (1.0f / DM) + RMS_EPS); } }
	v_fmamk_f32 v96, v58, 0x3a800000, v244
	v_rsq_f32_e32 v96, v96
	v_add_u32_e32 v19, 0x400000, v19
	v_lshlrev_b32_e32 v106, 16, v50
	v_and_b32_e32 v107, 0xffff0000, v50
	v_lshlrev_b32_e32 v108, 16, v42
	v_and_b32_e32 v109, 0xffff0000, v42
	v_pk_mul_f32 v[106:107], v[96:97], v[106:107] op_sel_hi:[0,1]
	v_pk_fma_f32 v[98:99], v[10:11], v[106:107], v[108:109]
	v_lshlrev_b32_e32 v106, 16, v51
	v_and_b32_e32 v107, 0xffff0000, v51
	v_lshlrev_b32_e32 v108, 16, v43
	v_and_b32_e32 v109, 0xffff0000, v43
	v_pk_mul_f32 v[106:107], v[96:97], v[106:107] op_sel_hi:[0,1]
	v_pk_fma_f32 v[100:101], v[12:13], v[106:107], v[108:109]
	v_lshlrev_b32_e32 v106, 16, v52
	v_and_b32_e32 v107, 0xffff0000, v52
	v_lshlrev_b32_e32 v108, 16, v44
	v_and_b32_e32 v109, 0xffff0000, v44
	v_pk_mul_f32 v[106:107], v[96:97], v[106:107] op_sel_hi:[0,1]
	v_pk_fma_f32 v[102:103], v[14:15], v[106:107], v[108:109]
	v_lshlrev_b32_e32 v106, 16, v53
	v_and_b32_e32 v107, 0xffff0000, v53
	v_lshlrev_b32_e32 v108, 16, v45
	v_and_b32_e32 v109, 0xffff0000, v45
	v_pk_mul_f32 v[106:107], v[96:97], v[106:107] op_sel_hi:[0,1]
	v_pk_fma_f32 v[104:105], v[16:17], v[106:107], v[108:109]
	v_pk_mul_f32 v[110:111], v[98:99], v[98:99]
	v_pk_fma_f32 v[110:111], v[100:101], v[100:101], v[110:111]
	v_pk_fma_f32 v[110:111], v[102:103], v[102:103], v[110:111]
	v_pk_fma_f32 v[110:111], v[104:105], v[104:105], v[110:111]
	v_cvt_pk_bf16_f32 v42, v98, v99
	v_cvt_pk_bf16_f32 v43, v100, v101
	v_cvt_pk_bf16_f32 v44, v102, v103
	v_cvt_pk_bf16_f32 v45, v104, v105
	global_store_dwordx4 v19, v[42:45], s[4:5]
	v_lshlrev_b32_e32 v106, 16, v54
	v_and_b32_e32 v107, 0xffff0000, v54
	v_lshlrev_b32_e32 v108, 16, v46
	v_and_b32_e32 v109, 0xffff0000, v46
	v_pk_mul_f32 v[106:107], v[96:97], v[106:107] op_sel_hi:[0,1]
	v_pk_fma_f32 v[98:99], v[2:3], v[106:107], v[108:109]
	v_lshlrev_b32_e32 v106, 16, v55
	v_and_b32_e32 v107, 0xffff0000, v55
	v_lshlrev_b32_e32 v108, 16, v47
	v_and_b32_e32 v109, 0xffff0000, v47
	v_pk_mul_f32 v[106:107], v[96:97], v[106:107] op_sel_hi:[0,1]
	v_pk_fma_f32 v[100:101], v[4:5], v[106:107], v[108:109]
	v_lshlrev_b32_e32 v106, 16, v56
	v_and_b32_e32 v107, 0xffff0000, v56
	v_lshlrev_b32_e32 v108, 16, v48
	v_and_b32_e32 v109, 0xffff0000, v48
	v_pk_mul_f32 v[106:107], v[96:97], v[106:107] op_sel_hi:[0,1]
	v_pk_fma_f32 v[102:103], v[6:7], v[106:107], v[108:109]
	v_lshlrev_b32_e32 v106, 16, v57
	v_and_b32_e32 v107, 0xffff0000, v57
	v_lshlrev_b32_e32 v108, 16, v49
	v_and_b32_e32 v109, 0xffff0000, v49
	v_pk_mul_f32 v[106:107], v[96:97], v[106:107] op_sel_hi:[0,1]
	v_pk_fma_f32 v[104:105], v[8:9], v[106:107], v[108:109]
	v_pk_fma_f32 v[110:111], v[98:99], v[98:99], v[110:111]
	v_pk_fma_f32 v[110:111], v[100:101], v[100:101], v[110:111]
	v_pk_fma_f32 v[110:111], v[102:103], v[102:103], v[110:111]
	v_pk_fma_f32 v[110:111], v[104:105], v[104:105], v[110:111]
	v_cvt_pk_bf16_f32 v46, v98, v99
	v_cvt_pk_bf16_f32 v47, v100, v101
	v_cvt_pk_bf16_f32 v48, v102, v103
	v_cvt_pk_bf16_f32 v49, v104, v105
	global_store_dwordx4 v19, v[46:49], s[4:5] offset:1024
	v_add_f32_e32 v112, v110, v111
	v_add_u32_e32 v22, 0x2000, v22
	s_nop 1
	v_add_f32_dpp v112, v112, v112 quad_perm:[1,0,3,2] row_mask:0xf bank_mask:0xf
	s_nop 1
	v_add_f32_dpp v112, v112, v112 quad_perm:[2,3,0,1] row_mask:0xf bank_mask:0xf
	s_nop 1
	v_add_f32_dpp v112, v112, v112 row_half_mirror row_mask:0xf bank_mask:0xf
	s_nop 1
	v_add_f32_dpp v112, v112, v112 row_mirror row_mask:0xf bank_mask:0xf
	s_nop 1
	v_add_f32_dpp v112, v112, v112 row_bcast:15 row_mask:0xa bank_mask:0xf
	s_nop 1
	v_add_f32_dpp v112, v112, v112 row_bcast:31 row_mask:0xc bank_mask:0xf
	v_fmamk_f32 v113, v112, 0x3a800000, v244
	v_rsq_f32_e32 v113, v113
	s_mov_b64 exec, s[6:7]
	global_store_dword v22, v113, s[4:5]
	s_mov_b64 exec, -1
	v_add_u32_e32 v18, 0x400000, v18
	v_add_u32_e32 v20, 0x400000, v20
	v_add_u32_e32 v21, 0x2000, v21
	global_load_dwordx4 v[42:45], v18, s[4:5]
	global_load_dwordx4 v[50:53], v20, s[4:5]
	global_load_dwordx4 v[46:49], v18, s[4:5] offset:1024
	global_load_dwordx4 v[54:57], v20, s[4:5] offset:1024
	global_load_dword v58, v21, s[4:5]
	s_waitcnt vmcnt(21)
	v_fmamk_f32 v96, v76, 0x3a800000, v244
	v_rsq_f32_e32 v96, v96
	v_add_u32_e32 v19, 0x400000, v19
	v_lshlrev_b32_e32 v106, 16, v68
	v_and_b32_e32 v107, 0xffff0000, v68
	v_lshlrev_b32_e32 v108, 16, v60
	v_and_b32_e32 v109, 0xffff0000, v60
	v_pk_mul_f32 v[106:107], v[96:97], v[106:107] op_sel_hi:[0,1]
	v_pk_fma_f32 v[98:99], v[10:11], v[106:107], v[108:109]
	v_lshlrev_b32_e32 v106, 16, v69
	v_and_b32_e32 v107, 0xffff0000, v69
	v_lshlrev_b32_e32 v108, 16, v61
	v_and_b32_e32 v109, 0xffff0000, v61
	v_pk_mul_f32 v[106:107], v[96:97], v[106:107] op_sel_hi:[0,1]
	v_pk_fma_f32 v[100:101], v[12:13], v[106:107], v[108:109]
	v_lshlrev_b32_e32 v106, 16, v70
	v_and_b32_e32 v107, 0xffff0000, v70
	v_lshlrev_b32_e32 v108, 16, v62
	v_and_b32_e32 v109, 0xffff0000, v62
	v_pk_mul_f32 v[106:107], v[96:97], v[106:107] op_sel_hi:[0,1]
	v_pk_fma_f32 v[102:103], v[14:15], v[106:107], v[108:109]
	v_lshlrev_b32_e32 v106, 16, v71
	v_and_b32_e32 v107, 0xffff0000, v71
	v_lshlrev_b32_e32 v108, 16, v63
	v_and_b32_e32 v109, 0xffff0000, v63
	v_pk_mul_f32 v[106:107], v[96:97], v[106:107] op_sel_hi:[0,1]
	v_pk_fma_f32 v[104:105], v[16:17], v[106:107], v[108:109]
	v_pk_mul_f32 v[110:111], v[98:99], v[98:99]
	v_pk_fma_f32 v[110:111], v[100:101], v[100:101], v[110:111]
	v_pk_fma_f32 v[110:111], v[102:103], v[102:103], v[110:111]
	v_pk_fma_f32 v[110:111], v[104:105], v[104:105], v[110:111]
	v_cvt_pk_bf16_f32 v60, v98, v99
	v_cvt_pk_bf16_f32 v61, v100, v101
	v_cvt_pk_bf16_f32 v62, v102, v103
	v_cvt_pk_bf16_f32 v63, v104, v105
	global_store_dwordx4 v19, v[60:63], s[4:5]
; __device__ __forceinline__ float bflo(unsigned w) { return __uint_as_float(w << 16); }
; __device__ __forceinline__ float bfhi(unsigned w) { return __uint_as_float(w & 0xffff0000u); }
; __device__ __forceinline__ void resid_rows(bf16_t* R, const bf16_t* Y, const float* ssqY, const float* g, float* rstd_out, float* outf, bool wf32, int row_lo, int row_hi, int yoff, int gw, int NGW, int lane) {
;     ...
;     for (int row0 = row_lo + gw; row0 < row_hi; row0 += RP * NGW) {
;         u32x4 rr[RP][2], oo[RP][2]; float ssv[RP];
; #pragma unroll
;         for (int k = 0; k < RP; ++k) { const int row = row0 + k * NGW; const bool ok = row < row_hi; const int rw = ok ? row : row0;
;             ssv[k] = ssqY[rw];
; #pragma unroll
;             for (int j = 0; j < 2; ++j) { const int c = 8 * lane + 512 * j; rr[k][j] = *(const u32x4*)(R + (size_t)rw * DM + c); oo[k][j] = *(const u32x4*)(Y + (size_t)(rw - yoff) * DM + c); } }
; #pragma unroll
;         for (int k = 0; k < RP; ++k) { const int row = row0 + k * NGW; if (row < row_hi) {
;             const float rs = __builtin_amdgcn_rsqf(ssv[k] * (1.0f / DM) + RMS_EPS); float s = 0.f;
; #pragma unroll
;             for (int j = 0; j < 2; ++j) { const int c = 8 * lane + 512 * j; const u32x4 r = rr[k][j], o = oo[k][j]; const f32x4 ga = gv[j][0], gb = gv[j][1];
;                 f32x4 ya, yb; ya[0] = bflo(r.x) + bflo(o.x) * rs * ga[0]; ya[1] = bfhi(r.x) + bfhi(o.x) * rs * ga[1]; ya[2] = bflo(r.y) + bflo(o.y) * rs * ga[2]; ya[3] = bfhi(r.y) + bfhi(o.y) * rs * ga[3];
;                 yb[0] = bflo(r.z) + bflo(o.z) * rs * gb[0]; yb[1] = bfhi(r.z) + bfhi(o.z) * rs * gb[1]; yb[2] = bflo(r.w) + bflo(o.w) * rs * gb[2]; yb[3] = bfhi(r.w) + bfhi(o.w) * rs * gb[3];
;                 if (wf32) { *(f32x4*)(outf + (size_t)row * DM + c) = ya; *(f32x4*)(outf + (size_t)row * DM + c + 4) = yb; }
;                 s += (ya[0] * ya[0] + ya[1] * ya[1]) + (ya[2] * ya[2] + ya[3] * ya[3]) + (yb[0] * yb[0] + yb[1] * yb[1]) + (yb[2] * yb[2] + yb[3] * yb[3]);
;                 u32x4 w; w.x = pk2(ya[0], ya[1]); w.y = pk2(ya[2], ya[3]); w.z = pk2(yb[0], yb[1]); w.w = pk2(yb[2], yb[3]); *(u32x4*)(R + (size_t)row * DM + c) = w; }
;             s = wave_sum(s); if (lane == 0) rstd_out[row] = __builtin_amdgcn_rsqf(s * (1.0f / DM) + RMS_EPS); } }
	v_lshlrev_b32_e32 v106, 16, v72
	v_and_b32_e32 v107, 0xffff0000, v72
	v_lshlrev_b32_e32 v108, 16, v64
	v_and_b32_e32 v109, 0xffff0000, v64
	v_pk_mul_f32 v[106:107], v[96:97], v[106:107] op_sel_hi:[0,1]
	v_pk_fma_f32 v[98:99], v[2:3], v[106:107], v[108:109]
	v_lshlrev_b32_e32 v106, 16, v73
	v_and_b32_e32 v107, 0xffff0000, v73
	v_lshlrev_b32_e32 v108, 16, v65
	v_and_b32_e32 v109, 0xffff0000, v65
	v_pk_mul_f32 v[106:107], v[96:97], v[106:107] op_sel_hi:[0,1]
	v_pk_fma_f32 v[100:101], v[4:5], v[106:107], v[108:109]
	v_lshlrev_b32_e32 v106, 16, v74
	v_and_b32_e32 v107, 0xffff0000, v74
	v_lshlrev_b32_e32 v108, 16, v66
	v_and_b32_e32 v109, 0xffff0000, v66
	v_pk_mul_f32 v[106:107], v[96:97], v[106:107] op_sel_hi:[0,1]
	v_pk_fma_f32 v[102:103], v[6:7], v[106:107], v[108:109]
	v_lshlrev_b32_e32 v106, 16, v75
	v_and_b32_e32 v107, 0xffff0000, v75
	v_lshlrev_b32_e32 v108, 16, v67
	v_and_b32_e32 v109, 0xffff0000, v67
	v_pk_mul_f32 v[106:107], v[96:97], v[106:107] op_sel_hi:[0,1]
	v_pk_fma_f32 v[104:105], v[8:9], v[106:107], v[108:109]
	v_pk_fma_f32 v[110:111], v[98:99], v[98:99], v[110:111]
	v_pk_fma_f32 v[110:111], v[100:101], v[100:101], v[110:111]
	v_pk_fma_f32 v[110:111], v[102:103], v[102:103], v[110:111]
	v_pk_fma_f32 v[110:111], v[104:105], v[104:105], v[110:111]
	v_cvt_pk_bf16_f32 v64, v98, v99
	v_cvt_pk_bf16_f32 v65, v100, v101
	v_cvt_pk_bf16_f32 v66, v102, v103
	v_cvt_pk_bf16_f32 v67, v104, v105
	global_store_dwordx4 v19, v[64:67], s[4:5] offset:1024
	v_add_f32_e32 v112, v110, v111
	v_add_u32_e32 v22, 0x2000, v22
	s_nop 1
	v_add_f32_dpp v112, v112, v112 quad_perm:[1,0,3,2] row_mask:0xf bank_mask:0xf
	s_nop 1
	v_add_f32_dpp v112, v112, v112 quad_perm:[2,3,0,1] row_mask:0xf bank_mask:0xf
	s_nop 1
	v_add_f32_dpp v112, v112, v112 row_half_mirror row_mask:0xf bank_mask:0xf
	s_nop 1
	v_add_f32_dpp v112, v112, v112 row_mirror row_mask:0xf bank_mask:0xf
	s_nop 1
	v_add_f32_dpp v112, v112, v112 row_bcast:15 row_mask:0xa bank_mask:0xf
	s_nop 1
	v_add_f32_dpp v112, v112, v112 row_bcast:31 row_mask:0xc bank_mask:0xf
	v_fmamk_f32 v113, v112, 0x3a800000, v244
	v_rsq_f32_e32 v113, v113
	s_mov_b64 exec, s[6:7]
	global_store_dword v22, v113, s[4:5]
	s_mov_b64 exec, -1
	v_add_u32_e32 v18, 0x400000, v18
	v_add_u32_e32 v20, 0x400000, v20
	v_add_u32_e32 v21, 0x2000, v21
	global_load_dwordx4 v[60:63], v18, s[4:5]
	global_load_dwordx4 v[68:71], v20, s[4:5]
	global_load_dwordx4 v[64:67], v18, s[4:5] offset:1024
	global_load_dwordx4 v[72:75], v20, s[4:5] offset:1024
	global_load_dword v76, v21, s[4:5]
	s_waitcnt vmcnt(24)
	v_fmamk_f32 v96, v94, 0x3a800000, v244
	v_rsq_f32_e32 v96, v96
	v_add_u32_e32 v19, 0x400000, v19
	v_lshlrev_b32_e32 v106, 16, v86
	v_and_b32_e32 v107, 0xffff0000, v86
	v_lshlrev_b32_e32 v108, 16, v78
	v_and_b32_e32 v109, 0xffff0000, v78
	v_pk_mul_f32 v[106:107], v[96:97], v[106:107] op_sel_hi:[0,1]
	v_pk_fma_f32 v[98:99], v[10:11], v[106:107], v[108:109]
	v_lshlrev_b32_e32 v106, 16, v87
	v_and_b32_e32 v107, 0xffff0000, v87
	v_lshlrev_b32_e32 v108, 16, v79
	v_and_b32_e32 v109, 0xffff0000, v79
	v_pk_mul_f32 v[106:107], v[96:97], v[106:107] op_sel_hi:[0,1]
	v_pk_fma_f32 v[100:101], v[12:13], v[106:107], v[108:109]
	v_lshlrev_b32_e32 v106, 16, v88
	v_and_b32_e32 v107, 0xffff0000, v88
	v_lshlrev_b32_e32 v108, 16, v80
	v_and_b32_e32 v109, 0xffff0000, v80
	v_pk_mul_f32 v[106:107], v[96:97], v[106:107] op_sel_hi:[0,1]
	v_pk_fma_f32 v[102:103], v[14:15], v[106:107], v[108:109]
	v_lshlrev_b32_e32 v106, 16, v89
	v_and_b32_e32 v107, 0xffff0000, v89
	v_lshlrev_b32_e32 v108, 16, v81
	v_and_b32_e32 v109, 0xffff0000, v81
	v_pk_mul_f32 v[106:107], v[96:97], v[106:107] op_sel_hi:[0,1]
	v_pk_fma_f32 v[104:105], v[16:17], v[106:107], v[108:109]
	v_pk_mul_f32 v[110:111], v[98:99], v[98:99]
	v_pk_fma_f32 v[110:111], v[100:101], v[100:101], v[110:111]
	v_pk_fma_f32 v[110:111], v[102:103], v[102:103], v[110:111]
	v_pk_fma_f32 v[110:111], v[104:105], v[104:105], v[110:111]
	v_cvt_pk_bf16_f32 v78, v98, v99
	v_cvt_pk_bf16_f32 v79, v100, v101
	v_cvt_pk_bf16_f32 v80, v102, v103
	v_cvt_pk_bf16_f32 v81, v104, v105
	global_store_dwordx4 v19, v[78:81], s[4:5]
	v_lshlrev_b32_e32 v106, 16, v90
	v_and_b32_e32 v107, 0xffff0000, v90
	v_lshlrev_b32_e32 v108, 16, v82
	v_and_b32_e32 v109, 0xffff0000, v82
	v_pk_mul_f32 v[106:107], v[96:97], v[106:107] op_sel_hi:[0,1]
	v_pk_fma_f32 v[98:99], v[2:3], v[106:107], v[108:109]
	v_lshlrev_b32_e32 v106, 16, v91
	v_and_b32_e32 v107, 0xffff0000, v91
	v_lshlrev_b32_e32 v108, 16, v83
	v_and_b32_e32 v109, 0xffff0000, v83
	v_pk_mul_f32 v[106:107], v[96:97], v[106:107] op_sel_hi:[0,1]
	v_pk_fma_f32 v[100:101], v[4:5], v[106:107], v[108:109]
	v_lshlrev_b32_e32 v106, 16, v92
	v_and_b32_e32 v107, 0xffff0000, v92
	v_lshlrev_b32_e32 v108, 16, v84
	v_and_b32_e32 v109, 0xffff0000, v84
	v_pk_mul_f32 v[106:107], v[96:97], v[106:107] op_sel_hi:[0,1]
	v_pk_fma_f32 v[102:103], v[6:7], v[106:107], v[108:109]
	v_lshlrev_b32_e32 v106, 16, v93
	v_and_b32_e32 v107, 0xffff0000, v93
	v_lshlrev_b32_e32 v108, 16, v85
	v_and_b32_e32 v109, 0xffff0000, v85
	v_pk_mul_f32 v[106:107], v[96:97], v[106:107] op_sel_hi:[0,1]
	v_pk_fma_f32 v[104:105], v[8:9], v[106:107], v[108:109]
	v_pk_fma_f32 v[110:111], v[98:99], v[98:99], v[110:111]
	v_pk_fma_f32 v[110:111], v[100:101], v[100:101], v[110:111]
	v_pk_fma_f32 v[110:111], v[102:103], v[102:103], v[110:111]
	v_pk_fma_f32 v[110:111], v[104:105], v[104:105], v[110:111]
	v_cvt_pk_bf16_f32 v82, v98, v99
	v_cvt_pk_bf16_f32 v83, v100, v101
	v_cvt_pk_bf16_f32 v84, v102, v103
	v_cvt_pk_bf16_f32 v85, v104, v105
	global_store_dwordx4 v19, v[82:85], s[4:5] offset:1024
	v_add_f32_e32 v112, v110, v111
	v_add_u32_e32 v22, 0x2000, v22
	s_nop 1
	v_add_f32_dpp v112, v112, v112 quad_perm:[1,0,3,2] row_mask:0xf bank_mask:0xf
	s_nop 1
	v_add_f32_dpp v112, v112, v112 quad_perm:[2,3,0,1] row_mask:0xf bank_mask:0xf
	s_nop 1
	v_add_f32_dpp v112, v112, v112 row_half_mirror row_mask:0xf bank_mask:0xf
	s_nop 1
	v_add_f32_dpp v112, v112, v112 row_mirror row_mask:0xf bank_mask:0xf
	s_nop 1
	v_add_f32_dpp v112, v112, v112 row_bcast:15 row_mask:0xa bank_mask:0xf
	s_nop 1
	v_add_f32_dpp v112, v112, v112 row_bcast:31 row_mask:0xc bank_mask:0xf
	v_fmamk_f32 v113, v112, 0x3a800000, v244
	v_rsq_f32_e32 v113, v113
	s_mov_b64 exec, s[6:7]
	global_store_dword v22, v113, s[4:5]
	s_mov_b64 exec, -1
	v_add_u32_e32 v18, 0x400000, v18
	v_add_u32_e32 v20, 0x400000, v20
	v_add_u32_e32 v21, 0x2000, v21
	global_load_dwordx4 v[78:81], v18, s[4:5]
	global_load_dwordx4 v[86:89], v20, s[4:5]
	global_load_dwordx4 v[82:85], v18, s[4:5] offset:1024
	global_load_dwordx4 v[90:93], v20, s[4:5] offset:1024
	global_load_dword v94, v21, s[4:5]
	s_waitcnt vmcnt(24)
; __device__ __forceinline__ float bflo(unsigned w) { return __uint_as_float(w << 16); }
; __device__ __forceinline__ float bfhi(unsigned w) { return __uint_as_float(w & 0xffff0000u); }
; __device__ __forceinline__ void resid_rows(bf16_t* R, const bf16_t* Y, const float* ssqY, const float* g, float* rstd_out, float* outf, bool wf32, int row_lo, int row_hi, int yoff, int gw, int NGW, int lane) {
;     ...
;     for (int row0 = row_lo + gw; row0 < row_hi; row0 += RP * NGW) {
;         u32x4 rr[RP][2], oo[RP][2]; float ssv[RP];
; #pragma unroll
;         for (int k = 0; k < RP; ++k) { const int row = row0 + k * NGW; const bool ok = row < row_hi; const int rw = ok ? row : row0;
;             ssv[k] = ssqY[rw];
; #pragma unroll
;             for (int j = 0; j < 2; ++j) { const int c = 8 * lane + 512 * j; rr[k][j] = *(const u32x4*)(R + (size_t)rw * DM + c); oo[k][j] = *(const u32x4*)(Y + (size_t)(rw - yoff) * DM + c); } }
; #pragma unroll
;         for (int k = 0; k < RP; ++k) { const int row = row0 + k * NGW; if (row < row_hi) {
;             const float rs = __builtin_amdgcn_rsqf(ssv[k] * (1.0f / DM) + RMS_EPS); float s = 0.f;
; #pragma unroll
;             for (int j = 0; j < 2; ++j) { const int c = 8 * lane + 512 * j; const u32x4 r = rr[k][j], o = oo[k][j]; const f32x4 ga = gv[j][0], gb = gv[j][1];
;                 f32x4 ya, yb; ya[0] = bflo(r.x) + bflo(o.x) * rs * ga[0]; ya[1] = bfhi(r.x) + bfhi(o.x) * rs * ga[1]; ya[2] = bflo(r.y) + bflo(o.y) * rs * ga[2]; ya[3] = bfhi(r.y) + bfhi(o.y) * rs * ga[3];
;                 yb[0] = bflo(r.z) + bflo(o.z) * rs * gb[0]; yb[1] = bfhi(r.z) + bfhi(o.z) * rs * gb[1]; yb[2] = bflo(r.w) + bflo(o.w) * rs * gb[2]; yb[3] = bfhi(r.w) + bfhi(o.w) * rs * gb[3];
;                 if (wf32) { *(f32x4*)(outf + (size_t)row * DM + c) = ya; *(f32x4*)(outf + (size_t)row * DM + c + 4) = yb; }
;                 s += (ya[0] * ya[0] + ya[1] * ya[1]) + (ya[2] * ya[2] + ya[3] * ya[3]) + (yb[0] * yb[0] + yb[1] * yb[1]) + (yb[2] * yb[2] + yb[3] * yb[3]);
;                 u32x4 w; w.x = pk2(ya[0], ya[1]); w.y = pk2(ya[2], ya[3]); w.z = pk2(yb[0], yb[1]); w.w = pk2(yb[2], yb[3]); *(u32x4*)(R + (size_t)row * DM + c) = w; }
;             s = wave_sum(s); if (lane == 0) rstd_out[row] = __builtin_amdgcn_rsqf(s * (1.0f / DM) + RMS_EPS); } }
	v_fmamk_f32 v96, v40, 0x3a800000, v244
	v_rsq_f32_e32 v96, v96
	v_add_u32_e32 v19, 0x400000, v19
	v_lshlrev_b32_e32 v106, 16, v32
	v_and_b32_e32 v107, 0xffff0000, v32
	v_lshlrev_b32_e32 v108, 16, v24
	v_and_b32_e32 v109, 0xffff0000, v24
	v_pk_mul_f32 v[106:107], v[96:97], v[106:107] op_sel_hi:[0,1]
	v_pk_fma_f32 v[98:99], v[10:11], v[106:107], v[108:109]
	v_lshlrev_b32_e32 v106, 16, v33
	v_and_b32_e32 v107, 0xffff0000, v33
	v_lshlrev_b32_e32 v108, 16, v25
	v_and_b32_e32 v109, 0xffff0000, v25
	v_pk_mul_f32 v[106:107], v[96:97], v[106:107] op_sel_hi:[0,1]
	v_pk_fma_f32 v[100:101], v[12:13], v[106:107], v[108:109]
	v_lshlrev_b32_e32 v106, 16, v34
	v_and_b32_e32 v107, 0xffff0000, v34
	v_lshlrev_b32_e32 v108, 16, v26
	v_and_b32_e32 v109, 0xffff0000, v26
	v_pk_mul_f32 v[106:107], v[96:97], v[106:107] op_sel_hi:[0,1]
	v_pk_fma_f32 v[102:103], v[14:15], v[106:107], v[108:109]
	v_lshlrev_b32_e32 v106, 16, v35
	v_and_b32_e32 v107, 0xffff0000, v35
	v_lshlrev_b32_e32 v108, 16, v27
	v_and_b32_e32 v109, 0xffff0000, v27
	v_pk_mul_f32 v[106:107], v[96:97], v[106:107] op_sel_hi:[0,1]
	v_pk_fma_f32 v[104:105], v[16:17], v[106:107], v[108:109]
	v_pk_mul_f32 v[110:111], v[98:99], v[98:99]
	v_pk_fma_f32 v[110:111], v[100:101], v[100:101], v[110:111]
	v_pk_fma_f32 v[110:111], v[102:103], v[102:103], v[110:111]
	v_pk_fma_f32 v[110:111], v[104:105], v[104:105], v[110:111]
	v_cvt_pk_bf16_f32 v24, v98, v99
	v_cvt_pk_bf16_f32 v25, v100, v101
	v_cvt_pk_bf16_f32 v26, v102, v103
	v_cvt_pk_bf16_f32 v27, v104, v105
	global_store_dwordx4 v19, v[24:27], s[4:5]
	v_lshlrev_b32_e32 v106, 16, v36
	v_and_b32_e32 v107, 0xffff0000, v36
	v_lshlrev_b32_e32 v108, 16, v28
	v_and_b32_e32 v109, 0xffff0000, v28
	v_pk_mul_f32 v[106:107], v[96:97], v[106:107] op_sel_hi:[0,1]
	v_pk_fma_f32 v[98:99], v[2:3], v[106:107], v[108:109]
	v_lshlrev_b32_e32 v106, 16, v37
	v_and_b32_e32 v107, 0xffff0000, v37
	v_lshlrev_b32_e32 v108, 16, v29
	v_and_b32_e32 v109, 0xffff0000, v29
	v_pk_mul_f32 v[106:107], v[96:97], v[106:107] op_sel_hi:[0,1]
	v_pk_fma_f32 v[100:101], v[4:5], v[106:107], v[108:109]
	v_lshlrev_b32_e32 v106, 16, v38
	v_and_b32_e32 v107, 0xffff0000, v38
	v_lshlrev_b32_e32 v108, 16, v30
	v_and_b32_e32 v109, 0xffff0000, v30
	v_pk_mul_f32 v[106:107], v[96:97], v[106:107] op_sel_hi:[0,1]
	v_pk_fma_f32 v[102:103], v[6:7], v[106:107], v[108:109]
	v_lshlrev_b32_e32 v106, 16, v39
	v_and_b32_e32 v107, 0xffff0000, v39
	v_lshlrev_b32_e32 v108, 16, v31
	v_and_b32_e32 v109, 0xffff0000, v31
	v_pk_mul_f32 v[106:107], v[96:97], v[106:107] op_sel_hi:[0,1]
	v_pk_fma_f32 v[104:105], v[8:9], v[106:107], v[108:109]
	v_pk_fma_f32 v[110:111], v[98:99], v[98:99], v[110:111]
	v_pk_fma_f32 v[110:111], v[100:101], v[100:101], v[110:111]
	v_pk_fma_f32 v[110:111], v[102:103], v[102:103], v[110:111]
	v_pk_fma_f32 v[110:111], v[104:105], v[104:105], v[110:111]
	v_cvt_pk_bf16_f32 v28, v98, v99
	v_cvt_pk_bf16_f32 v29, v100, v101
	v_cvt_pk_bf16_f32 v30, v102, v103
	v_cvt_pk_bf16_f32 v31, v104, v105
	global_store_dwordx4 v19, v[28:31], s[4:5] offset:1024
	v_add_f32_e32 v112, v110, v111
	v_add_u32_e32 v22, 0x2000, v22
	s_nop 1
	v_add_f32_dpp v112, v112, v112 quad_perm:[1,0,3,2] row_mask:0xf bank_mask:0xf
	s_nop 1
	v_add_f32_dpp v112, v112, v112 quad_perm:[2,3,0,1] row_mask:0xf bank_mask:0xf
	s_nop 1
	v_add_f32_dpp v112, v112, v112 row_half_mirror row_mask:0xf bank_mask:0xf
	s_nop 1
	v_add_f32_dpp v112, v112, v112 row_mirror row_mask:0xf bank_mask:0xf
	s_nop 1
	v_add_f32_dpp v112, v112, v112 row_bcast:15 row_mask:0xa bank_mask:0xf
	s_nop 1
	v_add_f32_dpp v112, v112, v112 row_bcast:31 row_mask:0xc bank_mask:0xf
	v_fmamk_f32 v113, v112, 0x3a800000, v244
	v_rsq_f32_e32 v113, v113
	s_mov_b64 exec, s[6:7]
	global_store_dword v22, v113, s[4:5]
	s_mov_b64 exec, -1
	v_add_u32_e32 v18, 0x400000, v18
	v_add_u32_e32 v20, 0x400000, v20
	v_add_u32_e32 v21, 0x2000, v21
	global_load_dwordx4 v[24:27], v18, s[4:5]
	global_load_dwordx4 v[32:35], v20, s[4:5]
	global_load_dwordx4 v[28:31], v18, s[4:5] offset:1024
	global_load_dwordx4 v[36:39], v20, s[4:5] offset:1024
	global_load_dword v40, v21, s[4:5]
	s_waitcnt vmcnt(24)
	v_fmamk_f32 v96, v58, 0x3a800000, v244
	v_rsq_f32_e32 v96, v96
	v_add_u32_e32 v19, 0x400000, v19
	v_lshlrev_b32_e32 v106, 16, v50
	v_and_b32_e32 v107, 0xffff0000, v50
	v_lshlrev_b32_e32 v108, 16, v42
	v_and_b32_e32 v109, 0xffff0000, v42
	v_pk_mul_f32 v[106:107], v[96:97], v[106:107] op_sel_hi:[0,1]
	v_pk_fma_f32 v[98:99], v[10:11], v[106:107], v[108:109]
	v_lshlrev_b32_e32 v106, 16, v51
	v_and_b32_e32 v107, 0xffff0000, v51
	v_lshlrev_b32_e32 v108, 16, v43
	v_and_b32_e32 v109, 0xffff0000, v43
	v_pk_mul_f32 v[106:107], v[96:97], v[106:107] op_sel_hi:[0,1]
	v_pk_fma_f32 v[100:101], v[12:13], v[106:107], v[108:109]
	v_lshlrev_b32_e32 v106, 16, v52
	v_and_b32_e32 v107, 0xffff0000, v52
	v_lshlrev_b32_e32 v108, 16, v44
	v_and_b32_e32 v109, 0xffff0000, v44
	v_pk_mul_f32 v[106:107], v[96:97], v[106:107] op_sel_hi:[0,1]
	v_pk_fma_f32 v[102:103], v[14:15], v[106:107], v[108:109]
	v_lshlrev_b32_e32 v106, 16, v53
	v_and_b32_e32 v107, 0xffff0000, v53
	v_lshlrev_b32_e32 v108, 16, v45
	v_and_b32_e32 v109, 0xffff0000, v45
	v_pk_mul_f32 v[106:107], v[96:97], v[106:107] op_sel_hi:[0,1]
	v_pk_fma_f32 v[104:105], v[16:17], v[106:107], v[108:109]
	v_pk_mul_f32 v[110:111], v[98:99], v[98:99]
	v_pk_fma_f32 v[110:111], v[100:101], v[100:101], v[110:111]
	v_pk_fma_f32 v[110:111], v[102:103], v[102:103], v[110:111]
	v_pk_fma_f32 v[110:111], v[104:105], v[104:105], v[110:111]
	v_cvt_pk_bf16_f32 v42, v98, v99
	v_cvt_pk_bf16_f32 v43, v100, v101
	v_cvt_pk_bf16_f32 v44, v102, v103
	v_cvt_pk_bf16_f32 v45, v104, v105
	global_store_dwordx4 v19, v[42:45], s[4:5]
; __device__ __forceinline__ float bflo(unsigned w) { return __uint_as_float(w << 16); }
; __device__ __forceinline__ float bfhi(unsigned w) { return __uint_as_float(w & 0xffff0000u); }
; __device__ __forceinline__ void resid_rows(bf16_t* R, const bf16_t* Y, const float* ssqY, const float* g, float* rstd_out, float* outf, bool wf32, int row_lo, int row_hi, int yoff, int gw, int NGW, int lane) {
;     ...
;     for (int row0 = row_lo + gw; row0 < row_hi; row0 += RP * NGW) {
;         u32x4 rr[RP][2], oo[RP][2]; float ssv[RP];
; #pragma unroll
;         for (int k = 0; k < RP; ++k) { const int row = row0 + k * NGW; const bool ok = row < row_hi; const int rw = ok ? row : row0;
;             ssv[k] = ssqY[rw];
; #pragma unroll
;             for (int j = 0; j < 2; ++j) { const int c = 8 * lane + 512 * j; rr[k][j] = *(const u32x4*)(R + (size_t)rw * DM + c); oo[k][j] = *(const u32x4*)(Y + (size_t)(rw - yoff) * DM + c); } }
; #pragma unroll
;         for (int k = 0; k < RP; ++k) { const int row = row0 + k * NGW; if (row < row_hi) {
;             const float rs = __builtin_amdgcn_rsqf(ssv[k] * (1.0f / DM) + RMS_EPS); float s = 0.f;
; #pragma unroll
;             for (int j = 0; j < 2; ++j) { const int c = 8 * lane + 512 * j; const u32x4 r = rr[k][j], o = oo[k][j]; const f32x4 ga = gv[j][0], gb = gv[j][1];
;                 f32x4 ya, yb; ya[0] = bflo(r.x) + bflo(o.x) * rs * ga[0]; ya[1] = bfhi(r.x) + bfhi(o.x) * rs * ga[1]; ya[2] = bflo(r.y) + bflo(o.y) * rs * ga[2]; ya[3] = bfhi(r.y) + bfhi(o.y) * rs * ga[3];
;                 yb[0] = bflo(r.z) + bflo(o.z) * rs * gb[0]; yb[1] = bfhi(r.z) + bfhi(o.z) * rs * gb[1]; yb[2] = bflo(r.w) + bflo(o.w) * rs * gb[2]; yb[3] = bfhi(r.w) + bfhi(o.w) * rs * gb[3];
;                 if (wf32) { *(f32x4*)(outf + (size_t)row * DM + c) = ya; *(f32x4*)(outf + (size_t)row * DM + c + 4) = yb; }
;                 s += (ya[0] * ya[0] + ya[1] * ya[1]) + (ya[2] * ya[2] + ya[3] * ya[3]) + (yb[0] * yb[0] + yb[1] * yb[1]) + (yb[2] * yb[2] + yb[3] * yb[3]);
;                 u32x4 w; w.x = pk2(ya[0], ya[1]); w.y = pk2(ya[2], ya[3]); w.z = pk2(yb[0], yb[1]); w.w = pk2(yb[2], yb[3]); *(u32x4*)(R + (size_t)row * DM + c) = w; }
;             s = wave_sum(s); if (lane == 0) rstd_out[row] = __builtin_amdgcn_rsqf(s * (1.0f / DM) + RMS_EPS); } }
	v_lshlrev_b32_e32 v106, 16, v54
	v_and_b32_e32 v107, 0xffff0000, v54
	v_lshlrev_b32_e32 v108, 16, v46
	v_and_b32_e32 v109, 0xffff0000, v46
	v_pk_mul_f32 v[106:107], v[96:97], v[106:107] op_sel_hi:[0,1]
	v_pk_fma_f32 v[98:99], v[2:3], v[106:107], v[108:109]
	v_lshlrev_b32_e32 v106, 16, v55
	v_and_b32_e32 v107, 0xffff0000, v55
	v_lshlrev_b32_e32 v108, 16, v47
	v_and_b32_e32 v109, 0xffff0000, v47
	v_pk_mul_f32 v[106:107], v[96:97], v[106:107] op_sel_hi:[0,1]
	v_pk_fma_f32 v[100:101], v[4:5], v[106:107], v[108:109]
	v_lshlrev_b32_e32 v106, 16, v56
	v_and_b32_e32 v107, 0xffff0000, v56
	v_lshlrev_b32_e32 v108, 16, v48
	v_and_b32_e32 v109, 0xffff0000, v48
	v_pk_mul_f32 v[106:107], v[96:97], v[106:107] op_sel_hi:[0,1]
	v_pk_fma_f32 v[102:103], v[6:7], v[106:107], v[108:109]
	v_lshlrev_b32_e32 v106, 16, v57
	v_and_b32_e32 v107, 0xffff0000, v57
	v_lshlrev_b32_e32 v108, 16, v49
	v_and_b32_e32 v109, 0xffff0000, v49
	v_pk_mul_f32 v[106:107], v[96:97], v[106:107] op_sel_hi:[0,1]
	v_pk_fma_f32 v[104:105], v[8:9], v[106:107], v[108:109]
	v_pk_fma_f32 v[110:111], v[98:99], v[98:99], v[110:111]
	v_pk_fma_f32 v[110:111], v[100:101], v[100:101], v[110:111]
	v_pk_fma_f32 v[110:111], v[102:103], v[102:103], v[110:111]
	v_pk_fma_f32 v[110:111], v[104:105], v[104:105], v[110:111]
	v_cvt_pk_bf16_f32 v46, v98, v99
	v_cvt_pk_bf16_f32 v47, v100, v101
	v_cvt_pk_bf16_f32 v48, v102, v103
	v_cvt_pk_bf16_f32 v49, v104, v105
	global_store_dwordx4 v19, v[46:49], s[4:5] offset:1024
	v_add_f32_e32 v112, v110, v111
	v_add_u32_e32 v22, 0x2000, v22
	s_nop 1
	v_add_f32_dpp v112, v112, v112 quad_perm:[1,0,3,2] row_mask:0xf bank_mask:0xf
	s_nop 1
	v_add_f32_dpp v112, v112, v112 quad_perm:[2,3,0,1] row_mask:0xf bank_mask:0xf
	s_nop 1
	v_add_f32_dpp v112, v112, v112 row_half_mirror row_mask:0xf bank_mask:0xf
	s_nop 1
	v_add_f32_dpp v112, v112, v112 row_mirror row_mask:0xf bank_mask:0xf
	s_nop 1
	v_add_f32_dpp v112, v112, v112 row_bcast:15 row_mask:0xa bank_mask:0xf
	s_nop 1
	v_add_f32_dpp v112, v112, v112 row_bcast:31 row_mask:0xc bank_mask:0xf
	v_fmamk_f32 v113, v112, 0x3a800000, v244
	v_rsq_f32_e32 v113, v113
	s_mov_b64 exec, s[6:7]
	global_store_dword v22, v113, s[4:5]
	s_mov_b64 exec, -1
	v_add_u32_e32 v18, 0x400000, v18
	v_add_u32_e32 v20, 0x400000, v20
	v_add_u32_e32 v21, 0x2000, v21
	global_load_dwordx4 v[42:45], v18, s[4:5]
	global_load_dwordx4 v[50:53], v20, s[4:5]
	global_load_dwordx4 v[46:49], v18, s[4:5] offset:1024
	global_load_dwordx4 v[54:57], v20, s[4:5] offset:1024
	global_load_dword v58, v21, s[4:5]
	s_waitcnt vmcnt(24)
	v_fmamk_f32 v96, v76, 0x3a800000, v244
	v_rsq_f32_e32 v96, v96
	v_add_u32_e32 v19, 0x400000, v19
	v_lshlrev_b32_e32 v106, 16, v68
	v_and_b32_e32 v107, 0xffff0000, v68
	v_lshlrev_b32_e32 v108, 16, v60
	v_and_b32_e32 v109, 0xffff0000, v60
	v_pk_mul_f32 v[106:107], v[96:97], v[106:107] op_sel_hi:[0,1]
	v_pk_fma_f32 v[98:99], v[10:11], v[106:107], v[108:109]
	v_lshlrev_b32_e32 v106, 16, v69
	v_and_b32_e32 v107, 0xffff0000, v69
	v_lshlrev_b32_e32 v108, 16, v61
	v_and_b32_e32 v109, 0xffff0000, v61
	v_pk_mul_f32 v[106:107], v[96:97], v[106:107] op_sel_hi:[0,1]
	v_pk_fma_f32 v[100:101], v[12:13], v[106:107], v[108:109]
	v_lshlrev_b32_e32 v106, 16, v70
	v_and_b32_e32 v107, 0xffff0000, v70
	v_lshlrev_b32_e32 v108, 16, v62
	v_and_b32_e32 v109, 0xffff0000, v62
	v_pk_mul_f32 v[106:107], v[96:97], v[106:107] op_sel_hi:[0,1]
	v_pk_fma_f32 v[102:103], v[14:15], v[106:107], v[108:109]
	v_lshlrev_b32_e32 v106, 16, v71
	v_and_b32_e32 v107, 0xffff0000, v71
	v_lshlrev_b32_e32 v108, 16, v63
	v_and_b32_e32 v109, 0xffff0000, v63
	v_pk_mul_f32 v[106:107], v[96:97], v[106:107] op_sel_hi:[0,1]
	v_pk_fma_f32 v[104:105], v[16:17], v[106:107], v[108:109]
	v_pk_mul_f32 v[110:111], v[98:99], v[98:99]
	v_pk_fma_f32 v[110:111], v[100:101], v[100:101], v[110:111]
	v_pk_fma_f32 v[110:111], v[102:103], v[102:103], v[110:111]
	v_pk_fma_f32 v[110:111], v[104:105], v[104:105], v[110:111]
	v_cvt_pk_bf16_f32 v60, v98, v99
	v_cvt_pk_bf16_f32 v61, v100, v101
	v_cvt_pk_bf16_f32 v62, v102, v103
	v_cvt_pk_bf16_f32 v63, v104, v105
	global_store_dwordx4 v19, v[60:63], s[4:5]
	v_lshlrev_b32_e32 v106, 16, v72
	v_and_b32_e32 v107, 0xffff0000, v72
	v_lshlrev_b32_e32 v108, 16, v64
	v_and_b32_e32 v109, 0xffff0000, v64
	v_pk_mul_f32 v[106:107], v[96:97], v[106:107] op_sel_hi:[0,1]
	v_pk_fma_f32 v[98:99], v[2:3], v[106:107], v[108:109]
	v_lshlrev_b32_e32 v106, 16, v73
	v_and_b32_e32 v107, 0xffff0000, v73
	v_lshlrev_b32_e32 v108, 16, v65
	v_and_b32_e32 v109, 0xffff0000, v65
	v_pk_mul_f32 v[106:107], v[96:97], v[106:107] op_sel_hi:[0,1]
	v_pk_fma_f32 v[100:101], v[4:5], v[106:107], v[108:109]
	v_lshlrev_b32_e32 v106, 16, v74
	v_and_b32_e32 v107, 0xffff0000, v74
	v_lshlrev_b32_e32 v108, 16, v66
	v_and_b32_e32 v109, 0xffff0000, v66
	v_pk_mul_f32 v[106:107], v[96:97], v[106:107] op_sel_hi:[0,1]
	v_pk_fma_f32 v[102:103], v[6:7], v[106:107], v[108:109]
	v_lshlrev_b32_e32 v106, 16, v75
	v_and_b32_e32 v107, 0xffff0000, v75
	v_lshlrev_b32_e32 v108, 16, v67
	v_and_b32_e32 v109, 0xffff0000, v67
	v_pk_mul_f32 v[106:107], v[96:97], v[106:107] op_sel_hi:[0,1]
	v_pk_fma_f32 v[104:105], v[8:9], v[106:107], v[108:109]
	v_pk_fma_f32 v[110:111], v[98:99], v[98:99], v[110:111]
	v_pk_fma_f32 v[110:111], v[100:101], v[100:101], v[110:111]
	v_pk_fma_f32 v[110:111], v[102:103], v[102:103], v[110:111]
	v_pk_fma_f32 v[110:111], v[104:105], v[104:105], v[110:111]
	v_cvt_pk_bf16_f32 v64, v98, v99
	v_cvt_pk_bf16_f32 v65, v100, v101
	v_cvt_pk_bf16_f32 v66, v102, v103
	v_cvt_pk_bf16_f32 v67, v104, v105
	global_store_dwordx4 v19, v[64:67], s[4:5] offset:1024
	v_add_f32_e32 v112, v110, v111
	v_add_u32_e32 v22, 0x2000, v22
	s_nop 1
	v_add_f32_dpp v112, v112, v112 quad_perm:[1,0,3,2] row_mask:0xf bank_mask:0xf
	s_nop 1
	v_add_f32_dpp v112, v112, v112 quad_perm:[2,3,0,1] row_mask:0xf bank_mask:0xf
	s_nop 1
	v_add_f32_dpp v112, v112, v112 row_half_mirror row_mask:0xf bank_mask:0xf
	s_nop 1
	v_add_f32_dpp v112, v112, v112 row_mirror row_mask:0xf bank_mask:0xf
	s_nop 1
	v_add_f32_dpp v112, v112, v112 row_bcast:15 row_mask:0xa bank_mask:0xf
	s_nop 1
	v_add_f32_dpp v112, v112, v112 row_bcast:31 row_mask:0xc bank_mask:0xf
	v_fmamk_f32 v113, v112, 0x3a800000, v244
	v_rsq_f32_e32 v113, v113
	s_mov_b64 exec, s[6:7]
	global_store_dword v22, v113, s[4:5]
	s_mov_b64 exec, -1
	v_add_u32_e32 v18, 0x400000, v18
	v_add_u32_e32 v20, 0x400000, v20
	v_add_u32_e32 v21, 0x2000, v21
	global_load_dwordx4 v[60:63], v18, s[4:5]
	global_load_dwordx4 v[68:71], v20, s[4:5]
	global_load_dwordx4 v[64:67], v18, s[4:5] offset:1024
	global_load_dwordx4 v[72:75], v20, s[4:5] offset:1024
	global_load_dword v76, v21, s[4:5]
	s_waitcnt vmcnt(24)
; __device__ __forceinline__ float bflo(unsigned w) { return __uint_as_float(w << 16); }
; __device__ __forceinline__ float bfhi(unsigned w) { return __uint_as_float(w & 0xffff0000u); }
; __device__ __forceinline__ void resid_rows(bf16_t* R, const bf16_t* Y, const float* ssqY, const float* g, float* rstd_out, float* outf, bool wf32, int row_lo, int row_hi, int yoff, int gw, int NGW, int lane) {
;     ...
;         for (int k = 0; k < RP; ++k) { const int row = row0 + k * NGW; if (row < row_hi) {
;             const float rs = __builtin_amdgcn_rsqf(ssv[k] * (1.0f / DM) + RMS_EPS); float s = 0.f;
; #pragma unroll
;             for (int j = 0; j < 2; ++j) { const int c = 8 * lane + 512 * j; const u32x4 r = rr[k][j], o = oo[k][j]; const f32x4 ga = gv[j][0], gb = gv[j][1];
;                 f32x4 ya, yb; ya[0] = bflo(r.x) + bflo(o.x) * rs * ga[0]; ya[1] = bfhi(r.x) + bfhi(o.x) * rs * ga[1]; ya[2] = bflo(r.y) + bflo(o.y) * rs * ga[2]; ya[3] = bfhi(r.y) + bfhi(o.y) * rs * ga[3];
;                 yb[0] = bflo(r.z) + bflo(o.z) * rs * gb[0]; yb[1] = bfhi(r.z) + bfhi(o.z) * rs * gb[1]; yb[2] = bflo(r.w) + bflo(o.w) * rs * gb[2]; yb[3] = bfhi(r.w) + bfhi(o.w) * rs * gb[3];
;                 if (wf32) { *(f32x4*)(outf + (size_t)row * DM + c) = ya; *(f32x4*)(outf + (size_t)row * DM + c + 4) = yb; }
;                 s += (ya[0] * ya[0] + ya[1] * ya[1]) + (ya[2] * ya[2] + ya[3] * ya[3]) + (yb[0] * yb[0] + yb[1] * yb[1]) + (yb[2] * yb[2] + yb[3] * yb[3]);
;                 u32x4 w; w.x = pk2(ya[0], ya[1]); w.y = pk2(ya[2], ya[3]); w.z = pk2(yb[0], yb[1]); w.w = pk2(yb[2], yb[3]); *(u32x4*)(R + (size_t)row * DM + c) = w; }
;             s = wave_sum(s); if (lane == 0) rstd_out[row] = __builtin_amdgcn_rsqf(s * (1.0f / DM) + RMS_EPS); } }
	v_fmamk_f32 v96, v94, 0x3a800000, v244
	v_rsq_f32_e32 v96, v96
	v_add_u32_e32 v19, 0x400000, v19
	v_lshlrev_b32_e32 v106, 16, v86
	v_and_b32_e32 v107, 0xffff0000, v86
	v_lshlrev_b32_e32 v108, 16, v78
	v_and_b32_e32 v109, 0xffff0000, v78
	v_pk_mul_f32 v[106:107], v[96:97], v[106:107] op_sel_hi:[0,1]
	v_pk_fma_f32 v[98:99], v[10:11], v[106:107], v[108:109]
	v_lshlrev_b32_e32 v106, 16, v87
	v_and_b32_e32 v107, 0xffff0000, v87
	v_lshlrev_b32_e32 v108, 16, v79
	v_and_b32_e32 v109, 0xffff0000, v79
	v_pk_mul_f32 v[106:107], v[96:97], v[106:107] op_sel_hi:[0,1]
	v_pk_fma_f32 v[100:101], v[12:13], v[106:107], v[108:109]
	v_lshlrev_b32_e32 v106, 16, v88
	v_and_b32_e32 v107, 0xffff0000, v88
	v_lshlrev_b32_e32 v108, 16, v80
	v_and_b32_e32 v109, 0xffff0000, v80
	v_pk_mul_f32 v[106:107], v[96:97], v[106:107] op_sel_hi:[0,1]
	v_pk_fma_f32 v[102:103], v[14:15], v[106:107], v[108:109]
	v_lshlrev_b32_e32 v106, 16, v89
	v_and_b32_e32 v107, 0xffff0000, v89
	v_lshlrev_b32_e32 v108, 16, v81
	v_and_b32_e32 v109, 0xffff0000, v81
	v_pk_mul_f32 v[106:107], v[96:97], v[106:107] op_sel_hi:[0,1]
	v_pk_fma_f32 v[104:105], v[16:17], v[106:107], v[108:109]
	v_pk_mul_f32 v[110:111], v[98:99], v[98:99]
	v_pk_fma_f32 v[110:111], v[100:101], v[100:101], v[110:111]
	v_pk_fma_f32 v[110:111], v[102:103], v[102:103], v[110:111]
	v_pk_fma_f32 v[110:111], v[104:105], v[104:105], v[110:111]
	v_cvt_pk_bf16_f32 v78, v98, v99
	v_cvt_pk_bf16_f32 v79, v100, v101
	v_cvt_pk_bf16_f32 v80, v102, v103
	v_cvt_pk_bf16_f32 v81, v104, v105
	global_store_dwordx4 v19, v[78:81], s[4:5]
	v_lshlrev_b32_e32 v106, 16, v90
	v_and_b32_e32 v107, 0xffff0000, v90
	v_lshlrev_b32_e32 v108, 16, v82
	v_and_b32_e32 v109, 0xffff0000, v82
	v_pk_mul_f32 v[106:107], v[96:97], v[106:107] op_sel_hi:[0,1]
	v_pk_fma_f32 v[98:99], v[2:3], v[106:107], v[108:109]
	v_lshlrev_b32_e32 v106, 16, v91
	v_and_b32_e32 v107, 0xffff0000, v91
	v_lshlrev_b32_e32 v108, 16, v83
	v_and_b32_e32 v109, 0xffff0000, v83
	v_pk_mul_f32 v[106:107], v[96:97], v[106:107] op_sel_hi:[0,1]
	v_pk_fma_f32 v[100:101], v[4:5], v[106:107], v[108:109]
	v_lshlrev_b32_e32 v106, 16, v92
	v_and_b32_e32 v107, 0xffff0000, v92
	v_lshlrev_b32_e32 v108, 16, v84
	v_and_b32_e32 v109, 0xffff0000, v84
	v_pk_mul_f32 v[106:107], v[96:97], v[106:107] op_sel_hi:[0,1]
	v_pk_fma_f32 v[102:103], v[6:7], v[106:107], v[108:109]
	v_lshlrev_b32_e32 v106, 16, v93
	v_and_b32_e32 v107, 0xffff0000, v93
	v_lshlrev_b32_e32 v108, 16, v85
	v_and_b32_e32 v109, 0xffff0000, v85
	v_pk_mul_f32 v[106:107], v[96:97], v[106:107] op_sel_hi:[0,1]
	v_pk_fma_f32 v[104:105], v[8:9], v[106:107], v[108:109]
	v_pk_fma_f32 v[110:111], v[98:99], v[98:99], v[110:111]
	v_pk_fma_f32 v[110:111], v[100:101], v[100:101], v[110:111]
	v_pk_fma_f32 v[110:111], v[102:103], v[102:103], v[110:111]
	v_pk_fma_f32 v[110:111], v[104:105], v[104:105], v[110:111]
	v_cvt_pk_bf16_f32 v82, v98, v99
	v_cvt_pk_bf16_f32 v83, v100, v101
	v_cvt_pk_bf16_f32 v84, v102, v103
	v_cvt_pk_bf16_f32 v85, v104, v105
	global_store_dwordx4 v19, v[82:85], s[4:5] offset:1024
	v_add_f32_e32 v112, v110, v111
	v_add_u32_e32 v22, 0x2000, v22
	s_nop 1
	v_add_f32_dpp v112, v112, v112 quad_perm:[1,0,3,2] row_mask:0xf bank_mask:0xf
	s_nop 1
	v_add_f32_dpp v112, v112, v112 quad_perm:[2,3,0,1] row_mask:0xf bank_mask:0xf
	s_nop 1
	v_add_f32_dpp v112, v112, v112 row_half_mirror row_mask:0xf bank_mask:0xf
	s_nop 1
	v_add_f32_dpp v112, v112, v112 row_mirror row_mask:0xf bank_mask:0xf
	s_nop 1
	v_add_f32_dpp v112, v112, v112 row_bcast:15 row_mask:0xa bank_mask:0xf
	s_nop 1
	v_add_f32_dpp v112, v112, v112 row_bcast:31 row_mask:0xc bank_mask:0xf
	v_fmamk_f32 v113, v112, 0x3a800000, v244
	v_rsq_f32_e32 v113, v113
	s_mov_b64 exec, s[6:7]
	global_store_dword v22, v113, s[4:5]
	s_mov_b64 exec, -1
	v_add_u32_e32 v18, 0x400000, v18
	v_add_u32_e32 v20, 0x400000, v20
	v_add_u32_e32 v21, 0x2000, v21
	global_load_dwordx4 v[78:81], v18, s[4:5]
	global_load_dwordx4 v[86:89], v20, s[4:5]
	global_load_dwordx4 v[82:85], v18, s[4:5] offset:1024
	global_load_dwordx4 v[90:93], v20, s[4:5] offset:1024
	global_load_dword v94, v21, s[4:5]
	s_waitcnt vmcnt(24)
	v_fmamk_f32 v96, v40, 0x3a800000, v244
	v_rsq_f32_e32 v96, v96
	v_add_u32_e32 v19, 0x400000, v19
	v_lshlrev_b32_e32 v106, 16, v32
	v_and_b32_e32 v107, 0xffff0000, v32
	v_lshlrev_b32_e32 v108, 16, v24
	v_and_b32_e32 v109, 0xffff0000, v24
	v_pk_mul_f32 v[106:107], v[96:97], v[106:107] op_sel_hi:[0,1]
	v_pk_fma_f32 v[98:99], v[10:11], v[106:107], v[108:109]
	v_lshlrev_b32_e32 v106, 16, v33
	v_and_b32_e32 v107, 0xffff0000, v33
	v_lshlrev_b32_e32 v108, 16, v25
	v_and_b32_e32 v109, 0xffff0000, v25
	v_pk_mul_f32 v[106:107], v[96:97], v[106:107] op_sel_hi:[0,1]
	v_pk_fma_f32 v[100:101], v[12:13], v[106:107], v[108:109]
	v_lshlrev_b32_e32 v106, 16, v34
	v_and_b32_e32 v107, 0xffff0000, v34
	v_lshlrev_b32_e32 v108, 16, v26
	v_and_b32_e32 v109, 0xffff0000, v26
	v_pk_mul_f32 v[106:107], v[96:97], v[106:107] op_sel_hi:[0,1]
	v_pk_fma_f32 v[102:103], v[14:15], v[106:107], v[108:109]
	v_lshlrev_b32_e32 v106, 16, v35
	v_and_b32_e32 v107, 0xffff0000, v35
	v_lshlrev_b32_e32 v108, 16, v27
	v_and_b32_e32 v109, 0xffff0000, v27
	v_pk_mul_f32 v[106:107], v[96:97], v[106:107] op_sel_hi:[0,1]
	v_pk_fma_f32 v[104:105], v[16:17], v[106:107], v[108:109]
	v_pk_mul_f32 v[110:111], v[98:99], v[98:99]
	v_pk_fma_f32 v[110:111], v[100:101], v[100:101], v[110:111]
	v_pk_fma_f32 v[110:111], v[102:103], v[102:103], v[110:111]
	v_pk_fma_f32 v[110:111], v[104:105], v[104:105], v[110:111]
	v_cvt_pk_bf16_f32 v24, v98, v99
	v_cvt_pk_bf16_f32 v25, v100, v101
	v_cvt_pk_bf16_f32 v26, v102, v103
	v_cvt_pk_bf16_f32 v27, v104, v105
	global_store_dwordx4 v19, v[24:27], s[4:5]
; __device__ __forceinline__ float bflo(unsigned w) { return __uint_as_float(w << 16); }
; __device__ __forceinline__ float bfhi(unsigned w) { return __uint_as_float(w & 0xffff0000u); }
; __device__ __forceinline__ void resid_rows(bf16_t* R, const bf16_t* Y, const float* ssqY, const float* g, float* rstd_out, float* outf, bool wf32, int row_lo, int row_hi, int yoff, int gw, int NGW, int lane) {
;     ...
;     for (int row0 = row_lo + gw; row0 < row_hi; row0 += RP * NGW) {
;         u32x4 rr[RP][2], oo[RP][2]; float ssv[RP];
; #pragma unroll
;         for (int k = 0; k < RP; ++k) { const int row = row0 + k * NGW; const bool ok = row < row_hi; const int rw = ok ? row : row0;
;             ssv[k] = ssqY[rw];
; #pragma unroll
;             for (int j = 0; j < 2; ++j) { const int c = 8 * lane + 512 * j; rr[k][j] = *(const u32x4*)(R + (size_t)rw * DM + c); oo[k][j] = *(const u32x4*)(Y + (size_t)(rw - yoff) * DM + c); } }
; #pragma unroll
;         for (int k = 0; k < RP; ++k) { const int row = row0 + k * NGW; if (row < row_hi) {
;             const float rs = __builtin_amdgcn_rsqf(ssv[k] * (1.0f / DM) + RMS_EPS); float s = 0.f;
; #pragma unroll
;             for (int j = 0; j < 2; ++j) { const int c = 8 * lane + 512 * j; const u32x4 r = rr[k][j], o = oo[k][j]; const f32x4 ga = gv[j][0], gb = gv[j][1];
;                 f32x4 ya, yb; ya[0] = bflo(r.x) + bflo(o.x) * rs * ga[0]; ya[1] = bfhi(r.x) + bfhi(o.x) * rs * ga[1]; ya[2] = bflo(r.y) + bflo(o.y) * rs * ga[2]; ya[3] = bfhi(r.y) + bfhi(o.y) * rs * ga[3];
;                 yb[0] = bflo(r.z) + bflo(o.z) * rs * gb[0]; yb[1] = bfhi(r.z) + bfhi(o.z) * rs * gb[1]; yb[2] = bflo(r.w) + bflo(o.w) * rs * gb[2]; yb[3] = bfhi(r.w) + bfhi(o.w) * rs * gb[3];
;                 if (wf32) { *(f32x4*)(outf + (size_t)row * DM + c) = ya; *(f32x4*)(outf + (size_t)row * DM + c + 4) = yb; }
;                 s += (ya[0] * ya[0] + ya[1] * ya[1]) + (ya[2] * ya[2] + ya[3] * ya[3]) + (yb[0] * yb[0] + yb[1] * yb[1]) + (yb[2] * yb[2] + yb[3] * yb[3]);
;                 u32x4 w; w.x = pk2(ya[0], ya[1]); w.y = pk2(ya[2], ya[3]); w.z = pk2(yb[0], yb[1]); w.w = pk2(yb[2], yb[3]); *(u32x4*)(R + (size_t)row * DM + c) = w; }
;             s = wave_sum(s); if (lane == 0) rstd_out[row] = __builtin_amdgcn_rsqf(s * (1.0f / DM) + RMS_EPS); } }
	v_lshlrev_b32_e32 v106, 16, v36
	v_and_b32_e32 v107, 0xffff0000, v36
	v_lshlrev_b32_e32 v108, 16, v28
	v_and_b32_e32 v109, 0xffff0000, v28
	v_pk_mul_f32 v[106:107], v[96:97], v[106:107] op_sel_hi:[0,1]
	v_pk_fma_f32 v[98:99], v[2:3], v[106:107], v[108:109]
	v_lshlrev_b32_e32 v106, 16, v37
	v_and_b32_e32 v107, 0xffff0000, v37
	v_lshlrev_b32_e32 v108, 16, v29
	v_and_b32_e32 v109, 0xffff0000, v29
	v_pk_mul_f32 v[106:107], v[96:97], v[106:107] op_sel_hi:[0,1]
	v_pk_fma_f32 v[100:101], v[4:5], v[106:107], v[108:109]
	v_lshlrev_b32_e32 v106, 16, v38
	v_and_b32_e32 v107, 0xffff0000, v38
	v_lshlrev_b32_e32 v108, 16, v30
	v_and_b32_e32 v109, 0xffff0000, v30
	v_pk_mul_f32 v[106:107], v[96:97], v[106:107] op_sel_hi:[0,1]
	v_pk_fma_f32 v[102:103], v[6:7], v[106:107], v[108:109]
	v_lshlrev_b32_e32 v106, 16, v39
	v_and_b32_e32 v107, 0xffff0000, v39
	v_lshlrev_b32_e32 v108, 16, v31
	v_and_b32_e32 v109, 0xffff0000, v31
	v_pk_mul_f32 v[106:107], v[96:97], v[106:107] op_sel_hi:[0,1]
	v_pk_fma_f32 v[104:105], v[8:9], v[106:107], v[108:109]
	v_pk_fma_f32 v[110:111], v[98:99], v[98:99], v[110:111]
	v_pk_fma_f32 v[110:111], v[100:101], v[100:101], v[110:111]
	v_pk_fma_f32 v[110:111], v[102:103], v[102:103], v[110:111]
	v_pk_fma_f32 v[110:111], v[104:105], v[104:105], v[110:111]
	v_cvt_pk_bf16_f32 v28, v98, v99
	v_cvt_pk_bf16_f32 v29, v100, v101
	v_cvt_pk_bf16_f32 v30, v102, v103
	v_cvt_pk_bf16_f32 v31, v104, v105
	global_store_dwordx4 v19, v[28:31], s[4:5] offset:1024
	v_add_f32_e32 v112, v110, v111
	v_add_u32_e32 v22, 0x2000, v22
	s_nop 1
	v_add_f32_dpp v112, v112, v112 quad_perm:[1,0,3,2] row_mask:0xf bank_mask:0xf
	s_nop 1
	v_add_f32_dpp v112, v112, v112 quad_perm:[2,3,0,1] row_mask:0xf bank_mask:0xf
	s_nop 1
	v_add_f32_dpp v112, v112, v112 row_half_mirror row_mask:0xf bank_mask:0xf
	s_nop 1
	v_add_f32_dpp v112, v112, v112 row_mirror row_mask:0xf bank_mask:0xf
	s_nop 1
	v_add_f32_dpp v112, v112, v112 row_bcast:15 row_mask:0xa bank_mask:0xf
	s_nop 1
	v_add_f32_dpp v112, v112, v112 row_bcast:31 row_mask:0xc bank_mask:0xf
	v_fmamk_f32 v113, v112, 0x3a800000, v244
	v_rsq_f32_e32 v113, v113
	s_mov_b64 exec, s[6:7]
	global_store_dword v22, v113, s[4:5]
	s_mov_b64 exec, -1
	v_add_u32_e32 v18, 0x400000, v18
	v_add_u32_e32 v20, 0x400000, v20
	v_add_u32_e32 v21, 0x2000, v21
	global_load_dwordx4 v[24:27], v18, s[4:5]
	global_load_dwordx4 v[32:35], v20, s[4:5]
	global_load_dwordx4 v[28:31], v18, s[4:5] offset:1024
	global_load_dwordx4 v[36:39], v20, s[4:5] offset:1024
	global_load_dword v40, v21, s[4:5]
	s_waitcnt vmcnt(24)
	v_fmamk_f32 v96, v58, 0x3a800000, v244
	v_rsq_f32_e32 v96, v96
	v_add_u32_e32 v19, 0x400000, v19
	v_lshlrev_b32_e32 v106, 16, v50
	v_and_b32_e32 v107, 0xffff0000, v50
	v_lshlrev_b32_e32 v108, 16, v42
	v_and_b32_e32 v109, 0xffff0000, v42
	v_pk_mul_f32 v[106:107], v[96:97], v[106:107] op_sel_hi:[0,1]
	v_pk_fma_f32 v[98:99], v[10:11], v[106:107], v[108:109]
	v_lshlrev_b32_e32 v106, 16, v51
	v_and_b32_e32 v107, 0xffff0000, v51
	v_lshlrev_b32_e32 v108, 16, v43
	v_and_b32_e32 v109, 0xffff0000, v43
	v_pk_mul_f32 v[106:107], v[96:97], v[106:107] op_sel_hi:[0,1]
	v_pk_fma_f32 v[100:101], v[12:13], v[106:107], v[108:109]
	v_lshlrev_b32_e32 v106, 16, v52
	v_and_b32_e32 v107, 0xffff0000, v52
	v_lshlrev_b32_e32 v108, 16, v44
	v_and_b32_e32 v109, 0xffff0000, v44
	v_pk_mul_f32 v[106:107], v[96:97], v[106:107] op_sel_hi:[0,1]
	v_pk_fma_f32 v[102:103], v[14:15], v[106:107], v[108:109]
	v_lshlrev_b32_e32 v106, 16, v53
	v_and_b32_e32 v107, 0xffff0000, v53
	v_lshlrev_b32_e32 v108, 16, v45
	v_and_b32_e32 v109, 0xffff0000, v45
	v_pk_mul_f32 v[106:107], v[96:97], v[106:107] op_sel_hi:[0,1]
	v_pk_fma_f32 v[104:105], v[16:17], v[106:107], v[108:109]
	v_pk_mul_f32 v[110:111], v[98:99], v[98:99]
	v_pk_fma_f32 v[110:111], v[100:101], v[100:101], v[110:111]
	v_pk_fma_f32 v[110:111], v[102:103], v[102:103], v[110:111]
	v_pk_fma_f32 v[110:111], v[104:105], v[104:105], v[110:111]
	v_cvt_pk_bf16_f32 v42, v98, v99
	v_cvt_pk_bf16_f32 v43, v100, v101
	v_cvt_pk_bf16_f32 v44, v102, v103
	v_cvt_pk_bf16_f32 v45, v104, v105
	global_store_dwordx4 v19, v[42:45], s[4:5]
	v_lshlrev_b32_e32 v106, 16, v54
	v_and_b32_e32 v107, 0xffff0000, v54
	v_lshlrev_b32_e32 v108, 16, v46
	v_and_b32_e32 v109, 0xffff0000, v46
	v_pk_mul_f32 v[106:107], v[96:97], v[106:107] op_sel_hi:[0,1]
	v_pk_fma_f32 v[98:99], v[2:3], v[106:107], v[108:109]
	v_lshlrev_b32_e32 v106, 16, v55
	v_and_b32_e32 v107, 0xffff0000, v55
	v_lshlrev_b32_e32 v108, 16, v47
	v_and_b32_e32 v109, 0xffff0000, v47
	v_pk_mul_f32 v[106:107], v[96:97], v[106:107] op_sel_hi:[0,1]
	v_pk_fma_f32 v[100:101], v[4:5], v[106:107], v[108:109]
	v_lshlrev_b32_e32 v106, 16, v56
	v_and_b32_e32 v107, 0xffff0000, v56
	v_lshlrev_b32_e32 v108, 16, v48
	v_and_b32_e32 v109, 0xffff0000, v48
	v_pk_mul_f32 v[106:107], v[96:97], v[106:107] op_sel_hi:[0,1]
	v_pk_fma_f32 v[102:103], v[6:7], v[106:107], v[108:109]
	v_lshlrev_b32_e32 v106, 16, v57
	v_and_b32_e32 v107, 0xffff0000, v57
	v_lshlrev_b32_e32 v108, 16, v49
	v_and_b32_e32 v109, 0xffff0000, v49
	v_pk_mul_f32 v[106:107], v[96:97], v[106:107] op_sel_hi:[0,1]
	v_pk_fma_f32 v[104:105], v[8:9], v[106:107], v[108:109]
	v_pk_fma_f32 v[110:111], v[98:99], v[98:99], v[110:111]
	v_pk_fma_f32 v[110:111], v[100:101], v[100:101], v[110:111]
	v_pk_fma_f32 v[110:111], v[102:103], v[102:103], v[110:111]
	v_pk_fma_f32 v[110:111], v[104:105], v[104:105], v[110:111]
	v_cvt_pk_bf16_f32 v46, v98, v99
	v_cvt_pk_bf16_f32 v47, v100, v101
	v_cvt_pk_bf16_f32 v48, v102, v103
	v_cvt_pk_bf16_f32 v49, v104, v105
	global_store_dwordx4 v19, v[46:49], s[4:5] offset:1024
	v_add_f32_e32 v112, v110, v111
	v_add_u32_e32 v22, 0x2000, v22
	s_nop 1
	v_add_f32_dpp v112, v112, v112 quad_perm:[1,0,3,2] row_mask:0xf bank_mask:0xf
	s_nop 1
	v_add_f32_dpp v112, v112, v112 quad_perm:[2,3,0,1] row_mask:0xf bank_mask:0xf
	s_nop 1
	v_add_f32_dpp v112, v112, v112 row_half_mirror row_mask:0xf bank_mask:0xf
	s_nop 1
	v_add_f32_dpp v112, v112, v112 row_mirror row_mask:0xf bank_mask:0xf
	s_nop 1
	v_add_f32_dpp v112, v112, v112 row_bcast:15 row_mask:0xa bank_mask:0xf
	s_nop 1
	v_add_f32_dpp v112, v112, v112 row_bcast:31 row_mask:0xc bank_mask:0xf
	v_fmamk_f32 v113, v112, 0x3a800000, v244
	v_rsq_f32_e32 v113, v113
	s_mov_b64 exec, s[6:7]
	global_store_dword v22, v113, s[4:5]
	s_mov_b64 exec, -1
	v_add_u32_e32 v18, 0x400000, v18
	v_add_u32_e32 v20, 0x400000, v20
	v_add_u32_e32 v21, 0x2000, v21
	global_load_dwordx4 v[42:45], v18, s[4:5]
	global_load_dwordx4 v[50:53], v20, s[4:5]
	global_load_dwordx4 v[46:49], v18, s[4:5] offset:1024
	global_load_dwordx4 v[54:57], v20, s[4:5] offset:1024
	global_load_dword v58, v21, s[4:5]
	s_waitcnt vmcnt(24)
; __device__ __forceinline__ float bflo(unsigned w) { return __uint_as_float(w << 16); }
; __device__ __forceinline__ float bfhi(unsigned w) { return __uint_as_float(w & 0xffff0000u); }
; __device__ __forceinline__ void resid_rows(bf16_t* R, const bf16_t* Y, const float* ssqY, const float* g, float* rstd_out, float* outf, bool wf32, int row_lo, int row_hi, int yoff, int gw, int NGW, int lane) {
;     ...
;     for (int row0 = row_lo + gw; row0 < row_hi; row0 += RP * NGW) {
;         u32x4 rr[RP][2], oo[RP][2]; float ssv[RP];
; #pragma unroll
;         for (int k = 0; k < RP; ++k) { const int row = row0 + k * NGW; const bool ok = row < row_hi; const int rw = ok ? row : row0;
;             ssv[k] = ssqY[rw];
; #pragma unroll
;             for (int j = 0; j < 2; ++j) { const int c = 8 * lane + 512 * j; rr[k][j] = *(const u32x4*)(R + (size_t)rw * DM + c); oo[k][j] = *(const u32x4*)(Y + (size_t)(rw - yoff) * DM + c); } }
; #pragma unroll
;         for (int k = 0; k < RP; ++k) { const int row = row0 + k * NGW; if (row < row_hi) {
;             const float rs = __builtin_amdgcn_rsqf(ssv[k] * (1.0f / DM) + RMS_EPS); float s = 0.f;
; #pragma unroll
;             for (int j = 0; j < 2; ++j) { const int c = 8 * lane + 512 * j; const u32x4 r = rr[k][j], o = oo[k][j]; const f32x4 ga = gv[j][0], gb = gv[j][1];
;                 f32x4 ya, yb; ya[0] = bflo(r.x) + bflo(o.x) * rs * ga[0]; ya[1] = bfhi(r.x) + bfhi(o.x) * rs * ga[1]; ya[2] = bflo(r.y) + bflo(o.y) * rs * ga[2]; ya[3] = bfhi(r.y) + bfhi(o.y) * rs * ga[3];
;                 yb[0] = bflo(r.z) + bflo(o.z) * rs * gb[0]; yb[1] = bfhi(r.z) + bfhi(o.z) * rs * gb[1]; yb[2] = bflo(r.w) + bflo(o.w) * rs * gb[2]; yb[3] = bfhi(r.w) + bfhi(o.w) * rs * gb[3];
;                 if (wf32) { *(f32x4*)(outf + (size_t)row * DM + c) = ya; *(f32x4*)(outf + (size_t)row * DM + c + 4) = yb; }
;                 s += (ya[0] * ya[0] + ya[1] * ya[1]) + (ya[2] * ya[2] + ya[3] * ya[3]) + (yb[0] * yb[0] + yb[1] * yb[1]) + (yb[2] * yb[2] + yb[3] * yb[3]);
;                 u32x4 w; w.x = pk2(ya[0], ya[1]); w.y = pk2(ya[2], ya[3]); w.z = pk2(yb[0], yb[1]); w.w = pk2(yb[2], yb[3]); *(u32x4*)(R + (size_t)row * DM + c) = w; }
;             s = wave_sum(s); if (lane == 0) rstd_out[row] = __builtin_amdgcn_rsqf(s * (1.0f / DM) + RMS_EPS); } }
	v_fmamk_f32 v96, v76, 0x3a800000, v244
	v_rsq_f32_e32 v96, v96
	v_add_u32_e32 v19, 0x400000, v19
	v_lshlrev_b32_e32 v106, 16, v68
	v_and_b32_e32 v107, 0xffff0000, v68
	v_lshlrev_b32_e32 v108, 16, v60
	v_and_b32_e32 v109, 0xffff0000, v60
	v_pk_mul_f32 v[106:107], v[96:97], v[106:107] op_sel_hi:[0,1]
	v_pk_fma_f32 v[98:99], v[10:11], v[106:107], v[108:109]
	v_lshlrev_b32_e32 v106, 16, v69
	v_and_b32_e32 v107, 0xffff0000, v69
	v_lshlrev_b32_e32 v108, 16, v61
	v_and_b32_e32 v109, 0xffff0000, v61
	v_pk_mul_f32 v[106:107], v[96:97], v[106:107] op_sel_hi:[0,1]
	v_pk_fma_f32 v[100:101], v[12:13], v[106:107], v[108:109]
	v_lshlrev_b32_e32 v106, 16, v70
	v_and_b32_e32 v107, 0xffff0000, v70
	v_lshlrev_b32_e32 v108, 16, v62
	v_and_b32_e32 v109, 0xffff0000, v62
	v_pk_mul_f32 v[106:107], v[96:97], v[106:107] op_sel_hi:[0,1]
	v_pk_fma_f32 v[102:103], v[14:15], v[106:107], v[108:109]
	v_lshlrev_b32_e32 v106, 16, v71
	v_and_b32_e32 v107, 0xffff0000, v71
	v_lshlrev_b32_e32 v108, 16, v63
	v_and_b32_e32 v109, 0xffff0000, v63
	v_pk_mul_f32 v[106:107], v[96:97], v[106:107] op_sel_hi:[0,1]
	v_pk_fma_f32 v[104:105], v[16:17], v[106:107], v[108:109]
	v_pk_mul_f32 v[110:111], v[98:99], v[98:99]
	v_pk_fma_f32 v[110:111], v[100:101], v[100:101], v[110:111]
	v_pk_fma_f32 v[110:111], v[102:103], v[102:103], v[110:111]
	v_pk_fma_f32 v[110:111], v[104:105], v[104:105], v[110:111]
	v_cvt_pk_bf16_f32 v60, v98, v99
	v_cvt_pk_bf16_f32 v61, v100, v101
	v_cvt_pk_bf16_f32 v62, v102, v103
	v_cvt_pk_bf16_f32 v63, v104, v105
	global_store_dwordx4 v19, v[60:63], s[4:5]
	v_lshlrev_b32_e32 v106, 16, v72
	v_and_b32_e32 v107, 0xffff0000, v72
	v_lshlrev_b32_e32 v108, 16, v64
	v_and_b32_e32 v109, 0xffff0000, v64
	v_pk_mul_f32 v[106:107], v[96:97], v[106:107] op_sel_hi:[0,1]
	v_pk_fma_f32 v[98:99], v[2:3], v[106:107], v[108:109]
	v_lshlrev_b32_e32 v106, 16, v73
	v_and_b32_e32 v107, 0xffff0000, v73
	v_lshlrev_b32_e32 v108, 16, v65
	v_and_b32_e32 v109, 0xffff0000, v65
	v_pk_mul_f32 v[106:107], v[96:97], v[106:107] op_sel_hi:[0,1]
	v_pk_fma_f32 v[100:101], v[4:5], v[106:107], v[108:109]
	v_lshlrev_b32_e32 v106, 16, v74
	v_and_b32_e32 v107, 0xffff0000, v74
	v_lshlrev_b32_e32 v108, 16, v66
	v_and_b32_e32 v109, 0xffff0000, v66
	v_pk_mul_f32 v[106:107], v[96:97], v[106:107] op_sel_hi:[0,1]
	v_pk_fma_f32 v[102:103], v[6:7], v[106:107], v[108:109]
	v_lshlrev_b32_e32 v106, 16, v75
	v_and_b32_e32 v107, 0xffff0000, v75
	v_lshlrev_b32_e32 v108, 16, v67
	v_and_b32_e32 v109, 0xffff0000, v67
	v_pk_mul_f32 v[106:107], v[96:97], v[106:107] op_sel_hi:[0,1]
	v_pk_fma_f32 v[104:105], v[8:9], v[106:107], v[108:109]
	v_pk_fma_f32 v[110:111], v[98:99], v[98:99], v[110:111]
	v_pk_fma_f32 v[110:111], v[100:101], v[100:101], v[110:111]
	v_pk_fma_f32 v[110:111], v[102:103], v[102:103], v[110:111]
	v_pk_fma_f32 v[110:111], v[104:105], v[104:105], v[110:111]
	v_cvt_pk_bf16_f32 v64, v98, v99
	v_cvt_pk_bf16_f32 v65, v100, v101
	v_cvt_pk_bf16_f32 v66, v102, v103
	v_cvt_pk_bf16_f32 v67, v104, v105
	global_store_dwordx4 v19, v[64:67], s[4:5] offset:1024
	v_add_f32_e32 v112, v110, v111
	v_add_u32_e32 v22, 0x2000, v22
	s_nop 1
	v_add_f32_dpp v112, v112, v112 quad_perm:[1,0,3,2] row_mask:0xf bank_mask:0xf
	s_nop 1
	v_add_f32_dpp v112, v112, v112 quad_perm:[2,3,0,1] row_mask:0xf bank_mask:0xf
	s_nop 1
	v_add_f32_dpp v112, v112, v112 row_half_mirror row_mask:0xf bank_mask:0xf
	s_nop 1
	v_add_f32_dpp v112, v112, v112 row_mirror row_mask:0xf bank_mask:0xf
	s_nop 1
	v_add_f32_dpp v112, v112, v112 row_bcast:15 row_mask:0xa bank_mask:0xf
	s_nop 1
	v_add_f32_dpp v112, v112, v112 row_bcast:31 row_mask:0xc bank_mask:0xf
	v_fmamk_f32 v113, v112, 0x3a800000, v244
	v_rsq_f32_e32 v113, v113
	s_mov_b64 exec, s[6:7]
	global_store_dword v22, v113, s[4:5]
	s_mov_b64 exec, -1
	v_add_u32_e32 v18, 0x400000, v18
	v_add_u32_e32 v20, 0x400000, v20
	v_add_u32_e32 v21, 0x2000, v21
	global_load_dwordx4 v[60:63], v18, s[4:5]
	global_load_dwordx4 v[68:71], v20, s[4:5]
	global_load_dwordx4 v[64:67], v18, s[4:5] offset:1024
	global_load_dwordx4 v[72:75], v20, s[4:5] offset:1024
	global_load_dword v76, v21, s[4:5]
	s_waitcnt vmcnt(24)
	v_fmamk_f32 v96, v94, 0x3a800000, v244
	v_rsq_f32_e32 v96, v96
	v_add_u32_e32 v19, 0x400000, v19
	v_lshlrev_b32_e32 v106, 16, v86
	v_and_b32_e32 v107, 0xffff0000, v86
	v_lshlrev_b32_e32 v108, 16, v78
	v_and_b32_e32 v109, 0xffff0000, v78
	v_pk_mul_f32 v[106:107], v[96:97], v[106:107] op_sel_hi:[0,1]
	v_pk_fma_f32 v[98:99], v[10:11], v[106:107], v[108:109]
	v_lshlrev_b32_e32 v106, 16, v87
	v_and_b32_e32 v107, 0xffff0000, v87
	v_lshlrev_b32_e32 v108, 16, v79
	v_and_b32_e32 v109, 0xffff0000, v79
	v_pk_mul_f32 v[106:107], v[96:97], v[106:107] op_sel_hi:[0,1]
	v_pk_fma_f32 v[100:101], v[12:13], v[106:107], v[108:109]
	v_lshlrev_b32_e32 v106, 16, v88
	v_and_b32_e32 v107, 0xffff0000, v88
	v_lshlrev_b32_e32 v108, 16, v80
	v_and_b32_e32 v109, 0xffff0000, v80
	v_pk_mul_f32 v[106:107], v[96:97], v[106:107] op_sel_hi:[0,1]
	v_pk_fma_f32 v[102:103], v[14:15], v[106:107], v[108:109]
	v_lshlrev_b32_e32 v106, 16, v89
	v_and_b32_e32 v107, 0xffff0000, v89
	v_lshlrev_b32_e32 v108, 16, v81
	v_and_b32_e32 v109, 0xffff0000, v81
	v_pk_mul_f32 v[106:107], v[96:97], v[106:107] op_sel_hi:[0,1]
	v_pk_fma_f32 v[104:105], v[16:17], v[106:107], v[108:109]
	v_pk_mul_f32 v[110:111], v[98:99], v[98:99]
	v_pk_fma_f32 v[110:111], v[100:101], v[100:101], v[110:111]
	v_pk_fma_f32 v[110:111], v[102:103], v[102:103], v[110:111]
	v_pk_fma_f32 v[110:111], v[104:105], v[104:105], v[110:111]
	v_cvt_pk_bf16_f32 v78, v98, v99
	v_cvt_pk_bf16_f32 v79, v100, v101
	v_cvt_pk_bf16_f32 v80, v102, v103
	v_cvt_pk_bf16_f32 v81, v104, v105
	global_store_dwordx4 v19, v[78:81], s[4:5]
; __device__ __forceinline__ float bflo(unsigned w) { return __uint_as_float(w << 16); }
; __device__ __forceinline__ float bfhi(unsigned w) { return __uint_as_float(w & 0xffff0000u); }
; __device__ __forceinline__ void resid_rows(bf16_t* R, const bf16_t* Y, const float* ssqY, const float* g, float* rstd_out, float* outf, bool wf32, int row_lo, int row_hi, int yoff, int gw, int NGW, int lane) {
;     ...
;     for (int row0 = row_lo + gw; row0 < row_hi; row0 += RP * NGW) {
;         u32x4 rr[RP][2], oo[RP][2]; float ssv[RP];
; #pragma unroll
;         for (int k = 0; k < RP; ++k) { const int row = row0 + k * NGW; const bool ok = row < row_hi; const int rw = ok ? row : row0;
;             ssv[k] = ssqY[rw];
; #pragma unroll
;             for (int j = 0; j < 2; ++j) { const int c = 8 * lane + 512 * j; rr[k][j] = *(const u32x4*)(R + (size_t)rw * DM + c); oo[k][j] = *(const u32x4*)(Y + (size_t)(rw - yoff) * DM + c); } }
; #pragma unroll
;         for (int k = 0; k < RP; ++k) { const int row = row0 + k * NGW; if (row < row_hi) {
;             const float rs = __builtin_amdgcn_rsqf(ssv[k] * (1.0f / DM) + RMS_EPS); float s = 0.f;
; #pragma unroll
;             for (int j = 0; j < 2; ++j) { const int c = 8 * lane + 512 * j; const u32x4 r = rr[k][j], o = oo[k][j]; const f32x4 ga = gv[j][0], gb = gv[j][1];
;                 f32x4 ya, yb; ya[0] = bflo(r.x) + bflo(o.x) * rs * ga[0]; ya[1] = bfhi(r.x) + bfhi(o.x) * rs * ga[1]; ya[2] = bflo(r.y) + bflo(o.y) * rs * ga[2]; ya[3] = bfhi(r.y) + bfhi(o.y) * rs * ga[3];
;                 yb[0] = bflo(r.z) + bflo(o.z) * rs * gb[0]; yb[1] = bfhi(r.z) + bfhi(o.z) * rs * gb[1]; yb[2] = bflo(r.w) + bflo(o.w) * rs * gb[2]; yb[3] = bfhi(r.w) + bfhi(o.w) * rs * gb[3];
;                 if (wf32) { *(f32x4*)(outf + (size_t)row * DM + c) = ya; *(f32x4*)(outf + (size_t)row * DM + c + 4) = yb; }
;                 s += (ya[0] * ya[0] + ya[1] * ya[1]) + (ya[2] * ya[2] + ya[3] * ya[3]) + (yb[0] * yb[0] + yb[1] * yb[1]) + (yb[2] * yb[2] + yb[3] * yb[3]);
;                 u32x4 w; w.x = pk2(ya[0], ya[1]); w.y = pk2(ya[2], ya[3]); w.z = pk2(yb[0], yb[1]); w.w = pk2(yb[2], yb[3]); *(u32x4*)(R + (size_t)row * DM + c) = w; }
;             s = wave_sum(s); if (lane == 0) rstd_out[row] = __builtin_amdgcn_rsqf(s * (1.0f / DM) + RMS_EPS); } }
	v_lshlrev_b32_e32 v106, 16, v90
	v_and_b32_e32 v107, 0xffff0000, v90
	v_lshlrev_b32_e32 v108, 16, v82
	v_and_b32_e32 v109, 0xffff0000, v82
	v_pk_mul_f32 v[106:107], v[96:97], v[106:107] op_sel_hi:[0,1]
	v_pk_fma_f32 v[98:99], v[2:3], v[106:107], v[108:109]
	v_lshlrev_b32_e32 v106, 16, v91
	v_and_b32_e32 v107, 0xffff0000, v91
	v_lshlrev_b32_e32 v108, 16, v83
	v_and_b32_e32 v109, 0xffff0000, v83
	v_pk_mul_f32 v[106:107], v[96:97], v[106:107] op_sel_hi:[0,1]
	v_pk_fma_f32 v[100:101], v[4:5], v[106:107], v[108:109]
	v_lshlrev_b32_e32 v106, 16, v92
	v_and_b32_e32 v107, 0xffff0000, v92
	v_lshlrev_b32_e32 v108, 16, v84
	v_and_b32_e32 v109, 0xffff0000, v84
	v_pk_mul_f32 v[106:107], v[96:97], v[106:107] op_sel_hi:[0,1]
	v_pk_fma_f32 v[102:103], v[6:7], v[106:107], v[108:109]
	v_lshlrev_b32_e32 v106, 16, v93
	v_and_b32_e32 v107, 0xffff0000, v93
	v_lshlrev_b32_e32 v108, 16, v85
	v_and_b32_e32 v109, 0xffff0000, v85
	v_pk_mul_f32 v[106:107], v[96:97], v[106:107] op_sel_hi:[0,1]
	v_pk_fma_f32 v[104:105], v[8:9], v[106:107], v[108:109]
	v_pk_fma_f32 v[110:111], v[98:99], v[98:99], v[110:111]
	v_pk_fma_f32 v[110:111], v[100:101], v[100:101], v[110:111]
	v_pk_fma_f32 v[110:111], v[102:103], v[102:103], v[110:111]
	v_pk_fma_f32 v[110:111], v[104:105], v[104:105], v[110:111]
	v_cvt_pk_bf16_f32 v82, v98, v99
	v_cvt_pk_bf16_f32 v83, v100, v101
	v_cvt_pk_bf16_f32 v84, v102, v103
	v_cvt_pk_bf16_f32 v85, v104, v105
	global_store_dwordx4 v19, v[82:85], s[4:5] offset:1024
	v_add_f32_e32 v112, v110, v111
	v_add_u32_e32 v22, 0x2000, v22
	s_nop 1
	v_add_f32_dpp v112, v112, v112 quad_perm:[1,0,3,2] row_mask:0xf bank_mask:0xf
	s_nop 1
	v_add_f32_dpp v112, v112, v112 quad_perm:[2,3,0,1] row_mask:0xf bank_mask:0xf
	s_nop 1
	v_add_f32_dpp v112, v112, v112 row_half_mirror row_mask:0xf bank_mask:0xf
	s_nop 1
	v_add_f32_dpp v112, v112, v112 row_mirror row_mask:0xf bank_mask:0xf
	s_nop 1
	v_add_f32_dpp v112, v112, v112 row_bcast:15 row_mask:0xa bank_mask:0xf
	s_nop 1
	v_add_f32_dpp v112, v112, v112 row_bcast:31 row_mask:0xc bank_mask:0xf
	v_fmamk_f32 v113, v112, 0x3a800000, v244
	v_rsq_f32_e32 v113, v113
	s_mov_b64 exec, s[6:7]
	global_store_dword v22, v113, s[4:5]
	s_mov_b64 exec, -1
	v_add_u32_e32 v18, 0x400000, v18
	v_add_u32_e32 v20, 0x400000, v20
	v_add_u32_e32 v21, 0x2000, v21
	global_load_dwordx4 v[78:81], v18, s[4:5]
	global_load_dwordx4 v[86:89], v20, s[4:5]
	global_load_dwordx4 v[82:85], v18, s[4:5] offset:1024
	global_load_dwordx4 v[90:93], v20, s[4:5] offset:1024
	global_load_dword v94, v21, s[4:5]
	s_waitcnt vmcnt(24)
	v_fmamk_f32 v96, v40, 0x3a800000, v244
	v_rsq_f32_e32 v96, v96
	v_add_u32_e32 v19, 0x400000, v19
	v_lshlrev_b32_e32 v106, 16, v32
	v_and_b32_e32 v107, 0xffff0000, v32
	v_lshlrev_b32_e32 v108, 16, v24
	v_and_b32_e32 v109, 0xffff0000, v24
	v_pk_mul_f32 v[106:107], v[96:97], v[106:107] op_sel_hi:[0,1]
	v_pk_fma_f32 v[98:99], v[10:11], v[106:107], v[108:109]
	v_lshlrev_b32_e32 v106, 16, v33
	v_and_b32_e32 v107, 0xffff0000, v33
	v_lshlrev_b32_e32 v108, 16, v25
	v_and_b32_e32 v109, 0xffff0000, v25
	v_pk_mul_f32 v[106:107], v[96:97], v[106:107] op_sel_hi:[0,1]
	v_pk_fma_f32 v[100:101], v[12:13], v[106:107], v[108:109]
	v_lshlrev_b32_e32 v106, 16, v34
	v_and_b32_e32 v107, 0xffff0000, v34
	v_lshlrev_b32_e32 v108, 16, v26
	v_and_b32_e32 v109, 0xffff0000, v26
	v_pk_mul_f32 v[106:107], v[96:97], v[106:107] op_sel_hi:[0,1]
	v_pk_fma_f32 v[102:103], v[14:15], v[106:107], v[108:109]
	v_lshlrev_b32_e32 v106, 16, v35
	v_and_b32_e32 v107, 0xffff0000, v35
	v_lshlrev_b32_e32 v108, 16, v27
	v_and_b32_e32 v109, 0xffff0000, v27
	v_pk_mul_f32 v[106:107], v[96:97], v[106:107] op_sel_hi:[0,1]
	v_pk_fma_f32 v[104:105], v[16:17], v[106:107], v[108:109]
	v_pk_mul_f32 v[110:111], v[98:99], v[98:99]
	v_pk_fma_f32 v[110:111], v[100:101], v[100:101], v[110:111]
	v_pk_fma_f32 v[110:111], v[102:103], v[102:103], v[110:111]
	v_pk_fma_f32 v[110:111], v[104:105], v[104:105], v[110:111]
	v_cvt_pk_bf16_f32 v24, v98, v99
	v_cvt_pk_bf16_f32 v25, v100, v101
	v_cvt_pk_bf16_f32 v26, v102, v103
	v_cvt_pk_bf16_f32 v27, v104, v105
	global_store_dwordx4 v19, v[24:27], s[4:5]
	v_lshlrev_b32_e32 v106, 16, v36
	v_and_b32_e32 v107, 0xffff0000, v36
	v_lshlrev_b32_e32 v108, 16, v28
	v_and_b32_e32 v109, 0xffff0000, v28
	v_pk_mul_f32 v[106:107], v[96:97], v[106:107] op_sel_hi:[0,1]
	v_pk_fma_f32 v[98:99], v[2:3], v[106:107], v[108:109]
	v_lshlrev_b32_e32 v106, 16, v37
	v_and_b32_e32 v107, 0xffff0000, v37
	v_lshlrev_b32_e32 v108, 16, v29
	v_and_b32_e32 v109, 0xffff0000, v29
	v_pk_mul_f32 v[106:107], v[96:97], v[106:107] op_sel_hi:[0,1]
	v_pk_fma_f32 v[100:101], v[4:5], v[106:107], v[108:109]
	v_lshlrev_b32_e32 v106, 16, v38
	v_and_b32_e32 v107, 0xffff0000, v38
	v_lshlrev_b32_e32 v108, 16, v30
	v_and_b32_e32 v109, 0xffff0000, v30
	v_pk_mul_f32 v[106:107], v[96:97], v[106:107] op_sel_hi:[0,1]
	v_pk_fma_f32 v[102:103], v[6:7], v[106:107], v[108:109]
	v_lshlrev_b32_e32 v106, 16, v39
	v_and_b32_e32 v107, 0xffff0000, v39
	v_lshlrev_b32_e32 v108, 16, v31
	v_and_b32_e32 v109, 0xffff0000, v31
	v_pk_mul_f32 v[106:107], v[96:97], v[106:107] op_sel_hi:[0,1]
	v_pk_fma_f32 v[104:105], v[8:9], v[106:107], v[108:109]
	v_pk_fma_f32 v[110:111], v[98:99], v[98:99], v[110:111]
	v_pk_fma_f32 v[110:111], v[100:101], v[100:101], v[110:111]
	v_pk_fma_f32 v[110:111], v[102:103], v[102:103], v[110:111]
	v_pk_fma_f32 v[110:111], v[104:105], v[104:105], v[110:111]
	v_cvt_pk_bf16_f32 v28, v98, v99
	v_cvt_pk_bf16_f32 v29, v100, v101
	v_cvt_pk_bf16_f32 v30, v102, v103
	v_cvt_pk_bf16_f32 v31, v104, v105
	global_store_dwordx4 v19, v[28:31], s[4:5] offset:1024
	v_add_f32_e32 v112, v110, v111
	v_add_u32_e32 v22, 0x2000, v22
	s_nop 1
	v_add_f32_dpp v112, v112, v112 quad_perm:[1,0,3,2] row_mask:0xf bank_mask:0xf
	s_nop 1
	v_add_f32_dpp v112, v112, v112 quad_perm:[2,3,0,1] row_mask:0xf bank_mask:0xf
	s_nop 1
	v_add_f32_dpp v112, v112, v112 row_half_mirror row_mask:0xf bank_mask:0xf
	s_nop 1
	v_add_f32_dpp v112, v112, v112 row_mirror row_mask:0xf bank_mask:0xf
	s_nop 1
	v_add_f32_dpp v112, v112, v112 row_bcast:15 row_mask:0xa bank_mask:0xf
	s_nop 1
	v_add_f32_dpp v112, v112, v112 row_bcast:31 row_mask:0xc bank_mask:0xf
	v_fmamk_f32 v113, v112, 0x3a800000, v244
	v_rsq_f32_e32 v113, v113
	s_mov_b64 exec, s[6:7]
	global_store_dword v22, v113, s[4:5]
	s_mov_b64 exec, -1
	s_waitcnt vmcnt(19)
; __device__ __forceinline__ float bflo(unsigned w) { return __uint_as_float(w << 16); }
; __device__ __forceinline__ float bfhi(unsigned w) { return __uint_as_float(w & 0xffff0000u); }
; __device__ __forceinline__ void resid_rows(bf16_t* R, const bf16_t* Y, const float* ssqY, const float* g, float* rstd_out, float* outf, bool wf32, int row_lo, int row_hi, int yoff, int gw, int NGW, int lane) {
;     ...
;     for (int row0 = row_lo + gw; row0 < row_hi; row0 += RP * NGW) {
;         u32x4 rr[RP][2], oo[RP][2]; float ssv[RP];
; #pragma unroll
;         for (int k = 0; k < RP; ++k) { const int row = row0 + k * NGW; const bool ok = row < row_hi; const int rw = ok ? row : row0;
;             ssv[k] = ssqY[rw];
; #pragma unroll
;             for (int j = 0; j < 2; ++j) { const int c = 8 * lane + 512 * j; rr[k][j] = *(const u32x4*)(R + (size_t)rw * DM + c); oo[k][j] = *(const u32x4*)(Y + (size_t)(rw - yoff) * DM + c); } }
; #pragma unroll
;         for (int k = 0; k < RP; ++k) { const int row = row0 + k * NGW; if (row < row_hi) {
;             const float rs = __builtin_amdgcn_rsqf(ssv[k] * (1.0f / DM) + RMS_EPS); float s = 0.f;
; #pragma unroll
;             for (int j = 0; j < 2; ++j) { const int c = 8 * lane + 512 * j; const u32x4 r = rr[k][j], o = oo[k][j]; const f32x4 ga = gv[j][0], gb = gv[j][1];
;                 f32x4 ya, yb; ya[0] = bflo(r.x) + bflo(o.x) * rs * ga[0]; ya[1] = bfhi(r.x) + bfhi(o.x) * rs * ga[1]; ya[2] = bflo(r.y) + bflo(o.y) * rs * ga[2]; ya[3] = bfhi(r.y) + bfhi(o.y) * rs * ga[3];
;                 yb[0] = bflo(r.z) + bflo(o.z) * rs * gb[0]; yb[1] = bfhi(r.z) + bfhi(o.z) * rs * gb[1]; yb[2] = bflo(r.w) + bflo(o.w) * rs * gb[2]; yb[3] = bfhi(r.w) + bfhi(o.w) * rs * gb[3];
;                 if (wf32) { *(f32x4*)(outf + (size_t)row * DM + c) = ya; *(f32x4*)(outf + (size_t)row * DM + c + 4) = yb; }
;                 s += (ya[0] * ya[0] + ya[1] * ya[1]) + (ya[2] * ya[2] + ya[3] * ya[3]) + (yb[0] * yb[0] + yb[1] * yb[1]) + (yb[2] * yb[2] + yb[3] * yb[3]);
;                 u32x4 w; w.x = pk2(ya[0], ya[1]); w.y = pk2(ya[2], ya[3]); w.z = pk2(yb[0], yb[1]); w.w = pk2(yb[2], yb[3]); *(u32x4*)(R + (size_t)row * DM + c) = w; }
;             s = wave_sum(s); if (lane == 0) rstd_out[row] = __builtin_amdgcn_rsqf(s * (1.0f / DM) + RMS_EPS); } }
	v_fmamk_f32 v96, v58, 0x3a800000, v244
	v_rsq_f32_e32 v96, v96
	v_add_u32_e32 v19, 0x400000, v19
	v_lshlrev_b32_e32 v106, 16, v50
	v_and_b32_e32 v107, 0xffff0000, v50
	v_lshlrev_b32_e32 v108, 16, v42
	v_and_b32_e32 v109, 0xffff0000, v42
	v_pk_mul_f32 v[106:107], v[96:97], v[106:107] op_sel_hi:[0,1]
	v_pk_fma_f32 v[98:99], v[10:11], v[106:107], v[108:109]
	v_lshlrev_b32_e32 v106, 16, v51
	v_and_b32_e32 v107, 0xffff0000, v51
	v_lshlrev_b32_e32 v108, 16, v43
	v_and_b32_e32 v109, 0xffff0000, v43
	v_pk_mul_f32 v[106:107], v[96:97], v[106:107] op_sel_hi:[0,1]
	v_pk_fma_f32 v[100:101], v[12:13], v[106:107], v[108:109]
	v_lshlrev_b32_e32 v106, 16, v52
	v_and_b32_e32 v107, 0xffff0000, v52
	v_lshlrev_b32_e32 v108, 16, v44
	v_and_b32_e32 v109, 0xffff0000, v44
	v_pk_mul_f32 v[106:107], v[96:97], v[106:107] op_sel_hi:[0,1]
	v_pk_fma_f32 v[102:103], v[14:15], v[106:107], v[108:109]
	v_lshlrev_b32_e32 v106, 16, v53
	v_and_b32_e32 v107, 0xffff0000, v53
	v_lshlrev_b32_e32 v108, 16, v45
	v_and_b32_e32 v109, 0xffff0000, v45
	v_pk_mul_f32 v[106:107], v[96:97], v[106:107] op_sel_hi:[0,1]
	v_pk_fma_f32 v[104:105], v[16:17], v[106:107], v[108:109]
	v_pk_mul_f32 v[110:111], v[98:99], v[98:99]
	v_pk_fma_f32 v[110:111], v[100:101], v[100:101], v[110:111]
	v_pk_fma_f32 v[110:111], v[102:103], v[102:103], v[110:111]
	v_pk_fma_f32 v[110:111], v[104:105], v[104:105], v[110:111]
	v_cvt_pk_bf16_f32 v42, v98, v99
	v_cvt_pk_bf16_f32 v43, v100, v101
	v_cvt_pk_bf16_f32 v44, v102, v103
	v_cvt_pk_bf16_f32 v45, v104, v105
	global_store_dwordx4 v19, v[42:45], s[4:5]
	v_lshlrev_b32_e32 v106, 16, v54
	v_and_b32_e32 v107, 0xffff0000, v54
	v_lshlrev_b32_e32 v108, 16, v46
	v_and_b32_e32 v109, 0xffff0000, v46
	v_pk_mul_f32 v[106:107], v[96:97], v[106:107] op_sel_hi:[0,1]
	v_pk_fma_f32 v[98:99], v[2:3], v[106:107], v[108:109]
	v_lshlrev_b32_e32 v106, 16, v55
	v_and_b32_e32 v107, 0xffff0000, v55
	v_lshlrev_b32_e32 v108, 16, v47
	v_and_b32_e32 v109, 0xffff0000, v47
	v_pk_mul_f32 v[106:107], v[96:97], v[106:107] op_sel_hi:[0,1]
	v_pk_fma_f32 v[100:101], v[4:5], v[106:107], v[108:109]
	v_lshlrev_b32_e32 v106, 16, v56
	v_and_b32_e32 v107, 0xffff0000, v56
	v_lshlrev_b32_e32 v108, 16, v48
	v_and_b32_e32 v109, 0xffff0000, v48
	v_pk_mul_f32 v[106:107], v[96:97], v[106:107] op_sel_hi:[0,1]
	v_pk_fma_f32 v[102:103], v[6:7], v[106:107], v[108:109]
	v_lshlrev_b32_e32 v106, 16, v57
	v_and_b32_e32 v107, 0xffff0000, v57
	v_lshlrev_b32_e32 v108, 16, v49
	v_and_b32_e32 v109, 0xffff0000, v49
	v_pk_mul_f32 v[106:107], v[96:97], v[106:107] op_sel_hi:[0,1]
	v_pk_fma_f32 v[104:105], v[8:9], v[106:107], v[108:109]
	v_pk_fma_f32 v[110:111], v[98:99], v[98:99], v[110:111]
	v_pk_fma_f32 v[110:111], v[100:101], v[100:101], v[110:111]
	v_pk_fma_f32 v[110:111], v[102:103], v[102:103], v[110:111]
	v_pk_fma_f32 v[110:111], v[104:105], v[104:105], v[110:111]
	v_cvt_pk_bf16_f32 v46, v98, v99
	v_cvt_pk_bf16_f32 v47, v100, v101
	v_cvt_pk_bf16_f32 v48, v102, v103
	v_cvt_pk_bf16_f32 v49, v104, v105
	global_store_dwordx4 v19, v[46:49], s[4:5] offset:1024
	v_add_f32_e32 v112, v110, v111
	v_add_u32_e32 v22, 0x2000, v22
	s_nop 1
	v_add_f32_dpp v112, v112, v112 quad_perm:[1,0,3,2] row_mask:0xf bank_mask:0xf
	s_nop 1
	v_add_f32_dpp v112, v112, v112 quad_perm:[2,3,0,1] row_mask:0xf bank_mask:0xf
	s_nop 1
	v_add_f32_dpp v112, v112, v112 row_half_mirror row_mask:0xf bank_mask:0xf
	s_nop 1
	v_add_f32_dpp v112, v112, v112 row_mirror row_mask:0xf bank_mask:0xf
	s_nop 1
	v_add_f32_dpp v112, v112, v112 row_bcast:15 row_mask:0xa bank_mask:0xf
	s_nop 1
	v_add_f32_dpp v112, v112, v112 row_bcast:31 row_mask:0xc bank_mask:0xf
	v_fmamk_f32 v113, v112, 0x3a800000, v244
	v_rsq_f32_e32 v113, v113
	s_mov_b64 exec, s[6:7]
	global_store_dword v22, v113, s[4:5]
	s_mov_b64 exec, -1
	s_waitcnt vmcnt(14)
	v_fmamk_f32 v96, v76, 0x3a800000, v244
	v_rsq_f32_e32 v96, v96
	v_add_u32_e32 v19, 0x400000, v19
	v_lshlrev_b32_e32 v106, 16, v68
	v_and_b32_e32 v107, 0xffff0000, v68
	v_lshlrev_b32_e32 v108, 16, v60
	v_and_b32_e32 v109, 0xffff0000, v60
	v_pk_mul_f32 v[106:107], v[96:97], v[106:107] op_sel_hi:[0,1]
	v_pk_fma_f32 v[98:99], v[10:11], v[106:107], v[108:109]
	v_lshlrev_b32_e32 v106, 16, v69
	v_and_b32_e32 v107, 0xffff0000, v69
	v_lshlrev_b32_e32 v108, 16, v61
	v_and_b32_e32 v109, 0xffff0000, v61
	v_pk_mul_f32 v[106:107], v[96:97], v[106:107] op_sel_hi:[0,1]
	v_pk_fma_f32 v[100:101], v[12:13], v[106:107], v[108:109]
	v_lshlrev_b32_e32 v106, 16, v70
	v_and_b32_e32 v107, 0xffff0000, v70
	v_lshlrev_b32_e32 v108, 16, v62
	v_and_b32_e32 v109, 0xffff0000, v62
	v_pk_mul_f32 v[106:107], v[96:97], v[106:107] op_sel_hi:[0,1]
	v_pk_fma_f32 v[102:103], v[14:15], v[106:107], v[108:109]
	v_lshlrev_b32_e32 v106, 16, v71
	v_and_b32_e32 v107, 0xffff0000, v71
	v_lshlrev_b32_e32 v108, 16, v63
	v_and_b32_e32 v109, 0xffff0000, v63
	v_pk_mul_f32 v[106:107], v[96:97], v[106:107] op_sel_hi:[0,1]
	v_pk_fma_f32 v[104:105], v[16:17], v[106:107], v[108:109]
	v_pk_mul_f32 v[110:111], v[98:99], v[98:99]
	v_pk_fma_f32 v[110:111], v[100:101], v[100:101], v[110:111]
	v_pk_fma_f32 v[110:111], v[102:103], v[102:103], v[110:111]
	v_pk_fma_f32 v[110:111], v[104:105], v[104:105], v[110:111]
	v_cvt_pk_bf16_f32 v60, v98, v99
	v_cvt_pk_bf16_f32 v61, v100, v101
	v_cvt_pk_bf16_f32 v62, v102, v103
	v_cvt_pk_bf16_f32 v63, v104, v105
	global_store_dwordx4 v19, v[60:63], s[4:5]
	v_lshlrev_b32_e32 v106, 16, v72
	v_and_b32_e32 v107, 0xffff0000, v72
	v_lshlrev_b32_e32 v108, 16, v64
	v_and_b32_e32 v109, 0xffff0000, v64
	v_pk_mul_f32 v[106:107], v[96:97], v[106:107] op_sel_hi:[0,1]
	v_pk_fma_f32 v[98:99], v[2:3], v[106:107], v[108:109]
	v_lshlrev_b32_e32 v106, 16, v73
	v_and_b32_e32 v107, 0xffff0000, v73
; __device__ __forceinline__ float bflo(unsigned w) { return __uint_as_float(w << 16); }
; __device__ __forceinline__ float bfhi(unsigned w) { return __uint_as_float(w & 0xffff0000u); }
; __device__ __forceinline__ void resid_rows(bf16_t* R, const bf16_t* Y, const float* ssqY, const float* g, float* rstd_out, float* outf, bool wf32, int row_lo, int row_hi, int yoff, int gw, int NGW, int lane) {
;     ...
;     for (int row0 = row_lo + gw; row0 < row_hi; row0 += RP * NGW) {
;         u32x4 rr[RP][2], oo[RP][2]; float ssv[RP];
; #pragma unroll
;         for (int k = 0; k < RP; ++k) { const int row = row0 + k * NGW; const bool ok = row < row_hi; const int rw = ok ? row : row0;
;             ssv[k] = ssqY[rw];
; #pragma unroll
;             for (int j = 0; j < 2; ++j) { const int c = 8 * lane + 512 * j; rr[k][j] = *(const u32x4*)(R + (size_t)rw * DM + c); oo[k][j] = *(const u32x4*)(Y + (size_t)(rw - yoff) * DM + c); } }
; #pragma unroll
;         for (int k = 0; k < RP; ++k) { const int row = row0 + k * NGW; if (row < row_hi) {
;             const float rs = __builtin_amdgcn_rsqf(ssv[k] * (1.0f / DM) + RMS_EPS); float s = 0.f;
; #pragma unroll
;             for (int j = 0; j < 2; ++j) { const int c = 8 * lane + 512 * j; const u32x4 r = rr[k][j], o = oo[k][j]; const f32x4 ga = gv[j][0], gb = gv[j][1];
;                 f32x4 ya, yb; ya[0] = bflo(r.x) + bflo(o.x) * rs * ga[0]; ya[1] = bfhi(r.x) + bfhi(o.x) * rs * ga[1]; ya[2] = bflo(r.y) + bflo(o.y) * rs * ga[2]; ya[3] = bfhi(r.y) + bfhi(o.y) * rs * ga[3];
;                 yb[0] = bflo(r.z) + bflo(o.z) * rs * gb[0]; yb[1] = bfhi(r.z) + bfhi(o.z) * rs * gb[1]; yb[2] = bflo(r.w) + bflo(o.w) * rs * gb[2]; yb[3] = bfhi(r.w) + bfhi(o.w) * rs * gb[3];
;                 if (wf32) { *(f32x4*)(outf + (size_t)row * DM + c) = ya; *(f32x4*)(outf + (size_t)row * DM + c + 4) = yb; }
;                 s += (ya[0] * ya[0] + ya[1] * ya[1]) + (ya[2] * ya[2] + ya[3] * ya[3]) + (yb[0] * yb[0] + yb[1] * yb[1]) + (yb[2] * yb[2] + yb[3] * yb[3]);
;                 u32x4 w; w.x = pk2(ya[0], ya[1]); w.y = pk2(ya[2], ya[3]); w.z = pk2(yb[0], yb[1]); w.w = pk2(yb[2], yb[3]); *(u32x4*)(R + (size_t)row * DM + c) = w; }
;             s = wave_sum(s); if (lane == 0) rstd_out[row] = __builtin_amdgcn_rsqf(s * (1.0f / DM) + RMS_EPS); } }
	v_lshlrev_b32_e32 v108, 16, v65
	v_and_b32_e32 v109, 0xffff0000, v65
	v_pk_mul_f32 v[106:107], v[96:97], v[106:107] op_sel_hi:[0,1]
	v_pk_fma_f32 v[100:101], v[4:5], v[106:107], v[108:109]
	v_lshlrev_b32_e32 v106, 16, v74
	v_and_b32_e32 v107, 0xffff0000, v74
	v_lshlrev_b32_e32 v108, 16, v66
	v_and_b32_e32 v109, 0xffff0000, v66
	v_pk_mul_f32 v[106:107], v[96:97], v[106:107] op_sel_hi:[0,1]
	v_pk_fma_f32 v[102:103], v[6:7], v[106:107], v[108:109]
	v_lshlrev_b32_e32 v106, 16, v75
	v_and_b32_e32 v107, 0xffff0000, v75
	v_lshlrev_b32_e32 v108, 16, v67
	v_and_b32_e32 v109, 0xffff0000, v67
	v_pk_mul_f32 v[106:107], v[96:97], v[106:107] op_sel_hi:[0,1]
	v_pk_fma_f32 v[104:105], v[8:9], v[106:107], v[108:109]
	v_pk_fma_f32 v[110:111], v[98:99], v[98:99], v[110:111]
	v_pk_fma_f32 v[110:111], v[100:101], v[100:101], v[110:111]
	v_pk_fma_f32 v[110:111], v[102:103], v[102:103], v[110:111]
	v_pk_fma_f32 v[110:111], v[104:105], v[104:105], v[110:111]
	v_cvt_pk_bf16_f32 v64, v98, v99
	v_cvt_pk_bf16_f32 v65, v100, v101
	v_cvt_pk_bf16_f32 v66, v102, v103
	v_cvt_pk_bf16_f32 v67, v104, v105
	global_store_dwordx4 v19, v[64:67], s[4:5] offset:1024
	v_add_f32_e32 v112, v110, v111
	v_add_u32_e32 v22, 0x2000, v22
	s_nop 1
	v_add_f32_dpp v112, v112, v112 quad_perm:[1,0,3,2] row_mask:0xf bank_mask:0xf
	s_nop 1
	v_add_f32_dpp v112, v112, v112 quad_perm:[2,3,0,1] row_mask:0xf bank_mask:0xf
	s_nop 1
	v_add_f32_dpp v112, v112, v112 row_half_mirror row_mask:0xf bank_mask:0xf
	s_nop 1
	v_add_f32_dpp v112, v112, v112 row_mirror row_mask:0xf bank_mask:0xf
	s_nop 1
	v_add_f32_dpp v112, v112, v112 row_bcast:15 row_mask:0xa bank_mask:0xf
	s_nop 1
	v_add_f32_dpp v112, v112, v112 row_bcast:31 row_mask:0xc bank_mask:0xf
	v_fmamk_f32 v113, v112, 0x3a800000, v244
	v_rsq_f32_e32 v113, v113
	s_mov_b64 exec, s[6:7]
	global_store_dword v22, v113, s[4:5]
	s_mov_b64 exec, -1
	s_waitcnt vmcnt(9)
	v_fmamk_f32 v96, v94, 0x3a800000, v244
	v_rsq_f32_e32 v96, v96
	v_add_u32_e32 v19, 0x400000, v19
	v_lshlrev_b32_e32 v106, 16, v86
	v_and_b32_e32 v107, 0xffff0000, v86
	v_lshlrev_b32_e32 v108, 16, v78
	v_and_b32_e32 v109, 0xffff0000, v78
	v_pk_mul_f32 v[106:107], v[96:97], v[106:107] op_sel_hi:[0,1]
	v_pk_fma_f32 v[98:99], v[10:11], v[106:107], v[108:109]
	v_lshlrev_b32_e32 v106, 16, v87
	v_and_b32_e32 v107, 0xffff0000, v87
	v_lshlrev_b32_e32 v108, 16, v79
	v_and_b32_e32 v109, 0xffff0000, v79
	v_pk_mul_f32 v[106:107], v[96:97], v[106:107] op_sel_hi:[0,1]
	v_pk_fma_f32 v[100:101], v[12:13], v[106:107], v[108:109]
	v_lshlrev_b32_e32 v106, 16, v88
	v_and_b32_e32 v107, 0xffff0000, v88
	v_lshlrev_b32_e32 v108, 16, v80
	v_and_b32_e32 v109, 0xffff0000, v80
	v_pk_mul_f32 v[106:107], v[96:97], v[106:107] op_sel_hi:[0,1]
	v_pk_fma_f32 v[102:103], v[14:15], v[106:107], v[108:109]
	v_lshlrev_b32_e32 v106, 16, v89
	v_and_b32_e32 v107, 0xffff0000, v89
	v_lshlrev_b32_e32 v108, 16, v81
	v_and_b32_e32 v109, 0xffff0000, v81
	v_pk_mul_f32 v[106:107], v[96:97], v[106:107] op_sel_hi:[0,1]
	v_pk_fma_f32 v[104:105], v[16:17], v[106:107], v[108:109]
	v_pk_mul_f32 v[110:111], v[98:99], v[98:99]
	v_pk_fma_f32 v[110:111], v[100:101], v[100:101], v[110:111]
	v_pk_fma_f32 v[110:111], v[102:103], v[102:103], v[110:111]
	v_pk_fma_f32 v[110:111], v[104:105], v[104:105], v[110:111]
	v_cvt_pk_bf16_f32 v78, v98, v99
	v_cvt_pk_bf16_f32 v79, v100, v101
	v_cvt_pk_bf16_f32 v80, v102, v103
	v_cvt_pk_bf16_f32 v81, v104, v105
	global_store_dwordx4 v19, v[78:81], s[4:5]
	v_lshlrev_b32_e32 v106, 16, v90
	v_and_b32_e32 v107, 0xffff0000, v90
	v_lshlrev_b32_e32 v108, 16, v82
	v_and_b32_e32 v109, 0xffff0000, v82
	v_pk_mul_f32 v[106:107], v[96:97], v[106:107] op_sel_hi:[0,1]
	v_pk_fma_f32 v[98:99], v[2:3], v[106:107], v[108:109]
	v_lshlrev_b32_e32 v106, 16, v91
	v_and_b32_e32 v107, 0xffff0000, v91
	v_lshlrev_b32_e32 v108, 16, v83
	v_and_b32_e32 v109, 0xffff0000, v83
	v_pk_mul_f32 v[106:107], v[96:97], v[106:107] op_sel_hi:[0,1]
	v_pk_fma_f32 v[100:101], v[4:5], v[106:107], v[108:109]
	v_lshlrev_b32_e32 v106, 16, v92
	v_and_b32_e32 v107, 0xffff0000, v92
	v_lshlrev_b32_e32 v108, 16, v84
	v_and_b32_e32 v109, 0xffff0000, v84
	v_pk_mul_f32 v[106:107], v[96:97], v[106:107] op_sel_hi:[0,1]
	v_pk_fma_f32 v[102:103], v[6:7], v[106:107], v[108:109]
	v_lshlrev_b32_e32 v106, 16, v93
	v_and_b32_e32 v107, 0xffff0000, v93
	v_lshlrev_b32_e32 v108, 16, v85
	v_and_b32_e32 v109, 0xffff0000, v85
	v_pk_mul_f32 v[106:107], v[96:97], v[106:107] op_sel_hi:[0,1]
	v_pk_fma_f32 v[104:105], v[8:9], v[106:107], v[108:109]
	v_pk_fma_f32 v[110:111], v[98:99], v[98:99], v[110:111]
	v_pk_fma_f32 v[110:111], v[100:101], v[100:101], v[110:111]
	v_pk_fma_f32 v[110:111], v[102:103], v[102:103], v[110:111]
	v_pk_fma_f32 v[110:111], v[104:105], v[104:105], v[110:111]
	v_cvt_pk_bf16_f32 v82, v98, v99
	v_cvt_pk_bf16_f32 v83, v100, v101
	v_cvt_pk_bf16_f32 v84, v102, v103
	v_cvt_pk_bf16_f32 v85, v104, v105
	global_store_dwordx4 v19, v[82:85], s[4:5] offset:1024
	v_add_f32_e32 v112, v110, v111
	v_add_u32_e32 v22, 0x2000, v22
	s_nop 1
	v_add_f32_dpp v112, v112, v112 quad_perm:[1,0,3,2] row_mask:0xf bank_mask:0xf
	s_nop 1
	v_add_f32_dpp v112, v112, v112 quad_perm:[2,3,0,1] row_mask:0xf bank_mask:0xf
	s_nop 1
	v_add_f32_dpp v112, v112, v112 row_half_mirror row_mask:0xf bank_mask:0xf
	s_nop 1
	v_add_f32_dpp v112, v112, v112 row_mirror row_mask:0xf bank_mask:0xf
	s_nop 1
	v_add_f32_dpp v112, v112, v112 row_bcast:15 row_mask:0xa bank_mask:0xf
	s_nop 1
	v_add_f32_dpp v112, v112, v112 row_bcast:31 row_mask:0xc bank_mask:0xf
	v_fmamk_f32 v113, v112, 0x3a800000, v244
	v_rsq_f32_e32 v113, v113
	s_mov_b64 exec, s[6:7]
	global_store_dword v22, v113, s[4:5]
	s_mov_b64 exec, -1

; #define LAS __attribute__((address_space(3)))
; __device__ __forceinline__ int otid() { int t = threadIdx.x; asm volatile("" : "+v"(t)); return t; }
; __device__ __forceinline__ unsigned xb_xcc_id() { return (unsigned)__builtin_amdgcn_s_getreg((3 << 11) | 20) & 0xFu; }
; #define PIN(i) karg_ptr(8 * (i))
; __device__ __forceinline__ void resid_rows(bf16_t* R, const bf16_t* Y, const float* ssqY, const float* g, float* rstd_out, float* outf, bool wf32, int row_lo, int row_hi, int yoff, int gw, int NGW, int lane) {
;     constexpr int RP = 4;
;     f32x4 gv[2][2];
; #pragma unroll
;     for (int j = 0; j < 2; ++j) { gv[j][0] = *(const f32x4*)(g + 8 * lane + 512 * j); gv[j][1] = *(const f32x4*)(g + 8 * lane + 512 * j + 4); }
;     for (int row0 = row_lo + gw; row0 < row_hi; row0 += RP * NGW) {
;         u32x4 rr[RP][2], oo[RP][2]; float ssv[RP];
; #pragma unroll
;         for (int k = 0; k < RP; ++k) { const int row = row0 + k * NGW; const bool ok = row < row_hi; const int rw = ok ? row : row0;
;             ssv[k] = ssqY[rw];
; #pragma unroll
;             for (int j = 0; j < 2; ++j) { const int c = 8 * lane + 512 * j; rr[k][j] = *(const u32x4*)(R + (size_t)rw * DM + c); oo[k][j] = *(const u32x4*)(Y + (size_t)(rw - yoff) * DM + c); } }
; __global__ void __launch_bounds__(512, 2) fwd_megakernel(Params P) {
;     ...
;         if (EN(7) && IN(pb + 8)) {
;             const bool lastl = (l == NLAYER - 1);
;             { const int lane = otid() & 63, gw = bx * 8 + (otid() >> 6);
;               resid_rows(XB, FH1, ssqF, PIN(I_LNFPOST) + l * DM, rstdA, out, lastl, HALF_TOK, MTOK, HALF_TOK, gw, NGW, lane); }
;             if (lastl && (P.ph_hi - P.ph_lo > 1)) { XcdBarrier xb_; xb_.bar = (unsigned*)(ws + OFF_BAR); xb_.x = xb_xcc_id(); xb_.st = (volatile LAS unsigned*)(lds + LDS_BYTES - 16); xcd_barrier(xb_); }
;             { const int lane = otid() & 63, gw = bx * 8 + (otid() >> 6);
;               resid_rows(XB, FH0, ssqF, PIN(I_LNFPOST) + l * DM, rstdA, out, lastl, 0, HALF_TOK, 0, gw, NGW, lane); }
.LBB0_792:
	s_cmp_le_i32 s88, s30
	s_cselect_b64 s[6:7], -1, 0
	s_and_b64 s[4:5], s[6:7], s[4:5]
	s_andn2_b64 vcc, exec, s[4:5]
	v_readlane_b32 s30, v255, 39
	v_readlane_b32 s31, v255, 40
	s_cbranch_vccnz .Ltr_145
	v_readlane_b32 s8, v255, 49
	v_mov_b32_e32 v2, v0
	v_mov_b32_e32 v3, v0
	v_readlane_b32 s9, v255, 50
	v_readlane_b32 s4, v255, 4
	v_ashrrev_i32_e32 v20, 6, v3
	s_mov_b32 s9, s49
	v_add_u32_e32 v18, s4, v20
	s_mov_b64 s[4:5], s[0:1]
	s_mov_b64 s[6:7], s[0:1]
	s_mov_b64 s[10:11], s[0:1]
	s_mov_b64 s[72:73], s[8:9]
	s_lshl_b32 s48, s8, 10
	s_mov_b64 s[12:13], s[0:1]
	s_mov_b64 s[8:9], s[0:1]
	v_cmp_gt_i32_e32 vcc, s47, v18
	s_and_saveexec_b64 s[16:17], vcc
	s_cbranch_execz .LBB0_823
	v_readlane_b32 s12, v255, 49
	s_cmp_eq_u32 s12, 1
	s_cbranch_scc1 .Lrs2_last1
	v_lshrrev_b32_e32 v114, 6, v0
	v_readlane_b32 s12, v255, 49
	v_readlane_b32 s13, v255, 4
	v_readfirstlane_b32 s18, v114
	s_load_dwordx2 s[4:5], s[0:1], 0x98
	s_load_dwordx2 s[10:11], s[0:1], 0x68
	s_load_dwordx2 s[6:7], s[0:1], 0x90
	s_add_i32 s13, s13, s18
	v_and_b32_e32 v115, 63, v0
	v_lshlrev_b32_e32 v114, 4, v115
	v_lshlrev_b32_e32 v115, 5, v115
	s_lshl_b32 s18, s12, 12
	s_lshl_b32 s19, s12, 18
	s_bfm_b64 s[8:9], 1, 63
	s_waitcnt lgkmcnt(0)
	s_add_u32 s10, s10, s18
	s_addc_u32 s11, s11, 0
	global_load_dwordx4 v[2:5], v115, s[10:11] offset:2048
	global_load_dwordx4 v[6:9], v115, s[10:11] offset:2064
	global_load_dwordx4 v[10:13], v115, s[10:11]
	global_load_dwordx4 v[14:17], v115, s[10:11] offset:16
	s_lshl_b32 s18, s13, 11
	v_add_u32_e32 v18, s18, v114
	v_mov_b32_e32 v19, v18
	v_mov_b32_e32 v20, v18
	s_lshl_b32 s18, s13, 2
	v_mov_b32_e32 v22, s18
	s_add_i32 s18, s18, s19
	v_mov_b32_e32 v21, s18
	s_lshl_b32 s18, s13, 12
	v_add_u32_e32 v23, s18, v115
	v_add_u32_e32 v18, 0x5001000, v18
	v_add_u32_e32 v21, 0x2d70000, v21
	global_load_dwordx4 v[24:27], v18, s[4:5]
	global_load_dwordx4 v[32:35], v20, s[6:7]
	global_load_dwordx4 v[28:31], v18, s[4:5] offset:1024
	global_load_dwordx4 v[36:39], v20, s[6:7] offset:1024
	global_load_dword v40, v21, s[4:5]
	v_add_u32_e32 v18, 0x400000, v18
	v_add_u32_e32 v20, 0x400000, v20
	v_add_u32_e32 v21, 0x2000, v21
	global_load_dwordx4 v[42:45], v18, s[4:5]
	global_load_dwordx4 v[50:53], v20, s[6:7]
	global_load_dwordx4 v[46:49], v18, s[4:5] offset:1024
	global_load_dwordx4 v[54:57], v20, s[6:7] offset:1024
	global_load_dword v58, v21, s[4:5]
	v_add_u32_e32 v18, 0x400000, v18
	v_add_u32_e32 v20, 0x400000, v20
	v_add_u32_e32 v21, 0x2000, v21
	global_load_dwordx4 v[60:63], v18, s[4:5]
	global_load_dwordx4 v[68:71], v20, s[6:7]
	global_load_dwordx4 v[64:67], v18, s[4:5] offset:1024
	global_load_dwordx4 v[72:75], v20, s[6:7] offset:1024
	global_load_dword v76, v21, s[4:5]
	v_add_u32_e32 v18, 0x400000, v18
	v_add_u32_e32 v20, 0x400000, v20
	v_add_u32_e32 v21, 0x2000, v21
	global_load_dwordx4 v[78:81], v18, s[4:5]
	global_load_dwordx4 v[86:89], v20, s[6:7]
	global_load_dwordx4 v[82:85], v18, s[4:5] offset:1024
	global_load_dwordx4 v[90:93], v20, s[6:7] offset:1024
	global_load_dword v94, v21, s[4:5]
	s_waitcnt vmcnt(15)
	v_fmamk_f32 v96, v40, 0x3a800000, v244
	v_rsq_f32_e32 v96, v96
	v_add_u32_e32 v19, 0x5001000, v19
	v_lshlrev_b32_e32 v106, 16, v32
	v_and_b32_e32 v107, 0xffff0000, v32
	v_lshlrev_b32_e32 v108, 16, v24
	v_and_b32_e32 v109, 0xffff0000, v24
	v_pk_mul_f32 v[106:107], v[96:97], v[106:107] op_sel_hi:[0,1]
	v_pk_fma_f32 v[98:99], v[10:11], v[106:107], v[108:109]
	v_lshlrev_b32_e32 v106, 16, v33
	v_and_b32_e32 v107, 0xffff0000, v33
	v_lshlrev_b32_e32 v108, 16, v25
	v_and_b32_e32 v109, 0xffff0000, v25
	v_pk_mul_f32 v[106:107], v[96:97], v[106:107] op_sel_hi:[0,1]
	v_pk_fma_f32 v[100:101], v[12:13], v[106:107], v[108:109]
	v_lshlrev_b32_e32 v106, 16, v34
	v_and_b32_e32 v107, 0xffff0000, v34
	v_lshlrev_b32_e32 v108, 16, v26
	v_and_b32_e32 v109, 0xffff0000, v26
	v_pk_mul_f32 v[106:107], v[96:97], v[106:107] op_sel_hi:[0,1]
	v_pk_fma_f32 v[102:103], v[14:15], v[106:107], v[108:109]
	v_lshlrev_b32_e32 v106, 16, v35
	v_and_b32_e32 v107, 0xffff0000, v35
	v_lshlrev_b32_e32 v108, 16, v27
	v_and_b32_e32 v109, 0xffff0000, v27
	v_pk_mul_f32 v[106:107], v[96:97], v[106:107] op_sel_hi:[0,1]
	v_pk_fma_f32 v[104:105], v[16:17], v[106:107], v[108:109]
	v_pk_mul_f32 v[110:111], v[98:99], v[98:99]
	v_pk_fma_f32 v[110:111], v[100:101], v[100:101], v[110:111]
	v_pk_fma_f32 v[110:111], v[102:103], v[102:103], v[110:111]
	v_pk_fma_f32 v[110:111], v[104:105], v[104:105], v[110:111]
	v_cvt_pk_bf16_f32 v24, v98, v99
	v_cvt_pk_bf16_f32 v25, v100, v101
	v_cvt_pk_bf16_f32 v26, v102, v103
	v_cvt_pk_bf16_f32 v27, v104, v105
	global_store_dwordx4 v19, v[24:27], s[4:5]
	v_lshlrev_b32_e32 v106, 16, v36
	v_and_b32_e32 v107, 0xffff0000, v36
	v_lshlrev_b32_e32 v108, 16, v28
	v_and_b32_e32 v109, 0xffff0000, v28
	v_pk_mul_f32 v[106:107], v[96:97], v[106:107] op_sel_hi:[0,1]
	v_pk_fma_f32 v[98:99], v[2:3], v[106:107], v[108:109]
	v_lshlrev_b32_e32 v106, 16, v37
	v_and_b32_e32 v107, 0xffff0000, v37
	v_lshlrev_b32_e32 v108, 16, v29
	v_and_b32_e32 v109, 0xffff0000, v29
	v_pk_mul_f32 v[106:107], v[96:97], v[106:107] op_sel_hi:[0,1]
	v_pk_fma_f32 v[100:101], v[4:5], v[106:107], v[108:109]
	v_lshlrev_b32_e32 v106, 16, v38
	v_and_b32_e32 v107, 0xffff0000, v38
	v_lshlrev_b32_e32 v108, 16, v30
	v_and_b32_e32 v109, 0xffff0000, v30
	v_pk_mul_f32 v[106:107], v[96:97], v[106:107] op_sel_hi:[0,1]
	v_pk_fma_f32 v[102:103], v[6:7], v[106:107], v[108:109]
	v_lshlrev_b32_e32 v106, 16, v39
	v_and_b32_e32 v107, 0xffff0000, v39
	v_lshlrev_b32_e32 v108, 16, v31
	v_and_b32_e32 v109, 0xffff0000, v31
	v_pk_mul_f32 v[106:107], v[96:97], v[106:107] op_sel_hi:[0,1]
	v_pk_fma_f32 v[104:105], v[8:9], v[106:107], v[108:109]
; __device__ __forceinline__ float bflo(unsigned w) { return __uint_as_float(w << 16); }
; __device__ __forceinline__ float bfhi(unsigned w) { return __uint_as_float(w & 0xffff0000u); }
; __device__ __forceinline__ void resid_rows(bf16_t* R, const bf16_t* Y, const float* ssqY, const float* g, float* rstd_out, float* outf, bool wf32, int row_lo, int row_hi, int yoff, int gw, int NGW, int lane) {
;     ...
;     for (int row0 = row_lo + gw; row0 < row_hi; row0 += RP * NGW) {
;         u32x4 rr[RP][2], oo[RP][2]; float ssv[RP];
; #pragma unroll
;         for (int k = 0; k < RP; ++k) { const int row = row0 + k * NGW; const bool ok = row < row_hi; const int rw = ok ? row : row0;
;             ssv[k] = ssqY[rw];
; #pragma unroll
;             for (int j = 0; j < 2; ++j) { const int c = 8 * lane + 512 * j; rr[k][j] = *(const u32x4*)(R + (size_t)rw * DM + c); oo[k][j] = *(const u32x4*)(Y + (size_t)(rw - yoff) * DM + c); } }
; #pragma unroll
;         for (int k = 0; k < RP; ++k) { const int row = row0 + k * NGW; if (row < row_hi) {
;             const float rs = __builtin_amdgcn_rsqf(ssv[k] * (1.0f / DM) + RMS_EPS); float s = 0.f;
; #pragma unroll
;             for (int j = 0; j < 2; ++j) { const int c = 8 * lane + 512 * j; const u32x4 r = rr[k][j], o = oo[k][j]; const f32x4 ga = gv[j][0], gb = gv[j][1];
;                 f32x4 ya, yb; ya[0] = bflo(r.x) + bflo(o.x) * rs * ga[0]; ya[1] = bfhi(r.x) + bfhi(o.x) * rs * ga[1]; ya[2] = bflo(r.y) + bflo(o.y) * rs * ga[2]; ya[3] = bfhi(r.y) + bfhi(o.y) * rs * ga[3];
;                 yb[0] = bflo(r.z) + bflo(o.z) * rs * gb[0]; yb[1] = bfhi(r.z) + bfhi(o.z) * rs * gb[1]; yb[2] = bflo(r.w) + bflo(o.w) * rs * gb[2]; yb[3] = bfhi(r.w) + bfhi(o.w) * rs * gb[3];
;                 if (wf32) { *(f32x4*)(outf + (size_t)row * DM + c) = ya; *(f32x4*)(outf + (size_t)row * DM + c + 4) = yb; }
;                 s += (ya[0] * ya[0] + ya[1] * ya[1]) + (ya[2] * ya[2] + ya[3] * ya[3]) + (yb[0] * yb[0] + yb[1] * yb[1]) + (yb[2] * yb[2] + yb[3] * yb[3]);
;                 u32x4 w; w.x = pk2(ya[0], ya[1]); w.y = pk2(ya[2], ya[3]); w.z = pk2(yb[0], yb[1]); w.w = pk2(yb[2], yb[3]); *(u32x4*)(R + (size_t)row * DM + c) = w; }
;             s = wave_sum(s); if (lane == 0) rstd_out[row] = __builtin_amdgcn_rsqf(s * (1.0f / DM) + RMS_EPS); } }
	v_pk_fma_f32 v[110:111], v[98:99], v[98:99], v[110:111]
	v_pk_fma_f32 v[110:111], v[100:101], v[100:101], v[110:111]
	v_pk_fma_f32 v[110:111], v[102:103], v[102:103], v[110:111]
	v_pk_fma_f32 v[110:111], v[104:105], v[104:105], v[110:111]
	v_cvt_pk_bf16_f32 v28, v98, v99
	v_cvt_pk_bf16_f32 v29, v100, v101
	v_cvt_pk_bf16_f32 v30, v102, v103
	v_cvt_pk_bf16_f32 v31, v104, v105
	global_store_dwordx4 v19, v[28:31], s[4:5] offset:1024
	v_add_f32_e32 v112, v110, v111
	v_add_u32_e32 v22, 0x2d10000, v22
	s_nop 1
	v_add_f32_dpp v112, v112, v112 quad_perm:[1,0,3,2] row_mask:0xf bank_mask:0xf
	s_nop 1
	v_add_f32_dpp v112, v112, v112 quad_perm:[2,3,0,1] row_mask:0xf bank_mask:0xf
	s_nop 1
	v_add_f32_dpp v112, v112, v112 row_half_mirror row_mask:0xf bank_mask:0xf
	s_nop 1
	v_add_f32_dpp v112, v112, v112 row_mirror row_mask:0xf bank_mask:0xf
	s_nop 1
	v_add_f32_dpp v112, v112, v112 row_bcast:15 row_mask:0xa bank_mask:0xf
	s_nop 1
	v_add_f32_dpp v112, v112, v112 row_bcast:31 row_mask:0xc bank_mask:0xf
	v_fmamk_f32 v113, v112, 0x3a800000, v244
	v_rsq_f32_e32 v113, v113
	s_mov_b64 exec, s[8:9]
	global_store_dword v22, v113, s[4:5]
	s_mov_b64 exec, -1
	v_add_u32_e32 v18, 0x400000, v18
	v_add_u32_e32 v20, 0x400000, v20
	v_add_u32_e32 v21, 0x2000, v21
	global_load_dwordx4 v[24:27], v18, s[4:5]
	global_load_dwordx4 v[32:35], v20, s[6:7]
	global_load_dwordx4 v[28:31], v18, s[4:5] offset:1024
	global_load_dwordx4 v[36:39], v20, s[6:7] offset:1024
	global_load_dword v40, v21, s[4:5]
	s_waitcnt vmcnt(18)
	v_fmamk_f32 v96, v58, 0x3a800000, v244
	v_rsq_f32_e32 v96, v96
	v_add_u32_e32 v19, 0x400000, v19
	v_lshlrev_b32_e32 v106, 16, v50
	v_and_b32_e32 v107, 0xffff0000, v50
	v_lshlrev_b32_e32 v108, 16, v42
	v_and_b32_e32 v109, 0xffff0000, v42
	v_pk_mul_f32 v[106:107], v[96:97], v[106:107] op_sel_hi:[0,1]
	v_pk_fma_f32 v[98:99], v[10:11], v[106:107], v[108:109]
	v_lshlrev_b32_e32 v106, 16, v51
	v_and_b32_e32 v107, 0xffff0000, v51
	v_lshlrev_b32_e32 v108, 16, v43
	v_and_b32_e32 v109, 0xffff0000, v43
	v_pk_mul_f32 v[106:107], v[96:97], v[106:107] op_sel_hi:[0,1]
	v_pk_fma_f32 v[100:101], v[12:13], v[106:107], v[108:109]
	v_lshlrev_b32_e32 v106, 16, v52
	v_and_b32_e32 v107, 0xffff0000, v52
	v_lshlrev_b32_e32 v108, 16, v44
	v_and_b32_e32 v109, 0xffff0000, v44
	v_pk_mul_f32 v[106:107], v[96:97], v[106:107] op_sel_hi:[0,1]
	v_pk_fma_f32 v[102:103], v[14:15], v[106:107], v[108:109]
	v_lshlrev_b32_e32 v106, 16, v53
	v_and_b32_e32 v107, 0xffff0000, v53
	v_lshlrev_b32_e32 v108, 16, v45
	v_and_b32_e32 v109, 0xffff0000, v45
	v_pk_mul_f32 v[106:107], v[96:97], v[106:107] op_sel_hi:[0,1]
	v_pk_fma_f32 v[104:105], v[16:17], v[106:107], v[108:109]
	v_pk_mul_f32 v[110:111], v[98:99], v[98:99]
	v_pk_fma_f32 v[110:111], v[100:101], v[100:101], v[110:111]
	v_pk_fma_f32 v[110:111], v[102:103], v[102:103], v[110:111]
	v_pk_fma_f32 v[110:111], v[104:105], v[104:105], v[110:111]
	v_cvt_pk_bf16_f32 v42, v98, v99
	v_cvt_pk_bf16_f32 v43, v100, v101
	v_cvt_pk_bf16_f32 v44, v102, v103
	v_cvt_pk_bf16_f32 v45, v104, v105
	global_store_dwordx4 v19, v[42:45], s[4:5]
	v_lshlrev_b32_e32 v106, 16, v54
	v_and_b32_e32 v107, 0xffff0000, v54
	v_lshlrev_b32_e32 v108, 16, v46
	v_and_b32_e32 v109, 0xffff0000, v46
	v_pk_mul_f32 v[106:107], v[96:97], v[106:107] op_sel_hi:[0,1]
	v_pk_fma_f32 v[98:99], v[2:3], v[106:107], v[108:109]
	v_lshlrev_b32_e32 v106, 16, v55
	v_and_b32_e32 v107, 0xffff0000, v55
	v_lshlrev_b32_e32 v108, 16, v47
	v_and_b32_e32 v109, 0xffff0000, v47
	v_pk_mul_f32 v[106:107], v[96:97], v[106:107] op_sel_hi:[0,1]
	v_pk_fma_f32 v[100:101], v[4:5], v[106:107], v[108:109]
	v_lshlrev_b32_e32 v106, 16, v56
	v_and_b32_e32 v107, 0xffff0000, v56
	v_lshlrev_b32_e32 v108, 16, v48
	v_and_b32_e32 v109, 0xffff0000, v48
	v_pk_mul_f32 v[106:107], v[96:97], v[106:107] op_sel_hi:[0,1]
	v_pk_fma_f32 v[102:103], v[6:7], v[106:107], v[108:109]
	v_lshlrev_b32_e32 v106, 16, v57
	v_and_b32_e32 v107, 0xffff0000, v57
	v_lshlrev_b32_e32 v108, 16, v49
	v_and_b32_e32 v109, 0xffff0000, v49
	v_pk_mul_f32 v[106:107], v[96:97], v[106:107] op_sel_hi:[0,1]
	v_pk_fma_f32 v[104:105], v[8:9], v[106:107], v[108:109]
	v_pk_fma_f32 v[110:111], v[98:99], v[98:99], v[110:111]
	v_pk_fma_f32 v[110:111], v[100:101], v[100:101], v[110:111]
	v_pk_fma_f32 v[110:111], v[102:103], v[102:103], v[110:111]
	v_pk_fma_f32 v[110:111], v[104:105], v[104:105], v[110:111]
	v_cvt_pk_bf16_f32 v46, v98, v99
	v_cvt_pk_bf16_f32 v47, v100, v101
	v_cvt_pk_bf16_f32 v48, v102, v103
	v_cvt_pk_bf16_f32 v49, v104, v105
	global_store_dwordx4 v19, v[46:49], s[4:5] offset:1024
	v_add_f32_e32 v112, v110, v111
	v_add_u32_e32 v22, 0x2000, v22
	s_nop 1
	v_add_f32_dpp v112, v112, v112 quad_perm:[1,0,3,2] row_mask:0xf bank_mask:0xf
	s_nop 1
	v_add_f32_dpp v112, v112, v112 quad_perm:[2,3,0,1] row_mask:0xf bank_mask:0xf
	s_nop 1
	v_add_f32_dpp v112, v112, v112 row_half_mirror row_mask:0xf bank_mask:0xf
	s_nop 1
	v_add_f32_dpp v112, v112, v112 row_mirror row_mask:0xf bank_mask:0xf
	s_nop 1
	v_add_f32_dpp v112, v112, v112 row_bcast:15 row_mask:0xa bank_mask:0xf
	s_nop 1
	v_add_f32_dpp v112, v112, v112 row_bcast:31 row_mask:0xc bank_mask:0xf
	v_fmamk_f32 v113, v112, 0x3a800000, v244
	v_rsq_f32_e32 v113, v113
	s_mov_b64 exec, s[8:9]
	global_store_dword v22, v113, s[4:5]
	s_mov_b64 exec, -1
	v_add_u32_e32 v18, 0x400000, v18
	v_add_u32_e32 v20, 0x400000, v20
	v_add_u32_e32 v21, 0x2000, v21
	global_load_dwordx4 v[42:45], v18, s[4:5]
	global_load_dwordx4 v[50:53], v20, s[6:7]
	global_load_dwordx4 v[46:49], v18, s[4:5] offset:1024
	global_load_dwordx4 v[54:57], v20, s[6:7] offset:1024
	global_load_dword v58, v21, s[4:5]
	s_waitcnt vmcnt(21)
; __device__ __forceinline__ float bflo(unsigned w) { return __uint_as_float(w << 16); }
; __device__ __forceinline__ float bfhi(unsigned w) { return __uint_as_float(w & 0xffff0000u); }
; __device__ __forceinline__ void resid_rows(bf16_t* R, const bf16_t* Y, const float* ssqY, const float* g, float* rstd_out, float* outf, bool wf32, int row_lo, int row_hi, int yoff, int gw, int NGW, int lane) {
;     ...
;     for (int row0 = row_lo + gw; row0 < row_hi; row0 += RP * NGW) {
;         u32x4 rr[RP][2], oo[RP][2]; float ssv[RP];
; #pragma unroll
;         for (int k = 0; k < RP; ++k) { const int row = row0 + k * NGW; const bool ok = row < row_hi; const int rw = ok ? row : row0;
;             ssv[k] = ssqY[rw];
; #pragma unroll
;             for (int j = 0; j < 2; ++j) { const int c = 8 * lane + 512 * j; rr[k][j] = *(const u32x4*)(R + (size_t)rw * DM + c); oo[k][j] = *(const u32x4*)(Y + (size_t)(rw - yoff) * DM + c); } }
; #pragma unroll
;         for (int k = 0; k < RP; ++k) { const int row = row0 + k * NGW; if (row < row_hi) {
;             const float rs = __builtin_amdgcn_rsqf(ssv[k] * (1.0f / DM) + RMS_EPS); float s = 0.f;
; #pragma unroll
;             for (int j = 0; j < 2; ++j) { const int c = 8 * lane + 512 * j; const u32x4 r = rr[k][j], o = oo[k][j]; const f32x4 ga = gv[j][0], gb = gv[j][1];
;                 f32x4 ya, yb; ya[0] = bflo(r.x) + bflo(o.x) * rs * ga[0]; ya[1] = bfhi(r.x) + bfhi(o.x) * rs * ga[1]; ya[2] = bflo(r.y) + bflo(o.y) * rs * ga[2]; ya[3] = bfhi(r.y) + bfhi(o.y) * rs * ga[3];
;                 yb[0] = bflo(r.z) + bflo(o.z) * rs * gb[0]; yb[1] = bfhi(r.z) + bfhi(o.z) * rs * gb[1]; yb[2] = bflo(r.w) + bflo(o.w) * rs * gb[2]; yb[3] = bfhi(r.w) + bfhi(o.w) * rs * gb[3];
;                 if (wf32) { *(f32x4*)(outf + (size_t)row * DM + c) = ya; *(f32x4*)(outf + (size_t)row * DM + c + 4) = yb; }
;                 s += (ya[0] * ya[0] + ya[1] * ya[1]) + (ya[2] * ya[2] + ya[3] * ya[3]) + (yb[0] * yb[0] + yb[1] * yb[1]) + (yb[2] * yb[2] + yb[3] * yb[3]);
;                 u32x4 w; w.x = pk2(ya[0], ya[1]); w.y = pk2(ya[2], ya[3]); w.z = pk2(yb[0], yb[1]); w.w = pk2(yb[2], yb[3]); *(u32x4*)(R + (size_t)row * DM + c) = w; }
;             s = wave_sum(s); if (lane == 0) rstd_out[row] = __builtin_amdgcn_rsqf(s * (1.0f / DM) + RMS_EPS); } }
	v_fmamk_f32 v96, v76, 0x3a800000, v244
	v_rsq_f32_e32 v96, v96
	v_add_u32_e32 v19, 0x400000, v19
	v_lshlrev_b32_e32 v106, 16, v68
	v_and_b32_e32 v107, 0xffff0000, v68
	v_lshlrev_b32_e32 v108, 16, v60
	v_and_b32_e32 v109, 0xffff0000, v60
	v_pk_mul_f32 v[106:107], v[96:97], v[106:107] op_sel_hi:[0,1]
	v_pk_fma_f32 v[98:99], v[10:11], v[106:107], v[108:109]
	v_lshlrev_b32_e32 v106, 16, v69
	v_and_b32_e32 v107, 0xffff0000, v69
	v_lshlrev_b32_e32 v108, 16, v61
	v_and_b32_e32 v109, 0xffff0000, v61
	v_pk_mul_f32 v[106:107], v[96:97], v[106:107] op_sel_hi:[0,1]
	v_pk_fma_f32 v[100:101], v[12:13], v[106:107], v[108:109]
	v_lshlrev_b32_e32 v106, 16, v70
	v_and_b32_e32 v107, 0xffff0000, v70
	v_lshlrev_b32_e32 v108, 16, v62
	v_and_b32_e32 v109, 0xffff0000, v62
	v_pk_mul_f32 v[106:107], v[96:97], v[106:107] op_sel_hi:[0,1]
	v_pk_fma_f32 v[102:103], v[14:15], v[106:107], v[108:109]
	v_lshlrev_b32_e32 v106, 16, v71
	v_and_b32_e32 v107, 0xffff0000, v71
	v_lshlrev_b32_e32 v108, 16, v63
	v_and_b32_e32 v109, 0xffff0000, v63
	v_pk_mul_f32 v[106:107], v[96:97], v[106:107] op_sel_hi:[0,1]
	v_pk_fma_f32 v[104:105], v[16:17], v[106:107], v[108:109]
	v_pk_mul_f32 v[110:111], v[98:99], v[98:99]
	v_pk_fma_f32 v[110:111], v[100:101], v[100:101], v[110:111]
	v_pk_fma_f32 v[110:111], v[102:103], v[102:103], v[110:111]
	v_pk_fma_f32 v[110:111], v[104:105], v[104:105], v[110:111]
	v_cvt_pk_bf16_f32 v60, v98, v99
	v_cvt_pk_bf16_f32 v61, v100, v101
	v_cvt_pk_bf16_f32 v62, v102, v103
	v_cvt_pk_bf16_f32 v63, v104, v105
	global_store_dwordx4 v19, v[60:63], s[4:5]
	v_lshlrev_b32_e32 v106, 16, v72
	v_and_b32_e32 v107, 0xffff0000, v72
	v_lshlrev_b32_e32 v108, 16, v64
	v_and_b32_e32 v109, 0xffff0000, v64
	v_pk_mul_f32 v[106:107], v[96:97], v[106:107] op_sel_hi:[0,1]
	v_pk_fma_f32 v[98:99], v[2:3], v[106:107], v[108:109]
	v_lshlrev_b32_e32 v106, 16, v73
	v_and_b32_e32 v107, 0xffff0000, v73
	v_lshlrev_b32_e32 v108, 16, v65
	v_and_b32_e32 v109, 0xffff0000, v65
	v_pk_mul_f32 v[106:107], v[96:97], v[106:107] op_sel_hi:[0,1]
	v_pk_fma_f32 v[100:101], v[4:5], v[106:107], v[108:109]
	v_lshlrev_b32_e32 v106, 16, v74
	v_and_b32_e32 v107, 0xffff0000, v74
	v_lshlrev_b32_e32 v108, 16, v66
	v_and_b32_e32 v109, 0xffff0000, v66
	v_pk_mul_f32 v[106:107], v[96:97], v[106:107] op_sel_hi:[0,1]
	v_pk_fma_f32 v[102:103], v[6:7], v[106:107], v[108:109]
	v_lshlrev_b32_e32 v106, 16, v75
	v_and_b32_e32 v107, 0xffff0000, v75
	v_lshlrev_b32_e32 v108, 16, v67
	v_and_b32_e32 v109, 0xffff0000, v67
	v_pk_mul_f32 v[106:107], v[96:97], v[106:107] op_sel_hi:[0,1]
	v_pk_fma_f32 v[104:105], v[8:9], v[106:107], v[108:109]
	v_pk_fma_f32 v[110:111], v[98:99], v[98:99], v[110:111]
	v_pk_fma_f32 v[110:111], v[100:101], v[100:101], v[110:111]
	v_pk_fma_f32 v[110:111], v[102:103], v[102:103], v[110:111]
	v_pk_fma_f32 v[110:111], v[104:105], v[104:105], v[110:111]
	v_cvt_pk_bf16_f32 v64, v98, v99
	v_cvt_pk_bf16_f32 v65, v100, v101
	v_cvt_pk_bf16_f32 v66, v102, v103
	v_cvt_pk_bf16_f32 v67, v104, v105
	global_store_dwordx4 v19, v[64:67], s[4:5] offset:1024
	v_add_f32_e32 v112, v110, v111
	v_add_u32_e32 v22, 0x2000, v22
	s_nop 1
	v_add_f32_dpp v112, v112, v112 quad_perm:[1,0,3,2] row_mask:0xf bank_mask:0xf
	s_nop 1
	v_add_f32_dpp v112, v112, v112 quad_perm:[2,3,0,1] row_mask:0xf bank_mask:0xf
	s_nop 1
	v_add_f32_dpp v112, v112, v112 row_half_mirror row_mask:0xf bank_mask:0xf
	s_nop 1
	v_add_f32_dpp v112, v112, v112 row_mirror row_mask:0xf bank_mask:0xf
	s_nop 1
	v_add_f32_dpp v112, v112, v112 row_bcast:15 row_mask:0xa bank_mask:0xf
	s_nop 1
	v_add_f32_dpp v112, v112, v112 row_bcast:31 row_mask:0xc bank_mask:0xf
	v_fmamk_f32 v113, v112, 0x3a800000, v244
	v_rsq_f32_e32 v113, v113
	s_mov_b64 exec, s[8:9]
	global_store_dword v22, v113, s[4:5]
	s_mov_b64 exec, -1
	v_add_u32_e32 v18, 0x400000, v18
	v_add_u32_e32 v20, 0x400000, v20
	v_add_u32_e32 v21, 0x2000, v21
	global_load_dwordx4 v[60:63], v18, s[4:5]
	global_load_dwordx4 v[68:71], v20, s[6:7]
	global_load_dwordx4 v[64:67], v18, s[4:5] offset:1024
	global_load_dwordx4 v[72:75], v20, s[6:7] offset:1024
	global_load_dword v76, v21, s[4:5]
	s_waitcnt vmcnt(24)
	v_fmamk_f32 v96, v94, 0x3a800000, v244
	v_rsq_f32_e32 v96, v96
	v_add_u32_e32 v19, 0x400000, v19
	v_lshlrev_b32_e32 v106, 16, v86
	v_and_b32_e32 v107, 0xffff0000, v86
	v_lshlrev_b32_e32 v108, 16, v78
	v_and_b32_e32 v109, 0xffff0000, v78
	v_pk_mul_f32 v[106:107], v[96:97], v[106:107] op_sel_hi:[0,1]
	v_pk_fma_f32 v[98:99], v[10:11], v[106:107], v[108:109]
	v_lshlrev_b32_e32 v106, 16, v87
	v_and_b32_e32 v107, 0xffff0000, v87
	v_lshlrev_b32_e32 v108, 16, v79
	v_and_b32_e32 v109, 0xffff0000, v79
	v_pk_mul_f32 v[106:107], v[96:97], v[106:107] op_sel_hi:[0,1]
	v_pk_fma_f32 v[100:101], v[12:13], v[106:107], v[108:109]
	v_lshlrev_b32_e32 v106, 16, v88
	v_and_b32_e32 v107, 0xffff0000, v88
	v_lshlrev_b32_e32 v108, 16, v80
	v_and_b32_e32 v109, 0xffff0000, v80
	v_pk_mul_f32 v[106:107], v[96:97], v[106:107] op_sel_hi:[0,1]
	v_pk_fma_f32 v[102:103], v[14:15], v[106:107], v[108:109]
	v_lshlrev_b32_e32 v106, 16, v89
	v_and_b32_e32 v107, 0xffff0000, v89
	v_lshlrev_b32_e32 v108, 16, v81
	v_and_b32_e32 v109, 0xffff0000, v81
	v_pk_mul_f32 v[106:107], v[96:97], v[106:107] op_sel_hi:[0,1]
	v_pk_fma_f32 v[104:105], v[16:17], v[106:107], v[108:109]
	v_pk_mul_f32 v[110:111], v[98:99], v[98:99]
	v_pk_fma_f32 v[110:111], v[100:101], v[100:101], v[110:111]
	v_pk_fma_f32 v[110:111], v[102:103], v[102:103], v[110:111]
	v_pk_fma_f32 v[110:111], v[104:105], v[104:105], v[110:111]
	v_cvt_pk_bf16_f32 v78, v98, v99
	v_cvt_pk_bf16_f32 v79, v100, v101
	v_cvt_pk_bf16_f32 v80, v102, v103
	v_cvt_pk_bf16_f32 v81, v104, v105
	global_store_dwordx4 v19, v[78:81], s[4:5]
; __device__ __forceinline__ float bflo(unsigned w) { return __uint_as_float(w << 16); }
; __device__ __forceinline__ float bfhi(unsigned w) { return __uint_as_float(w & 0xffff0000u); }
; __device__ __forceinline__ void resid_rows(bf16_t* R, const bf16_t* Y, const float* ssqY, const float* g, float* rstd_out, float* outf, bool wf32, int row_lo, int row_hi, int yoff, int gw, int NGW, int lane) {
;     ...
;     for (int row0 = row_lo + gw; row0 < row_hi; row0 += RP * NGW) {
;         u32x4 rr[RP][2], oo[RP][2]; float ssv[RP];
; #pragma unroll
;         for (int k = 0; k < RP; ++k) { const int row = row0 + k * NGW; const bool ok = row < row_hi; const int rw = ok ? row : row0;
;             ssv[k] = ssqY[rw];
; #pragma unroll
;             for (int j = 0; j < 2; ++j) { const int c = 8 * lane + 512 * j; rr[k][j] = *(const u32x4*)(R + (size_t)rw * DM + c); oo[k][j] = *(const u32x4*)(Y + (size_t)(rw - yoff) * DM + c); } }
; #pragma unroll
;         for (int k = 0; k < RP; ++k) { const int row = row0 + k * NGW; if (row < row_hi) {
;             const float rs = __builtin_amdgcn_rsqf(ssv[k] * (1.0f / DM) + RMS_EPS); float s = 0.f;
; #pragma unroll
;             for (int j = 0; j < 2; ++j) { const int c = 8 * lane + 512 * j; const u32x4 r = rr[k][j], o = oo[k][j]; const f32x4 ga = gv[j][0], gb = gv[j][1];
;                 f32x4 ya, yb; ya[0] = bflo(r.x) + bflo(o.x) * rs * ga[0]; ya[1] = bfhi(r.x) + bfhi(o.x) * rs * ga[1]; ya[2] = bflo(r.y) + bflo(o.y) * rs * ga[2]; ya[3] = bfhi(r.y) + bfhi(o.y) * rs * ga[3];
;                 yb[0] = bflo(r.z) + bflo(o.z) * rs * gb[0]; yb[1] = bfhi(r.z) + bfhi(o.z) * rs * gb[1]; yb[2] = bflo(r.w) + bflo(o.w) * rs * gb[2]; yb[3] = bfhi(r.w) + bfhi(o.w) * rs * gb[3];
;                 if (wf32) { *(f32x4*)(outf + (size_t)row * DM + c) = ya; *(f32x4*)(outf + (size_t)row * DM + c + 4) = yb; }
;                 s += (ya[0] * ya[0] + ya[1] * ya[1]) + (ya[2] * ya[2] + ya[3] * ya[3]) + (yb[0] * yb[0] + yb[1] * yb[1]) + (yb[2] * yb[2] + yb[3] * yb[3]);
;                 u32x4 w; w.x = pk2(ya[0], ya[1]); w.y = pk2(ya[2], ya[3]); w.z = pk2(yb[0], yb[1]); w.w = pk2(yb[2], yb[3]); *(u32x4*)(R + (size_t)row * DM + c) = w; }
;             s = wave_sum(s); if (lane == 0) rstd_out[row] = __builtin_amdgcn_rsqf(s * (1.0f / DM) + RMS_EPS); } }
	v_lshlrev_b32_e32 v106, 16, v90
	v_and_b32_e32 v107, 0xffff0000, v90
	v_lshlrev_b32_e32 v108, 16, v82
	v_and_b32_e32 v109, 0xffff0000, v82
	v_pk_mul_f32 v[106:107], v[96:97], v[106:107] op_sel_hi:[0,1]
	v_pk_fma_f32 v[98:99], v[2:3], v[106:107], v[108:109]
	v_lshlrev_b32_e32 v106, 16, v91
	v_and_b32_e32 v107, 0xffff0000, v91
	v_lshlrev_b32_e32 v108, 16, v83
	v_and_b32_e32 v109, 0xffff0000, v83
	v_pk_mul_f32 v[106:107], v[96:97], v[106:107] op_sel_hi:[0,1]
	v_pk_fma_f32 v[100:101], v[4:5], v[106:107], v[108:109]
	v_lshlrev_b32_e32 v106, 16, v92
	v_and_b32_e32 v107, 0xffff0000, v92
	v_lshlrev_b32_e32 v108, 16, v84
	v_and_b32_e32 v109, 0xffff0000, v84
	v_pk_mul_f32 v[106:107], v[96:97], v[106:107] op_sel_hi:[0,1]
	v_pk_fma_f32 v[102:103], v[6:7], v[106:107], v[108:109]
	v_lshlrev_b32_e32 v106, 16, v93
	v_and_b32_e32 v107, 0xffff0000, v93
	v_lshlrev_b32_e32 v108, 16, v85
	v_and_b32_e32 v109, 0xffff0000, v85
	v_pk_mul_f32 v[106:107], v[96:97], v[106:107] op_sel_hi:[0,1]
	v_pk_fma_f32 v[104:105], v[8:9], v[106:107], v[108:109]
	v_pk_fma_f32 v[110:111], v[98:99], v[98:99], v[110:111]
	v_pk_fma_f32 v[110:111], v[100:101], v[100:101], v[110:111]
	v_pk_fma_f32 v[110:111], v[102:103], v[102:103], v[110:111]
	v_pk_fma_f32 v[110:111], v[104:105], v[104:105], v[110:111]
	v_cvt_pk_bf16_f32 v82, v98, v99
	v_cvt_pk_bf16_f32 v83, v100, v101
	v_cvt_pk_bf16_f32 v84, v102, v103
	v_cvt_pk_bf16_f32 v85, v104, v105
	global_store_dwordx4 v19, v[82:85], s[4:5] offset:1024
	v_add_f32_e32 v112, v110, v111
	v_add_u32_e32 v22, 0x2000, v22
	s_nop 1
	v_add_f32_dpp v112, v112, v112 quad_perm:[1,0,3,2] row_mask:0xf bank_mask:0xf
	s_nop 1
	v_add_f32_dpp v112, v112, v112 quad_perm:[2,3,0,1] row_mask:0xf bank_mask:0xf
	s_nop 1
	v_add_f32_dpp v112, v112, v112 row_half_mirror row_mask:0xf bank_mask:0xf
	s_nop 1
	v_add_f32_dpp v112, v112, v112 row_mirror row_mask:0xf bank_mask:0xf
	s_nop 1
	v_add_f32_dpp v112, v112, v112 row_bcast:15 row_mask:0xa bank_mask:0xf
	s_nop 1
	v_add_f32_dpp v112, v112, v112 row_bcast:31 row_mask:0xc bank_mask:0xf
	v_fmamk_f32 v113, v112, 0x3a800000, v244
	v_rsq_f32_e32 v113, v113
	s_mov_b64 exec, s[8:9]
	global_store_dword v22, v113, s[4:5]
	s_mov_b64 exec, -1
	v_add_u32_e32 v18, 0x400000, v18
	v_add_u32_e32 v20, 0x400000, v20
	v_add_u32_e32 v21, 0x2000, v21
	global_load_dwordx4 v[78:81], v18, s[4:5]
	global_load_dwordx4 v[86:89], v20, s[6:7]
	global_load_dwordx4 v[82:85], v18, s[4:5] offset:1024
	global_load_dwordx4 v[90:93], v20, s[6:7] offset:1024
	global_load_dword v94, v21, s[4:5]
	s_waitcnt vmcnt(24)
	v_fmamk_f32 v96, v40, 0x3a800000, v244
	v_rsq_f32_e32 v96, v96
	v_add_u32_e32 v19, 0x400000, v19
	v_lshlrev_b32_e32 v106, 16, v32
	v_and_b32_e32 v107, 0xffff0000, v32
	v_lshlrev_b32_e32 v108, 16, v24
	v_and_b32_e32 v109, 0xffff0000, v24
	v_pk_mul_f32 v[106:107], v[96:97], v[106:107] op_sel_hi:[0,1]
	v_pk_fma_f32 v[98:99], v[10:11], v[106:107], v[108:109]
	v_lshlrev_b32_e32 v106, 16, v33
	v_and_b32_e32 v107, 0xffff0000, v33
	v_lshlrev_b32_e32 v108, 16, v25
	v_and_b32_e32 v109, 0xffff0000, v25
	v_pk_mul_f32 v[106:107], v[96:97], v[106:107] op_sel_hi:[0,1]
	v_pk_fma_f32 v[100:101], v[12:13], v[106:107], v[108:109]
	v_lshlrev_b32_e32 v106, 16, v34
	v_and_b32_e32 v107, 0xffff0000, v34
	v_lshlrev_b32_e32 v108, 16, v26
	v_and_b32_e32 v109, 0xffff0000, v26
	v_pk_mul_f32 v[106:107], v[96:97], v[106:107] op_sel_hi:[0,1]
	v_pk_fma_f32 v[102:103], v[14:15], v[106:107], v[108:109]
	v_lshlrev_b32_e32 v106, 16, v35
	v_and_b32_e32 v107, 0xffff0000, v35
	v_lshlrev_b32_e32 v108, 16, v27
	v_and_b32_e32 v109, 0xffff0000, v27
	v_pk_mul_f32 v[106:107], v[96:97], v[106:107] op_sel_hi:[0,1]
	v_pk_fma_f32 v[104:105], v[16:17], v[106:107], v[108:109]
	v_pk_mul_f32 v[110:111], v[98:99], v[98:99]
	v_pk_fma_f32 v[110:111], v[100:101], v[100:101], v[110:111]
	v_pk_fma_f32 v[110:111], v[102:103], v[102:103], v[110:111]
	v_pk_fma_f32 v[110:111], v[104:105], v[104:105], v[110:111]
	v_cvt_pk_bf16_f32 v24, v98, v99
	v_cvt_pk_bf16_f32 v25, v100, v101
	v_cvt_pk_bf16_f32 v26, v102, v103
	v_cvt_pk_bf16_f32 v27, v104, v105
	global_store_dwordx4 v19, v[24:27], s[4:5]
	v_lshlrev_b32_e32 v106, 16, v36
	v_and_b32_e32 v107, 0xffff0000, v36
	v_lshlrev_b32_e32 v108, 16, v28
	v_and_b32_e32 v109, 0xffff0000, v28
	v_pk_mul_f32 v[106:107], v[96:97], v[106:107] op_sel_hi:[0,1]
	v_pk_fma_f32 v[98:99], v[2:3], v[106:107], v[108:109]
	v_lshlrev_b32_e32 v106, 16, v37
	v_and_b32_e32 v107, 0xffff0000, v37
	v_lshlrev_b32_e32 v108, 16, v29
	v_and_b32_e32 v109, 0xffff0000, v29
	v_pk_mul_f32 v[106:107], v[96:97], v[106:107] op_sel_hi:[0,1]
	v_pk_fma_f32 v[100:101], v[4:5], v[106:107], v[108:109]
	v_lshlrev_b32_e32 v106, 16, v38
	v_and_b32_e32 v107, 0xffff0000, v38
	v_lshlrev_b32_e32 v108, 16, v30
	v_and_b32_e32 v109, 0xffff0000, v30
	v_pk_mul_f32 v[106:107], v[96:97], v[106:107] op_sel_hi:[0,1]
	v_pk_fma_f32 v[102:103], v[6:7], v[106:107], v[108:109]
	v_lshlrev_b32_e32 v106, 16, v39
	v_and_b32_e32 v107, 0xffff0000, v39
	v_lshlrev_b32_e32 v108, 16, v31
	v_and_b32_e32 v109, 0xffff0000, v31
	v_pk_mul_f32 v[106:107], v[96:97], v[106:107] op_sel_hi:[0,1]
	v_pk_fma_f32 v[104:105], v[8:9], v[106:107], v[108:109]
	v_pk_fma_f32 v[110:111], v[98:99], v[98:99], v[110:111]
	v_pk_fma_f32 v[110:111], v[100:101], v[100:101], v[110:111]
	v_pk_fma_f32 v[110:111], v[102:103], v[102:103], v[110:111]
	v_pk_fma_f32 v[110:111], v[104:105], v[104:105], v[110:111]
	v_cvt_pk_bf16_f32 v28, v98, v99
	v_cvt_pk_bf16_f32 v29, v100, v101
	v_cvt_pk_bf16_f32 v30, v102, v103
	v_cvt_pk_bf16_f32 v31, v104, v105
	global_store_dwordx4 v19, v[28:31], s[4:5] offset:1024
	v_add_f32_e32 v112, v110, v111
	v_add_u32_e32 v22, 0x2000, v22
	s_nop 1
	v_add_f32_dpp v112, v112, v112 quad_perm:[1,0,3,2] row_mask:0xf bank_mask:0xf
	s_nop 1
	v_add_f32_dpp v112, v112, v112 quad_perm:[2,3,0,1] row_mask:0xf bank_mask:0xf
	s_nop 1
	v_add_f32_dpp v112, v112, v112 row_half_mirror row_mask:0xf bank_mask:0xf
	s_nop 1
	v_add_f32_dpp v112, v112, v112 row_mirror row_mask:0xf bank_mask:0xf
	s_nop 1
	v_add_f32_dpp v112, v112, v112 row_bcast:15 row_mask:0xa bank_mask:0xf
	s_nop 1
	v_add_f32_dpp v112, v112, v112 row_bcast:31 row_mask:0xc bank_mask:0xf
	v_fmamk_f32 v113, v112, 0x3a800000, v244
	v_rsq_f32_e32 v113, v113
	s_mov_b64 exec, s[8:9]
	global_store_dword v22, v113, s[4:5]
	s_mov_b64 exec, -1
	v_add_u32_e32 v18, 0xfc400000, v18
	v_add_u32_e32 v20, 0xb400000, v20
	v_add_u32_e32 v21, 0xfffe2000, v21
	global_load_dwordx4 v[24:27], v18, s[4:5]
	global_load_dwordx4 v[32:35], v20, s[4:5]
	global_load_dwordx4 v[28:31], v18, s[4:5] offset:1024
	global_load_dwordx4 v[36:39], v20, s[4:5] offset:1024
	global_load_dword v40, v21, s[4:5]
	s_waitcnt vmcnt(24)
; __device__ __forceinline__ float bflo(unsigned w) { return __uint_as_float(w << 16); }
; __device__ __forceinline__ float bfhi(unsigned w) { return __uint_as_float(w & 0xffff0000u); }
; __device__ __forceinline__ void resid_rows(bf16_t* R, const bf16_t* Y, const float* ssqY, const float* g, float* rstd_out, float* outf, bool wf32, int row_lo, int row_hi, int yoff, int gw, int NGW, int lane) {
;     ...
;     for (int row0 = row_lo + gw; row0 < row_hi; row0 += RP * NGW) {
;         u32x4 rr[RP][2], oo[RP][2]; float ssv[RP];
; #pragma unroll
;         for (int k = 0; k < RP; ++k) { const int row = row0 + k * NGW; const bool ok = row < row_hi; const int rw = ok ? row : row0;
;             ssv[k] = ssqY[rw];
; #pragma unroll
;             for (int j = 0; j < 2; ++j) { const int c = 8 * lane + 512 * j; rr[k][j] = *(const u32x4*)(R + (size_t)rw * DM + c); oo[k][j] = *(const u32x4*)(Y + (size_t)(rw - yoff) * DM + c); } }
; #pragma unroll
;         for (int k = 0; k < RP; ++k) { const int row = row0 + k * NGW; if (row < row_hi) {
;             const float rs = __builtin_amdgcn_rsqf(ssv[k] * (1.0f / DM) + RMS_EPS); float s = 0.f;
; #pragma unroll
;             for (int j = 0; j < 2; ++j) { const int c = 8 * lane + 512 * j; const u32x4 r = rr[k][j], o = oo[k][j]; const f32x4 ga = gv[j][0], gb = gv[j][1];
;                 f32x4 ya, yb; ya[0] = bflo(r.x) + bflo(o.x) * rs * ga[0]; ya[1] = bfhi(r.x) + bfhi(o.x) * rs * ga[1]; ya[2] = bflo(r.y) + bflo(o.y) * rs * ga[2]; ya[3] = bfhi(r.y) + bfhi(o.y) * rs * ga[3];
;                 yb[0] = bflo(r.z) + bflo(o.z) * rs * gb[0]; yb[1] = bfhi(r.z) + bfhi(o.z) * rs * gb[1]; yb[2] = bflo(r.w) + bflo(o.w) * rs * gb[2]; yb[3] = bfhi(r.w) + bfhi(o.w) * rs * gb[3];
;                 if (wf32) { *(f32x4*)(outf + (size_t)row * DM + c) = ya; *(f32x4*)(outf + (size_t)row * DM + c + 4) = yb; }
;                 s += (ya[0] * ya[0] + ya[1] * ya[1]) + (ya[2] * ya[2] + ya[3] * ya[3]) + (yb[0] * yb[0] + yb[1] * yb[1]) + (yb[2] * yb[2] + yb[3] * yb[3]);
;                 u32x4 w; w.x = pk2(ya[0], ya[1]); w.y = pk2(ya[2], ya[3]); w.z = pk2(yb[0], yb[1]); w.w = pk2(yb[2], yb[3]); *(u32x4*)(R + (size_t)row * DM + c) = w; }
;             s = wave_sum(s); if (lane == 0) rstd_out[row] = __builtin_amdgcn_rsqf(s * (1.0f / DM) + RMS_EPS); } }
	v_fmamk_f32 v96, v58, 0x3a800000, v244
	v_rsq_f32_e32 v96, v96
	v_add_u32_e32 v19, 0x400000, v19
	v_lshlrev_b32_e32 v106, 16, v50
	v_and_b32_e32 v107, 0xffff0000, v50
	v_lshlrev_b32_e32 v108, 16, v42
	v_and_b32_e32 v109, 0xffff0000, v42
	v_pk_mul_f32 v[106:107], v[96:97], v[106:107] op_sel_hi:[0,1]
	v_pk_fma_f32 v[98:99], v[10:11], v[106:107], v[108:109]
	v_lshlrev_b32_e32 v106, 16, v51
	v_and_b32_e32 v107, 0xffff0000, v51
	v_lshlrev_b32_e32 v108, 16, v43
	v_and_b32_e32 v109, 0xffff0000, v43
	v_pk_mul_f32 v[106:107], v[96:97], v[106:107] op_sel_hi:[0,1]
	v_pk_fma_f32 v[100:101], v[12:13], v[106:107], v[108:109]
	v_lshlrev_b32_e32 v106, 16, v52
	v_and_b32_e32 v107, 0xffff0000, v52
	v_lshlrev_b32_e32 v108, 16, v44
	v_and_b32_e32 v109, 0xffff0000, v44
	v_pk_mul_f32 v[106:107], v[96:97], v[106:107] op_sel_hi:[0,1]
	v_pk_fma_f32 v[102:103], v[14:15], v[106:107], v[108:109]
	v_lshlrev_b32_e32 v106, 16, v53
	v_and_b32_e32 v107, 0xffff0000, v53
	v_lshlrev_b32_e32 v108, 16, v45
	v_and_b32_e32 v109, 0xffff0000, v45
	v_pk_mul_f32 v[106:107], v[96:97], v[106:107] op_sel_hi:[0,1]
	v_pk_fma_f32 v[104:105], v[16:17], v[106:107], v[108:109]
	v_pk_mul_f32 v[110:111], v[98:99], v[98:99]
	v_pk_fma_f32 v[110:111], v[100:101], v[100:101], v[110:111]
	v_pk_fma_f32 v[110:111], v[102:103], v[102:103], v[110:111]
	v_pk_fma_f32 v[110:111], v[104:105], v[104:105], v[110:111]
	v_cvt_pk_bf16_f32 v42, v98, v99
	v_cvt_pk_bf16_f32 v43, v100, v101
	v_cvt_pk_bf16_f32 v44, v102, v103
	v_cvt_pk_bf16_f32 v45, v104, v105
	global_store_dwordx4 v19, v[42:45], s[4:5]
	v_lshlrev_b32_e32 v106, 16, v54
	v_and_b32_e32 v107, 0xffff0000, v54
	v_lshlrev_b32_e32 v108, 16, v46
	v_and_b32_e32 v109, 0xffff0000, v46
	v_pk_mul_f32 v[106:107], v[96:97], v[106:107] op_sel_hi:[0,1]
	v_pk_fma_f32 v[98:99], v[2:3], v[106:107], v[108:109]
	v_lshlrev_b32_e32 v106, 16, v55
	v_and_b32_e32 v107, 0xffff0000, v55
	v_lshlrev_b32_e32 v108, 16, v47
	v_and_b32_e32 v109, 0xffff0000, v47
	v_pk_mul_f32 v[106:107], v[96:97], v[106:107] op_sel_hi:[0,1]
	v_pk_fma_f32 v[100:101], v[4:5], v[106:107], v[108:109]
	v_lshlrev_b32_e32 v106, 16, v56
	v_and_b32_e32 v107, 0xffff0000, v56
	v_lshlrev_b32_e32 v108, 16, v48
	v_and_b32_e32 v109, 0xffff0000, v48
	v_pk_mul_f32 v[106:107], v[96:97], v[106:107] op_sel_hi:[0,1]
	v_pk_fma_f32 v[102:103], v[6:7], v[106:107], v[108:109]
	v_lshlrev_b32_e32 v106, 16, v57
	v_and_b32_e32 v107, 0xffff0000, v57
	v_lshlrev_b32_e32 v108, 16, v49
	v_and_b32_e32 v109, 0xffff0000, v49
	v_pk_mul_f32 v[106:107], v[96:97], v[106:107] op_sel_hi:[0,1]
	v_pk_fma_f32 v[104:105], v[8:9], v[106:107], v[108:109]
	v_pk_fma_f32 v[110:111], v[98:99], v[98:99], v[110:111]
	v_pk_fma_f32 v[110:111], v[100:101], v[100:101], v[110:111]
	v_pk_fma_f32 v[110:111], v[102:103], v[102:103], v[110:111]
	v_pk_fma_f32 v[110:111], v[104:105], v[104:105], v[110:111]
	v_cvt_pk_bf16_f32 v46, v98, v99
	v_cvt_pk_bf16_f32 v47, v100, v101
	v_cvt_pk_bf16_f32 v48, v102, v103
	v_cvt_pk_bf16_f32 v49, v104, v105
	global_store_dwordx4 v19, v[46:49], s[4:5] offset:1024
	v_add_f32_e32 v112, v110, v111
	v_add_u32_e32 v22, 0x2000, v22
	s_nop 1
	v_add_f32_dpp v112, v112, v112 quad_perm:[1,0,3,2] row_mask:0xf bank_mask:0xf
	s_nop 1
	v_add_f32_dpp v112, v112, v112 quad_perm:[2,3,0,1] row_mask:0xf bank_mask:0xf
	s_nop 1
	v_add_f32_dpp v112, v112, v112 row_half_mirror row_mask:0xf bank_mask:0xf
	s_nop 1
	v_add_f32_dpp v112, v112, v112 row_mirror row_mask:0xf bank_mask:0xf
	s_nop 1
	v_add_f32_dpp v112, v112, v112 row_bcast:15 row_mask:0xa bank_mask:0xf
	s_nop 1
	v_add_f32_dpp v112, v112, v112 row_bcast:31 row_mask:0xc bank_mask:0xf
	v_fmamk_f32 v113, v112, 0x3a800000, v244
	v_rsq_f32_e32 v113, v113
	s_mov_b64 exec, s[8:9]
	global_store_dword v22, v113, s[4:5]
	s_mov_b64 exec, -1
	v_add_u32_e32 v18, 0x400000, v18
	v_add_u32_e32 v20, 0x400000, v20
	v_add_u32_e32 v21, 0x2000, v21
	global_load_dwordx4 v[42:45], v18, s[4:5]
	global_load_dwordx4 v[50:53], v20, s[4:5]
	global_load_dwordx4 v[46:49], v18, s[4:5] offset:1024
	global_load_dwordx4 v[54:57], v20, s[4:5] offset:1024
	global_load_dword v58, v21, s[4:5]
	s_waitcnt vmcnt(24)
	v_fmamk_f32 v96, v76, 0x3a800000, v244
	v_rsq_f32_e32 v96, v96
	v_add_u32_e32 v19, 0x400000, v19
	v_lshlrev_b32_e32 v106, 16, v68
	v_and_b32_e32 v107, 0xffff0000, v68
	v_lshlrev_b32_e32 v108, 16, v60
	v_and_b32_e32 v109, 0xffff0000, v60
	v_pk_mul_f32 v[106:107], v[96:97], v[106:107] op_sel_hi:[0,1]
	v_pk_fma_f32 v[98:99], v[10:11], v[106:107], v[108:109]
	v_lshlrev_b32_e32 v106, 16, v69
	v_and_b32_e32 v107, 0xffff0000, v69
	v_lshlrev_b32_e32 v108, 16, v61
	v_and_b32_e32 v109, 0xffff0000, v61
	v_pk_mul_f32 v[106:107], v[96:97], v[106:107] op_sel_hi:[0,1]
	v_pk_fma_f32 v[100:101], v[12:13], v[106:107], v[108:109]
	v_lshlrev_b32_e32 v106, 16, v70
	v_and_b32_e32 v107, 0xffff0000, v70
	v_lshlrev_b32_e32 v108, 16, v62
	v_and_b32_e32 v109, 0xffff0000, v62
	v_pk_mul_f32 v[106:107], v[96:97], v[106:107] op_sel_hi:[0,1]
	v_pk_fma_f32 v[102:103], v[14:15], v[106:107], v[108:109]
	v_lshlrev_b32_e32 v106, 16, v71
	v_and_b32_e32 v107, 0xffff0000, v71
	v_lshlrev_b32_e32 v108, 16, v63
	v_and_b32_e32 v109, 0xffff0000, v63
	v_pk_mul_f32 v[106:107], v[96:97], v[106:107] op_sel_hi:[0,1]
	v_pk_fma_f32 v[104:105], v[16:17], v[106:107], v[108:109]
	v_pk_mul_f32 v[110:111], v[98:99], v[98:99]
	v_pk_fma_f32 v[110:111], v[100:101], v[100:101], v[110:111]
	v_pk_fma_f32 v[110:111], v[102:103], v[102:103], v[110:111]
	v_pk_fma_f32 v[110:111], v[104:105], v[104:105], v[110:111]
	v_cvt_pk_bf16_f32 v60, v98, v99
	v_cvt_pk_bf16_f32 v61, v100, v101
	v_cvt_pk_bf16_f32 v62, v102, v103
	v_cvt_pk_bf16_f32 v63, v104, v105
	global_store_dwordx4 v19, v[60:63], s[4:5]
; __device__ __forceinline__ float bflo(unsigned w) { return __uint_as_float(w << 16); }
; __device__ __forceinline__ float bfhi(unsigned w) { return __uint_as_float(w & 0xffff0000u); }
; __device__ __forceinline__ void resid_rows(bf16_t* R, const bf16_t* Y, const float* ssqY, const float* g, float* rstd_out, float* outf, bool wf32, int row_lo, int row_hi, int yoff, int gw, int NGW, int lane) {
;     ...
;     for (int row0 = row_lo + gw; row0 < row_hi; row0 += RP * NGW) {
;         u32x4 rr[RP][2], oo[RP][2]; float ssv[RP];
; #pragma unroll
;         for (int k = 0; k < RP; ++k) { const int row = row0 + k * NGW; const bool ok = row < row_hi; const int rw = ok ? row : row0;
;             ssv[k] = ssqY[rw];
; #pragma unroll
;             for (int j = 0; j < 2; ++j) { const int c = 8 * lane + 512 * j; rr[k][j] = *(const u32x4*)(R + (size_t)rw * DM + c); oo[k][j] = *(const u32x4*)(Y + (size_t)(rw - yoff) * DM + c); } }
; #pragma unroll
;         for (int k = 0; k < RP; ++k) { const int row = row0 + k * NGW; if (row < row_hi) {
;             const float rs = __builtin_amdgcn_rsqf(ssv[k] * (1.0f / DM) + RMS_EPS); float s = 0.f;
; #pragma unroll
;             for (int j = 0; j < 2; ++j) { const int c = 8 * lane + 512 * j; const u32x4 r = rr[k][j], o = oo[k][j]; const f32x4 ga = gv[j][0], gb = gv[j][1];
;                 f32x4 ya, yb; ya[0] = bflo(r.x) + bflo(o.x) * rs * ga[0]; ya[1] = bfhi(r.x) + bfhi(o.x) * rs * ga[1]; ya[2] = bflo(r.y) + bflo(o.y) * rs * ga[2]; ya[3] = bfhi(r.y) + bfhi(o.y) * rs * ga[3];
;                 yb[0] = bflo(r.z) + bflo(o.z) * rs * gb[0]; yb[1] = bfhi(r.z) + bfhi(o.z) * rs * gb[1]; yb[2] = bflo(r.w) + bflo(o.w) * rs * gb[2]; yb[3] = bfhi(r.w) + bfhi(o.w) * rs * gb[3];
;                 if (wf32) { *(f32x4*)(outf + (size_t)row * DM + c) = ya; *(f32x4*)(outf + (size_t)row * DM + c + 4) = yb; }
;                 s += (ya[0] * ya[0] + ya[1] * ya[1]) + (ya[2] * ya[2] + ya[3] * ya[3]) + (yb[0] * yb[0] + yb[1] * yb[1]) + (yb[2] * yb[2] + yb[3] * yb[3]);
;                 u32x4 w; w.x = pk2(ya[0], ya[1]); w.y = pk2(ya[2], ya[3]); w.z = pk2(yb[0], yb[1]); w.w = pk2(yb[2], yb[3]); *(u32x4*)(R + (size_t)row * DM + c) = w; }
;             s = wave_sum(s); if (lane == 0) rstd_out[row] = __builtin_amdgcn_rsqf(s * (1.0f / DM) + RMS_EPS); } }
	v_lshlrev_b32_e32 v106, 16, v72
	v_and_b32_e32 v107, 0xffff0000, v72
	v_lshlrev_b32_e32 v108, 16, v64
	v_and_b32_e32 v109, 0xffff0000, v64
	v_pk_mul_f32 v[106:107], v[96:97], v[106:107] op_sel_hi:[0,1]
	v_pk_fma_f32 v[98:99], v[2:3], v[106:107], v[108:109]
	v_lshlrev_b32_e32 v106, 16, v73
	v_and_b32_e32 v107, 0xffff0000, v73
	v_lshlrev_b32_e32 v108, 16, v65
	v_and_b32_e32 v109, 0xffff0000, v65
	v_pk_mul_f32 v[106:107], v[96:97], v[106:107] op_sel_hi:[0,1]
	v_pk_fma_f32 v[100:101], v[4:5], v[106:107], v[108:109]
	v_lshlrev_b32_e32 v106, 16, v74
	v_and_b32_e32 v107, 0xffff0000, v74
	v_lshlrev_b32_e32 v108, 16, v66
	v_and_b32_e32 v109, 0xffff0000, v66
	v_pk_mul_f32 v[106:107], v[96:97], v[106:107] op_sel_hi:[0,1]
	v_pk_fma_f32 v[102:103], v[6:7], v[106:107], v[108:109]
	v_lshlrev_b32_e32 v106, 16, v75
	v_and_b32_e32 v107, 0xffff0000, v75
	v_lshlrev_b32_e32 v108, 16, v67
	v_and_b32_e32 v109, 0xffff0000, v67
	v_pk_mul_f32 v[106:107], v[96:97], v[106:107] op_sel_hi:[0,1]
	v_pk_fma_f32 v[104:105], v[8:9], v[106:107], v[108:109]
	v_pk_fma_f32 v[110:111], v[98:99], v[98:99], v[110:111]
	v_pk_fma_f32 v[110:111], v[100:101], v[100:101], v[110:111]
	v_pk_fma_f32 v[110:111], v[102:103], v[102:103], v[110:111]
	v_pk_fma_f32 v[110:111], v[104:105], v[104:105], v[110:111]
	v_cvt_pk_bf16_f32 v64, v98, v99
	v_cvt_pk_bf16_f32 v65, v100, v101
	v_cvt_pk_bf16_f32 v66, v102, v103
	v_cvt_pk_bf16_f32 v67, v104, v105
	global_store_dwordx4 v19, v[64:67], s[4:5] offset:1024
	v_add_f32_e32 v112, v110, v111
	v_add_u32_e32 v22, 0x2000, v22
	s_nop 1
	v_add_f32_dpp v112, v112, v112 quad_perm:[1,0,3,2] row_mask:0xf bank_mask:0xf
	s_nop 1
	v_add_f32_dpp v112, v112, v112 quad_perm:[2,3,0,1] row_mask:0xf bank_mask:0xf
	s_nop 1
	v_add_f32_dpp v112, v112, v112 row_half_mirror row_mask:0xf bank_mask:0xf
	s_nop 1
	v_add_f32_dpp v112, v112, v112 row_mirror row_mask:0xf bank_mask:0xf
	s_nop 1
	v_add_f32_dpp v112, v112, v112 row_bcast:15 row_mask:0xa bank_mask:0xf
	s_nop 1
	v_add_f32_dpp v112, v112, v112 row_bcast:31 row_mask:0xc bank_mask:0xf
	v_fmamk_f32 v113, v112, 0x3a800000, v244
	v_rsq_f32_e32 v113, v113
	s_mov_b64 exec, s[8:9]
	global_store_dword v22, v113, s[4:5]
	s_mov_b64 exec, -1
	v_add_u32_e32 v18, 0x400000, v18
	v_add_u32_e32 v20, 0x400000, v20
	v_add_u32_e32 v21, 0x2000, v21
	global_load_dwordx4 v[60:63], v18, s[4:5]
	global_load_dwordx4 v[68:71], v20, s[4:5]
	global_load_dwordx4 v[64:67], v18, s[4:5] offset:1024
	global_load_dwordx4 v[72:75], v20, s[4:5] offset:1024
	global_load_dword v76, v21, s[4:5]
	s_waitcnt vmcnt(24)
	v_fmamk_f32 v96, v94, 0x3a800000, v244
	v_rsq_f32_e32 v96, v96
	v_add_u32_e32 v19, 0x400000, v19
	v_lshlrev_b32_e32 v106, 16, v86
	v_and_b32_e32 v107, 0xffff0000, v86
	v_lshlrev_b32_e32 v108, 16, v78
	v_and_b32_e32 v109, 0xffff0000, v78
	v_pk_mul_f32 v[106:107], v[96:97], v[106:107] op_sel_hi:[0,1]
	v_pk_fma_f32 v[98:99], v[10:11], v[106:107], v[108:109]
	v_lshlrev_b32_e32 v106, 16, v87
	v_and_b32_e32 v107, 0xffff0000, v87
	v_lshlrev_b32_e32 v108, 16, v79
	v_and_b32_e32 v109, 0xffff0000, v79
	v_pk_mul_f32 v[106:107], v[96:97], v[106:107] op_sel_hi:[0,1]
	v_pk_fma_f32 v[100:101], v[12:13], v[106:107], v[108:109]
	v_lshlrev_b32_e32 v106, 16, v88
	v_and_b32_e32 v107, 0xffff0000, v88
	v_lshlrev_b32_e32 v108, 16, v80
	v_and_b32_e32 v109, 0xffff0000, v80
	v_pk_mul_f32 v[106:107], v[96:97], v[106:107] op_sel_hi:[0,1]
	v_pk_fma_f32 v[102:103], v[14:15], v[106:107], v[108:109]
	v_lshlrev_b32_e32 v106, 16, v89
	v_and_b32_e32 v107, 0xffff0000, v89
	v_lshlrev_b32_e32 v108, 16, v81
	v_and_b32_e32 v109, 0xffff0000, v81
	v_pk_mul_f32 v[106:107], v[96:97], v[106:107] op_sel_hi:[0,1]
	v_pk_fma_f32 v[104:105], v[16:17], v[106:107], v[108:109]
	v_pk_mul_f32 v[110:111], v[98:99], v[98:99]
	v_pk_fma_f32 v[110:111], v[100:101], v[100:101], v[110:111]
	v_pk_fma_f32 v[110:111], v[102:103], v[102:103], v[110:111]
	v_pk_fma_f32 v[110:111], v[104:105], v[104:105], v[110:111]
	v_cvt_pk_bf16_f32 v78, v98, v99
	v_cvt_pk_bf16_f32 v79, v100, v101
	v_cvt_pk_bf16_f32 v80, v102, v103
	v_cvt_pk_bf16_f32 v81, v104, v105
	global_store_dwordx4 v19, v[78:81], s[4:5]
	v_lshlrev_b32_e32 v106, 16, v90
	v_and_b32_e32 v107, 0xffff0000, v90
	v_lshlrev_b32_e32 v108, 16, v82
	v_and_b32_e32 v109, 0xffff0000, v82
	v_pk_mul_f32 v[106:107], v[96:97], v[106:107] op_sel_hi:[0,1]
	v_pk_fma_f32 v[98:99], v[2:3], v[106:107], v[108:109]
	v_lshlrev_b32_e32 v106, 16, v91
	v_and_b32_e32 v107, 0xffff0000, v91
	v_lshlrev_b32_e32 v108, 16, v83
	v_and_b32_e32 v109, 0xffff0000, v83
	v_pk_mul_f32 v[106:107], v[96:97], v[106:107] op_sel_hi:[0,1]
	v_pk_fma_f32 v[100:101], v[4:5], v[106:107], v[108:109]
	v_lshlrev_b32_e32 v106, 16, v92
	v_and_b32_e32 v107, 0xffff0000, v92
	v_lshlrev_b32_e32 v108, 16, v84
	v_and_b32_e32 v109, 0xffff0000, v84
	v_pk_mul_f32 v[106:107], v[96:97], v[106:107] op_sel_hi:[0,1]
	v_pk_fma_f32 v[102:103], v[6:7], v[106:107], v[108:109]
	v_lshlrev_b32_e32 v106, 16, v93
	v_and_b32_e32 v107, 0xffff0000, v93
	v_lshlrev_b32_e32 v108, 16, v85
	v_and_b32_e32 v109, 0xffff0000, v85
	v_pk_mul_f32 v[106:107], v[96:97], v[106:107] op_sel_hi:[0,1]
	v_pk_fma_f32 v[104:105], v[8:9], v[106:107], v[108:109]
	v_pk_fma_f32 v[110:111], v[98:99], v[98:99], v[110:111]
	v_pk_fma_f32 v[110:111], v[100:101], v[100:101], v[110:111]
	v_pk_fma_f32 v[110:111], v[102:103], v[102:103], v[110:111]
	v_pk_fma_f32 v[110:111], v[104:105], v[104:105], v[110:111]
	v_cvt_pk_bf16_f32 v82, v98, v99
	v_cvt_pk_bf16_f32 v83, v100, v101
	v_cvt_pk_bf16_f32 v84, v102, v103
	v_cvt_pk_bf16_f32 v85, v104, v105
	global_store_dwordx4 v19, v[82:85], s[4:5] offset:1024
	v_add_f32_e32 v112, v110, v111
	v_add_u32_e32 v22, 0x2000, v22
	s_nop 1
	v_add_f32_dpp v112, v112, v112 quad_perm:[1,0,3,2] row_mask:0xf bank_mask:0xf
	s_nop 1
	v_add_f32_dpp v112, v112, v112 quad_perm:[2,3,0,1] row_mask:0xf bank_mask:0xf
	s_nop 1
	v_add_f32_dpp v112, v112, v112 row_half_mirror row_mask:0xf bank_mask:0xf
	s_nop 1
	v_add_f32_dpp v112, v112, v112 row_mirror row_mask:0xf bank_mask:0xf
	s_nop 1
	v_add_f32_dpp v112, v112, v112 row_bcast:15 row_mask:0xa bank_mask:0xf
	s_nop 1
	v_add_f32_dpp v112, v112, v112 row_bcast:31 row_mask:0xc bank_mask:0xf
	v_fmamk_f32 v113, v112, 0x3a800000, v244
	v_rsq_f32_e32 v113, v113
	s_mov_b64 exec, s[8:9]
	global_store_dword v22, v113, s[4:5]
	s_mov_b64 exec, -1
	v_add_u32_e32 v18, 0x400000, v18
	v_add_u32_e32 v20, 0x400000, v20
	v_add_u32_e32 v21, 0x2000, v21
	global_load_dwordx4 v[78:81], v18, s[4:5]
	global_load_dwordx4 v[86:89], v20, s[4:5]
	global_load_dwordx4 v[82:85], v18, s[4:5] offset:1024
	global_load_dwordx4 v[90:93], v20, s[4:5] offset:1024
	global_load_dword v94, v21, s[4:5]
	s_waitcnt vmcnt(24)
; __device__ __forceinline__ float bflo(unsigned w) { return __uint_as_float(w << 16); }
; __device__ __forceinline__ float bfhi(unsigned w) { return __uint_as_float(w & 0xffff0000u); }
; __device__ __forceinline__ void resid_rows(bf16_t* R, const bf16_t* Y, const float* ssqY, const float* g, float* rstd_out, float* outf, bool wf32, int row_lo, int row_hi, int yoff, int gw, int NGW, int lane) {
;     ...
;     for (int row0 = row_lo + gw; row0 < row_hi; row0 += RP * NGW) {
;         u32x4 rr[RP][2], oo[RP][2]; float ssv[RP];
; #pragma unroll
;         for (int k = 0; k < RP; ++k) { const int row = row0 + k * NGW; const bool ok = row < row_hi; const int rw = ok ? row : row0;
;             ssv[k] = ssqY[rw];
; #pragma unroll
;             for (int j = 0; j < 2; ++j) { const int c = 8 * lane + 512 * j; rr[k][j] = *(const u32x4*)(R + (size_t)rw * DM + c); oo[k][j] = *(const u32x4*)(Y + (size_t)(rw - yoff) * DM + c); } }
; #pragma unroll
;         for (int k = 0; k < RP; ++k) { const int row = row0 + k * NGW; if (row < row_hi) {
;             const float rs = __builtin_amdgcn_rsqf(ssv[k] * (1.0f / DM) + RMS_EPS); float s = 0.f;
; #pragma unroll
;             for (int j = 0; j < 2; ++j) { const int c = 8 * lane + 512 * j; const u32x4 r = rr[k][j], o = oo[k][j]; const f32x4 ga = gv[j][0], gb = gv[j][1];
;                 f32x4 ya, yb; ya[0] = bflo(r.x) + bflo(o.x) * rs * ga[0]; ya[1] = bfhi(r.x) + bfhi(o.x) * rs * ga[1]; ya[2] = bflo(r.y) + bflo(o.y) * rs * ga[2]; ya[3] = bfhi(r.y) + bfhi(o.y) * rs * ga[3];
;                 yb[0] = bflo(r.z) + bflo(o.z) * rs * gb[0]; yb[1] = bfhi(r.z) + bfhi(o.z) * rs * gb[1]; yb[2] = bflo(r.w) + bflo(o.w) * rs * gb[2]; yb[3] = bfhi(r.w) + bfhi(o.w) * rs * gb[3];
;                 if (wf32) { *(f32x4*)(outf + (size_t)row * DM + c) = ya; *(f32x4*)(outf + (size_t)row * DM + c + 4) = yb; }
;                 s += (ya[0] * ya[0] + ya[1] * ya[1]) + (ya[2] * ya[2] + ya[3] * ya[3]) + (yb[0] * yb[0] + yb[1] * yb[1]) + (yb[2] * yb[2] + yb[3] * yb[3]);
;                 u32x4 w; w.x = pk2(ya[0], ya[1]); w.y = pk2(ya[2], ya[3]); w.z = pk2(yb[0], yb[1]); w.w = pk2(yb[2], yb[3]); *(u32x4*)(R + (size_t)row * DM + c) = w; }
;             s = wave_sum(s); if (lane == 0) rstd_out[row] = __builtin_amdgcn_rsqf(s * (1.0f / DM) + RMS_EPS); } }
	v_fmamk_f32 v96, v40, 0x3a800000, v244
	v_rsq_f32_e32 v96, v96
	v_add_u32_e32 v19, 0xfc400000, v19
	v_lshlrev_b32_e32 v106, 16, v32
	v_and_b32_e32 v107, 0xffff0000, v32
	v_lshlrev_b32_e32 v108, 16, v24
	v_and_b32_e32 v109, 0xffff0000, v24
	v_pk_mul_f32 v[106:107], v[96:97], v[106:107] op_sel_hi:[0,1]
	v_pk_fma_f32 v[98:99], v[10:11], v[106:107], v[108:109]
	v_lshlrev_b32_e32 v106, 16, v33
	v_and_b32_e32 v107, 0xffff0000, v33
	v_lshlrev_b32_e32 v108, 16, v25
	v_and_b32_e32 v109, 0xffff0000, v25
	v_pk_mul_f32 v[106:107], v[96:97], v[106:107] op_sel_hi:[0,1]
	v_pk_fma_f32 v[100:101], v[12:13], v[106:107], v[108:109]
	v_lshlrev_b32_e32 v106, 16, v34
	v_and_b32_e32 v107, 0xffff0000, v34
	v_lshlrev_b32_e32 v108, 16, v26
	v_and_b32_e32 v109, 0xffff0000, v26
	v_pk_mul_f32 v[106:107], v[96:97], v[106:107] op_sel_hi:[0,1]
	v_pk_fma_f32 v[102:103], v[14:15], v[106:107], v[108:109]
	v_lshlrev_b32_e32 v106, 16, v35
	v_and_b32_e32 v107, 0xffff0000, v35
	v_lshlrev_b32_e32 v108, 16, v27
	v_and_b32_e32 v109, 0xffff0000, v27
	v_pk_mul_f32 v[106:107], v[96:97], v[106:107] op_sel_hi:[0,1]
	v_pk_fma_f32 v[104:105], v[16:17], v[106:107], v[108:109]
	v_pk_mul_f32 v[110:111], v[98:99], v[98:99]
	v_pk_fma_f32 v[110:111], v[100:101], v[100:101], v[110:111]
	v_pk_fma_f32 v[110:111], v[102:103], v[102:103], v[110:111]
	v_pk_fma_f32 v[110:111], v[104:105], v[104:105], v[110:111]
	v_cvt_pk_bf16_f32 v24, v98, v99
	v_cvt_pk_bf16_f32 v25, v100, v101
	v_cvt_pk_bf16_f32 v26, v102, v103
	v_cvt_pk_bf16_f32 v27, v104, v105
	global_store_dwordx4 v19, v[24:27], s[4:5]
	v_lshlrev_b32_e32 v106, 16, v36
	v_and_b32_e32 v107, 0xffff0000, v36
	v_lshlrev_b32_e32 v108, 16, v28
	v_and_b32_e32 v109, 0xffff0000, v28
	v_pk_mul_f32 v[106:107], v[96:97], v[106:107] op_sel_hi:[0,1]
	v_pk_fma_f32 v[98:99], v[2:3], v[106:107], v[108:109]
	v_lshlrev_b32_e32 v106, 16, v37
	v_and_b32_e32 v107, 0xffff0000, v37
	v_lshlrev_b32_e32 v108, 16, v29
	v_and_b32_e32 v109, 0xffff0000, v29
	v_pk_mul_f32 v[106:107], v[96:97], v[106:107] op_sel_hi:[0,1]
	v_pk_fma_f32 v[100:101], v[4:5], v[106:107], v[108:109]
	v_lshlrev_b32_e32 v106, 16, v38
	v_and_b32_e32 v107, 0xffff0000, v38
	v_lshlrev_b32_e32 v108, 16, v30
	v_and_b32_e32 v109, 0xffff0000, v30
	v_pk_mul_f32 v[106:107], v[96:97], v[106:107] op_sel_hi:[0,1]
	v_pk_fma_f32 v[102:103], v[6:7], v[106:107], v[108:109]
	v_lshlrev_b32_e32 v106, 16, v39
	v_and_b32_e32 v107, 0xffff0000, v39
	v_lshlrev_b32_e32 v108, 16, v31
	v_and_b32_e32 v109, 0xffff0000, v31
	v_pk_mul_f32 v[106:107], v[96:97], v[106:107] op_sel_hi:[0,1]
	v_pk_fma_f32 v[104:105], v[8:9], v[106:107], v[108:109]
	v_pk_fma_f32 v[110:111], v[98:99], v[98:99], v[110:111]
	v_pk_fma_f32 v[110:111], v[100:101], v[100:101], v[110:111]
	v_pk_fma_f32 v[110:111], v[102:103], v[102:103], v[110:111]
	v_pk_fma_f32 v[110:111], v[104:105], v[104:105], v[110:111]
	v_cvt_pk_bf16_f32 v28, v98, v99
	v_cvt_pk_bf16_f32 v29, v100, v101
	v_cvt_pk_bf16_f32 v30, v102, v103
	v_cvt_pk_bf16_f32 v31, v104, v105
	global_store_dwordx4 v19, v[28:31], s[4:5] offset:1024
	v_add_f32_e32 v112, v110, v111
	v_add_u32_e32 v22, 0xfffe2000, v22
	s_nop 1
	v_add_f32_dpp v112, v112, v112 quad_perm:[1,0,3,2] row_mask:0xf bank_mask:0xf
	s_nop 1
	v_add_f32_dpp v112, v112, v112 quad_perm:[2,3,0,1] row_mask:0xf bank_mask:0xf
	s_nop 1
	v_add_f32_dpp v112, v112, v112 row_half_mirror row_mask:0xf bank_mask:0xf
	s_nop 1
	v_add_f32_dpp v112, v112, v112 row_mirror row_mask:0xf bank_mask:0xf
	s_nop 1
	v_add_f32_dpp v112, v112, v112 row_bcast:15 row_mask:0xa bank_mask:0xf
	s_nop 1
	v_add_f32_dpp v112, v112, v112 row_bcast:31 row_mask:0xc bank_mask:0xf
	v_fmamk_f32 v113, v112, 0x3a800000, v244
	v_rsq_f32_e32 v113, v113
	s_mov_b64 exec, s[8:9]
	global_store_dword v22, v113, s[4:5]
	s_mov_b64 exec, -1
	v_add_u32_e32 v18, 0x400000, v18
	v_add_u32_e32 v20, 0x400000, v20
	v_add_u32_e32 v21, 0x2000, v21
	global_load_dwordx4 v[24:27], v18, s[4:5]
	global_load_dwordx4 v[32:35], v20, s[4:5]
	global_load_dwordx4 v[28:31], v18, s[4:5] offset:1024
	global_load_dwordx4 v[36:39], v20, s[4:5] offset:1024
	global_load_dword v40, v21, s[4:5]
	s_waitcnt vmcnt(24)
	v_fmamk_f32 v96, v58, 0x3a800000, v244
	v_rsq_f32_e32 v96, v96
	v_add_u32_e32 v19, 0x400000, v19
	v_lshlrev_b32_e32 v106, 16, v50
	v_and_b32_e32 v107, 0xffff0000, v50
	v_lshlrev_b32_e32 v108, 16, v42
	v_and_b32_e32 v109, 0xffff0000, v42
	v_pk_mul_f32 v[106:107], v[96:97], v[106:107] op_sel_hi:[0,1]
	v_pk_fma_f32 v[98:99], v[10:11], v[106:107], v[108:109]
	v_lshlrev_b32_e32 v106, 16, v51
	v_and_b32_e32 v107, 0xffff0000, v51
	v_lshlrev_b32_e32 v108, 16, v43
	v_and_b32_e32 v109, 0xffff0000, v43
	v_pk_mul_f32 v[106:107], v[96:97], v[106:107] op_sel_hi:[0,1]
	v_pk_fma_f32 v[100:101], v[12:13], v[106:107], v[108:109]
	v_lshlrev_b32_e32 v106, 16, v52
	v_and_b32_e32 v107, 0xffff0000, v52
	v_lshlrev_b32_e32 v108, 16, v44
	v_and_b32_e32 v109, 0xffff0000, v44
	v_pk_mul_f32 v[106:107], v[96:97], v[106:107] op_sel_hi:[0,1]
	v_pk_fma_f32 v[102:103], v[14:15], v[106:107], v[108:109]
	v_lshlrev_b32_e32 v106, 16, v53
	v_and_b32_e32 v107, 0xffff0000, v53
	v_lshlrev_b32_e32 v108, 16, v45
	v_and_b32_e32 v109, 0xffff0000, v45
	v_pk_mul_f32 v[106:107], v[96:97], v[106:107] op_sel_hi:[0,1]
	v_pk_fma_f32 v[104:105], v[16:17], v[106:107], v[108:109]
	v_pk_mul_f32 v[110:111], v[98:99], v[98:99]
	v_pk_fma_f32 v[110:111], v[100:101], v[100:101], v[110:111]
	v_pk_fma_f32 v[110:111], v[102:103], v[102:103], v[110:111]
	v_pk_fma_f32 v[110:111], v[104:105], v[104:105], v[110:111]
	v_cvt_pk_bf16_f32 v42, v98, v99
	v_cvt_pk_bf16_f32 v43, v100, v101
	v_cvt_pk_bf16_f32 v44, v102, v103
	v_cvt_pk_bf16_f32 v45, v104, v105
	global_store_dwordx4 v19, v[42:45], s[4:5]
; __device__ __forceinline__ float bflo(unsigned w) { return __uint_as_float(w << 16); }
; __device__ __forceinline__ float bfhi(unsigned w) { return __uint_as_float(w & 0xffff0000u); }
; __device__ __forceinline__ void resid_rows(bf16_t* R, const bf16_t* Y, const float* ssqY, const float* g, float* rstd_out, float* outf, bool wf32, int row_lo, int row_hi, int yoff, int gw, int NGW, int lane) {
;     ...
;     for (int row0 = row_lo + gw; row0 < row_hi; row0 += RP * NGW) {
;         u32x4 rr[RP][2], oo[RP][2]; float ssv[RP];
; #pragma unroll
;         for (int k = 0; k < RP; ++k) { const int row = row0 + k * NGW; const bool ok = row < row_hi; const int rw = ok ? row : row0;
;             ssv[k] = ssqY[rw];
; #pragma unroll
;             for (int j = 0; j < 2; ++j) { const int c = 8 * lane + 512 * j; rr[k][j] = *(const u32x4*)(R + (size_t)rw * DM + c); oo[k][j] = *(const u32x4*)(Y + (size_t)(rw - yoff) * DM + c); } }
; #pragma unroll
;         for (int k = 0; k < RP; ++k) { const int row = row0 + k * NGW; if (row < row_hi) {
;             const float rs = __builtin_amdgcn_rsqf(ssv[k] * (1.0f / DM) + RMS_EPS); float s = 0.f;
; #pragma unroll
;             for (int j = 0; j < 2; ++j) { const int c = 8 * lane + 512 * j; const u32x4 r = rr[k][j], o = oo[k][j]; const f32x4 ga = gv[j][0], gb = gv[j][1];
;                 f32x4 ya, yb; ya[0] = bflo(r.x) + bflo(o.x) * rs * ga[0]; ya[1] = bfhi(r.x) + bfhi(o.x) * rs * ga[1]; ya[2] = bflo(r.y) + bflo(o.y) * rs * ga[2]; ya[3] = bfhi(r.y) + bfhi(o.y) * rs * ga[3];
;                 yb[0] = bflo(r.z) + bflo(o.z) * rs * gb[0]; yb[1] = bfhi(r.z) + bfhi(o.z) * rs * gb[1]; yb[2] = bflo(r.w) + bflo(o.w) * rs * gb[2]; yb[3] = bfhi(r.w) + bfhi(o.w) * rs * gb[3];
;                 if (wf32) { *(f32x4*)(outf + (size_t)row * DM + c) = ya; *(f32x4*)(outf + (size_t)row * DM + c + 4) = yb; }
;                 s += (ya[0] * ya[0] + ya[1] * ya[1]) + (ya[2] * ya[2] + ya[3] * ya[3]) + (yb[0] * yb[0] + yb[1] * yb[1]) + (yb[2] * yb[2] + yb[3] * yb[3]);
;                 u32x4 w; w.x = pk2(ya[0], ya[1]); w.y = pk2(ya[2], ya[3]); w.z = pk2(yb[0], yb[1]); w.w = pk2(yb[2], yb[3]); *(u32x4*)(R + (size_t)row * DM + c) = w; }
;             s = wave_sum(s); if (lane == 0) rstd_out[row] = __builtin_amdgcn_rsqf(s * (1.0f / DM) + RMS_EPS); } }
	v_lshlrev_b32_e32 v106, 16, v54
	v_and_b32_e32 v107, 0xffff0000, v54
	v_lshlrev_b32_e32 v108, 16, v46
	v_and_b32_e32 v109, 0xffff0000, v46
	v_pk_mul_f32 v[106:107], v[96:97], v[106:107] op_sel_hi:[0,1]
	v_pk_fma_f32 v[98:99], v[2:3], v[106:107], v[108:109]
	v_lshlrev_b32_e32 v106, 16, v55
	v_and_b32_e32 v107, 0xffff0000, v55
	v_lshlrev_b32_e32 v108, 16, v47
	v_and_b32_e32 v109, 0xffff0000, v47
	v_pk_mul_f32 v[106:107], v[96:97], v[106:107] op_sel_hi:[0,1]
	v_pk_fma_f32 v[100:101], v[4:5], v[106:107], v[108:109]
	v_lshlrev_b32_e32 v106, 16, v56
	v_and_b32_e32 v107, 0xffff0000, v56
	v_lshlrev_b32_e32 v108, 16, v48
	v_and_b32_e32 v109, 0xffff0000, v48
	v_pk_mul_f32 v[106:107], v[96:97], v[106:107] op_sel_hi:[0,1]
	v_pk_fma_f32 v[102:103], v[6:7], v[106:107], v[108:109]
	v_lshlrev_b32_e32 v106, 16, v57
	v_and_b32_e32 v107, 0xffff0000, v57
	v_lshlrev_b32_e32 v108, 16, v49
	v_and_b32_e32 v109, 0xffff0000, v49
	v_pk_mul_f32 v[106:107], v[96:97], v[106:107] op_sel_hi:[0,1]
	v_pk_fma_f32 v[104:105], v[8:9], v[106:107], v[108:109]
	v_pk_fma_f32 v[110:111], v[98:99], v[98:99], v[110:111]
	v_pk_fma_f32 v[110:111], v[100:101], v[100:101], v[110:111]
	v_pk_fma_f32 v[110:111], v[102:103], v[102:103], v[110:111]
	v_pk_fma_f32 v[110:111], v[104:105], v[104:105], v[110:111]
	v_cvt_pk_bf16_f32 v46, v98, v99
	v_cvt_pk_bf16_f32 v47, v100, v101
	v_cvt_pk_bf16_f32 v48, v102, v103
	v_cvt_pk_bf16_f32 v49, v104, v105
	global_store_dwordx4 v19, v[46:49], s[4:5] offset:1024
	v_add_f32_e32 v112, v110, v111
	v_add_u32_e32 v22, 0x2000, v22
	s_nop 1
	v_add_f32_dpp v112, v112, v112 quad_perm:[1,0,3,2] row_mask:0xf bank_mask:0xf
	s_nop 1
	v_add_f32_dpp v112, v112, v112 quad_perm:[2,3,0,1] row_mask:0xf bank_mask:0xf
	s_nop 1
	v_add_f32_dpp v112, v112, v112 row_half_mirror row_mask:0xf bank_mask:0xf
	s_nop 1
	v_add_f32_dpp v112, v112, v112 row_mirror row_mask:0xf bank_mask:0xf
	s_nop 1
	v_add_f32_dpp v112, v112, v112 row_bcast:15 row_mask:0xa bank_mask:0xf
	s_nop 1
	v_add_f32_dpp v112, v112, v112 row_bcast:31 row_mask:0xc bank_mask:0xf
	v_fmamk_f32 v113, v112, 0x3a800000, v244
	v_rsq_f32_e32 v113, v113
	s_mov_b64 exec, s[8:9]
	global_store_dword v22, v113, s[4:5]
	s_mov_b64 exec, -1
	v_add_u32_e32 v18, 0x400000, v18
	v_add_u32_e32 v20, 0x400000, v20
	v_add_u32_e32 v21, 0x2000, v21
	global_load_dwordx4 v[42:45], v18, s[4:5]
	global_load_dwordx4 v[50:53], v20, s[4:5]
	global_load_dwordx4 v[46:49], v18, s[4:5] offset:1024
	global_load_dwordx4 v[54:57], v20, s[4:5] offset:1024
	global_load_dword v58, v21, s[4:5]
	s_waitcnt vmcnt(24)
	v_fmamk_f32 v96, v76, 0x3a800000, v244
	v_rsq_f32_e32 v96, v96
	v_add_u32_e32 v19, 0x400000, v19
	v_lshlrev_b32_e32 v106, 16, v68
	v_and_b32_e32 v107, 0xffff0000, v68
	v_lshlrev_b32_e32 v108, 16, v60
	v_and_b32_e32 v109, 0xffff0000, v60
	v_pk_mul_f32 v[106:107], v[96:97], v[106:107] op_sel_hi:[0,1]
	v_pk_fma_f32 v[98:99], v[10:11], v[106:107], v[108:109]
	v_lshlrev_b32_e32 v106, 16, v69
	v_and_b32_e32 v107, 0xffff0000, v69
	v_lshlrev_b32_e32 v108, 16, v61
	v_and_b32_e32 v109, 0xffff0000, v61
	v_pk_mul_f32 v[106:107], v[96:97], v[106:107] op_sel_hi:[0,1]
	v_pk_fma_f32 v[100:101], v[12:13], v[106:107], v[108:109]
	v_lshlrev_b32_e32 v106, 16, v70
	v_and_b32_e32 v107, 0xffff0000, v70
	v_lshlrev_b32_e32 v108, 16, v62
	v_and_b32_e32 v109, 0xffff0000, v62
	v_pk_mul_f32 v[106:107], v[96:97], v[106:107] op_sel_hi:[0,1]
	v_pk_fma_f32 v[102:103], v[14:15], v[106:107], v[108:109]
	v_lshlrev_b32_e32 v106, 16, v71
	v_and_b32_e32 v107, 0xffff0000, v71
	v_lshlrev_b32_e32 v108, 16, v63
	v_and_b32_e32 v109, 0xffff0000, v63
	v_pk_mul_f32 v[106:107], v[96:97], v[106:107] op_sel_hi:[0,1]
	v_pk_fma_f32 v[104:105], v[16:17], v[106:107], v[108:109]
	v_pk_mul_f32 v[110:111], v[98:99], v[98:99]
	v_pk_fma_f32 v[110:111], v[100:101], v[100:101], v[110:111]
	v_pk_fma_f32 v[110:111], v[102:103], v[102:103], v[110:111]
	v_pk_fma_f32 v[110:111], v[104:105], v[104:105], v[110:111]
	v_cvt_pk_bf16_f32 v60, v98, v99
	v_cvt_pk_bf16_f32 v61, v100, v101
	v_cvt_pk_bf16_f32 v62, v102, v103
	v_cvt_pk_bf16_f32 v63, v104, v105
	global_store_dwordx4 v19, v[60:63], s[4:5]
	v_lshlrev_b32_e32 v106, 16, v72
	v_and_b32_e32 v107, 0xffff0000, v72
	v_lshlrev_b32_e32 v108, 16, v64
	v_and_b32_e32 v109, 0xffff0000, v64
	v_pk_mul_f32 v[106:107], v[96:97], v[106:107] op_sel_hi:[0,1]
	v_pk_fma_f32 v[98:99], v[2:3], v[106:107], v[108:109]
	v_lshlrev_b32_e32 v106, 16, v73
	v_and_b32_e32 v107, 0xffff0000, v73
	v_lshlrev_b32_e32 v108, 16, v65
	v_and_b32_e32 v109, 0xffff0000, v65
	v_pk_mul_f32 v[106:107], v[96:97], v[106:107] op_sel_hi:[0,1]
	v_pk_fma_f32 v[100:101], v[4:5], v[106:107], v[108:109]
	v_lshlrev_b32_e32 v106, 16, v74
	v_and_b32_e32 v107, 0xffff0000, v74
	v_lshlrev_b32_e32 v108, 16, v66
	v_and_b32_e32 v109, 0xffff0000, v66
	v_pk_mul_f32 v[106:107], v[96:97], v[106:107] op_sel_hi:[0,1]
	v_pk_fma_f32 v[102:103], v[6:7], v[106:107], v[108:109]
	v_lshlrev_b32_e32 v106, 16, v75
	v_and_b32_e32 v107, 0xffff0000, v75
	v_lshlrev_b32_e32 v108, 16, v67
	v_and_b32_e32 v109, 0xffff0000, v67
	v_pk_mul_f32 v[106:107], v[96:97], v[106:107] op_sel_hi:[0,1]
	v_pk_fma_f32 v[104:105], v[8:9], v[106:107], v[108:109]
	v_pk_fma_f32 v[110:111], v[98:99], v[98:99], v[110:111]
	v_pk_fma_f32 v[110:111], v[100:101], v[100:101], v[110:111]
	v_pk_fma_f32 v[110:111], v[102:103], v[102:103], v[110:111]
	v_pk_fma_f32 v[110:111], v[104:105], v[104:105], v[110:111]
	v_cvt_pk_bf16_f32 v64, v98, v99
	v_cvt_pk_bf16_f32 v65, v100, v101
	v_cvt_pk_bf16_f32 v66, v102, v103
	v_cvt_pk_bf16_f32 v67, v104, v105
	global_store_dwordx4 v19, v[64:67], s[4:5] offset:1024
	v_add_f32_e32 v112, v110, v111
	v_add_u32_e32 v22, 0x2000, v22
	s_nop 1
	v_add_f32_dpp v112, v112, v112 quad_perm:[1,0,3,2] row_mask:0xf bank_mask:0xf
	s_nop 1
	v_add_f32_dpp v112, v112, v112 quad_perm:[2,3,0,1] row_mask:0xf bank_mask:0xf
	s_nop 1
	v_add_f32_dpp v112, v112, v112 row_half_mirror row_mask:0xf bank_mask:0xf
	s_nop 1
	v_add_f32_dpp v112, v112, v112 row_mirror row_mask:0xf bank_mask:0xf
	s_nop 1
	v_add_f32_dpp v112, v112, v112 row_bcast:15 row_mask:0xa bank_mask:0xf
	s_nop 1
	v_add_f32_dpp v112, v112, v112 row_bcast:31 row_mask:0xc bank_mask:0xf
	v_fmamk_f32 v113, v112, 0x3a800000, v244
	v_rsq_f32_e32 v113, v113
	s_mov_b64 exec, s[8:9]
	global_store_dword v22, v113, s[4:5]
	s_mov_b64 exec, -1
	v_add_u32_e32 v18, 0x400000, v18
	v_add_u32_e32 v20, 0x400000, v20
	v_add_u32_e32 v21, 0x2000, v21
	global_load_dwordx4 v[60:63], v18, s[4:5]
	global_load_dwordx4 v[68:71], v20, s[4:5]
	global_load_dwordx4 v[64:67], v18, s[4:5] offset:1024
	global_load_dwordx4 v[72:75], v20, s[4:5] offset:1024
	global_load_dword v76, v21, s[4:5]
	s_waitcnt vmcnt(24)
; __device__ __forceinline__ float bflo(unsigned w) { return __uint_as_float(w << 16); }
; __device__ __forceinline__ float bfhi(unsigned w) { return __uint_as_float(w & 0xffff0000u); }
; __device__ __forceinline__ void resid_rows(bf16_t* R, const bf16_t* Y, const float* ssqY, const float* g, float* rstd_out, float* outf, bool wf32, int row_lo, int row_hi, int yoff, int gw, int NGW, int lane) {
;     ...
;     for (int row0 = row_lo + gw; row0 < row_hi; row0 += RP * NGW) {
;         u32x4 rr[RP][2], oo[RP][2]; float ssv[RP];
; #pragma unroll
;         for (int k = 0; k < RP; ++k) { const int row = row0 + k * NGW; const bool ok = row < row_hi; const int rw = ok ? row : row0;
;             ssv[k] = ssqY[rw];
; #pragma unroll
;             for (int j = 0; j < 2; ++j) { const int c = 8 * lane + 512 * j; rr[k][j] = *(const u32x4*)(R + (size_t)rw * DM + c); oo[k][j] = *(const u32x4*)(Y + (size_t)(rw - yoff) * DM + c); } }
; #pragma unroll
;         for (int k = 0; k < RP; ++k) { const int row = row0 + k * NGW; if (row < row_hi) {
;             const float rs = __builtin_amdgcn_rsqf(ssv[k] * (1.0f / DM) + RMS_EPS); float s = 0.f;
; #pragma unroll
;             for (int j = 0; j < 2; ++j) { const int c = 8 * lane + 512 * j; const u32x4 r = rr[k][j], o = oo[k][j]; const f32x4 ga = gv[j][0], gb = gv[j][1];
;                 f32x4 ya, yb; ya[0] = bflo(r.x) + bflo(o.x) * rs * ga[0]; ya[1] = bfhi(r.x) + bfhi(o.x) * rs * ga[1]; ya[2] = bflo(r.y) + bflo(o.y) * rs * ga[2]; ya[3] = bfhi(r.y) + bfhi(o.y) * rs * ga[3];
;                 yb[0] = bflo(r.z) + bflo(o.z) * rs * gb[0]; yb[1] = bfhi(r.z) + bfhi(o.z) * rs * gb[1]; yb[2] = bflo(r.w) + bflo(o.w) * rs * gb[2]; yb[3] = bfhi(r.w) + bfhi(o.w) * rs * gb[3];
;                 if (wf32) { *(f32x4*)(outf + (size_t)row * DM + c) = ya; *(f32x4*)(outf + (size_t)row * DM + c + 4) = yb; }
;                 s += (ya[0] * ya[0] + ya[1] * ya[1]) + (ya[2] * ya[2] + ya[3] * ya[3]) + (yb[0] * yb[0] + yb[1] * yb[1]) + (yb[2] * yb[2] + yb[3] * yb[3]);
;                 u32x4 w; w.x = pk2(ya[0], ya[1]); w.y = pk2(ya[2], ya[3]); w.z = pk2(yb[0], yb[1]); w.w = pk2(yb[2], yb[3]); *(u32x4*)(R + (size_t)row * DM + c) = w; }
;             s = wave_sum(s); if (lane == 0) rstd_out[row] = __builtin_amdgcn_rsqf(s * (1.0f / DM) + RMS_EPS); } }
	v_fmamk_f32 v96, v94, 0x3a800000, v244
	v_rsq_f32_e32 v96, v96
	v_add_u32_e32 v19, 0x400000, v19
	v_lshlrev_b32_e32 v106, 16, v86
	v_and_b32_e32 v107, 0xffff0000, v86
	v_lshlrev_b32_e32 v108, 16, v78
	v_and_b32_e32 v109, 0xffff0000, v78
	v_pk_mul_f32 v[106:107], v[96:97], v[106:107] op_sel_hi:[0,1]
	v_pk_fma_f32 v[98:99], v[10:11], v[106:107], v[108:109]
	v_lshlrev_b32_e32 v106, 16, v87
	v_and_b32_e32 v107, 0xffff0000, v87
	v_lshlrev_b32_e32 v108, 16, v79
	v_and_b32_e32 v109, 0xffff0000, v79
	v_pk_mul_f32 v[106:107], v[96:97], v[106:107] op_sel_hi:[0,1]
	v_pk_fma_f32 v[100:101], v[12:13], v[106:107], v[108:109]
	v_lshlrev_b32_e32 v106, 16, v88
	v_and_b32_e32 v107, 0xffff0000, v88
	v_lshlrev_b32_e32 v108, 16, v80
	v_and_b32_e32 v109, 0xffff0000, v80
	v_pk_mul_f32 v[106:107], v[96:97], v[106:107] op_sel_hi:[0,1]
	v_pk_fma_f32 v[102:103], v[14:15], v[106:107], v[108:109]
	v_lshlrev_b32_e32 v106, 16, v89
	v_and_b32_e32 v107, 0xffff0000, v89
	v_lshlrev_b32_e32 v108, 16, v81
	v_and_b32_e32 v109, 0xffff0000, v81
	v_pk_mul_f32 v[106:107], v[96:97], v[106:107] op_sel_hi:[0,1]
	v_pk_fma_f32 v[104:105], v[16:17], v[106:107], v[108:109]
	v_pk_mul_f32 v[110:111], v[98:99], v[98:99]
	v_pk_fma_f32 v[110:111], v[100:101], v[100:101], v[110:111]
	v_pk_fma_f32 v[110:111], v[102:103], v[102:103], v[110:111]
	v_pk_fma_f32 v[110:111], v[104:105], v[104:105], v[110:111]
	v_cvt_pk_bf16_f32 v78, v98, v99
	v_cvt_pk_bf16_f32 v79, v100, v101
	v_cvt_pk_bf16_f32 v80, v102, v103
	v_cvt_pk_bf16_f32 v81, v104, v105
	global_store_dwordx4 v19, v[78:81], s[4:5]
	v_lshlrev_b32_e32 v106, 16, v90
	v_and_b32_e32 v107, 0xffff0000, v90
	v_lshlrev_b32_e32 v108, 16, v82
	v_and_b32_e32 v109, 0xffff0000, v82
	v_pk_mul_f32 v[106:107], v[96:97], v[106:107] op_sel_hi:[0,1]
	v_pk_fma_f32 v[98:99], v[2:3], v[106:107], v[108:109]
	v_lshlrev_b32_e32 v106, 16, v91
	v_and_b32_e32 v107, 0xffff0000, v91
	v_lshlrev_b32_e32 v108, 16, v83
	v_and_b32_e32 v109, 0xffff0000, v83
	v_pk_mul_f32 v[106:107], v[96:97], v[106:107] op_sel_hi:[0,1]
	v_pk_fma_f32 v[100:101], v[4:5], v[106:107], v[108:109]
	v_lshlrev_b32_e32 v106, 16, v92
	v_and_b32_e32 v107, 0xffff0000, v92
	v_lshlrev_b32_e32 v108, 16, v84
	v_and_b32_e32 v109, 0xffff0000, v84
	v_pk_mul_f32 v[106:107], v[96:97], v[106:107] op_sel_hi:[0,1]
	v_pk_fma_f32 v[102:103], v[6:7], v[106:107], v[108:109]
	v_lshlrev_b32_e32 v106, 16, v93
	v_and_b32_e32 v107, 0xffff0000, v93
	v_lshlrev_b32_e32 v108, 16, v85
	v_and_b32_e32 v109, 0xffff0000, v85
	v_pk_mul_f32 v[106:107], v[96:97], v[106:107] op_sel_hi:[0,1]
	v_pk_fma_f32 v[104:105], v[8:9], v[106:107], v[108:109]
	v_pk_fma_f32 v[110:111], v[98:99], v[98:99], v[110:111]
	v_pk_fma_f32 v[110:111], v[100:101], v[100:101], v[110:111]
	v_pk_fma_f32 v[110:111], v[102:103], v[102:103], v[110:111]
	v_pk_fma_f32 v[110:111], v[104:105], v[104:105], v[110:111]
	v_cvt_pk_bf16_f32 v82, v98, v99
	v_cvt_pk_bf16_f32 v83, v100, v101
	v_cvt_pk_bf16_f32 v84, v102, v103
	v_cvt_pk_bf16_f32 v85, v104, v105
	global_store_dwordx4 v19, v[82:85], s[4:5] offset:1024
	v_add_f32_e32 v112, v110, v111
	v_add_u32_e32 v22, 0x2000, v22
	s_nop 1
	v_add_f32_dpp v112, v112, v112 quad_perm:[1,0,3,2] row_mask:0xf bank_mask:0xf
	s_nop 1
	v_add_f32_dpp v112, v112, v112 quad_perm:[2,3,0,1] row_mask:0xf bank_mask:0xf
	s_nop 1
	v_add_f32_dpp v112, v112, v112 row_half_mirror row_mask:0xf bank_mask:0xf
	s_nop 1
	v_add_f32_dpp v112, v112, v112 row_mirror row_mask:0xf bank_mask:0xf
	s_nop 1
	v_add_f32_dpp v112, v112, v112 row_bcast:15 row_mask:0xa bank_mask:0xf
	s_nop 1
	v_add_f32_dpp v112, v112, v112 row_bcast:31 row_mask:0xc bank_mask:0xf
	v_fmamk_f32 v113, v112, 0x3a800000, v244
	v_rsq_f32_e32 v113, v113
	s_mov_b64 exec, s[8:9]
	global_store_dword v22, v113, s[4:5]
	s_mov_b64 exec, -1
	v_add_u32_e32 v18, 0x400000, v18
	v_add_u32_e32 v20, 0x400000, v20
	v_add_u32_e32 v21, 0x2000, v21
	global_load_dwordx4 v[78:81], v18, s[4:5]
	global_load_dwordx4 v[86:89], v20, s[4:5]
	global_load_dwordx4 v[82:85], v18, s[4:5] offset:1024
	global_load_dwordx4 v[90:93], v20, s[4:5] offset:1024
	global_load_dword v94, v21, s[4:5]
	s_waitcnt vmcnt(24)
	v_fmamk_f32 v96, v40, 0x3a800000, v244
	v_rsq_f32_e32 v96, v96
	v_add_u32_e32 v19, 0x400000, v19
	v_lshlrev_b32_e32 v106, 16, v32
	v_and_b32_e32 v107, 0xffff0000, v32
	v_lshlrev_b32_e32 v108, 16, v24
	v_and_b32_e32 v109, 0xffff0000, v24
	v_pk_mul_f32 v[106:107], v[96:97], v[106:107] op_sel_hi:[0,1]
	v_pk_fma_f32 v[98:99], v[10:11], v[106:107], v[108:109]
	v_lshlrev_b32_e32 v106, 16, v33
	v_and_b32_e32 v107, 0xffff0000, v33
	v_lshlrev_b32_e32 v108, 16, v25
	v_and_b32_e32 v109, 0xffff0000, v25
	v_pk_mul_f32 v[106:107], v[96:97], v[106:107] op_sel_hi:[0,1]
	v_pk_fma_f32 v[100:101], v[12:13], v[106:107], v[108:109]
	v_lshlrev_b32_e32 v106, 16, v34
	v_and_b32_e32 v107, 0xffff0000, v34
	v_lshlrev_b32_e32 v108, 16, v26
	v_and_b32_e32 v109, 0xffff0000, v26
	v_pk_mul_f32 v[106:107], v[96:97], v[106:107] op_sel_hi:[0,1]
	v_pk_fma_f32 v[102:103], v[14:15], v[106:107], v[108:109]
	v_lshlrev_b32_e32 v106, 16, v35
	v_and_b32_e32 v107, 0xffff0000, v35
	v_lshlrev_b32_e32 v108, 16, v27
	v_and_b32_e32 v109, 0xffff0000, v27
	v_pk_mul_f32 v[106:107], v[96:97], v[106:107] op_sel_hi:[0,1]
	v_pk_fma_f32 v[104:105], v[16:17], v[106:107], v[108:109]
	v_pk_mul_f32 v[110:111], v[98:99], v[98:99]
	v_pk_fma_f32 v[110:111], v[100:101], v[100:101], v[110:111]
	v_pk_fma_f32 v[110:111], v[102:103], v[102:103], v[110:111]
	v_pk_fma_f32 v[110:111], v[104:105], v[104:105], v[110:111]
	v_cvt_pk_bf16_f32 v24, v98, v99
	v_cvt_pk_bf16_f32 v25, v100, v101
	v_cvt_pk_bf16_f32 v26, v102, v103
	v_cvt_pk_bf16_f32 v27, v104, v105
	global_store_dwordx4 v19, v[24:27], s[4:5]
; __device__ __forceinline__ float bflo(unsigned w) { return __uint_as_float(w << 16); }
; __device__ __forceinline__ float bfhi(unsigned w) { return __uint_as_float(w & 0xffff0000u); }
; __device__ __forceinline__ void resid_rows(bf16_t* R, const bf16_t* Y, const float* ssqY, const float* g, float* rstd_out, float* outf, bool wf32, int row_lo, int row_hi, int yoff, int gw, int NGW, int lane) {
;     ...
;     for (int row0 = row_lo + gw; row0 < row_hi; row0 += RP * NGW) {
;         u32x4 rr[RP][2], oo[RP][2]; float ssv[RP];
; #pragma unroll
;         for (int k = 0; k < RP; ++k) { const int row = row0 + k * NGW; const bool ok = row < row_hi; const int rw = ok ? row : row0;
;             ssv[k] = ssqY[rw];
; #pragma unroll
;             for (int j = 0; j < 2; ++j) { const int c = 8 * lane + 512 * j; rr[k][j] = *(const u32x4*)(R + (size_t)rw * DM + c); oo[k][j] = *(const u32x4*)(Y + (size_t)(rw - yoff) * DM + c); } }
; #pragma unroll
;         for (int k = 0; k < RP; ++k) { const int row = row0 + k * NGW; if (row < row_hi) {
;             const float rs = __builtin_amdgcn_rsqf(ssv[k] * (1.0f / DM) + RMS_EPS); float s = 0.f;
; #pragma unroll
;             for (int j = 0; j < 2; ++j) { const int c = 8 * lane + 512 * j; const u32x4 r = rr[k][j], o = oo[k][j]; const f32x4 ga = gv[j][0], gb = gv[j][1];
;                 f32x4 ya, yb; ya[0] = bflo(r.x) + bflo(o.x) * rs * ga[0]; ya[1] = bfhi(r.x) + bfhi(o.x) * rs * ga[1]; ya[2] = bflo(r.y) + bflo(o.y) * rs * ga[2]; ya[3] = bfhi(r.y) + bfhi(o.y) * rs * ga[3];
;                 yb[0] = bflo(r.z) + bflo(o.z) * rs * gb[0]; yb[1] = bfhi(r.z) + bfhi(o.z) * rs * gb[1]; yb[2] = bflo(r.w) + bflo(o.w) * rs * gb[2]; yb[3] = bfhi(r.w) + bfhi(o.w) * rs * gb[3];
;                 if (wf32) { *(f32x4*)(outf + (size_t)row * DM + c) = ya; *(f32x4*)(outf + (size_t)row * DM + c + 4) = yb; }
;                 s += (ya[0] * ya[0] + ya[1] * ya[1]) + (ya[2] * ya[2] + ya[3] * ya[3]) + (yb[0] * yb[0] + yb[1] * yb[1]) + (yb[2] * yb[2] + yb[3] * yb[3]);
;                 u32x4 w; w.x = pk2(ya[0], ya[1]); w.y = pk2(ya[2], ya[3]); w.z = pk2(yb[0], yb[1]); w.w = pk2(yb[2], yb[3]); *(u32x4*)(R + (size_t)row * DM + c) = w; }
;             s = wave_sum(s); if (lane == 0) rstd_out[row] = __builtin_amdgcn_rsqf(s * (1.0f / DM) + RMS_EPS); } }
	v_lshlrev_b32_e32 v106, 16, v36
	v_and_b32_e32 v107, 0xffff0000, v36
	v_lshlrev_b32_e32 v108, 16, v28
	v_and_b32_e32 v109, 0xffff0000, v28
	v_pk_mul_f32 v[106:107], v[96:97], v[106:107] op_sel_hi:[0,1]
	v_pk_fma_f32 v[98:99], v[2:3], v[106:107], v[108:109]
	v_lshlrev_b32_e32 v106, 16, v37
	v_and_b32_e32 v107, 0xffff0000, v37
	v_lshlrev_b32_e32 v108, 16, v29
	v_and_b32_e32 v109, 0xffff0000, v29
	v_pk_mul_f32 v[106:107], v[96:97], v[106:107] op_sel_hi:[0,1]
	v_pk_fma_f32 v[100:101], v[4:5], v[106:107], v[108:109]
	v_lshlrev_b32_e32 v106, 16, v38
	v_and_b32_e32 v107, 0xffff0000, v38
	v_lshlrev_b32_e32 v108, 16, v30
	v_and_b32_e32 v109, 0xffff0000, v30
	v_pk_mul_f32 v[106:107], v[96:97], v[106:107] op_sel_hi:[0,1]
	v_pk_fma_f32 v[102:103], v[6:7], v[106:107], v[108:109]
	v_lshlrev_b32_e32 v106, 16, v39
	v_and_b32_e32 v107, 0xffff0000, v39
	v_lshlrev_b32_e32 v108, 16, v31
	v_and_b32_e32 v109, 0xffff0000, v31
	v_pk_mul_f32 v[106:107], v[96:97], v[106:107] op_sel_hi:[0,1]
	v_pk_fma_f32 v[104:105], v[8:9], v[106:107], v[108:109]
	v_pk_fma_f32 v[110:111], v[98:99], v[98:99], v[110:111]
	v_pk_fma_f32 v[110:111], v[100:101], v[100:101], v[110:111]
	v_pk_fma_f32 v[110:111], v[102:103], v[102:103], v[110:111]
	v_pk_fma_f32 v[110:111], v[104:105], v[104:105], v[110:111]
	v_cvt_pk_bf16_f32 v28, v98, v99
	v_cvt_pk_bf16_f32 v29, v100, v101
	v_cvt_pk_bf16_f32 v30, v102, v103
	v_cvt_pk_bf16_f32 v31, v104, v105
	global_store_dwordx4 v19, v[28:31], s[4:5] offset:1024
	v_add_f32_e32 v112, v110, v111
	v_add_u32_e32 v22, 0x2000, v22
	s_nop 1
	v_add_f32_dpp v112, v112, v112 quad_perm:[1,0,3,2] row_mask:0xf bank_mask:0xf
	s_nop 1
	v_add_f32_dpp v112, v112, v112 quad_perm:[2,3,0,1] row_mask:0xf bank_mask:0xf
	s_nop 1
	v_add_f32_dpp v112, v112, v112 row_half_mirror row_mask:0xf bank_mask:0xf
	s_nop 1
	v_add_f32_dpp v112, v112, v112 row_mirror row_mask:0xf bank_mask:0xf
	s_nop 1
	v_add_f32_dpp v112, v112, v112 row_bcast:15 row_mask:0xa bank_mask:0xf
	s_nop 1
	v_add_f32_dpp v112, v112, v112 row_bcast:31 row_mask:0xc bank_mask:0xf
	v_fmamk_f32 v113, v112, 0x3a800000, v244
	v_rsq_f32_e32 v113, v113
	s_mov_b64 exec, s[8:9]
	global_store_dword v22, v113, s[4:5]
	s_mov_b64 exec, -1
	s_waitcnt vmcnt(19)
	v_fmamk_f32 v96, v58, 0x3a800000, v244
	v_rsq_f32_e32 v96, v96
	v_add_u32_e32 v19, 0x400000, v19
	v_lshlrev_b32_e32 v106, 16, v50
	v_and_b32_e32 v107, 0xffff0000, v50
	v_lshlrev_b32_e32 v108, 16, v42
	v_and_b32_e32 v109, 0xffff0000, v42
	v_pk_mul_f32 v[106:107], v[96:97], v[106:107] op_sel_hi:[0,1]
	v_pk_fma_f32 v[98:99], v[10:11], v[106:107], v[108:109]
	v_lshlrev_b32_e32 v106, 16, v51
	v_and_b32_e32 v107, 0xffff0000, v51
	v_lshlrev_b32_e32 v108, 16, v43
	v_and_b32_e32 v109, 0xffff0000, v43
	v_pk_mul_f32 v[106:107], v[96:97], v[106:107] op_sel_hi:[0,1]
	v_pk_fma_f32 v[100:101], v[12:13], v[106:107], v[108:109]
	v_lshlrev_b32_e32 v106, 16, v52
	v_and_b32_e32 v107, 0xffff0000, v52
	v_lshlrev_b32_e32 v108, 16, v44
	v_and_b32_e32 v109, 0xffff0000, v44
	v_pk_mul_f32 v[106:107], v[96:97], v[106:107] op_sel_hi:[0,1]
	v_pk_fma_f32 v[102:103], v[14:15], v[106:107], v[108:109]
	v_lshlrev_b32_e32 v106, 16, v53
	v_and_b32_e32 v107, 0xffff0000, v53
	v_lshlrev_b32_e32 v108, 16, v45
	v_and_b32_e32 v109, 0xffff0000, v45
	v_pk_mul_f32 v[106:107], v[96:97], v[106:107] op_sel_hi:[0,1]
	v_pk_fma_f32 v[104:105], v[16:17], v[106:107], v[108:109]
	v_pk_mul_f32 v[110:111], v[98:99], v[98:99]
	v_pk_fma_f32 v[110:111], v[100:101], v[100:101], v[110:111]
	v_pk_fma_f32 v[110:111], v[102:103], v[102:103], v[110:111]
	v_pk_fma_f32 v[110:111], v[104:105], v[104:105], v[110:111]
	v_cvt_pk_bf16_f32 v42, v98, v99
	v_cvt_pk_bf16_f32 v43, v100, v101
	v_cvt_pk_bf16_f32 v44, v102, v103
	v_cvt_pk_bf16_f32 v45, v104, v105
	global_store_dwordx4 v19, v[42:45], s[4:5]
	v_lshlrev_b32_e32 v106, 16, v54
	v_and_b32_e32 v107, 0xffff0000, v54
	v_lshlrev_b32_e32 v108, 16, v46
	v_and_b32_e32 v109, 0xffff0000, v46
	v_pk_mul_f32 v[106:107], v[96:97], v[106:107] op_sel_hi:[0,1]
	v_pk_fma_f32 v[98:99], v[2:3], v[106:107], v[108:109]
	v_lshlrev_b32_e32 v106, 16, v55
	v_and_b32_e32 v107, 0xffff0000, v55
	v_lshlrev_b32_e32 v108, 16, v47
	v_and_b32_e32 v109, 0xffff0000, v47
	v_pk_mul_f32 v[106:107], v[96:97], v[106:107] op_sel_hi:[0,1]
	v_pk_fma_f32 v[100:101], v[4:5], v[106:107], v[108:109]
	v_lshlrev_b32_e32 v106, 16, v56
	v_and_b32_e32 v107, 0xffff0000, v56
	v_lshlrev_b32_e32 v108, 16, v48
	v_and_b32_e32 v109, 0xffff0000, v48
	v_pk_mul_f32 v[106:107], v[96:97], v[106:107] op_sel_hi:[0,1]
	v_pk_fma_f32 v[102:103], v[6:7], v[106:107], v[108:109]
	v_lshlrev_b32_e32 v106, 16, v57
	v_and_b32_e32 v107, 0xffff0000, v57
	v_lshlrev_b32_e32 v108, 16, v49
	v_and_b32_e32 v109, 0xffff0000, v49
	v_pk_mul_f32 v[106:107], v[96:97], v[106:107] op_sel_hi:[0,1]
	v_pk_fma_f32 v[104:105], v[8:9], v[106:107], v[108:109]
	v_pk_fma_f32 v[110:111], v[98:99], v[98:99], v[110:111]
	v_pk_fma_f32 v[110:111], v[100:101], v[100:101], v[110:111]
	v_pk_fma_f32 v[110:111], v[102:103], v[102:103], v[110:111]
	v_pk_fma_f32 v[110:111], v[104:105], v[104:105], v[110:111]
	v_cvt_pk_bf16_f32 v46, v98, v99
	v_cvt_pk_bf16_f32 v47, v100, v101
	v_cvt_pk_bf16_f32 v48, v102, v103
	v_cvt_pk_bf16_f32 v49, v104, v105
	global_store_dwordx4 v19, v[46:49], s[4:5] offset:1024
	v_add_f32_e32 v112, v110, v111
	v_add_u32_e32 v22, 0x2000, v22
	s_nop 1
	v_add_f32_dpp v112, v112, v112 quad_perm:[1,0,3,2] row_mask:0xf bank_mask:0xf
	s_nop 1
	v_add_f32_dpp v112, v112, v112 quad_perm:[2,3,0,1] row_mask:0xf bank_mask:0xf
	s_nop 1
	v_add_f32_dpp v112, v112, v112 row_half_mirror row_mask:0xf bank_mask:0xf
	s_nop 1
	v_add_f32_dpp v112, v112, v112 row_mirror row_mask:0xf bank_mask:0xf
	s_nop 1
	v_add_f32_dpp v112, v112, v112 row_bcast:15 row_mask:0xa bank_mask:0xf
	s_nop 1
	v_add_f32_dpp v112, v112, v112 row_bcast:31 row_mask:0xc bank_mask:0xf
	v_fmamk_f32 v113, v112, 0x3a800000, v244
	v_rsq_f32_e32 v113, v113
	s_mov_b64 exec, s[8:9]
	global_store_dword v22, v113, s[4:5]
	s_mov_b64 exec, -1
	s_waitcnt vmcnt(14)
; __device__ __forceinline__ float bflo(unsigned w) { return __uint_as_float(w << 16); }
; __device__ __forceinline__ float bfhi(unsigned w) { return __uint_as_float(w & 0xffff0000u); }
; __device__ __forceinline__ void resid_rows(bf16_t* R, const bf16_t* Y, const float* ssqY, const float* g, float* rstd_out, float* outf, bool wf32, int row_lo, int row_hi, int yoff, int gw, int NGW, int lane) {
;     ...
;         for (int k = 0; k < RP; ++k) { const int row = row0 + k * NGW; if (row < row_hi) {
;             const float rs = __builtin_amdgcn_rsqf(ssv[k] * (1.0f / DM) + RMS_EPS); float s = 0.f;
; #pragma unroll
;             for (int j = 0; j < 2; ++j) { const int c = 8 * lane + 512 * j; const u32x4 r = rr[k][j], o = oo[k][j]; const f32x4 ga = gv[j][0], gb = gv[j][1];
;                 f32x4 ya, yb; ya[0] = bflo(r.x) + bflo(o.x) * rs * ga[0]; ya[1] = bfhi(r.x) + bfhi(o.x) * rs * ga[1]; ya[2] = bflo(r.y) + bflo(o.y) * rs * ga[2]; ya[3] = bfhi(r.y) + bfhi(o.y) * rs * ga[3];
;                 yb[0] = bflo(r.z) + bflo(o.z) * rs * gb[0]; yb[1] = bfhi(r.z) + bfhi(o.z) * rs * gb[1]; yb[2] = bflo(r.w) + bflo(o.w) * rs * gb[2]; yb[3] = bfhi(r.w) + bfhi(o.w) * rs * gb[3];
;                 if (wf32) { *(f32x4*)(outf + (size_t)row * DM + c) = ya; *(f32x4*)(outf + (size_t)row * DM + c + 4) = yb; }
;                 s += (ya[0] * ya[0] + ya[1] * ya[1]) + (ya[2] * ya[2] + ya[3] * ya[3]) + (yb[0] * yb[0] + yb[1] * yb[1]) + (yb[2] * yb[2] + yb[3] * yb[3]);
;                 u32x4 w; w.x = pk2(ya[0], ya[1]); w.y = pk2(ya[2], ya[3]); w.z = pk2(yb[0], yb[1]); w.w = pk2(yb[2], yb[3]); *(u32x4*)(R + (size_t)row * DM + c) = w; }
;             s = wave_sum(s); if (lane == 0) rstd_out[row] = __builtin_amdgcn_rsqf(s * (1.0f / DM) + RMS_EPS); } }
	v_fmamk_f32 v96, v76, 0x3a800000, v244
	v_rsq_f32_e32 v96, v96
	v_add_u32_e32 v19, 0x400000, v19
	v_lshlrev_b32_e32 v106, 16, v68
	v_and_b32_e32 v107, 0xffff0000, v68
	v_lshlrev_b32_e32 v108, 16, v60
	v_and_b32_e32 v109, 0xffff0000, v60
	v_pk_mul_f32 v[106:107], v[96:97], v[106:107] op_sel_hi:[0,1]
	v_pk_fma_f32 v[98:99], v[10:11], v[106:107], v[108:109]
	v_lshlrev_b32_e32 v106, 16, v69
	v_and_b32_e32 v107, 0xffff0000, v69
	v_lshlrev_b32_e32 v108, 16, v61
	v_and_b32_e32 v109, 0xffff0000, v61
	v_pk_mul_f32 v[106:107], v[96:97], v[106:107] op_sel_hi:[0,1]
	v_pk_fma_f32 v[100:101], v[12:13], v[106:107], v[108:109]
	v_lshlrev_b32_e32 v106, 16, v70
	v_and_b32_e32 v107, 0xffff0000, v70
	v_lshlrev_b32_e32 v108, 16, v62
	v_and_b32_e32 v109, 0xffff0000, v62
	v_pk_mul_f32 v[106:107], v[96:97], v[106:107] op_sel_hi:[0,1]
	v_pk_fma_f32 v[102:103], v[14:15], v[106:107], v[108:109]
	v_lshlrev_b32_e32 v106, 16, v71
	v_and_b32_e32 v107, 0xffff0000, v71
	v_lshlrev_b32_e32 v108, 16, v63
	v_and_b32_e32 v109, 0xffff0000, v63
	v_pk_mul_f32 v[106:107], v[96:97], v[106:107] op_sel_hi:[0,1]
	v_pk_fma_f32 v[104:105], v[16:17], v[106:107], v[108:109]
	v_pk_mul_f32 v[110:111], v[98:99], v[98:99]
	v_pk_fma_f32 v[110:111], v[100:101], v[100:101], v[110:111]
	v_pk_fma_f32 v[110:111], v[102:103], v[102:103], v[110:111]
	v_pk_fma_f32 v[110:111], v[104:105], v[104:105], v[110:111]
	v_cvt_pk_bf16_f32 v60, v98, v99
	v_cvt_pk_bf16_f32 v61, v100, v101
	v_cvt_pk_bf16_f32 v62, v102, v103
	v_cvt_pk_bf16_f32 v63, v104, v105
	global_store_dwordx4 v19, v[60:63], s[4:5]
	v_lshlrev_b32_e32 v106, 16, v72
	v_and_b32_e32 v107, 0xffff0000, v72
	v_lshlrev_b32_e32 v108, 16, v64
	v_and_b32_e32 v109, 0xffff0000, v64
	v_pk_mul_f32 v[106:107], v[96:97], v[106:107] op_sel_hi:[0,1]
	v_pk_fma_f32 v[98:99], v[2:3], v[106:107], v[108:109]
	v_lshlrev_b32_e32 v106, 16, v73
	v_and_b32_e32 v107, 0xffff0000, v73
	v_lshlrev_b32_e32 v108, 16, v65
	v_and_b32_e32 v109, 0xffff0000, v65
	v_pk_mul_f32 v[106:107], v[96:97], v[106:107] op_sel_hi:[0,1]
	v_pk_fma_f32 v[100:101], v[4:5], v[106:107], v[108:109]
	v_lshlrev_b32_e32 v106, 16, v74
	v_and_b32_e32 v107, 0xffff0000, v74
	v_lshlrev_b32_e32 v108, 16, v66
	v_and_b32_e32 v109, 0xffff0000, v66
	v_pk_mul_f32 v[106:107], v[96:97], v[106:107] op_sel_hi:[0,1]
	v_pk_fma_f32 v[102:103], v[6:7], v[106:107], v[108:109]
	v_lshlrev_b32_e32 v106, 16, v75
	v_and_b32_e32 v107, 0xffff0000, v75
	v_lshlrev_b32_e32 v108, 16, v67
	v_and_b32_e32 v109, 0xffff0000, v67
	v_pk_mul_f32 v[106:107], v[96:97], v[106:107] op_sel_hi:[0,1]
	v_pk_fma_f32 v[104:105], v[8:9], v[106:107], v[108:109]
	v_pk_fma_f32 v[110:111], v[98:99], v[98:99], v[110:111]
	v_pk_fma_f32 v[110:111], v[100:101], v[100:101], v[110:111]
	v_pk_fma_f32 v[110:111], v[102:103], v[102:103], v[110:111]
	v_pk_fma_f32 v[110:111], v[104:105], v[104:105], v[110:111]
	v_cvt_pk_bf16_f32 v64, v98, v99
	v_cvt_pk_bf16_f32 v65, v100, v101
	v_cvt_pk_bf16_f32 v66, v102, v103
	v_cvt_pk_bf16_f32 v67, v104, v105
	global_store_dwordx4 v19, v[64:67], s[4:5] offset:1024
	v_add_f32_e32 v112, v110, v111
	v_add_u32_e32 v22, 0x2000, v22
	s_nop 1
	v_add_f32_dpp v112, v112, v112 quad_perm:[1,0,3,2] row_mask:0xf bank_mask:0xf
	s_nop 1
	v_add_f32_dpp v112, v112, v112 quad_perm:[2,3,0,1] row_mask:0xf bank_mask:0xf
	s_nop 1
	v_add_f32_dpp v112, v112, v112 row_half_mirror row_mask:0xf bank_mask:0xf
	s_nop 1
	v_add_f32_dpp v112, v112, v112 row_mirror row_mask:0xf bank_mask:0xf
	s_nop 1
	v_add_f32_dpp v112, v112, v112 row_bcast:15 row_mask:0xa bank_mask:0xf
	s_nop 1
	v_add_f32_dpp v112, v112, v112 row_bcast:31 row_mask:0xc bank_mask:0xf
	v_fmamk_f32 v113, v112, 0x3a800000, v244
	v_rsq_f32_e32 v113, v113
	s_mov_b64 exec, s[8:9]
	global_store_dword v22, v113, s[4:5]
	s_mov_b64 exec, -1
	s_waitcnt vmcnt(9)
	v_fmamk_f32 v96, v94, 0x3a800000, v244
	v_rsq_f32_e32 v96, v96
	v_add_u32_e32 v19, 0x400000, v19
	v_lshlrev_b32_e32 v106, 16, v86
	v_and_b32_e32 v107, 0xffff0000, v86
	v_lshlrev_b32_e32 v108, 16, v78
	v_and_b32_e32 v109, 0xffff0000, v78
	v_pk_mul_f32 v[106:107], v[96:97], v[106:107] op_sel_hi:[0,1]
	v_pk_fma_f32 v[98:99], v[10:11], v[106:107], v[108:109]
	v_lshlrev_b32_e32 v106, 16, v87
	v_and_b32_e32 v107, 0xffff0000, v87
	v_lshlrev_b32_e32 v108, 16, v79
	v_and_b32_e32 v109, 0xffff0000, v79
	v_pk_mul_f32 v[106:107], v[96:97], v[106:107] op_sel_hi:[0,1]
	v_pk_fma_f32 v[100:101], v[12:13], v[106:107], v[108:109]
	v_lshlrev_b32_e32 v106, 16, v88
	v_and_b32_e32 v107, 0xffff0000, v88
	v_lshlrev_b32_e32 v108, 16, v80
	v_and_b32_e32 v109, 0xffff0000, v80
	v_pk_mul_f32 v[106:107], v[96:97], v[106:107] op_sel_hi:[0,1]
	v_pk_fma_f32 v[102:103], v[14:15], v[106:107], v[108:109]
	v_lshlrev_b32_e32 v106, 16, v89
	v_and_b32_e32 v107, 0xffff0000, v89
	v_lshlrev_b32_e32 v108, 16, v81
	v_and_b32_e32 v109, 0xffff0000, v81
	v_pk_mul_f32 v[106:107], v[96:97], v[106:107] op_sel_hi:[0,1]
	v_pk_fma_f32 v[104:105], v[16:17], v[106:107], v[108:109]
	v_pk_mul_f32 v[110:111], v[98:99], v[98:99]
	v_pk_fma_f32 v[110:111], v[100:101], v[100:101], v[110:111]
	v_pk_fma_f32 v[110:111], v[102:103], v[102:103], v[110:111]
	v_pk_fma_f32 v[110:111], v[104:105], v[104:105], v[110:111]
	v_cvt_pk_bf16_f32 v78, v98, v99
	v_cvt_pk_bf16_f32 v79, v100, v101
	v_cvt_pk_bf16_f32 v80, v102, v103
	v_cvt_pk_bf16_f32 v81, v104, v105
	global_store_dwordx4 v19, v[78:81], s[4:5]
	v_lshlrev_b32_e32 v106, 16, v90
	v_and_b32_e32 v107, 0xffff0000, v90
	v_lshlrev_b32_e32 v108, 16, v82
	v_and_b32_e32 v109, 0xffff0000, v82
	v_pk_mul_f32 v[106:107], v[96:97], v[106:107] op_sel_hi:[0,1]
	v_pk_fma_f32 v[98:99], v[2:3], v[106:107], v[108:109]
	v_lshlrev_b32_e32 v106, 16, v91
	v_and_b32_e32 v107, 0xffff0000, v91
; __device__ __forceinline__ float bflo(unsigned w) { return __uint_as_float(w << 16); }
; __device__ __forceinline__ void resid_rows(bf16_t* R, const bf16_t* Y, const float* ssqY, const float* g, float* rstd_out, float* outf, bool wf32, int row_lo, int row_hi, int yoff, int gw, int NGW, int lane) {
;     ...
;     for (int row0 = row_lo + gw; row0 < row_hi; row0 += RP * NGW) {
;         u32x4 rr[RP][2], oo[RP][2]; float ssv[RP];
; #pragma unroll
;         for (int k = 0; k < RP; ++k) { const int row = row0 + k * NGW; const bool ok = row < row_hi; const int rw = ok ? row : row0;
;             ssv[k] = ssqY[rw];
; #pragma unroll
;             for (int j = 0; j < 2; ++j) { const int c = 8 * lane + 512 * j; rr[k][j] = *(const u32x4*)(R + (size_t)rw * DM + c); oo[k][j] = *(const u32x4*)(Y + (size_t)(rw - yoff) * DM + c); } }
; #pragma unroll
;         for (int k = 0; k < RP; ++k) { const int row = row0 + k * NGW; if (row < row_hi) {
;             const float rs = __builtin_amdgcn_rsqf(ssv[k] * (1.0f / DM) + RMS_EPS); float s = 0.f;
; #pragma unroll
;             for (int j = 0; j < 2; ++j) { const int c = 8 * lane + 512 * j; const u32x4 r = rr[k][j], o = oo[k][j]; const f32x4 ga = gv[j][0], gb = gv[j][1];
;                 f32x4 ya, yb; ya[0] = bflo(r.x) + bflo(o.x) * rs * ga[0]; ya[1] = bfhi(r.x) + bfhi(o.x) * rs * ga[1]; ya[2] = bflo(r.y) + bflo(o.y) * rs * ga[2]; ya[3] = bfhi(r.y) + bfhi(o.y) * rs * ga[3];
;                 yb[0] = bflo(r.z) + bflo(o.z) * rs * gb[0]; yb[1] = bfhi(r.z) + bfhi(o.z) * rs * gb[1]; yb[2] = bflo(r.w) + bflo(o.w) * rs * gb[2]; yb[3] = bfhi(r.w) + bfhi(o.w) * rs * gb[3];
;                 if (wf32) { *(f32x4*)(outf + (size_t)row * DM + c) = ya; *(f32x4*)(outf + (size_t)row * DM + c + 4) = yb; }
;                 s += (ya[0] * ya[0] + ya[1] * ya[1]) + (ya[2] * ya[2] + ya[3] * ya[3]) + (yb[0] * yb[0] + yb[1] * yb[1]) + (yb[2] * yb[2] + yb[3] * yb[3]);
;                 u32x4 w; w.x = pk2(ya[0], ya[1]); w.y = pk2(ya[2], ya[3]); w.z = pk2(yb[0], yb[1]); w.w = pk2(yb[2], yb[3]); *(u32x4*)(R + (size_t)row * DM + c) = w; }
;             s = wave_sum(s); if (lane == 0) rstd_out[row] = __builtin_amdgcn_rsqf(s * (1.0f / DM) + RMS_EPS); } }
; __global__ void __launch_bounds__(512, 2) fwd_megakernel(Params P) {
;     ...
;             const bool lastl = (l == NLAYER - 1);
;             { const int lane = otid() & 63, gw = bx * 8 + (otid() >> 6);
	v_lshlrev_b32_e32 v108, 16, v83
	v_and_b32_e32 v109, 0xffff0000, v83
	v_pk_mul_f32 v[106:107], v[96:97], v[106:107] op_sel_hi:[0,1]
	v_pk_fma_f32 v[100:101], v[4:5], v[106:107], v[108:109]
	v_lshlrev_b32_e32 v106, 16, v92
	v_and_b32_e32 v107, 0xffff0000, v92
	v_lshlrev_b32_e32 v108, 16, v84
	v_and_b32_e32 v109, 0xffff0000, v84
	v_pk_mul_f32 v[106:107], v[96:97], v[106:107] op_sel_hi:[0,1]
	v_pk_fma_f32 v[102:103], v[6:7], v[106:107], v[108:109]
	v_lshlrev_b32_e32 v106, 16, v93
	v_and_b32_e32 v107, 0xffff0000, v93
	v_lshlrev_b32_e32 v108, 16, v85
	v_and_b32_e32 v109, 0xffff0000, v85
	v_pk_mul_f32 v[106:107], v[96:97], v[106:107] op_sel_hi:[0,1]
	v_pk_fma_f32 v[104:105], v[8:9], v[106:107], v[108:109]
	v_pk_fma_f32 v[110:111], v[98:99], v[98:99], v[110:111]
	v_pk_fma_f32 v[110:111], v[100:101], v[100:101], v[110:111]
	v_pk_fma_f32 v[110:111], v[102:103], v[102:103], v[110:111]
	v_pk_fma_f32 v[110:111], v[104:105], v[104:105], v[110:111]
	v_cvt_pk_bf16_f32 v82, v98, v99
	v_cvt_pk_bf16_f32 v83, v100, v101
	v_cvt_pk_bf16_f32 v84, v102, v103
	v_cvt_pk_bf16_f32 v85, v104, v105
	global_store_dwordx4 v19, v[82:85], s[4:5] offset:1024
	v_add_f32_e32 v112, v110, v111
	v_add_u32_e32 v22, 0x2000, v22
	s_nop 1
	v_add_f32_dpp v112, v112, v112 quad_perm:[1,0,3,2] row_mask:0xf bank_mask:0xf
	s_nop 1
	v_add_f32_dpp v112, v112, v112 quad_perm:[2,3,0,1] row_mask:0xf bank_mask:0xf
	s_nop 1
	v_add_f32_dpp v112, v112, v112 row_half_mirror row_mask:0xf bank_mask:0xf
	s_nop 1
	v_add_f32_dpp v112, v112, v112 row_mirror row_mask:0xf bank_mask:0xf
	s_nop 1
	v_add_f32_dpp v112, v112, v112 row_bcast:15 row_mask:0xa bank_mask:0xf
	s_nop 1
	v_add_f32_dpp v112, v112, v112 row_bcast:31 row_mask:0xc bank_mask:0xf
	v_fmamk_f32 v113, v112, 0x3a800000, v244
	v_rsq_f32_e32 v113, v113
	s_mov_b64 exec, s[8:9]
	global_store_dword v22, v113, s[4:5]
	s_mov_b64 exec, -1
	s_branch .LBB0_823
.Lrs2_last1:
	v_lshrrev_b32_e32 v114, 6, v0
	v_readlane_b32 s12, v255, 49
	v_readlane_b32 s13, v255, 4
	v_readfirstlane_b32 s18, v114
	s_load_dwordx2 s[4:5], s[0:1], 0x98
	s_load_dwordx2 s[10:11], s[0:1], 0x68
	s_load_dwordx2 s[6:7], s[0:1], 0x90
	s_add_i32 s13, s13, s18
	v_and_b32_e32 v115, 63, v0
	v_lshlrev_b32_e32 v114, 4, v115
	v_lshlrev_b32_e32 v115, 5, v115
	s_lshl_b32 s18, s12, 12
	s_lshl_b32 s19, s12, 18
	s_bfm_b64 s[8:9], 1, 63
	s_waitcnt lgkmcnt(0)
	s_add_u32 s10, s10, s18
	s_addc_u32 s11, s11, 0
	global_load_dwordx4 v[2:5], v115, s[10:11] offset:2048
	global_load_dwordx4 v[6:9], v115, s[10:11] offset:2064
	global_load_dwordx4 v[10:13], v115, s[10:11]
	global_load_dwordx4 v[14:17], v115, s[10:11] offset:16
	s_lshl_b32 s18, s13, 11
	v_add_u32_e32 v18, s18, v114
	v_mov_b32_e32 v19, v18
	v_mov_b32_e32 v20, v18
	s_lshl_b32 s18, s13, 2
	v_mov_b32_e32 v22, s18
	s_add_i32 s18, s18, s19
	v_mov_b32_e32 v21, s18
	s_lshl_b32 s18, s13, 12
	v_add_u32_e32 v23, s18, v115
	v_add_u32_e32 v18, 0x5001000, v18
	v_add_u32_e32 v21, 0x2d70000, v21
	global_load_dwordx4 v[24:27], v18, s[4:5]
	global_load_dwordx4 v[32:35], v20, s[6:7]
	global_load_dwordx4 v[28:31], v18, s[4:5] offset:1024
	global_load_dwordx4 v[36:39], v20, s[6:7] offset:1024
	global_load_dword v40, v21, s[4:5]
	v_add_u32_e32 v18, 0x400000, v18
	v_add_u32_e32 v20, 0x400000, v20
	v_add_u32_e32 v21, 0x2000, v21
	global_load_dwordx4 v[42:45], v18, s[4:5]
	global_load_dwordx4 v[50:53], v20, s[6:7]
	global_load_dwordx4 v[46:49], v18, s[4:5] offset:1024
	global_load_dwordx4 v[54:57], v20, s[6:7] offset:1024
	global_load_dword v58, v21, s[4:5]
	v_add_u32_e32 v18, 0x400000, v18
	v_add_u32_e32 v20, 0x400000, v20
	v_add_u32_e32 v21, 0x2000, v21
	global_load_dwordx4 v[60:63], v18, s[4:5]
	global_load_dwordx4 v[68:71], v20, s[6:7]
	global_load_dwordx4 v[64:67], v18, s[4:5] offset:1024
	global_load_dwordx4 v[72:75], v20, s[6:7] offset:1024
	global_load_dword v76, v21, s[4:5]
	v_add_u32_e32 v18, 0x400000, v18
	v_add_u32_e32 v20, 0x400000, v20
	v_add_u32_e32 v21, 0x2000, v21
	global_load_dwordx4 v[78:81], v18, s[4:5]
	global_load_dwordx4 v[86:89], v20, s[6:7]
	global_load_dwordx4 v[82:85], v18, s[4:5] offset:1024
	global_load_dwordx4 v[90:93], v20, s[6:7] offset:1024
	global_load_dword v94, v21, s[4:5]
	s_waitcnt vmcnt(15)
	v_fmamk_f32 v96, v40, 0x3a800000, v244
	v_rsq_f32_e32 v96, v96
	v_add_u32_e32 v19, 0x5001000, v19
	v_add_u32_e32 v23, 0x4000000, v23
	v_lshlrev_b32_e32 v106, 16, v32
	v_and_b32_e32 v107, 0xffff0000, v32
	v_lshlrev_b32_e32 v108, 16, v24
	v_and_b32_e32 v109, 0xffff0000, v24
	v_pk_mul_f32 v[106:107], v[96:97], v[106:107] op_sel_hi:[0,1]
	v_pk_fma_f32 v[98:99], v[10:11], v[106:107], v[108:109]
	v_lshlrev_b32_e32 v106, 16, v33
	v_and_b32_e32 v107, 0xffff0000, v33
	v_lshlrev_b32_e32 v108, 16, v25
	v_and_b32_e32 v109, 0xffff0000, v25
	v_pk_mul_f32 v[106:107], v[96:97], v[106:107] op_sel_hi:[0,1]
	v_pk_fma_f32 v[100:101], v[12:13], v[106:107], v[108:109]
	v_lshlrev_b32_e32 v106, 16, v34
	v_and_b32_e32 v107, 0xffff0000, v34
	v_lshlrev_b32_e32 v108, 16, v26
	v_and_b32_e32 v109, 0xffff0000, v26
	v_pk_mul_f32 v[106:107], v[96:97], v[106:107] op_sel_hi:[0,1]
	v_pk_fma_f32 v[102:103], v[14:15], v[106:107], v[108:109]
	v_lshlrev_b32_e32 v106, 16, v35
	v_and_b32_e32 v107, 0xffff0000, v35
	v_lshlrev_b32_e32 v108, 16, v27
	v_and_b32_e32 v109, 0xffff0000, v27
	v_pk_mul_f32 v[106:107], v[96:97], v[106:107] op_sel_hi:[0,1]
	v_pk_fma_f32 v[104:105], v[16:17], v[106:107], v[108:109]
	v_pk_mul_f32 v[110:111], v[98:99], v[98:99]
	v_pk_fma_f32 v[110:111], v[100:101], v[100:101], v[110:111]
	v_pk_fma_f32 v[110:111], v[102:103], v[102:103], v[110:111]
	v_pk_fma_f32 v[110:111], v[104:105], v[104:105], v[110:111]
	v_cvt_pk_bf16_f32 v24, v98, v99
	v_cvt_pk_bf16_f32 v25, v100, v101
; __device__ __forceinline__ float bflo(unsigned w) { return __uint_as_float(w << 16); }
; __device__ __forceinline__ float bfhi(unsigned w) { return __uint_as_float(w & 0xffff0000u); }
; __device__ __forceinline__ void resid_rows(bf16_t* R, const bf16_t* Y, const float* ssqY, const float* g, float* rstd_out, float* outf, bool wf32, int row_lo, int row_hi, int yoff, int gw, int NGW, int lane) {
;     ...
;     for (int row0 = row_lo + gw; row0 < row_hi; row0 += RP * NGW) {
;         u32x4 rr[RP][2], oo[RP][2]; float ssv[RP];
; #pragma unroll
;         for (int k = 0; k < RP; ++k) { const int row = row0 + k * NGW; const bool ok = row < row_hi; const int rw = ok ? row : row0;
;             ssv[k] = ssqY[rw];
; #pragma unroll
;             for (int j = 0; j < 2; ++j) { const int c = 8 * lane + 512 * j; rr[k][j] = *(const u32x4*)(R + (size_t)rw * DM + c); oo[k][j] = *(const u32x4*)(Y + (size_t)(rw - yoff) * DM + c); } }
; #pragma unroll
;         for (int k = 0; k < RP; ++k) { const int row = row0 + k * NGW; if (row < row_hi) {
;             const float rs = __builtin_amdgcn_rsqf(ssv[k] * (1.0f / DM) + RMS_EPS); float s = 0.f;
; #pragma unroll
;             for (int j = 0; j < 2; ++j) { const int c = 8 * lane + 512 * j; const u32x4 r = rr[k][j], o = oo[k][j]; const f32x4 ga = gv[j][0], gb = gv[j][1];
;                 f32x4 ya, yb; ya[0] = bflo(r.x) + bflo(o.x) * rs * ga[0]; ya[1] = bfhi(r.x) + bfhi(o.x) * rs * ga[1]; ya[2] = bflo(r.y) + bflo(o.y) * rs * ga[2]; ya[3] = bfhi(r.y) + bfhi(o.y) * rs * ga[3];
;                 yb[0] = bflo(r.z) + bflo(o.z) * rs * gb[0]; yb[1] = bfhi(r.z) + bfhi(o.z) * rs * gb[1]; yb[2] = bflo(r.w) + bflo(o.w) * rs * gb[2]; yb[3] = bfhi(r.w) + bfhi(o.w) * rs * gb[3];
;                 if (wf32) { *(f32x4*)(outf + (size_t)row * DM + c) = ya; *(f32x4*)(outf + (size_t)row * DM + c + 4) = yb; }
;                 s += (ya[0] * ya[0] + ya[1] * ya[1]) + (ya[2] * ya[2] + ya[3] * ya[3]) + (yb[0] * yb[0] + yb[1] * yb[1]) + (yb[2] * yb[2] + yb[3] * yb[3]);
;                 u32x4 w; w.x = pk2(ya[0], ya[1]); w.y = pk2(ya[2], ya[3]); w.z = pk2(yb[0], yb[1]); w.w = pk2(yb[2], yb[3]); *(u32x4*)(R + (size_t)row * DM + c) = w; }
;             s = wave_sum(s); if (lane == 0) rstd_out[row] = __builtin_amdgcn_rsqf(s * (1.0f / DM) + RMS_EPS); } }
	v_cvt_pk_bf16_f32 v26, v102, v103
	v_cvt_pk_bf16_f32 v27, v104, v105
	global_store_dwordx4 v19, v[24:27], s[4:5]
	global_store_dwordx4 v23, v[98:101], s[6:7]
	global_store_dwordx4 v23, v[102:105], s[6:7] offset:16
	v_lshlrev_b32_e32 v106, 16, v36
	v_and_b32_e32 v107, 0xffff0000, v36
	v_lshlrev_b32_e32 v108, 16, v28
	v_and_b32_e32 v109, 0xffff0000, v28
	v_pk_mul_f32 v[106:107], v[96:97], v[106:107] op_sel_hi:[0,1]
	v_pk_fma_f32 v[98:99], v[2:3], v[106:107], v[108:109]
	v_lshlrev_b32_e32 v106, 16, v37
	v_and_b32_e32 v107, 0xffff0000, v37
	v_lshlrev_b32_e32 v108, 16, v29
	v_and_b32_e32 v109, 0xffff0000, v29
	v_pk_mul_f32 v[106:107], v[96:97], v[106:107] op_sel_hi:[0,1]
	v_pk_fma_f32 v[100:101], v[4:5], v[106:107], v[108:109]
	v_lshlrev_b32_e32 v106, 16, v38
	v_and_b32_e32 v107, 0xffff0000, v38
	v_lshlrev_b32_e32 v108, 16, v30
	v_and_b32_e32 v109, 0xffff0000, v30
	v_pk_mul_f32 v[106:107], v[96:97], v[106:107] op_sel_hi:[0,1]
	v_pk_fma_f32 v[102:103], v[6:7], v[106:107], v[108:109]
	v_lshlrev_b32_e32 v106, 16, v39
	v_and_b32_e32 v107, 0xffff0000, v39
	v_lshlrev_b32_e32 v108, 16, v31
	v_and_b32_e32 v109, 0xffff0000, v31
	v_pk_mul_f32 v[106:107], v[96:97], v[106:107] op_sel_hi:[0,1]
	v_pk_fma_f32 v[104:105], v[8:9], v[106:107], v[108:109]
	v_pk_fma_f32 v[110:111], v[98:99], v[98:99], v[110:111]
	v_pk_fma_f32 v[110:111], v[100:101], v[100:101], v[110:111]
	v_pk_fma_f32 v[110:111], v[102:103], v[102:103], v[110:111]
	v_pk_fma_f32 v[110:111], v[104:105], v[104:105], v[110:111]
	v_cvt_pk_bf16_f32 v28, v98, v99
	v_cvt_pk_bf16_f32 v29, v100, v101
	v_cvt_pk_bf16_f32 v30, v102, v103
	v_cvt_pk_bf16_f32 v31, v104, v105
	global_store_dwordx4 v19, v[28:31], s[4:5] offset:1024
	global_store_dwordx4 v23, v[98:101], s[6:7] offset:2048
	global_store_dwordx4 v23, v[102:105], s[6:7] offset:2064
	v_add_f32_e32 v112, v110, v111
	v_add_u32_e32 v22, 0x2d10000, v22
	s_nop 1
	v_add_f32_dpp v112, v112, v112 quad_perm:[1,0,3,2] row_mask:0xf bank_mask:0xf
	s_nop 1
	v_add_f32_dpp v112, v112, v112 quad_perm:[2,3,0,1] row_mask:0xf bank_mask:0xf
	s_nop 1
	v_add_f32_dpp v112, v112, v112 row_half_mirror row_mask:0xf bank_mask:0xf
	s_nop 1
	v_add_f32_dpp v112, v112, v112 row_mirror row_mask:0xf bank_mask:0xf
	s_nop 1
	v_add_f32_dpp v112, v112, v112 row_bcast:15 row_mask:0xa bank_mask:0xf
	s_nop 1
	v_add_f32_dpp v112, v112, v112 row_bcast:31 row_mask:0xc bank_mask:0xf
	v_fmamk_f32 v113, v112, 0x3a800000, v244
	v_rsq_f32_e32 v113, v113
	s_mov_b64 exec, s[8:9]
	global_store_dword v22, v113, s[4:5]
	s_mov_b64 exec, -1
	v_add_u32_e32 v18, 0x400000, v18
	v_add_u32_e32 v20, 0x400000, v20
	v_add_u32_e32 v21, 0x2000, v21
	global_load_dwordx4 v[24:27], v18, s[4:5]
	global_load_dwordx4 v[32:35], v20, s[6:7]
	global_load_dwordx4 v[28:31], v18, s[4:5] offset:1024
	global_load_dwordx4 v[36:39], v20, s[6:7] offset:1024
	global_load_dword v40, v21, s[4:5]
	s_waitcnt vmcnt(22)
	v_fmamk_f32 v96, v58, 0x3a800000, v244
	v_rsq_f32_e32 v96, v96
	v_add_u32_e32 v19, 0x400000, v19
	v_add_u32_e32 v23, 0x800000, v23
	v_lshlrev_b32_e32 v106, 16, v50
	v_and_b32_e32 v107, 0xffff0000, v50
	v_lshlrev_b32_e32 v108, 16, v42
	v_and_b32_e32 v109, 0xffff0000, v42
	v_pk_mul_f32 v[106:107], v[96:97], v[106:107] op_sel_hi:[0,1]
	v_pk_fma_f32 v[98:99], v[10:11], v[106:107], v[108:109]
	v_lshlrev_b32_e32 v106, 16, v51
	v_and_b32_e32 v107, 0xffff0000, v51
	v_lshlrev_b32_e32 v108, 16, v43
	v_and_b32_e32 v109, 0xffff0000, v43
	v_pk_mul_f32 v[106:107], v[96:97], v[106:107] op_sel_hi:[0,1]
	v_pk_fma_f32 v[100:101], v[12:13], v[106:107], v[108:109]
	v_lshlrev_b32_e32 v106, 16, v52
	v_and_b32_e32 v107, 0xffff0000, v52
	v_lshlrev_b32_e32 v108, 16, v44
	v_and_b32_e32 v109, 0xffff0000, v44
	v_pk_mul_f32 v[106:107], v[96:97], v[106:107] op_sel_hi:[0,1]
	v_pk_fma_f32 v[102:103], v[14:15], v[106:107], v[108:109]
	v_lshlrev_b32_e32 v106, 16, v53
	v_and_b32_e32 v107, 0xffff0000, v53
	v_lshlrev_b32_e32 v108, 16, v45
	v_and_b32_e32 v109, 0xffff0000, v45
	v_pk_mul_f32 v[106:107], v[96:97], v[106:107] op_sel_hi:[0,1]
	v_pk_fma_f32 v[104:105], v[16:17], v[106:107], v[108:109]
	v_pk_mul_f32 v[110:111], v[98:99], v[98:99]
	v_pk_fma_f32 v[110:111], v[100:101], v[100:101], v[110:111]
	v_pk_fma_f32 v[110:111], v[102:103], v[102:103], v[110:111]
	v_pk_fma_f32 v[110:111], v[104:105], v[104:105], v[110:111]
	v_cvt_pk_bf16_f32 v42, v98, v99
	v_cvt_pk_bf16_f32 v43, v100, v101
	v_cvt_pk_bf16_f32 v44, v102, v103
	v_cvt_pk_bf16_f32 v45, v104, v105
	global_store_dwordx4 v19, v[42:45], s[4:5]
	global_store_dwordx4 v23, v[98:101], s[6:7]
	global_store_dwordx4 v23, v[102:105], s[6:7] offset:16
	v_lshlrev_b32_e32 v106, 16, v54
	v_and_b32_e32 v107, 0xffff0000, v54
	v_lshlrev_b32_e32 v108, 16, v46
	v_and_b32_e32 v109, 0xffff0000, v46
	v_pk_mul_f32 v[106:107], v[96:97], v[106:107] op_sel_hi:[0,1]
	v_pk_fma_f32 v[98:99], v[2:3], v[106:107], v[108:109]
	v_lshlrev_b32_e32 v106, 16, v55
	v_and_b32_e32 v107, 0xffff0000, v55
	v_lshlrev_b32_e32 v108, 16, v47
	v_and_b32_e32 v109, 0xffff0000, v47
	v_pk_mul_f32 v[106:107], v[96:97], v[106:107] op_sel_hi:[0,1]
	v_pk_fma_f32 v[100:101], v[4:5], v[106:107], v[108:109]
	v_lshlrev_b32_e32 v106, 16, v56
	v_and_b32_e32 v107, 0xffff0000, v56
	v_lshlrev_b32_e32 v108, 16, v48
	v_and_b32_e32 v109, 0xffff0000, v48
	v_pk_mul_f32 v[106:107], v[96:97], v[106:107] op_sel_hi:[0,1]
	v_pk_fma_f32 v[102:103], v[6:7], v[106:107], v[108:109]
	v_lshlrev_b32_e32 v106, 16, v57
	v_and_b32_e32 v107, 0xffff0000, v57
	v_lshlrev_b32_e32 v108, 16, v49
	v_and_b32_e32 v109, 0xffff0000, v49
	v_pk_mul_f32 v[106:107], v[96:97], v[106:107] op_sel_hi:[0,1]
	v_pk_fma_f32 v[104:105], v[8:9], v[106:107], v[108:109]
	v_pk_fma_f32 v[110:111], v[98:99], v[98:99], v[110:111]
; __device__ __forceinline__ float bflo(unsigned w) { return __uint_as_float(w << 16); }
; __device__ __forceinline__ float bfhi(unsigned w) { return __uint_as_float(w & 0xffff0000u); }
; __device__ __forceinline__ void resid_rows(bf16_t* R, const bf16_t* Y, const float* ssqY, const float* g, float* rstd_out, float* outf, bool wf32, int row_lo, int row_hi, int yoff, int gw, int NGW, int lane) {
;     ...
;     for (int row0 = row_lo + gw; row0 < row_hi; row0 += RP * NGW) {
;         u32x4 rr[RP][2], oo[RP][2]; float ssv[RP];
; #pragma unroll
;         for (int k = 0; k < RP; ++k) { const int row = row0 + k * NGW; const bool ok = row < row_hi; const int rw = ok ? row : row0;
;             ssv[k] = ssqY[rw];
; #pragma unroll
;             for (int j = 0; j < 2; ++j) { const int c = 8 * lane + 512 * j; rr[k][j] = *(const u32x4*)(R + (size_t)rw * DM + c); oo[k][j] = *(const u32x4*)(Y + (size_t)(rw - yoff) * DM + c); } }
; #pragma unroll
;         for (int k = 0; k < RP; ++k) { const int row = row0 + k * NGW; if (row < row_hi) {
;             const float rs = __builtin_amdgcn_rsqf(ssv[k] * (1.0f / DM) + RMS_EPS); float s = 0.f;
; #pragma unroll
;             for (int j = 0; j < 2; ++j) { const int c = 8 * lane + 512 * j; const u32x4 r = rr[k][j], o = oo[k][j]; const f32x4 ga = gv[j][0], gb = gv[j][1];
;                 f32x4 ya, yb; ya[0] = bflo(r.x) + bflo(o.x) * rs * ga[0]; ya[1] = bfhi(r.x) + bfhi(o.x) * rs * ga[1]; ya[2] = bflo(r.y) + bflo(o.y) * rs * ga[2]; ya[3] = bfhi(r.y) + bfhi(o.y) * rs * ga[3];
;                 yb[0] = bflo(r.z) + bflo(o.z) * rs * gb[0]; yb[1] = bfhi(r.z) + bfhi(o.z) * rs * gb[1]; yb[2] = bflo(r.w) + bflo(o.w) * rs * gb[2]; yb[3] = bfhi(r.w) + bfhi(o.w) * rs * gb[3];
;                 if (wf32) { *(f32x4*)(outf + (size_t)row * DM + c) = ya; *(f32x4*)(outf + (size_t)row * DM + c + 4) = yb; }
;                 s += (ya[0] * ya[0] + ya[1] * ya[1]) + (ya[2] * ya[2] + ya[3] * ya[3]) + (yb[0] * yb[0] + yb[1] * yb[1]) + (yb[2] * yb[2] + yb[3] * yb[3]);
;                 u32x4 w; w.x = pk2(ya[0], ya[1]); w.y = pk2(ya[2], ya[3]); w.z = pk2(yb[0], yb[1]); w.w = pk2(yb[2], yb[3]); *(u32x4*)(R + (size_t)row * DM + c) = w; }
;             s = wave_sum(s); if (lane == 0) rstd_out[row] = __builtin_amdgcn_rsqf(s * (1.0f / DM) + RMS_EPS); } }
	v_pk_fma_f32 v[110:111], v[100:101], v[100:101], v[110:111]
	v_pk_fma_f32 v[110:111], v[102:103], v[102:103], v[110:111]
	v_pk_fma_f32 v[110:111], v[104:105], v[104:105], v[110:111]
	v_cvt_pk_bf16_f32 v46, v98, v99
	v_cvt_pk_bf16_f32 v47, v100, v101
	v_cvt_pk_bf16_f32 v48, v102, v103
	v_cvt_pk_bf16_f32 v49, v104, v105
	global_store_dwordx4 v19, v[46:49], s[4:5] offset:1024
	global_store_dwordx4 v23, v[98:101], s[6:7] offset:2048
	global_store_dwordx4 v23, v[102:105], s[6:7] offset:2064
	v_add_f32_e32 v112, v110, v111
	v_add_u32_e32 v22, 0x2000, v22
	s_nop 1
	v_add_f32_dpp v112, v112, v112 quad_perm:[1,0,3,2] row_mask:0xf bank_mask:0xf
	s_nop 1
	v_add_f32_dpp v112, v112, v112 quad_perm:[2,3,0,1] row_mask:0xf bank_mask:0xf
	s_nop 1
	v_add_f32_dpp v112, v112, v112 row_half_mirror row_mask:0xf bank_mask:0xf
	s_nop 1
	v_add_f32_dpp v112, v112, v112 row_mirror row_mask:0xf bank_mask:0xf
	s_nop 1
	v_add_f32_dpp v112, v112, v112 row_bcast:15 row_mask:0xa bank_mask:0xf
	s_nop 1
	v_add_f32_dpp v112, v112, v112 row_bcast:31 row_mask:0xc bank_mask:0xf
	v_fmamk_f32 v113, v112, 0x3a800000, v244
	v_rsq_f32_e32 v113, v113
	s_mov_b64 exec, s[8:9]
	global_store_dword v22, v113, s[4:5]
	s_mov_b64 exec, -1
	v_add_u32_e32 v18, 0x400000, v18
	v_add_u32_e32 v20, 0x400000, v20
	v_add_u32_e32 v21, 0x2000, v21
	global_load_dwordx4 v[42:45], v18, s[4:5]
	global_load_dwordx4 v[50:53], v20, s[6:7]
	global_load_dwordx4 v[46:49], v18, s[4:5] offset:1024
	global_load_dwordx4 v[54:57], v20, s[6:7] offset:1024
	global_load_dword v58, v21, s[4:5]
	s_waitcnt vmcnt(29)
	v_fmamk_f32 v96, v76, 0x3a800000, v244
	v_rsq_f32_e32 v96, v96
	v_add_u32_e32 v19, 0x400000, v19
	v_add_u32_e32 v23, 0x800000, v23
	v_lshlrev_b32_e32 v106, 16, v68
	v_and_b32_e32 v107, 0xffff0000, v68
	v_lshlrev_b32_e32 v108, 16, v60
	v_and_b32_e32 v109, 0xffff0000, v60
	v_pk_mul_f32 v[106:107], v[96:97], v[106:107] op_sel_hi:[0,1]
	v_pk_fma_f32 v[98:99], v[10:11], v[106:107], v[108:109]
	v_lshlrev_b32_e32 v106, 16, v69
	v_and_b32_e32 v107, 0xffff0000, v69
	v_lshlrev_b32_e32 v108, 16, v61
	v_and_b32_e32 v109, 0xffff0000, v61
	v_pk_mul_f32 v[106:107], v[96:97], v[106:107] op_sel_hi:[0,1]
	v_pk_fma_f32 v[100:101], v[12:13], v[106:107], v[108:109]
	v_lshlrev_b32_e32 v106, 16, v70
	v_and_b32_e32 v107, 0xffff0000, v70
	v_lshlrev_b32_e32 v108, 16, v62
	v_and_b32_e32 v109, 0xffff0000, v62
	v_pk_mul_f32 v[106:107], v[96:97], v[106:107] op_sel_hi:[0,1]
	v_pk_fma_f32 v[102:103], v[14:15], v[106:107], v[108:109]
	v_lshlrev_b32_e32 v106, 16, v71
	v_and_b32_e32 v107, 0xffff0000, v71
	v_lshlrev_b32_e32 v108, 16, v63
	v_and_b32_e32 v109, 0xffff0000, v63
	v_pk_mul_f32 v[106:107], v[96:97], v[106:107] op_sel_hi:[0,1]
	v_pk_fma_f32 v[104:105], v[16:17], v[106:107], v[108:109]
	v_pk_mul_f32 v[110:111], v[98:99], v[98:99]
	v_pk_fma_f32 v[110:111], v[100:101], v[100:101], v[110:111]
	v_pk_fma_f32 v[110:111], v[102:103], v[102:103], v[110:111]
	v_pk_fma_f32 v[110:111], v[104:105], v[104:105], v[110:111]
	v_cvt_pk_bf16_f32 v60, v98, v99
	v_cvt_pk_bf16_f32 v61, v100, v101
	v_cvt_pk_bf16_f32 v62, v102, v103
	v_cvt_pk_bf16_f32 v63, v104, v105
	global_store_dwordx4 v19, v[60:63], s[4:5]
	global_store_dwordx4 v23, v[98:101], s[6:7]
	global_store_dwordx4 v23, v[102:105], s[6:7] offset:16
	v_lshlrev_b32_e32 v106, 16, v72
	v_and_b32_e32 v107, 0xffff0000, v72
	v_lshlrev_b32_e32 v108, 16, v64
	v_and_b32_e32 v109, 0xffff0000, v64
	v_pk_mul_f32 v[106:107], v[96:97], v[106:107] op_sel_hi:[0,1]
	v_pk_fma_f32 v[98:99], v[2:3], v[106:107], v[108:109]
	v_lshlrev_b32_e32 v106, 16, v73
	v_and_b32_e32 v107, 0xffff0000, v73
	v_lshlrev_b32_e32 v108, 16, v65
	v_and_b32_e32 v109, 0xffff0000, v65
	v_pk_mul_f32 v[106:107], v[96:97], v[106:107] op_sel_hi:[0,1]
	v_pk_fma_f32 v[100:101], v[4:5], v[106:107], v[108:109]
	v_lshlrev_b32_e32 v106, 16, v74
	v_and_b32_e32 v107, 0xffff0000, v74
	v_lshlrev_b32_e32 v108, 16, v66
	v_and_b32_e32 v109, 0xffff0000, v66
	v_pk_mul_f32 v[106:107], v[96:97], v[106:107] op_sel_hi:[0,1]
	v_pk_fma_f32 v[102:103], v[6:7], v[106:107], v[108:109]
	v_lshlrev_b32_e32 v106, 16, v75
	v_and_b32_e32 v107, 0xffff0000, v75
	v_lshlrev_b32_e32 v108, 16, v67
	v_and_b32_e32 v109, 0xffff0000, v67
	v_pk_mul_f32 v[106:107], v[96:97], v[106:107] op_sel_hi:[0,1]
	v_pk_fma_f32 v[104:105], v[8:9], v[106:107], v[108:109]
	v_pk_fma_f32 v[110:111], v[98:99], v[98:99], v[110:111]
	v_pk_fma_f32 v[110:111], v[100:101], v[100:101], v[110:111]
	v_pk_fma_f32 v[110:111], v[102:103], v[102:103], v[110:111]
	v_pk_fma_f32 v[110:111], v[104:105], v[104:105], v[110:111]
	v_cvt_pk_bf16_f32 v64, v98, v99
	v_cvt_pk_bf16_f32 v65, v100, v101
	v_cvt_pk_bf16_f32 v66, v102, v103
	v_cvt_pk_bf16_f32 v67, v104, v105
	global_store_dwordx4 v19, v[64:67], s[4:5] offset:1024
	global_store_dwordx4 v23, v[98:101], s[6:7] offset:2048
	global_store_dwordx4 v23, v[102:105], s[6:7] offset:2064
	v_add_f32_e32 v112, v110, v111
	v_add_u32_e32 v22, 0x2000, v22
	s_nop 1
	v_add_f32_dpp v112, v112, v112 quad_perm:[1,0,3,2] row_mask:0xf bank_mask:0xf
	s_nop 1
	v_add_f32_dpp v112, v112, v112 quad_perm:[2,3,0,1] row_mask:0xf bank_mask:0xf
	s_nop 1
	v_add_f32_dpp v112, v112, v112 row_half_mirror row_mask:0xf bank_mask:0xf
	s_nop 1
	v_add_f32_dpp v112, v112, v112 row_mirror row_mask:0xf bank_mask:0xf
	s_nop 1
	v_add_f32_dpp v112, v112, v112 row_bcast:15 row_mask:0xa bank_mask:0xf
	s_nop 1
	v_add_f32_dpp v112, v112, v112 row_bcast:31 row_mask:0xc bank_mask:0xf
	v_fmamk_f32 v113, v112, 0x3a800000, v244
	v_rsq_f32_e32 v113, v113
	s_mov_b64 exec, s[8:9]
	global_store_dword v22, v113, s[4:5]
	s_mov_b64 exec, -1
	v_add_u32_e32 v18, 0x400000, v18
	v_add_u32_e32 v20, 0x400000, v20
	v_add_u32_e32 v21, 0x2000, v21
	global_load_dwordx4 v[60:63], v18, s[4:5]
	global_load_dwordx4 v[68:71], v20, s[6:7]
	global_load_dwordx4 v[64:67], v18, s[4:5] offset:1024
	global_load_dwordx4 v[72:75], v20, s[6:7] offset:1024
	global_load_dword v76, v21, s[4:5]
	s_waitcnt vmcnt(36)
; __device__ __forceinline__ float bflo(unsigned w) { return __uint_as_float(w << 16); }
; __device__ __forceinline__ float bfhi(unsigned w) { return __uint_as_float(w & 0xffff0000u); }
; __device__ __forceinline__ void resid_rows(bf16_t* R, const bf16_t* Y, const float* ssqY, const float* g, float* rstd_out, float* outf, bool wf32, int row_lo, int row_hi, int yoff, int gw, int NGW, int lane) {
;     ...
;     for (int row0 = row_lo + gw; row0 < row_hi; row0 += RP * NGW) {
;         u32x4 rr[RP][2], oo[RP][2]; float ssv[RP];
; #pragma unroll
;         for (int k = 0; k < RP; ++k) { const int row = row0 + k * NGW; const bool ok = row < row_hi; const int rw = ok ? row : row0;
;             ssv[k] = ssqY[rw];
; #pragma unroll
;             for (int j = 0; j < 2; ++j) { const int c = 8 * lane + 512 * j; rr[k][j] = *(const u32x4*)(R + (size_t)rw * DM + c); oo[k][j] = *(const u32x4*)(Y + (size_t)(rw - yoff) * DM + c); } }
; #pragma unroll
;         for (int k = 0; k < RP; ++k) { const int row = row0 + k * NGW; if (row < row_hi) {
;             const float rs = __builtin_amdgcn_rsqf(ssv[k] * (1.0f / DM) + RMS_EPS); float s = 0.f;
; #pragma unroll
;             for (int j = 0; j < 2; ++j) { const int c = 8 * lane + 512 * j; const u32x4 r = rr[k][j], o = oo[k][j]; const f32x4 ga = gv[j][0], gb = gv[j][1];
;                 f32x4 ya, yb; ya[0] = bflo(r.x) + bflo(o.x) * rs * ga[0]; ya[1] = bfhi(r.x) + bfhi(o.x) * rs * ga[1]; ya[2] = bflo(r.y) + bflo(o.y) * rs * ga[2]; ya[3] = bfhi(r.y) + bfhi(o.y) * rs * ga[3];
;                 yb[0] = bflo(r.z) + bflo(o.z) * rs * gb[0]; yb[1] = bfhi(r.z) + bfhi(o.z) * rs * gb[1]; yb[2] = bflo(r.w) + bflo(o.w) * rs * gb[2]; yb[3] = bfhi(r.w) + bfhi(o.w) * rs * gb[3];
;                 if (wf32) { *(f32x4*)(outf + (size_t)row * DM + c) = ya; *(f32x4*)(outf + (size_t)row * DM + c + 4) = yb; }
;                 s += (ya[0] * ya[0] + ya[1] * ya[1]) + (ya[2] * ya[2] + ya[3] * ya[3]) + (yb[0] * yb[0] + yb[1] * yb[1]) + (yb[2] * yb[2] + yb[3] * yb[3]);
;                 u32x4 w; w.x = pk2(ya[0], ya[1]); w.y = pk2(ya[2], ya[3]); w.z = pk2(yb[0], yb[1]); w.w = pk2(yb[2], yb[3]); *(u32x4*)(R + (size_t)row * DM + c) = w; }
;             s = wave_sum(s); if (lane == 0) rstd_out[row] = __builtin_amdgcn_rsqf(s * (1.0f / DM) + RMS_EPS); } }
	v_fmamk_f32 v96, v94, 0x3a800000, v244
	v_rsq_f32_e32 v96, v96
	v_add_u32_e32 v19, 0x400000, v19
	v_add_u32_e32 v23, 0x800000, v23
	v_lshlrev_b32_e32 v106, 16, v86
	v_and_b32_e32 v107, 0xffff0000, v86
	v_lshlrev_b32_e32 v108, 16, v78
	v_and_b32_e32 v109, 0xffff0000, v78
	v_pk_mul_f32 v[106:107], v[96:97], v[106:107] op_sel_hi:[0,1]
	v_pk_fma_f32 v[98:99], v[10:11], v[106:107], v[108:109]
	v_lshlrev_b32_e32 v106, 16, v87
	v_and_b32_e32 v107, 0xffff0000, v87
	v_lshlrev_b32_e32 v108, 16, v79
	v_and_b32_e32 v109, 0xffff0000, v79
	v_pk_mul_f32 v[106:107], v[96:97], v[106:107] op_sel_hi:[0,1]
	v_pk_fma_f32 v[100:101], v[12:13], v[106:107], v[108:109]
	v_lshlrev_b32_e32 v106, 16, v88
	v_and_b32_e32 v107, 0xffff0000, v88
	v_lshlrev_b32_e32 v108, 16, v80
	v_and_b32_e32 v109, 0xffff0000, v80
	v_pk_mul_f32 v[106:107], v[96:97], v[106:107] op_sel_hi:[0,1]
	v_pk_fma_f32 v[102:103], v[14:15], v[106:107], v[108:109]
	v_lshlrev_b32_e32 v106, 16, v89
	v_and_b32_e32 v107, 0xffff0000, v89
	v_lshlrev_b32_e32 v108, 16, v81
	v_and_b32_e32 v109, 0xffff0000, v81
	v_pk_mul_f32 v[106:107], v[96:97], v[106:107] op_sel_hi:[0,1]
	v_pk_fma_f32 v[104:105], v[16:17], v[106:107], v[108:109]
	v_pk_mul_f32 v[110:111], v[98:99], v[98:99]
	v_pk_fma_f32 v[110:111], v[100:101], v[100:101], v[110:111]
	v_pk_fma_f32 v[110:111], v[102:103], v[102:103], v[110:111]
	v_pk_fma_f32 v[110:111], v[104:105], v[104:105], v[110:111]
	v_cvt_pk_bf16_f32 v78, v98, v99
	v_cvt_pk_bf16_f32 v79, v100, v101
	v_cvt_pk_bf16_f32 v80, v102, v103
	v_cvt_pk_bf16_f32 v81, v104, v105
	global_store_dwordx4 v19, v[78:81], s[4:5]
	global_store_dwordx4 v23, v[98:101], s[6:7]
	global_store_dwordx4 v23, v[102:105], s[6:7] offset:16
	v_lshlrev_b32_e32 v106, 16, v90
	v_and_b32_e32 v107, 0xffff0000, v90
	v_lshlrev_b32_e32 v108, 16, v82
	v_and_b32_e32 v109, 0xffff0000, v82
	v_pk_mul_f32 v[106:107], v[96:97], v[106:107] op_sel_hi:[0,1]
	v_pk_fma_f32 v[98:99], v[2:3], v[106:107], v[108:109]
	v_lshlrev_b32_e32 v106, 16, v91
	v_and_b32_e32 v107, 0xffff0000, v91
	v_lshlrev_b32_e32 v108, 16, v83
	v_and_b32_e32 v109, 0xffff0000, v83
	v_pk_mul_f32 v[106:107], v[96:97], v[106:107] op_sel_hi:[0,1]
	v_pk_fma_f32 v[100:101], v[4:5], v[106:107], v[108:109]
	v_lshlrev_b32_e32 v106, 16, v92
	v_and_b32_e32 v107, 0xffff0000, v92
	v_lshlrev_b32_e32 v108, 16, v84
	v_and_b32_e32 v109, 0xffff0000, v84
	v_pk_mul_f32 v[106:107], v[96:97], v[106:107] op_sel_hi:[0,1]
	v_pk_fma_f32 v[102:103], v[6:7], v[106:107], v[108:109]
	v_lshlrev_b32_e32 v106, 16, v93
	v_and_b32_e32 v107, 0xffff0000, v93
	v_lshlrev_b32_e32 v108, 16, v85
	v_and_b32_e32 v109, 0xffff0000, v85
	v_pk_mul_f32 v[106:107], v[96:97], v[106:107] op_sel_hi:[0,1]
	v_pk_fma_f32 v[104:105], v[8:9], v[106:107], v[108:109]
	v_pk_fma_f32 v[110:111], v[98:99], v[98:99], v[110:111]
	v_pk_fma_f32 v[110:111], v[100:101], v[100:101], v[110:111]
	v_pk_fma_f32 v[110:111], v[102:103], v[102:103], v[110:111]
	v_pk_fma_f32 v[110:111], v[104:105], v[104:105], v[110:111]
	v_cvt_pk_bf16_f32 v82, v98, v99
	v_cvt_pk_bf16_f32 v83, v100, v101
	v_cvt_pk_bf16_f32 v84, v102, v103
	v_cvt_pk_bf16_f32 v85, v104, v105
	global_store_dwordx4 v19, v[82:85], s[4:5] offset:1024
	global_store_dwordx4 v23, v[98:101], s[6:7] offset:2048
	global_store_dwordx4 v23, v[102:105], s[6:7] offset:2064
	v_add_f32_e32 v112, v110, v111
	v_add_u32_e32 v22, 0x2000, v22
	s_nop 1
	v_add_f32_dpp v112, v112, v112 quad_perm:[1,0,3,2] row_mask:0xf bank_mask:0xf
	s_nop 1
	v_add_f32_dpp v112, v112, v112 quad_perm:[2,3,0,1] row_mask:0xf bank_mask:0xf
	s_nop 1
	v_add_f32_dpp v112, v112, v112 row_half_mirror row_mask:0xf bank_mask:0xf
	s_nop 1
	v_add_f32_dpp v112, v112, v112 row_mirror row_mask:0xf bank_mask:0xf
	s_nop 1
	v_add_f32_dpp v112, v112, v112 row_bcast:15 row_mask:0xa bank_mask:0xf
	s_nop 1
	v_add_f32_dpp v112, v112, v112 row_bcast:31 row_mask:0xc bank_mask:0xf
	v_fmamk_f32 v113, v112, 0x3a800000, v244
	v_rsq_f32_e32 v113, v113
	s_mov_b64 exec, s[8:9]
	global_store_dword v22, v113, s[4:5]
	s_mov_b64 exec, -1
	v_add_u32_e32 v18, 0x400000, v18
	v_add_u32_e32 v20, 0x400000, v20
	v_add_u32_e32 v21, 0x2000, v21
	global_load_dwordx4 v[78:81], v18, s[4:5]
	global_load_dwordx4 v[86:89], v20, s[6:7]
	global_load_dwordx4 v[82:85], v18, s[4:5] offset:1024
	global_load_dwordx4 v[90:93], v20, s[6:7] offset:1024
	global_load_dword v94, v21, s[4:5]
	s_waitcnt vmcnt(36)
; __device__ __forceinline__ float bflo(unsigned w) { return __uint_as_float(w << 16); }
; __device__ __forceinline__ float bfhi(unsigned w) { return __uint_as_float(w & 0xffff0000u); }
; __device__ __forceinline__ void resid_rows(bf16_t* R, const bf16_t* Y, const float* ssqY, const float* g, float* rstd_out, float* outf, bool wf32, int row_lo, int row_hi, int yoff, int gw, int NGW, int lane) {
;     ...
;     for (int row0 = row_lo + gw; row0 < row_hi; row0 += RP * NGW) {
;         u32x4 rr[RP][2], oo[RP][2]; float ssv[RP];
; #pragma unroll
;         for (int k = 0; k < RP; ++k) { const int row = row0 + k * NGW; const bool ok = row < row_hi; const int rw = ok ? row : row0;
;             ssv[k] = ssqY[rw];
; #pragma unroll
;             for (int j = 0; j < 2; ++j) { const int c = 8 * lane + 512 * j; rr[k][j] = *(const u32x4*)(R + (size_t)rw * DM + c); oo[k][j] = *(const u32x4*)(Y + (size_t)(rw - yoff) * DM + c); } }
; #pragma unroll
;         for (int k = 0; k < RP; ++k) { const int row = row0 + k * NGW; if (row < row_hi) {
;             const float rs = __builtin_amdgcn_rsqf(ssv[k] * (1.0f / DM) + RMS_EPS); float s = 0.f;
; #pragma unroll
;             for (int j = 0; j < 2; ++j) { const int c = 8 * lane + 512 * j; const u32x4 r = rr[k][j], o = oo[k][j]; const f32x4 ga = gv[j][0], gb = gv[j][1];
;                 f32x4 ya, yb; ya[0] = bflo(r.x) + bflo(o.x) * rs * ga[0]; ya[1] = bfhi(r.x) + bfhi(o.x) * rs * ga[1]; ya[2] = bflo(r.y) + bflo(o.y) * rs * ga[2]; ya[3] = bfhi(r.y) + bfhi(o.y) * rs * ga[3];
;                 yb[0] = bflo(r.z) + bflo(o.z) * rs * gb[0]; yb[1] = bfhi(r.z) + bfhi(o.z) * rs * gb[1]; yb[2] = bflo(r.w) + bflo(o.w) * rs * gb[2]; yb[3] = bfhi(r.w) + bfhi(o.w) * rs * gb[3];
;                 if (wf32) { *(f32x4*)(outf + (size_t)row * DM + c) = ya; *(f32x4*)(outf + (size_t)row * DM + c + 4) = yb; }
;                 s += (ya[0] * ya[0] + ya[1] * ya[1]) + (ya[2] * ya[2] + ya[3] * ya[3]) + (yb[0] * yb[0] + yb[1] * yb[1]) + (yb[2] * yb[2] + yb[3] * yb[3]);
;                 u32x4 w; w.x = pk2(ya[0], ya[1]); w.y = pk2(ya[2], ya[3]); w.z = pk2(yb[0], yb[1]); w.w = pk2(yb[2], yb[3]); *(u32x4*)(R + (size_t)row * DM + c) = w; }
;             s = wave_sum(s); if (lane == 0) rstd_out[row] = __builtin_amdgcn_rsqf(s * (1.0f / DM) + RMS_EPS); } }
	v_fmamk_f32 v96, v40, 0x3a800000, v244
	v_rsq_f32_e32 v96, v96
	v_add_u32_e32 v19, 0x400000, v19
	v_add_u32_e32 v23, 0x800000, v23
	v_lshlrev_b32_e32 v106, 16, v32
	v_and_b32_e32 v107, 0xffff0000, v32
	v_lshlrev_b32_e32 v108, 16, v24
	v_and_b32_e32 v109, 0xffff0000, v24
	v_pk_mul_f32 v[106:107], v[96:97], v[106:107] op_sel_hi:[0,1]
	v_pk_fma_f32 v[98:99], v[10:11], v[106:107], v[108:109]
	v_lshlrev_b32_e32 v106, 16, v33
	v_and_b32_e32 v107, 0xffff0000, v33
	v_lshlrev_b32_e32 v108, 16, v25
	v_and_b32_e32 v109, 0xffff0000, v25
	v_pk_mul_f32 v[106:107], v[96:97], v[106:107] op_sel_hi:[0,1]
	v_pk_fma_f32 v[100:101], v[12:13], v[106:107], v[108:109]
	v_lshlrev_b32_e32 v106, 16, v34
	v_and_b32_e32 v107, 0xffff0000, v34
	v_lshlrev_b32_e32 v108, 16, v26
	v_and_b32_e32 v109, 0xffff0000, v26
	v_pk_mul_f32 v[106:107], v[96:97], v[106:107] op_sel_hi:[0,1]
	v_pk_fma_f32 v[102:103], v[14:15], v[106:107], v[108:109]
	v_lshlrev_b32_e32 v106, 16, v35
	v_and_b32_e32 v107, 0xffff0000, v35
	v_lshlrev_b32_e32 v108, 16, v27
	v_and_b32_e32 v109, 0xffff0000, v27
	v_pk_mul_f32 v[106:107], v[96:97], v[106:107] op_sel_hi:[0,1]
	v_pk_fma_f32 v[104:105], v[16:17], v[106:107], v[108:109]
	v_pk_mul_f32 v[110:111], v[98:99], v[98:99]
	v_pk_fma_f32 v[110:111], v[100:101], v[100:101], v[110:111]
	v_pk_fma_f32 v[110:111], v[102:103], v[102:103], v[110:111]
	v_pk_fma_f32 v[110:111], v[104:105], v[104:105], v[110:111]
	v_cvt_pk_bf16_f32 v24, v98, v99
	v_cvt_pk_bf16_f32 v25, v100, v101
	v_cvt_pk_bf16_f32 v26, v102, v103
	v_cvt_pk_bf16_f32 v27, v104, v105
	global_store_dwordx4 v19, v[24:27], s[4:5]
	global_store_dwordx4 v23, v[98:101], s[6:7]
	global_store_dwordx4 v23, v[102:105], s[6:7] offset:16
	v_lshlrev_b32_e32 v106, 16, v36
	v_and_b32_e32 v107, 0xffff0000, v36
	v_lshlrev_b32_e32 v108, 16, v28
	v_and_b32_e32 v109, 0xffff0000, v28
	v_pk_mul_f32 v[106:107], v[96:97], v[106:107] op_sel_hi:[0,1]
	v_pk_fma_f32 v[98:99], v[2:3], v[106:107], v[108:109]
	v_lshlrev_b32_e32 v106, 16, v37
	v_and_b32_e32 v107, 0xffff0000, v37
	v_lshlrev_b32_e32 v108, 16, v29
	v_and_b32_e32 v109, 0xffff0000, v29
	v_pk_mul_f32 v[106:107], v[96:97], v[106:107] op_sel_hi:[0,1]
	v_pk_fma_f32 v[100:101], v[4:5], v[106:107], v[108:109]
	v_lshlrev_b32_e32 v106, 16, v38
	v_and_b32_e32 v107, 0xffff0000, v38
	v_lshlrev_b32_e32 v108, 16, v30
	v_and_b32_e32 v109, 0xffff0000, v30
	v_pk_mul_f32 v[106:107], v[96:97], v[106:107] op_sel_hi:[0,1]
	v_pk_fma_f32 v[102:103], v[6:7], v[106:107], v[108:109]
	v_lshlrev_b32_e32 v106, 16, v39
	v_and_b32_e32 v107, 0xffff0000, v39
	v_lshlrev_b32_e32 v108, 16, v31
	v_and_b32_e32 v109, 0xffff0000, v31
	v_pk_mul_f32 v[106:107], v[96:97], v[106:107] op_sel_hi:[0,1]
	v_pk_fma_f32 v[104:105], v[8:9], v[106:107], v[108:109]
	v_pk_fma_f32 v[110:111], v[98:99], v[98:99], v[110:111]
	v_pk_fma_f32 v[110:111], v[100:101], v[100:101], v[110:111]
	v_pk_fma_f32 v[110:111], v[102:103], v[102:103], v[110:111]
	v_pk_fma_f32 v[110:111], v[104:105], v[104:105], v[110:111]
	v_cvt_pk_bf16_f32 v28, v98, v99
	v_cvt_pk_bf16_f32 v29, v100, v101
	v_cvt_pk_bf16_f32 v30, v102, v103
	v_cvt_pk_bf16_f32 v31, v104, v105
	global_store_dwordx4 v19, v[28:31], s[4:5] offset:1024
	global_store_dwordx4 v23, v[98:101], s[6:7] offset:2048
	global_store_dwordx4 v23, v[102:105], s[6:7] offset:2064
	v_add_f32_e32 v112, v110, v111
	v_add_u32_e32 v22, 0x2000, v22
	s_nop 1
	v_add_f32_dpp v112, v112, v112 quad_perm:[1,0,3,2] row_mask:0xf bank_mask:0xf
	s_nop 1
	v_add_f32_dpp v112, v112, v112 quad_perm:[2,3,0,1] row_mask:0xf bank_mask:0xf
	s_nop 1
	v_add_f32_dpp v112, v112, v112 row_half_mirror row_mask:0xf bank_mask:0xf
	s_nop 1
	v_add_f32_dpp v112, v112, v112 row_mirror row_mask:0xf bank_mask:0xf
	s_nop 1
	v_add_f32_dpp v112, v112, v112 row_bcast:15 row_mask:0xa bank_mask:0xf
	s_nop 1
	v_add_f32_dpp v112, v112, v112 row_bcast:31 row_mask:0xc bank_mask:0xf
	v_fmamk_f32 v113, v112, 0x3a800000, v244
	v_rsq_f32_e32 v113, v113
	s_mov_b64 exec, s[8:9]
	global_store_dword v22, v113, s[4:5]
	s_mov_b64 exec, -1
	s_waitcnt vmcnt(31)
	v_fmamk_f32 v96, v58, 0x3a800000, v244
	v_rsq_f32_e32 v96, v96
	v_add_u32_e32 v19, 0x400000, v19
	v_add_u32_e32 v23, 0x800000, v23
	v_lshlrev_b32_e32 v106, 16, v50
	v_and_b32_e32 v107, 0xffff0000, v50
	v_lshlrev_b32_e32 v108, 16, v42
	v_and_b32_e32 v109, 0xffff0000, v42
	v_pk_mul_f32 v[106:107], v[96:97], v[106:107] op_sel_hi:[0,1]
	v_pk_fma_f32 v[98:99], v[10:11], v[106:107], v[108:109]
	v_lshlrev_b32_e32 v106, 16, v51
	v_and_b32_e32 v107, 0xffff0000, v51
	v_lshlrev_b32_e32 v108, 16, v43
	v_and_b32_e32 v109, 0xffff0000, v43
	v_pk_mul_f32 v[106:107], v[96:97], v[106:107] op_sel_hi:[0,1]
	v_pk_fma_f32 v[100:101], v[12:13], v[106:107], v[108:109]
	v_lshlrev_b32_e32 v106, 16, v52
	v_and_b32_e32 v107, 0xffff0000, v52
	v_lshlrev_b32_e32 v108, 16, v44
	v_and_b32_e32 v109, 0xffff0000, v44
	v_pk_mul_f32 v[106:107], v[96:97], v[106:107] op_sel_hi:[0,1]
	v_pk_fma_f32 v[102:103], v[14:15], v[106:107], v[108:109]
	v_lshlrev_b32_e32 v106, 16, v53
	v_and_b32_e32 v107, 0xffff0000, v53
	v_lshlrev_b32_e32 v108, 16, v45
	v_and_b32_e32 v109, 0xffff0000, v45
	v_pk_mul_f32 v[106:107], v[96:97], v[106:107] op_sel_hi:[0,1]
	v_pk_fma_f32 v[104:105], v[16:17], v[106:107], v[108:109]
	v_pk_mul_f32 v[110:111], v[98:99], v[98:99]
	v_pk_fma_f32 v[110:111], v[100:101], v[100:101], v[110:111]
	v_pk_fma_f32 v[110:111], v[102:103], v[102:103], v[110:111]
	v_pk_fma_f32 v[110:111], v[104:105], v[104:105], v[110:111]
	v_cvt_pk_bf16_f32 v42, v98, v99
	v_cvt_pk_bf16_f32 v43, v100, v101
	v_cvt_pk_bf16_f32 v44, v102, v103
	v_cvt_pk_bf16_f32 v45, v104, v105
	global_store_dwordx4 v19, v[42:45], s[4:5]
	global_store_dwordx4 v23, v[98:101], s[6:7]
; __device__ __forceinline__ float bflo(unsigned w) { return __uint_as_float(w << 16); }
; __device__ __forceinline__ float bfhi(unsigned w) { return __uint_as_float(w & 0xffff0000u); }
; __device__ __forceinline__ void resid_rows(bf16_t* R, const bf16_t* Y, const float* ssqY, const float* g, float* rstd_out, float* outf, bool wf32, int row_lo, int row_hi, int yoff, int gw, int NGW, int lane) {
;     ...
;     for (int row0 = row_lo + gw; row0 < row_hi; row0 += RP * NGW) {
;         u32x4 rr[RP][2], oo[RP][2]; float ssv[RP];
; #pragma unroll
;         for (int k = 0; k < RP; ++k) { const int row = row0 + k * NGW; const bool ok = row < row_hi; const int rw = ok ? row : row0;
;             ssv[k] = ssqY[rw];
; #pragma unroll
;             for (int j = 0; j < 2; ++j) { const int c = 8 * lane + 512 * j; rr[k][j] = *(const u32x4*)(R + (size_t)rw * DM + c); oo[k][j] = *(const u32x4*)(Y + (size_t)(rw - yoff) * DM + c); } }
; #pragma unroll
;         for (int k = 0; k < RP; ++k) { const int row = row0 + k * NGW; if (row < row_hi) {
;             const float rs = __builtin_amdgcn_rsqf(ssv[k] * (1.0f / DM) + RMS_EPS); float s = 0.f;
; #pragma unroll
;             for (int j = 0; j < 2; ++j) { const int c = 8 * lane + 512 * j; const u32x4 r = rr[k][j], o = oo[k][j]; const f32x4 ga = gv[j][0], gb = gv[j][1];
;                 f32x4 ya, yb; ya[0] = bflo(r.x) + bflo(o.x) * rs * ga[0]; ya[1] = bfhi(r.x) + bfhi(o.x) * rs * ga[1]; ya[2] = bflo(r.y) + bflo(o.y) * rs * ga[2]; ya[3] = bfhi(r.y) + bfhi(o.y) * rs * ga[3];
;                 yb[0] = bflo(r.z) + bflo(o.z) * rs * gb[0]; yb[1] = bfhi(r.z) + bfhi(o.z) * rs * gb[1]; yb[2] = bflo(r.w) + bflo(o.w) * rs * gb[2]; yb[3] = bfhi(r.w) + bfhi(o.w) * rs * gb[3];
;                 if (wf32) { *(f32x4*)(outf + (size_t)row * DM + c) = ya; *(f32x4*)(outf + (size_t)row * DM + c + 4) = yb; }
;                 s += (ya[0] * ya[0] + ya[1] * ya[1]) + (ya[2] * ya[2] + ya[3] * ya[3]) + (yb[0] * yb[0] + yb[1] * yb[1]) + (yb[2] * yb[2] + yb[3] * yb[3]);
;                 u32x4 w; w.x = pk2(ya[0], ya[1]); w.y = pk2(ya[2], ya[3]); w.z = pk2(yb[0], yb[1]); w.w = pk2(yb[2], yb[3]); *(u32x4*)(R + (size_t)row * DM + c) = w; }
;             s = wave_sum(s); if (lane == 0) rstd_out[row] = __builtin_amdgcn_rsqf(s * (1.0f / DM) + RMS_EPS); } }
	global_store_dwordx4 v23, v[102:105], s[6:7] offset:16
	v_lshlrev_b32_e32 v106, 16, v54
	v_and_b32_e32 v107, 0xffff0000, v54
	v_lshlrev_b32_e32 v108, 16, v46
	v_and_b32_e32 v109, 0xffff0000, v46
	v_pk_mul_f32 v[106:107], v[96:97], v[106:107] op_sel_hi:[0,1]
	v_pk_fma_f32 v[98:99], v[2:3], v[106:107], v[108:109]
	v_lshlrev_b32_e32 v106, 16, v55
	v_and_b32_e32 v107, 0xffff0000, v55
	v_lshlrev_b32_e32 v108, 16, v47
	v_and_b32_e32 v109, 0xffff0000, v47
	v_pk_mul_f32 v[106:107], v[96:97], v[106:107] op_sel_hi:[0,1]
	v_pk_fma_f32 v[100:101], v[4:5], v[106:107], v[108:109]
	v_lshlrev_b32_e32 v106, 16, v56
	v_and_b32_e32 v107, 0xffff0000, v56
	v_lshlrev_b32_e32 v108, 16, v48
	v_and_b32_e32 v109, 0xffff0000, v48
	v_pk_mul_f32 v[106:107], v[96:97], v[106:107] op_sel_hi:[0,1]
	v_pk_fma_f32 v[102:103], v[6:7], v[106:107], v[108:109]
	v_lshlrev_b32_e32 v106, 16, v57
	v_and_b32_e32 v107, 0xffff0000, v57
	v_lshlrev_b32_e32 v108, 16, v49
	v_and_b32_e32 v109, 0xffff0000, v49
	v_pk_mul_f32 v[106:107], v[96:97], v[106:107] op_sel_hi:[0,1]
	v_pk_fma_f32 v[104:105], v[8:9], v[106:107], v[108:109]
	v_pk_fma_f32 v[110:111], v[98:99], v[98:99], v[110:111]
	v_pk_fma_f32 v[110:111], v[100:101], v[100:101], v[110:111]
	v_pk_fma_f32 v[110:111], v[102:103], v[102:103], v[110:111]
	v_pk_fma_f32 v[110:111], v[104:105], v[104:105], v[110:111]
	v_cvt_pk_bf16_f32 v46, v98, v99
	v_cvt_pk_bf16_f32 v47, v100, v101
	v_cvt_pk_bf16_f32 v48, v102, v103
	v_cvt_pk_bf16_f32 v49, v104, v105
	global_store_dwordx4 v19, v[46:49], s[4:5] offset:1024
	global_store_dwordx4 v23, v[98:101], s[6:7] offset:2048
	global_store_dwordx4 v23, v[102:105], s[6:7] offset:2064
	v_add_f32_e32 v112, v110, v111
	v_add_u32_e32 v22, 0x2000, v22
	s_nop 1
	v_add_f32_dpp v112, v112, v112 quad_perm:[1,0,3,2] row_mask:0xf bank_mask:0xf
	s_nop 1
	v_add_f32_dpp v112, v112, v112 quad_perm:[2,3,0,1] row_mask:0xf bank_mask:0xf
	s_nop 1
	v_add_f32_dpp v112, v112, v112 row_half_mirror row_mask:0xf bank_mask:0xf
	s_nop 1
	v_add_f32_dpp v112, v112, v112 row_mirror row_mask:0xf bank_mask:0xf
	s_nop 1
	v_add_f32_dpp v112, v112, v112 row_bcast:15 row_mask:0xa bank_mask:0xf
	s_nop 1
	v_add_f32_dpp v112, v112, v112 row_bcast:31 row_mask:0xc bank_mask:0xf
	v_fmamk_f32 v113, v112, 0x3a800000, v244
	v_rsq_f32_e32 v113, v113
	s_mov_b64 exec, s[8:9]
	global_store_dword v22, v113, s[4:5]
	s_mov_b64 exec, -1
	s_waitcnt vmcnt(26)
	v_fmamk_f32 v96, v76, 0x3a800000, v244
	v_rsq_f32_e32 v96, v96
	v_add_u32_e32 v19, 0x400000, v19
	v_add_u32_e32 v23, 0x800000, v23
	v_lshlrev_b32_e32 v106, 16, v68
	v_and_b32_e32 v107, 0xffff0000, v68
	v_lshlrev_b32_e32 v108, 16, v60
	v_and_b32_e32 v109, 0xffff0000, v60
	v_pk_mul_f32 v[106:107], v[96:97], v[106:107] op_sel_hi:[0,1]
	v_pk_fma_f32 v[98:99], v[10:11], v[106:107], v[108:109]
	v_lshlrev_b32_e32 v106, 16, v69
	v_and_b32_e32 v107, 0xffff0000, v69
	v_lshlrev_b32_e32 v108, 16, v61
	v_and_b32_e32 v109, 0xffff0000, v61
	v_pk_mul_f32 v[106:107], v[96:97], v[106:107] op_sel_hi:[0,1]
	v_pk_fma_f32 v[100:101], v[12:13], v[106:107], v[108:109]
	v_lshlrev_b32_e32 v106, 16, v70
	v_and_b32_e32 v107, 0xffff0000, v70
	v_lshlrev_b32_e32 v108, 16, v62
	v_and_b32_e32 v109, 0xffff0000, v62
	v_pk_mul_f32 v[106:107], v[96:97], v[106:107] op_sel_hi:[0,1]
	v_pk_fma_f32 v[102:103], v[14:15], v[106:107], v[108:109]
	v_lshlrev_b32_e32 v106, 16, v71
	v_and_b32_e32 v107, 0xffff0000, v71
	v_lshlrev_b32_e32 v108, 16, v63
	v_and_b32_e32 v109, 0xffff0000, v63
	v_pk_mul_f32 v[106:107], v[96:97], v[106:107] op_sel_hi:[0,1]
	v_pk_fma_f32 v[104:105], v[16:17], v[106:107], v[108:109]
	v_pk_mul_f32 v[110:111], v[98:99], v[98:99]
	v_pk_fma_f32 v[110:111], v[100:101], v[100:101], v[110:111]
	v_pk_fma_f32 v[110:111], v[102:103], v[102:103], v[110:111]
	v_pk_fma_f32 v[110:111], v[104:105], v[104:105], v[110:111]
	v_cvt_pk_bf16_f32 v60, v98, v99
	v_cvt_pk_bf16_f32 v61, v100, v101
	v_cvt_pk_bf16_f32 v62, v102, v103
	v_cvt_pk_bf16_f32 v63, v104, v105
	global_store_dwordx4 v19, v[60:63], s[4:5]
	global_store_dwordx4 v23, v[98:101], s[6:7]
	global_store_dwordx4 v23, v[102:105], s[6:7] offset:16
	v_lshlrev_b32_e32 v106, 16, v72
	v_and_b32_e32 v107, 0xffff0000, v72
	v_lshlrev_b32_e32 v108, 16, v64
	v_and_b32_e32 v109, 0xffff0000, v64
	v_pk_mul_f32 v[106:107], v[96:97], v[106:107] op_sel_hi:[0,1]
	v_pk_fma_f32 v[98:99], v[2:3], v[106:107], v[108:109]
	v_lshlrev_b32_e32 v106, 16, v73
	v_and_b32_e32 v107, 0xffff0000, v73
	v_lshlrev_b32_e32 v108, 16, v65
	v_and_b32_e32 v109, 0xffff0000, v65
	v_pk_mul_f32 v[106:107], v[96:97], v[106:107] op_sel_hi:[0,1]
	v_pk_fma_f32 v[100:101], v[4:5], v[106:107], v[108:109]
	v_lshlrev_b32_e32 v106, 16, v74
	v_and_b32_e32 v107, 0xffff0000, v74
	v_lshlrev_b32_e32 v108, 16, v66
	v_and_b32_e32 v109, 0xffff0000, v66
	v_pk_mul_f32 v[106:107], v[96:97], v[106:107] op_sel_hi:[0,1]
	v_pk_fma_f32 v[102:103], v[6:7], v[106:107], v[108:109]
	v_lshlrev_b32_e32 v106, 16, v75
	v_and_b32_e32 v107, 0xffff0000, v75
	v_lshlrev_b32_e32 v108, 16, v67
	v_and_b32_e32 v109, 0xffff0000, v67
	v_pk_mul_f32 v[106:107], v[96:97], v[106:107] op_sel_hi:[0,1]
	v_pk_fma_f32 v[104:105], v[8:9], v[106:107], v[108:109]
	v_pk_fma_f32 v[110:111], v[98:99], v[98:99], v[110:111]
	v_pk_fma_f32 v[110:111], v[100:101], v[100:101], v[110:111]
	v_pk_fma_f32 v[110:111], v[102:103], v[102:103], v[110:111]
	v_pk_fma_f32 v[110:111], v[104:105], v[104:105], v[110:111]
	v_cvt_pk_bf16_f32 v64, v98, v99
	v_cvt_pk_bf16_f32 v65, v100, v101
	v_cvt_pk_bf16_f32 v66, v102, v103
	v_cvt_pk_bf16_f32 v67, v104, v105
	global_store_dwordx4 v19, v[64:67], s[4:5] offset:1024
	global_store_dwordx4 v23, v[98:101], s[6:7] offset:2048
	global_store_dwordx4 v23, v[102:105], s[6:7] offset:2064
	v_add_f32_e32 v112, v110, v111
	v_add_u32_e32 v22, 0x2000, v22
	s_nop 1
	v_add_f32_dpp v112, v112, v112 quad_perm:[1,0,3,2] row_mask:0xf bank_mask:0xf
	s_nop 1
	v_add_f32_dpp v112, v112, v112 quad_perm:[2,3,0,1] row_mask:0xf bank_mask:0xf
	s_nop 1
	v_add_f32_dpp v112, v112, v112 row_half_mirror row_mask:0xf bank_mask:0xf
	s_nop 1
	v_add_f32_dpp v112, v112, v112 row_mirror row_mask:0xf bank_mask:0xf
	s_nop 1
	v_add_f32_dpp v112, v112, v112 row_bcast:15 row_mask:0xa bank_mask:0xf
	s_nop 1
	v_add_f32_dpp v112, v112, v112 row_bcast:31 row_mask:0xc bank_mask:0xf
	v_fmamk_f32 v113, v112, 0x3a800000, v244
	v_rsq_f32_e32 v113, v113
	s_mov_b64 exec, s[8:9]
	global_store_dword v22, v113, s[4:5]
	s_mov_b64 exec, -1
	s_waitcnt vmcnt(21)
; __device__ __forceinline__ float bflo(unsigned w) { return __uint_as_float(w << 16); }
; __device__ __forceinline__ float bfhi(unsigned w) { return __uint_as_float(w & 0xffff0000u); }
; __device__ __forceinline__ void resid_rows(bf16_t* R, const bf16_t* Y, const float* ssqY, const float* g, float* rstd_out, float* outf, bool wf32, int row_lo, int row_hi, int yoff, int gw, int NGW, int lane) {
;     ...
;     for (int row0 = row_lo + gw; row0 < row_hi; row0 += RP * NGW) {
;         u32x4 rr[RP][2], oo[RP][2]; float ssv[RP];
; #pragma unroll
;         for (int k = 0; k < RP; ++k) { const int row = row0 + k * NGW; const bool ok = row < row_hi; const int rw = ok ? row : row0;
;             ssv[k] = ssqY[rw];
; #pragma unroll
;             for (int j = 0; j < 2; ++j) { const int c = 8 * lane + 512 * j; rr[k][j] = *(const u32x4*)(R + (size_t)rw * DM + c); oo[k][j] = *(const u32x4*)(Y + (size_t)(rw - yoff) * DM + c); } }
; #pragma unroll
;         for (int k = 0; k < RP; ++k) { const int row = row0 + k * NGW; if (row < row_hi) {
;             const float rs = __builtin_amdgcn_rsqf(ssv[k] * (1.0f / DM) + RMS_EPS); float s = 0.f;
; #pragma unroll
;             for (int j = 0; j < 2; ++j) { const int c = 8 * lane + 512 * j; const u32x4 r = rr[k][j], o = oo[k][j]; const f32x4 ga = gv[j][0], gb = gv[j][1];
;                 f32x4 ya, yb; ya[0] = bflo(r.x) + bflo(o.x) * rs * ga[0]; ya[1] = bfhi(r.x) + bfhi(o.x) * rs * ga[1]; ya[2] = bflo(r.y) + bflo(o.y) * rs * ga[2]; ya[3] = bfhi(r.y) + bfhi(o.y) * rs * ga[3];
;                 yb[0] = bflo(r.z) + bflo(o.z) * rs * gb[0]; yb[1] = bfhi(r.z) + bfhi(o.z) * rs * gb[1]; yb[2] = bflo(r.w) + bflo(o.w) * rs * gb[2]; yb[3] = bfhi(r.w) + bfhi(o.w) * rs * gb[3];
;                 if (wf32) { *(f32x4*)(outf + (size_t)row * DM + c) = ya; *(f32x4*)(outf + (size_t)row * DM + c + 4) = yb; }
;                 s += (ya[0] * ya[0] + ya[1] * ya[1]) + (ya[2] * ya[2] + ya[3] * ya[3]) + (yb[0] * yb[0] + yb[1] * yb[1]) + (yb[2] * yb[2] + yb[3] * yb[3]);
;                 u32x4 w; w.x = pk2(ya[0], ya[1]); w.y = pk2(ya[2], ya[3]); w.z = pk2(yb[0], yb[1]); w.w = pk2(yb[2], yb[3]); *(u32x4*)(R + (size_t)row * DM + c) = w; }
;             s = wave_sum(s); if (lane == 0) rstd_out[row] = __builtin_amdgcn_rsqf(s * (1.0f / DM) + RMS_EPS); } }
	v_fmamk_f32 v96, v94, 0x3a800000, v244
	v_rsq_f32_e32 v96, v96
	v_add_u32_e32 v19, 0x400000, v19
	v_add_u32_e32 v23, 0x800000, v23
	v_lshlrev_b32_e32 v106, 16, v86
	v_and_b32_e32 v107, 0xffff0000, v86
	v_lshlrev_b32_e32 v108, 16, v78
	v_and_b32_e32 v109, 0xffff0000, v78
	v_pk_mul_f32 v[106:107], v[96:97], v[106:107] op_sel_hi:[0,1]
	v_pk_fma_f32 v[98:99], v[10:11], v[106:107], v[108:109]
	v_lshlrev_b32_e32 v106, 16, v87
	v_and_b32_e32 v107, 0xffff0000, v87
	v_lshlrev_b32_e32 v108, 16, v79
	v_and_b32_e32 v109, 0xffff0000, v79
	v_pk_mul_f32 v[106:107], v[96:97], v[106:107] op_sel_hi:[0,1]
	v_pk_fma_f32 v[100:101], v[12:13], v[106:107], v[108:109]
	v_lshlrev_b32_e32 v106, 16, v88
	v_and_b32_e32 v107, 0xffff0000, v88
	v_lshlrev_b32_e32 v108, 16, v80
	v_and_b32_e32 v109, 0xffff0000, v80
	v_pk_mul_f32 v[106:107], v[96:97], v[106:107] op_sel_hi:[0,1]
	v_pk_fma_f32 v[102:103], v[14:15], v[106:107], v[108:109]
	v_lshlrev_b32_e32 v106, 16, v89
	v_and_b32_e32 v107, 0xffff0000, v89
	v_lshlrev_b32_e32 v108, 16, v81
	v_and_b32_e32 v109, 0xffff0000, v81
	v_pk_mul_f32 v[106:107], v[96:97], v[106:107] op_sel_hi:[0,1]
	v_pk_fma_f32 v[104:105], v[16:17], v[106:107], v[108:109]
	v_pk_mul_f32 v[110:111], v[98:99], v[98:99]
	v_pk_fma_f32 v[110:111], v[100:101], v[100:101], v[110:111]
	v_pk_fma_f32 v[110:111], v[102:103], v[102:103], v[110:111]
	v_pk_fma_f32 v[110:111], v[104:105], v[104:105], v[110:111]
	v_cvt_pk_bf16_f32 v78, v98, v99
	v_cvt_pk_bf16_f32 v79, v100, v101
	v_cvt_pk_bf16_f32 v80, v102, v103
	v_cvt_pk_bf16_f32 v81, v104, v105
	global_store_dwordx4 v19, v[78:81], s[4:5]
	global_store_dwordx4 v23, v[98:101], s[6:7]
	global_store_dwordx4 v23, v[102:105], s[6:7] offset:16
	v_lshlrev_b32_e32 v106, 16, v90
	v_and_b32_e32 v107, 0xffff0000, v90
	v_lshlrev_b32_e32 v108, 16, v82
	v_and_b32_e32 v109, 0xffff0000, v82
	v_pk_mul_f32 v[106:107], v[96:97], v[106:107] op_sel_hi:[0,1]
	v_pk_fma_f32 v[98:99], v[2:3], v[106:107], v[108:109]
	v_lshlrev_b32_e32 v106, 16, v91
	v_and_b32_e32 v107, 0xffff0000, v91
	v_lshlrev_b32_e32 v108, 16, v83
	v_and_b32_e32 v109, 0xffff0000, v83
	v_pk_mul_f32 v[106:107], v[96:97], v[106:107] op_sel_hi:[0,1]
	v_pk_fma_f32 v[100:101], v[4:5], v[106:107], v[108:109]
	v_lshlrev_b32_e32 v106, 16, v92
	v_and_b32_e32 v107, 0xffff0000, v92
	v_lshlrev_b32_e32 v108, 16, v84
	v_and_b32_e32 v109, 0xffff0000, v84
	v_pk_mul_f32 v[106:107], v[96:97], v[106:107] op_sel_hi:[0,1]
	v_pk_fma_f32 v[102:103], v[6:7], v[106:107], v[108:109]
	v_lshlrev_b32_e32 v106, 16, v93
	v_and_b32_e32 v107, 0xffff0000, v93
	v_lshlrev_b32_e32 v108, 16, v85
	v_and_b32_e32 v109, 0xffff0000, v85
	v_pk_mul_f32 v[106:107], v[96:97], v[106:107] op_sel_hi:[0,1]
	v_pk_fma_f32 v[104:105], v[8:9], v[106:107], v[108:109]
	v_pk_fma_f32 v[110:111], v[98:99], v[98:99], v[110:111]
	v_pk_fma_f32 v[110:111], v[100:101], v[100:101], v[110:111]
	v_pk_fma_f32 v[110:111], v[102:103], v[102:103], v[110:111]
	v_pk_fma_f32 v[110:111], v[104:105], v[104:105], v[110:111]
	v_cvt_pk_bf16_f32 v82, v98, v99
	v_cvt_pk_bf16_f32 v83, v100, v101
	v_cvt_pk_bf16_f32 v84, v102, v103
	v_cvt_pk_bf16_f32 v85, v104, v105
	global_store_dwordx4 v19, v[82:85], s[4:5] offset:1024
	global_store_dwordx4 v23, v[98:101], s[6:7] offset:2048
	global_store_dwordx4 v23, v[102:105], s[6:7] offset:2064
	v_add_f32_e32 v112, v110, v111
	v_add_u32_e32 v22, 0x2000, v22
	s_nop 1
	v_add_f32_dpp v112, v112, v112 quad_perm:[1,0,3,2] row_mask:0xf bank_mask:0xf
	s_nop 1
	v_add_f32_dpp v112, v112, v112 quad_perm:[2,3,0,1] row_mask:0xf bank_mask:0xf
	s_nop 1
	v_add_f32_dpp v112, v112, v112 row_half_mirror row_mask:0xf bank_mask:0xf
	s_nop 1
	v_add_f32_dpp v112, v112, v112 row_mirror row_mask:0xf bank_mask:0xf
	s_nop 1
	v_add_f32_dpp v112, v112, v112 row_bcast:15 row_mask:0xa bank_mask:0xf
	s_nop 1
	v_add_f32_dpp v112, v112, v112 row_bcast:31 row_mask:0xc bank_mask:0xf
	v_fmamk_f32 v113, v112, 0x3a800000, v244
	v_rsq_f32_e32 v113, v113
	s_mov_b64 exec, s[8:9]
	global_store_dword v22, v113, s[4:5]
	s_mov_b64 exec, -1

; __device__ __forceinline__ float bflo(unsigned w) { return __uint_as_float(w << 16); }
; __device__ __forceinline__ void resid_rows(bf16_t* R, const bf16_t* Y, const float* ssqY, const float* g, float* rstd_out, float* outf, bool wf32, int row_lo, int row_hi, int yoff, int gw, int NGW, int lane) {
;     ...
;     for (int j = 0; j < 2; ++j) { gv[j][0] = *(const f32x4*)(g + 8 * lane + 512 * j); gv[j][1] = *(const f32x4*)(g + 8 * lane + 512 * j + 4); }
;     for (int row0 = row_lo + gw; row0 < row_hi; row0 += RP * NGW) {
;         u32x4 rr[RP][2], oo[RP][2]; float ssv[RP];
; #pragma unroll
;         for (int k = 0; k < RP; ++k) { const int row = row0 + k * NGW; const bool ok = row < row_hi; const int rw = ok ? row : row0;
;             ssv[k] = ssqY[rw];
; #pragma unroll
;             for (int j = 0; j < 2; ++j) { const int c = 8 * lane + 512 * j; rr[k][j] = *(const u32x4*)(R + (size_t)rw * DM + c); oo[k][j] = *(const u32x4*)(Y + (size_t)(rw - yoff) * DM + c); } }
; #pragma unroll
;         for (int k = 0; k < RP; ++k) { const int row = row0 + k * NGW; if (row < row_hi) {
;             const float rs = __builtin_amdgcn_rsqf(ssv[k] * (1.0f / DM) + RMS_EPS); float s = 0.f;
; #pragma unroll
;             for (int j = 0; j < 2; ++j) { const int c = 8 * lane + 512 * j; const u32x4 r = rr[k][j], o = oo[k][j]; const f32x4 ga = gv[j][0], gb = gv[j][1];
;                 f32x4 ya, yb; ya[0] = bflo(r.x) + bflo(o.x) * rs * ga[0]; ya[1] = bfhi(r.x) + bfhi(o.x) * rs * ga[1]; ya[2] = bflo(r.y) + bflo(o.y) * rs * ga[2]; ya[3] = bfhi(r.y) + bfhi(o.y) * rs * ga[3];
;                 yb[0] = bflo(r.z) + bflo(o.z) * rs * gb[0]; yb[1] = bfhi(r.z) + bfhi(o.z) * rs * gb[1]; yb[2] = bflo(r.w) + bflo(o.w) * rs * gb[2]; yb[3] = bfhi(r.w) + bfhi(o.w) * rs * gb[3];
;                 if (wf32) { *(f32x4*)(outf + (size_t)row * DM + c) = ya; *(f32x4*)(outf + (size_t)row * DM + c + 4) = yb; }
;                 s += (ya[0] * ya[0] + ya[1] * ya[1]) + (ya[2] * ya[2] + ya[3] * ya[3]) + (yb[0] * yb[0] + yb[1] * yb[1]) + (yb[2] * yb[2] + yb[3] * yb[3]);
;                 u32x4 w; w.x = pk2(ya[0], ya[1]); w.y = pk2(ya[2], ya[3]); w.z = pk2(yb[0], yb[1]); w.w = pk2(yb[2], yb[3]); *(u32x4*)(R + (size_t)row * DM + c) = w; }
;             s = wave_sum(s); if (lane == 0) rstd_out[row] = __builtin_amdgcn_rsqf(s * (1.0f / DM) + RMS_EPS); } }
.LBB0_877:
	v_mov_b32_e32 v2, v0
	v_mov_b32_e32 v3, v0
	v_readlane_b32 s4, v255, 4
	v_ashrrev_i32_e32 v18, 6, v3
	s_mov_b64 s[6:7], s[0:1]
	v_add_u32_e32 v86, s4, v18
	s_mov_b64 s[4:5], s[0:1]
	s_mov_b64 s[10:11], s[0:1]
	s_mov_b64 s[12:13], s[0:1]
	s_mov_b64 s[8:9], s[0:1]
	v_cmp_gt_i32_e32 vcc, s47, v86
	s_and_saveexec_b64 s[16:17], vcc
	s_cbranch_execz .LBB0_907
	v_readlane_b32 s12, v255, 49
	s_cmp_eq_u32 s12, 1
	s_cbranch_scc0 .LBB0_907
	v_lshrrev_b32_e32 v114, 6, v0
	v_readlane_b32 s12, v255, 49
	v_readlane_b32 s13, v255, 4
	v_readfirstlane_b32 s18, v114
	s_load_dwordx2 s[4:5], s[0:1], 0x98
	s_load_dwordx2 s[10:11], s[0:1], 0x68
	s_load_dwordx2 s[6:7], s[0:1], 0x90
	s_add_i32 s13, s13, s18
	v_and_b32_e32 v115, 63, v0
	v_lshlrev_b32_e32 v114, 4, v115
	v_lshlrev_b32_e32 v115, 5, v115
	s_lshl_b32 s18, s12, 12
	s_lshl_b32 s19, s12, 18
	s_bfm_b64 s[8:9], 1, 63
	s_waitcnt lgkmcnt(0)
	s_add_u32 s10, s10, s18
	s_addc_u32 s11, s11, 0
	global_load_dwordx4 v[2:5], v115, s[10:11] offset:2048
	global_load_dwordx4 v[6:9], v115, s[10:11] offset:2064
	global_load_dwordx4 v[10:13], v115, s[10:11]
	global_load_dwordx4 v[14:17], v115, s[10:11] offset:16
	s_lshl_b32 s18, s13, 11
	v_add_u32_e32 v18, s18, v114
	v_mov_b32_e32 v19, v18
	v_mov_b32_e32 v20, v18
	s_lshl_b32 s18, s13, 2
	v_mov_b32_e32 v22, s18
	s_add_i32 s18, s18, s19
	v_mov_b32_e32 v21, s18
	s_lshl_b32 s18, s13, 12
	v_add_u32_e32 v23, s18, v115
	v_add_u32_e32 v18, 0x3001000, v18
	v_add_u32_e32 v20, 0xd000000, v20
	v_add_u32_e32 v21, 0x2d60000, v21
	global_load_dwordx4 v[24:27], v18, s[4:5]
	global_load_dwordx4 v[32:35], v20, s[4:5]
	global_load_dwordx4 v[28:31], v18, s[4:5] offset:1024
	global_load_dwordx4 v[36:39], v20, s[4:5] offset:1024
	global_load_dword v40, v21, s[4:5]
	v_add_u32_e32 v18, 0x400000, v18
	v_add_u32_e32 v20, 0x400000, v20
	v_add_u32_e32 v21, 0x2000, v21
	global_load_dwordx4 v[42:45], v18, s[4:5]
	global_load_dwordx4 v[50:53], v20, s[4:5]
	global_load_dwordx4 v[46:49], v18, s[4:5] offset:1024
	global_load_dwordx4 v[54:57], v20, s[4:5] offset:1024
	global_load_dword v58, v21, s[4:5]
	v_add_u32_e32 v18, 0x400000, v18
	v_add_u32_e32 v20, 0x400000, v20
	v_add_u32_e32 v21, 0x2000, v21
	global_load_dwordx4 v[60:63], v18, s[4:5]
	global_load_dwordx4 v[68:71], v20, s[4:5]
	global_load_dwordx4 v[64:67], v18, s[4:5] offset:1024
	global_load_dwordx4 v[72:75], v20, s[4:5] offset:1024
	global_load_dword v76, v21, s[4:5]
	v_add_u32_e32 v18, 0x400000, v18
	v_add_u32_e32 v20, 0x400000, v20
	v_add_u32_e32 v21, 0x2000, v21
	global_load_dwordx4 v[78:81], v18, s[4:5]
	global_load_dwordx4 v[86:89], v20, s[4:5]
	global_load_dwordx4 v[82:85], v18, s[4:5] offset:1024
	global_load_dwordx4 v[90:93], v20, s[4:5] offset:1024
	global_load_dword v94, v21, s[4:5]
	s_waitcnt vmcnt(15)
	v_fmamk_f32 v96, v40, 0x3a800000, v244
	v_rsq_f32_e32 v96, v96
	v_add_u32_e32 v19, 0x3001000, v19
	v_lshlrev_b32_e32 v106, 16, v32
	v_and_b32_e32 v107, 0xffff0000, v32
	v_lshlrev_b32_e32 v108, 16, v24
	v_and_b32_e32 v109, 0xffff0000, v24
	v_pk_mul_f32 v[106:107], v[96:97], v[106:107] op_sel_hi:[0,1]
	v_pk_fma_f32 v[98:99], v[10:11], v[106:107], v[108:109]
	v_lshlrev_b32_e32 v106, 16, v33
	v_and_b32_e32 v107, 0xffff0000, v33
	v_lshlrev_b32_e32 v108, 16, v25
	v_and_b32_e32 v109, 0xffff0000, v25
	v_pk_mul_f32 v[106:107], v[96:97], v[106:107] op_sel_hi:[0,1]
	v_pk_fma_f32 v[100:101], v[12:13], v[106:107], v[108:109]
	v_lshlrev_b32_e32 v106, 16, v34
	v_and_b32_e32 v107, 0xffff0000, v34
	v_lshlrev_b32_e32 v108, 16, v26
	v_and_b32_e32 v109, 0xffff0000, v26
	v_pk_mul_f32 v[106:107], v[96:97], v[106:107] op_sel_hi:[0,1]
	v_pk_fma_f32 v[102:103], v[14:15], v[106:107], v[108:109]
	v_lshlrev_b32_e32 v106, 16, v35
	v_and_b32_e32 v107, 0xffff0000, v35
	v_lshlrev_b32_e32 v108, 16, v27
	v_and_b32_e32 v109, 0xffff0000, v27
	v_pk_mul_f32 v[106:107], v[96:97], v[106:107] op_sel_hi:[0,1]
	v_pk_fma_f32 v[104:105], v[16:17], v[106:107], v[108:109]
	v_pk_mul_f32 v[110:111], v[98:99], v[98:99]
	v_pk_fma_f32 v[110:111], v[100:101], v[100:101], v[110:111]
	v_pk_fma_f32 v[110:111], v[102:103], v[102:103], v[110:111]
	v_pk_fma_f32 v[110:111], v[104:105], v[104:105], v[110:111]
	v_cvt_pk_bf16_f32 v24, v98, v99
	v_cvt_pk_bf16_f32 v25, v100, v101
	v_cvt_pk_bf16_f32 v26, v102, v103
	v_cvt_pk_bf16_f32 v27, v104, v105
	global_store_dwordx4 v19, v[24:27], s[4:5]
	global_store_dwordx4 v23, v[98:101], s[6:7]
	global_store_dwordx4 v23, v[102:105], s[6:7] offset:16
	v_lshlrev_b32_e32 v106, 16, v36
	v_and_b32_e32 v107, 0xffff0000, v36
	v_lshlrev_b32_e32 v108, 16, v28
	v_and_b32_e32 v109, 0xffff0000, v28
	v_pk_mul_f32 v[106:107], v[96:97], v[106:107] op_sel_hi:[0,1]
	v_pk_fma_f32 v[98:99], v[2:3], v[106:107], v[108:109]
	v_lshlrev_b32_e32 v106, 16, v37
	v_and_b32_e32 v107, 0xffff0000, v37
	v_lshlrev_b32_e32 v108, 16, v29
	v_and_b32_e32 v109, 0xffff0000, v29
	v_pk_mul_f32 v[106:107], v[96:97], v[106:107] op_sel_hi:[0,1]
	v_pk_fma_f32 v[100:101], v[4:5], v[106:107], v[108:109]
	v_lshlrev_b32_e32 v106, 16, v38
	v_and_b32_e32 v107, 0xffff0000, v38
	v_lshlrev_b32_e32 v108, 16, v30
	v_and_b32_e32 v109, 0xffff0000, v30
	v_pk_mul_f32 v[106:107], v[96:97], v[106:107] op_sel_hi:[0,1]
	v_pk_fma_f32 v[102:103], v[6:7], v[106:107], v[108:109]
	v_lshlrev_b32_e32 v106, 16, v39
	v_and_b32_e32 v107, 0xffff0000, v39
	v_lshlrev_b32_e32 v108, 16, v31
	v_and_b32_e32 v109, 0xffff0000, v31
	v_pk_mul_f32 v[106:107], v[96:97], v[106:107] op_sel_hi:[0,1]
	v_pk_fma_f32 v[104:105], v[8:9], v[106:107], v[108:109]
	v_pk_fma_f32 v[110:111], v[98:99], v[98:99], v[110:111]
	v_pk_fma_f32 v[110:111], v[100:101], v[100:101], v[110:111]
	v_pk_fma_f32 v[110:111], v[102:103], v[102:103], v[110:111]
; __device__ __forceinline__ float bflo(unsigned w) { return __uint_as_float(w << 16); }
; __device__ __forceinline__ float bfhi(unsigned w) { return __uint_as_float(w & 0xffff0000u); }
; __device__ __forceinline__ void resid_rows(bf16_t* R, const bf16_t* Y, const float* ssqY, const float* g, float* rstd_out, float* outf, bool wf32, int row_lo, int row_hi, int yoff, int gw, int NGW, int lane) {
;     ...
;     for (int row0 = row_lo + gw; row0 < row_hi; row0 += RP * NGW) {
;         u32x4 rr[RP][2], oo[RP][2]; float ssv[RP];
; #pragma unroll
;         for (int k = 0; k < RP; ++k) { const int row = row0 + k * NGW; const bool ok = row < row_hi; const int rw = ok ? row : row0;
;             ssv[k] = ssqY[rw];
; #pragma unroll
;             for (int j = 0; j < 2; ++j) { const int c = 8 * lane + 512 * j; rr[k][j] = *(const u32x4*)(R + (size_t)rw * DM + c); oo[k][j] = *(const u32x4*)(Y + (size_t)(rw - yoff) * DM + c); } }
; #pragma unroll
;         for (int k = 0; k < RP; ++k) { const int row = row0 + k * NGW; if (row < row_hi) {
;             const float rs = __builtin_amdgcn_rsqf(ssv[k] * (1.0f / DM) + RMS_EPS); float s = 0.f;
; #pragma unroll
;             for (int j = 0; j < 2; ++j) { const int c = 8 * lane + 512 * j; const u32x4 r = rr[k][j], o = oo[k][j]; const f32x4 ga = gv[j][0], gb = gv[j][1];
;                 f32x4 ya, yb; ya[0] = bflo(r.x) + bflo(o.x) * rs * ga[0]; ya[1] = bfhi(r.x) + bfhi(o.x) * rs * ga[1]; ya[2] = bflo(r.y) + bflo(o.y) * rs * ga[2]; ya[3] = bfhi(r.y) + bfhi(o.y) * rs * ga[3];
;                 yb[0] = bflo(r.z) + bflo(o.z) * rs * gb[0]; yb[1] = bfhi(r.z) + bfhi(o.z) * rs * gb[1]; yb[2] = bflo(r.w) + bflo(o.w) * rs * gb[2]; yb[3] = bfhi(r.w) + bfhi(o.w) * rs * gb[3];
;                 if (wf32) { *(f32x4*)(outf + (size_t)row * DM + c) = ya; *(f32x4*)(outf + (size_t)row * DM + c + 4) = yb; }
;                 s += (ya[0] * ya[0] + ya[1] * ya[1]) + (ya[2] * ya[2] + ya[3] * ya[3]) + (yb[0] * yb[0] + yb[1] * yb[1]) + (yb[2] * yb[2] + yb[3] * yb[3]);
;                 u32x4 w; w.x = pk2(ya[0], ya[1]); w.y = pk2(ya[2], ya[3]); w.z = pk2(yb[0], yb[1]); w.w = pk2(yb[2], yb[3]); *(u32x4*)(R + (size_t)row * DM + c) = w; }
;             s = wave_sum(s); if (lane == 0) rstd_out[row] = __builtin_amdgcn_rsqf(s * (1.0f / DM) + RMS_EPS); } }
	v_pk_fma_f32 v[110:111], v[104:105], v[104:105], v[110:111]
	v_cvt_pk_bf16_f32 v28, v98, v99
	v_cvt_pk_bf16_f32 v29, v100, v101
	v_cvt_pk_bf16_f32 v30, v102, v103
	v_cvt_pk_bf16_f32 v31, v104, v105
	global_store_dwordx4 v19, v[28:31], s[4:5] offset:1024
	global_store_dwordx4 v23, v[98:101], s[6:7] offset:2048
	global_store_dwordx4 v23, v[102:105], s[6:7] offset:2064
	v_add_f32_e32 v112, v110, v111
	v_add_u32_e32 v22, 0x2d00000, v22
	s_nop 1
	v_add_f32_dpp v112, v112, v112 quad_perm:[1,0,3,2] row_mask:0xf bank_mask:0xf
	s_nop 1
	v_add_f32_dpp v112, v112, v112 quad_perm:[2,3,0,1] row_mask:0xf bank_mask:0xf
	s_nop 1
	v_add_f32_dpp v112, v112, v112 row_half_mirror row_mask:0xf bank_mask:0xf
	s_nop 1
	v_add_f32_dpp v112, v112, v112 row_mirror row_mask:0xf bank_mask:0xf
	s_nop 1
	v_add_f32_dpp v112, v112, v112 row_bcast:15 row_mask:0xa bank_mask:0xf
	s_nop 1
	v_add_f32_dpp v112, v112, v112 row_bcast:31 row_mask:0xc bank_mask:0xf
	v_fmamk_f32 v113, v112, 0x3a800000, v244
	v_rsq_f32_e32 v113, v113
	s_mov_b64 exec, s[8:9]
	global_store_dword v22, v113, s[4:5]
	s_mov_b64 exec, -1
	v_add_u32_e32 v18, 0x400000, v18
	v_add_u32_e32 v20, 0x400000, v20
	v_add_u32_e32 v21, 0x2000, v21
	global_load_dwordx4 v[24:27], v18, s[4:5]
	global_load_dwordx4 v[32:35], v20, s[4:5]
	global_load_dwordx4 v[28:31], v18, s[4:5] offset:1024
	global_load_dwordx4 v[36:39], v20, s[4:5] offset:1024
	global_load_dword v40, v21, s[4:5]
	s_waitcnt vmcnt(22)
	v_fmamk_f32 v96, v58, 0x3a800000, v244
	v_rsq_f32_e32 v96, v96
	v_add_u32_e32 v19, 0x400000, v19
	v_add_u32_e32 v23, 0x800000, v23
	v_lshlrev_b32_e32 v106, 16, v50
	v_and_b32_e32 v107, 0xffff0000, v50
	v_lshlrev_b32_e32 v108, 16, v42
	v_and_b32_e32 v109, 0xffff0000, v42
	v_pk_mul_f32 v[106:107], v[96:97], v[106:107] op_sel_hi:[0,1]
	v_pk_fma_f32 v[98:99], v[10:11], v[106:107], v[108:109]
	v_lshlrev_b32_e32 v106, 16, v51
	v_and_b32_e32 v107, 0xffff0000, v51
	v_lshlrev_b32_e32 v108, 16, v43
	v_and_b32_e32 v109, 0xffff0000, v43
	v_pk_mul_f32 v[106:107], v[96:97], v[106:107] op_sel_hi:[0,1]
	v_pk_fma_f32 v[100:101], v[12:13], v[106:107], v[108:109]
	v_lshlrev_b32_e32 v106, 16, v52
	v_and_b32_e32 v107, 0xffff0000, v52
	v_lshlrev_b32_e32 v108, 16, v44
	v_and_b32_e32 v109, 0xffff0000, v44
	v_pk_mul_f32 v[106:107], v[96:97], v[106:107] op_sel_hi:[0,1]
	v_pk_fma_f32 v[102:103], v[14:15], v[106:107], v[108:109]
	v_lshlrev_b32_e32 v106, 16, v53
	v_and_b32_e32 v107, 0xffff0000, v53
	v_lshlrev_b32_e32 v108, 16, v45
	v_and_b32_e32 v109, 0xffff0000, v45
	v_pk_mul_f32 v[106:107], v[96:97], v[106:107] op_sel_hi:[0,1]
	v_pk_fma_f32 v[104:105], v[16:17], v[106:107], v[108:109]
	v_pk_mul_f32 v[110:111], v[98:99], v[98:99]
	v_pk_fma_f32 v[110:111], v[100:101], v[100:101], v[110:111]
	v_pk_fma_f32 v[110:111], v[102:103], v[102:103], v[110:111]
	v_pk_fma_f32 v[110:111], v[104:105], v[104:105], v[110:111]
	v_cvt_pk_bf16_f32 v42, v98, v99
	v_cvt_pk_bf16_f32 v43, v100, v101
	v_cvt_pk_bf16_f32 v44, v102, v103
	v_cvt_pk_bf16_f32 v45, v104, v105
	global_store_dwordx4 v19, v[42:45], s[4:5]
	global_store_dwordx4 v23, v[98:101], s[6:7]
	global_store_dwordx4 v23, v[102:105], s[6:7] offset:16
	v_lshlrev_b32_e32 v106, 16, v54
	v_and_b32_e32 v107, 0xffff0000, v54
	v_lshlrev_b32_e32 v108, 16, v46
	v_and_b32_e32 v109, 0xffff0000, v46
	v_pk_mul_f32 v[106:107], v[96:97], v[106:107] op_sel_hi:[0,1]
	v_pk_fma_f32 v[98:99], v[2:3], v[106:107], v[108:109]
	v_lshlrev_b32_e32 v106, 16, v55
	v_and_b32_e32 v107, 0xffff0000, v55
	v_lshlrev_b32_e32 v108, 16, v47
	v_and_b32_e32 v109, 0xffff0000, v47
	v_pk_mul_f32 v[106:107], v[96:97], v[106:107] op_sel_hi:[0,1]
	v_pk_fma_f32 v[100:101], v[4:5], v[106:107], v[108:109]
	v_lshlrev_b32_e32 v106, 16, v56
	v_and_b32_e32 v107, 0xffff0000, v56
	v_lshlrev_b32_e32 v108, 16, v48
	v_and_b32_e32 v109, 0xffff0000, v48
	v_pk_mul_f32 v[106:107], v[96:97], v[106:107] op_sel_hi:[0,1]
	v_pk_fma_f32 v[102:103], v[6:7], v[106:107], v[108:109]
	v_lshlrev_b32_e32 v106, 16, v57
	v_and_b32_e32 v107, 0xffff0000, v57
	v_lshlrev_b32_e32 v108, 16, v49
	v_and_b32_e32 v109, 0xffff0000, v49
	v_pk_mul_f32 v[106:107], v[96:97], v[106:107] op_sel_hi:[0,1]
	v_pk_fma_f32 v[104:105], v[8:9], v[106:107], v[108:109]
	v_pk_fma_f32 v[110:111], v[98:99], v[98:99], v[110:111]
	v_pk_fma_f32 v[110:111], v[100:101], v[100:101], v[110:111]
	v_pk_fma_f32 v[110:111], v[102:103], v[102:103], v[110:111]
	v_pk_fma_f32 v[110:111], v[104:105], v[104:105], v[110:111]
	v_cvt_pk_bf16_f32 v46, v98, v99
	v_cvt_pk_bf16_f32 v47, v100, v101
	v_cvt_pk_bf16_f32 v48, v102, v103
	v_cvt_pk_bf16_f32 v49, v104, v105
	global_store_dwordx4 v19, v[46:49], s[4:5] offset:1024
	global_store_dwordx4 v23, v[98:101], s[6:7] offset:2048
	global_store_dwordx4 v23, v[102:105], s[6:7] offset:2064
	v_add_f32_e32 v112, v110, v111
	v_add_u32_e32 v22, 0x2000, v22
	s_nop 1
	v_add_f32_dpp v112, v112, v112 quad_perm:[1,0,3,2] row_mask:0xf bank_mask:0xf
	s_nop 1
	v_add_f32_dpp v112, v112, v112 quad_perm:[2,3,0,1] row_mask:0xf bank_mask:0xf
	s_nop 1
	v_add_f32_dpp v112, v112, v112 row_half_mirror row_mask:0xf bank_mask:0xf
	s_nop 1
	v_add_f32_dpp v112, v112, v112 row_mirror row_mask:0xf bank_mask:0xf
	s_nop 1
	v_add_f32_dpp v112, v112, v112 row_bcast:15 row_mask:0xa bank_mask:0xf
	s_nop 1
	v_add_f32_dpp v112, v112, v112 row_bcast:31 row_mask:0xc bank_mask:0xf
	v_fmamk_f32 v113, v112, 0x3a800000, v244
	v_rsq_f32_e32 v113, v113
	s_mov_b64 exec, s[8:9]
	global_store_dword v22, v113, s[4:5]
	s_mov_b64 exec, -1
	v_add_u32_e32 v18, 0x400000, v18
	v_add_u32_e32 v20, 0x400000, v20
	v_add_u32_e32 v21, 0x2000, v21
	global_load_dwordx4 v[42:45], v18, s[4:5]
	global_load_dwordx4 v[50:53], v20, s[4:5]
	global_load_dwordx4 v[46:49], v18, s[4:5] offset:1024
	global_load_dwordx4 v[54:57], v20, s[4:5] offset:1024
	global_load_dword v58, v21, s[4:5]
	s_waitcnt vmcnt(29)
; __device__ __forceinline__ float bflo(unsigned w) { return __uint_as_float(w << 16); }
; __device__ __forceinline__ float bfhi(unsigned w) { return __uint_as_float(w & 0xffff0000u); }
; __device__ __forceinline__ void resid_rows(bf16_t* R, const bf16_t* Y, const float* ssqY, const float* g, float* rstd_out, float* outf, bool wf32, int row_lo, int row_hi, int yoff, int gw, int NGW, int lane) {
;     ...
;     for (int row0 = row_lo + gw; row0 < row_hi; row0 += RP * NGW) {
;         u32x4 rr[RP][2], oo[RP][2]; float ssv[RP];
; #pragma unroll
;         for (int k = 0; k < RP; ++k) { const int row = row0 + k * NGW; const bool ok = row < row_hi; const int rw = ok ? row : row0;
;             ssv[k] = ssqY[rw];
; #pragma unroll
;             for (int j = 0; j < 2; ++j) { const int c = 8 * lane + 512 * j; rr[k][j] = *(const u32x4*)(R + (size_t)rw * DM + c); oo[k][j] = *(const u32x4*)(Y + (size_t)(rw - yoff) * DM + c); } }
; #pragma unroll
;         for (int k = 0; k < RP; ++k) { const int row = row0 + k * NGW; if (row < row_hi) {
;             const float rs = __builtin_amdgcn_rsqf(ssv[k] * (1.0f / DM) + RMS_EPS); float s = 0.f;
; #pragma unroll
;             for (int j = 0; j < 2; ++j) { const int c = 8 * lane + 512 * j; const u32x4 r = rr[k][j], o = oo[k][j]; const f32x4 ga = gv[j][0], gb = gv[j][1];
;                 f32x4 ya, yb; ya[0] = bflo(r.x) + bflo(o.x) * rs * ga[0]; ya[1] = bfhi(r.x) + bfhi(o.x) * rs * ga[1]; ya[2] = bflo(r.y) + bflo(o.y) * rs * ga[2]; ya[3] = bfhi(r.y) + bfhi(o.y) * rs * ga[3];
;                 yb[0] = bflo(r.z) + bflo(o.z) * rs * gb[0]; yb[1] = bfhi(r.z) + bfhi(o.z) * rs * gb[1]; yb[2] = bflo(r.w) + bflo(o.w) * rs * gb[2]; yb[3] = bfhi(r.w) + bfhi(o.w) * rs * gb[3];
;                 if (wf32) { *(f32x4*)(outf + (size_t)row * DM + c) = ya; *(f32x4*)(outf + (size_t)row * DM + c + 4) = yb; }
;                 s += (ya[0] * ya[0] + ya[1] * ya[1]) + (ya[2] * ya[2] + ya[3] * ya[3]) + (yb[0] * yb[0] + yb[1] * yb[1]) + (yb[2] * yb[2] + yb[3] * yb[3]);
;                 u32x4 w; w.x = pk2(ya[0], ya[1]); w.y = pk2(ya[2], ya[3]); w.z = pk2(yb[0], yb[1]); w.w = pk2(yb[2], yb[3]); *(u32x4*)(R + (size_t)row * DM + c) = w; }
;             s = wave_sum(s); if (lane == 0) rstd_out[row] = __builtin_amdgcn_rsqf(s * (1.0f / DM) + RMS_EPS); } }
	v_fmamk_f32 v96, v76, 0x3a800000, v244
	v_rsq_f32_e32 v96, v96
	v_add_u32_e32 v19, 0x400000, v19
	v_add_u32_e32 v23, 0x800000, v23
	v_lshlrev_b32_e32 v106, 16, v68
	v_and_b32_e32 v107, 0xffff0000, v68
	v_lshlrev_b32_e32 v108, 16, v60
	v_and_b32_e32 v109, 0xffff0000, v60
	v_pk_mul_f32 v[106:107], v[96:97], v[106:107] op_sel_hi:[0,1]
	v_pk_fma_f32 v[98:99], v[10:11], v[106:107], v[108:109]
	v_lshlrev_b32_e32 v106, 16, v69
	v_and_b32_e32 v107, 0xffff0000, v69
	v_lshlrev_b32_e32 v108, 16, v61
	v_and_b32_e32 v109, 0xffff0000, v61
	v_pk_mul_f32 v[106:107], v[96:97], v[106:107] op_sel_hi:[0,1]
	v_pk_fma_f32 v[100:101], v[12:13], v[106:107], v[108:109]
	v_lshlrev_b32_e32 v106, 16, v70
	v_and_b32_e32 v107, 0xffff0000, v70
	v_lshlrev_b32_e32 v108, 16, v62
	v_and_b32_e32 v109, 0xffff0000, v62
	v_pk_mul_f32 v[106:107], v[96:97], v[106:107] op_sel_hi:[0,1]
	v_pk_fma_f32 v[102:103], v[14:15], v[106:107], v[108:109]
	v_lshlrev_b32_e32 v106, 16, v71
	v_and_b32_e32 v107, 0xffff0000, v71
	v_lshlrev_b32_e32 v108, 16, v63
	v_and_b32_e32 v109, 0xffff0000, v63
	v_pk_mul_f32 v[106:107], v[96:97], v[106:107] op_sel_hi:[0,1]
	v_pk_fma_f32 v[104:105], v[16:17], v[106:107], v[108:109]
	v_pk_mul_f32 v[110:111], v[98:99], v[98:99]
	v_pk_fma_f32 v[110:111], v[100:101], v[100:101], v[110:111]
	v_pk_fma_f32 v[110:111], v[102:103], v[102:103], v[110:111]
	v_pk_fma_f32 v[110:111], v[104:105], v[104:105], v[110:111]
	v_cvt_pk_bf16_f32 v60, v98, v99
	v_cvt_pk_bf16_f32 v61, v100, v101
	v_cvt_pk_bf16_f32 v62, v102, v103
	v_cvt_pk_bf16_f32 v63, v104, v105
	global_store_dwordx4 v19, v[60:63], s[4:5]
	global_store_dwordx4 v23, v[98:101], s[6:7]
	global_store_dwordx4 v23, v[102:105], s[6:7] offset:16
	v_lshlrev_b32_e32 v106, 16, v72
	v_and_b32_e32 v107, 0xffff0000, v72
	v_lshlrev_b32_e32 v108, 16, v64
	v_and_b32_e32 v109, 0xffff0000, v64
	v_pk_mul_f32 v[106:107], v[96:97], v[106:107] op_sel_hi:[0,1]
	v_pk_fma_f32 v[98:99], v[2:3], v[106:107], v[108:109]
	v_lshlrev_b32_e32 v106, 16, v73
	v_and_b32_e32 v107, 0xffff0000, v73
	v_lshlrev_b32_e32 v108, 16, v65
	v_and_b32_e32 v109, 0xffff0000, v65
	v_pk_mul_f32 v[106:107], v[96:97], v[106:107] op_sel_hi:[0,1]
	v_pk_fma_f32 v[100:101], v[4:5], v[106:107], v[108:109]
	v_lshlrev_b32_e32 v106, 16, v74
	v_and_b32_e32 v107, 0xffff0000, v74
	v_lshlrev_b32_e32 v108, 16, v66
	v_and_b32_e32 v109, 0xffff0000, v66
	v_pk_mul_f32 v[106:107], v[96:97], v[106:107] op_sel_hi:[0,1]
	v_pk_fma_f32 v[102:103], v[6:7], v[106:107], v[108:109]
	v_lshlrev_b32_e32 v106, 16, v75
	v_and_b32_e32 v107, 0xffff0000, v75
	v_lshlrev_b32_e32 v108, 16, v67
	v_and_b32_e32 v109, 0xffff0000, v67
	v_pk_mul_f32 v[106:107], v[96:97], v[106:107] op_sel_hi:[0,1]
	v_pk_fma_f32 v[104:105], v[8:9], v[106:107], v[108:109]
	v_pk_fma_f32 v[110:111], v[98:99], v[98:99], v[110:111]
	v_pk_fma_f32 v[110:111], v[100:101], v[100:101], v[110:111]
	v_pk_fma_f32 v[110:111], v[102:103], v[102:103], v[110:111]
	v_pk_fma_f32 v[110:111], v[104:105], v[104:105], v[110:111]
	v_cvt_pk_bf16_f32 v64, v98, v99
	v_cvt_pk_bf16_f32 v65, v100, v101
	v_cvt_pk_bf16_f32 v66, v102, v103
	v_cvt_pk_bf16_f32 v67, v104, v105
	global_store_dwordx4 v19, v[64:67], s[4:5] offset:1024
	global_store_dwordx4 v23, v[98:101], s[6:7] offset:2048
	global_store_dwordx4 v23, v[102:105], s[6:7] offset:2064
	v_add_f32_e32 v112, v110, v111
	v_add_u32_e32 v22, 0x2000, v22
	s_nop 1
	v_add_f32_dpp v112, v112, v112 quad_perm:[1,0,3,2] row_mask:0xf bank_mask:0xf
	s_nop 1
	v_add_f32_dpp v112, v112, v112 quad_perm:[2,3,0,1] row_mask:0xf bank_mask:0xf
	s_nop 1
	v_add_f32_dpp v112, v112, v112 row_half_mirror row_mask:0xf bank_mask:0xf
	s_nop 1
	v_add_f32_dpp v112, v112, v112 row_mirror row_mask:0xf bank_mask:0xf
	s_nop 1
	v_add_f32_dpp v112, v112, v112 row_bcast:15 row_mask:0xa bank_mask:0xf
	s_nop 1
	v_add_f32_dpp v112, v112, v112 row_bcast:31 row_mask:0xc bank_mask:0xf
	v_fmamk_f32 v113, v112, 0x3a800000, v244
	v_rsq_f32_e32 v113, v113
	s_mov_b64 exec, s[8:9]
	global_store_dword v22, v113, s[4:5]
	s_mov_b64 exec, -1
	v_add_u32_e32 v18, 0x400000, v18
	v_add_u32_e32 v20, 0x400000, v20
	v_add_u32_e32 v21, 0x2000, v21
	global_load_dwordx4 v[60:63], v18, s[4:5]
	global_load_dwordx4 v[68:71], v20, s[4:5]
	global_load_dwordx4 v[64:67], v18, s[4:5] offset:1024
	global_load_dwordx4 v[72:75], v20, s[4:5] offset:1024
	global_load_dword v76, v21, s[4:5]
	s_waitcnt vmcnt(36)
; __device__ __forceinline__ float bflo(unsigned w) { return __uint_as_float(w << 16); }
; __device__ __forceinline__ float bfhi(unsigned w) { return __uint_as_float(w & 0xffff0000u); }
; __device__ __forceinline__ void resid_rows(bf16_t* R, const bf16_t* Y, const float* ssqY, const float* g, float* rstd_out, float* outf, bool wf32, int row_lo, int row_hi, int yoff, int gw, int NGW, int lane) {
;     ...
;     for (int row0 = row_lo + gw; row0 < row_hi; row0 += RP * NGW) {
;         u32x4 rr[RP][2], oo[RP][2]; float ssv[RP];
; #pragma unroll
;         for (int k = 0; k < RP; ++k) { const int row = row0 + k * NGW; const bool ok = row < row_hi; const int rw = ok ? row : row0;
;             ssv[k] = ssqY[rw];
; #pragma unroll
;             for (int j = 0; j < 2; ++j) { const int c = 8 * lane + 512 * j; rr[k][j] = *(const u32x4*)(R + (size_t)rw * DM + c); oo[k][j] = *(const u32x4*)(Y + (size_t)(rw - yoff) * DM + c); } }
; #pragma unroll
;         for (int k = 0; k < RP; ++k) { const int row = row0 + k * NGW; if (row < row_hi) {
;             const float rs = __builtin_amdgcn_rsqf(ssv[k] * (1.0f / DM) + RMS_EPS); float s = 0.f;
; #pragma unroll
;             for (int j = 0; j < 2; ++j) { const int c = 8 * lane + 512 * j; const u32x4 r = rr[k][j], o = oo[k][j]; const f32x4 ga = gv[j][0], gb = gv[j][1];
;                 f32x4 ya, yb; ya[0] = bflo(r.x) + bflo(o.x) * rs * ga[0]; ya[1] = bfhi(r.x) + bfhi(o.x) * rs * ga[1]; ya[2] = bflo(r.y) + bflo(o.y) * rs * ga[2]; ya[3] = bfhi(r.y) + bfhi(o.y) * rs * ga[3];
;                 yb[0] = bflo(r.z) + bflo(o.z) * rs * gb[0]; yb[1] = bfhi(r.z) + bfhi(o.z) * rs * gb[1]; yb[2] = bflo(r.w) + bflo(o.w) * rs * gb[2]; yb[3] = bfhi(r.w) + bfhi(o.w) * rs * gb[3];
;                 if (wf32) { *(f32x4*)(outf + (size_t)row * DM + c) = ya; *(f32x4*)(outf + (size_t)row * DM + c + 4) = yb; }
;                 s += (ya[0] * ya[0] + ya[1] * ya[1]) + (ya[2] * ya[2] + ya[3] * ya[3]) + (yb[0] * yb[0] + yb[1] * yb[1]) + (yb[2] * yb[2] + yb[3] * yb[3]);
;                 u32x4 w; w.x = pk2(ya[0], ya[1]); w.y = pk2(ya[2], ya[3]); w.z = pk2(yb[0], yb[1]); w.w = pk2(yb[2], yb[3]); *(u32x4*)(R + (size_t)row * DM + c) = w; }
;             s = wave_sum(s); if (lane == 0) rstd_out[row] = __builtin_amdgcn_rsqf(s * (1.0f / DM) + RMS_EPS); } }
	v_fmamk_f32 v96, v94, 0x3a800000, v244
	v_rsq_f32_e32 v96, v96
	v_add_u32_e32 v19, 0x400000, v19
	v_add_u32_e32 v23, 0x800000, v23
	v_lshlrev_b32_e32 v106, 16, v86
	v_and_b32_e32 v107, 0xffff0000, v86
	v_lshlrev_b32_e32 v108, 16, v78
	v_and_b32_e32 v109, 0xffff0000, v78
	v_pk_mul_f32 v[106:107], v[96:97], v[106:107] op_sel_hi:[0,1]
	v_pk_fma_f32 v[98:99], v[10:11], v[106:107], v[108:109]
	v_lshlrev_b32_e32 v106, 16, v87
	v_and_b32_e32 v107, 0xffff0000, v87
	v_lshlrev_b32_e32 v108, 16, v79
	v_and_b32_e32 v109, 0xffff0000, v79
	v_pk_mul_f32 v[106:107], v[96:97], v[106:107] op_sel_hi:[0,1]
	v_pk_fma_f32 v[100:101], v[12:13], v[106:107], v[108:109]
	v_lshlrev_b32_e32 v106, 16, v88
	v_and_b32_e32 v107, 0xffff0000, v88
	v_lshlrev_b32_e32 v108, 16, v80
	v_and_b32_e32 v109, 0xffff0000, v80
	v_pk_mul_f32 v[106:107], v[96:97], v[106:107] op_sel_hi:[0,1]
	v_pk_fma_f32 v[102:103], v[14:15], v[106:107], v[108:109]
	v_lshlrev_b32_e32 v106, 16, v89
	v_and_b32_e32 v107, 0xffff0000, v89
	v_lshlrev_b32_e32 v108, 16, v81
	v_and_b32_e32 v109, 0xffff0000, v81
	v_pk_mul_f32 v[106:107], v[96:97], v[106:107] op_sel_hi:[0,1]
	v_pk_fma_f32 v[104:105], v[16:17], v[106:107], v[108:109]
	v_pk_mul_f32 v[110:111], v[98:99], v[98:99]
	v_pk_fma_f32 v[110:111], v[100:101], v[100:101], v[110:111]
	v_pk_fma_f32 v[110:111], v[102:103], v[102:103], v[110:111]
	v_pk_fma_f32 v[110:111], v[104:105], v[104:105], v[110:111]
	v_cvt_pk_bf16_f32 v78, v98, v99
	v_cvt_pk_bf16_f32 v79, v100, v101
	v_cvt_pk_bf16_f32 v80, v102, v103
	v_cvt_pk_bf16_f32 v81, v104, v105
	global_store_dwordx4 v19, v[78:81], s[4:5]
	global_store_dwordx4 v23, v[98:101], s[6:7]
	global_store_dwordx4 v23, v[102:105], s[6:7] offset:16
	v_lshlrev_b32_e32 v106, 16, v90
	v_and_b32_e32 v107, 0xffff0000, v90
	v_lshlrev_b32_e32 v108, 16, v82
	v_and_b32_e32 v109, 0xffff0000, v82
	v_pk_mul_f32 v[106:107], v[96:97], v[106:107] op_sel_hi:[0,1]
	v_pk_fma_f32 v[98:99], v[2:3], v[106:107], v[108:109]
	v_lshlrev_b32_e32 v106, 16, v91
	v_and_b32_e32 v107, 0xffff0000, v91
	v_lshlrev_b32_e32 v108, 16, v83
	v_and_b32_e32 v109, 0xffff0000, v83
	v_pk_mul_f32 v[106:107], v[96:97], v[106:107] op_sel_hi:[0,1]
	v_pk_fma_f32 v[100:101], v[4:5], v[106:107], v[108:109]
	v_lshlrev_b32_e32 v106, 16, v92
	v_and_b32_e32 v107, 0xffff0000, v92
	v_lshlrev_b32_e32 v108, 16, v84
	v_and_b32_e32 v109, 0xffff0000, v84
	v_pk_mul_f32 v[106:107], v[96:97], v[106:107] op_sel_hi:[0,1]
	v_pk_fma_f32 v[102:103], v[6:7], v[106:107], v[108:109]
	v_lshlrev_b32_e32 v106, 16, v93
	v_and_b32_e32 v107, 0xffff0000, v93
	v_lshlrev_b32_e32 v108, 16, v85
	v_and_b32_e32 v109, 0xffff0000, v85
	v_pk_mul_f32 v[106:107], v[96:97], v[106:107] op_sel_hi:[0,1]
	v_pk_fma_f32 v[104:105], v[8:9], v[106:107], v[108:109]
	v_pk_fma_f32 v[110:111], v[98:99], v[98:99], v[110:111]
	v_pk_fma_f32 v[110:111], v[100:101], v[100:101], v[110:111]
	v_pk_fma_f32 v[110:111], v[102:103], v[102:103], v[110:111]
	v_pk_fma_f32 v[110:111], v[104:105], v[104:105], v[110:111]
	v_cvt_pk_bf16_f32 v82, v98, v99
	v_cvt_pk_bf16_f32 v83, v100, v101
	v_cvt_pk_bf16_f32 v84, v102, v103
	v_cvt_pk_bf16_f32 v85, v104, v105
	global_store_dwordx4 v19, v[82:85], s[4:5] offset:1024
	global_store_dwordx4 v23, v[98:101], s[6:7] offset:2048
	global_store_dwordx4 v23, v[102:105], s[6:7] offset:2064
	v_add_f32_e32 v112, v110, v111
	v_add_u32_e32 v22, 0x2000, v22
	s_nop 1
	v_add_f32_dpp v112, v112, v112 quad_perm:[1,0,3,2] row_mask:0xf bank_mask:0xf
	s_nop 1
	v_add_f32_dpp v112, v112, v112 quad_perm:[2,3,0,1] row_mask:0xf bank_mask:0xf
	s_nop 1
	v_add_f32_dpp v112, v112, v112 row_half_mirror row_mask:0xf bank_mask:0xf
	s_nop 1
	v_add_f32_dpp v112, v112, v112 row_mirror row_mask:0xf bank_mask:0xf
	s_nop 1
	v_add_f32_dpp v112, v112, v112 row_bcast:15 row_mask:0xa bank_mask:0xf
	s_nop 1
	v_add_f32_dpp v112, v112, v112 row_bcast:31 row_mask:0xc bank_mask:0xf
	v_fmamk_f32 v113, v112, 0x3a800000, v244
	v_rsq_f32_e32 v113, v113
	s_mov_b64 exec, s[8:9]
	global_store_dword v22, v113, s[4:5]
	s_mov_b64 exec, -1
	v_add_u32_e32 v18, 0x400000, v18
	v_add_u32_e32 v20, 0x400000, v20
	v_add_u32_e32 v21, 0x2000, v21
	global_load_dwordx4 v[78:81], v18, s[4:5]
	global_load_dwordx4 v[86:89], v20, s[4:5]
	global_load_dwordx4 v[82:85], v18, s[4:5] offset:1024
	global_load_dwordx4 v[90:93], v20, s[4:5] offset:1024
	global_load_dword v94, v21, s[4:5]
	s_waitcnt vmcnt(36)
; __device__ __forceinline__ float bflo(unsigned w) { return __uint_as_float(w << 16); }
; __device__ __forceinline__ float bfhi(unsigned w) { return __uint_as_float(w & 0xffff0000u); }
; __device__ __forceinline__ void resid_rows(bf16_t* R, const bf16_t* Y, const float* ssqY, const float* g, float* rstd_out, float* outf, bool wf32, int row_lo, int row_hi, int yoff, int gw, int NGW, int lane) {
;     ...
;     for (int row0 = row_lo + gw; row0 < row_hi; row0 += RP * NGW) {
;         u32x4 rr[RP][2], oo[RP][2]; float ssv[RP];
; #pragma unroll
;         for (int k = 0; k < RP; ++k) { const int row = row0 + k * NGW; const bool ok = row < row_hi; const int rw = ok ? row : row0;
;             ssv[k] = ssqY[rw];
; #pragma unroll
;             for (int j = 0; j < 2; ++j) { const int c = 8 * lane + 512 * j; rr[k][j] = *(const u32x4*)(R + (size_t)rw * DM + c); oo[k][j] = *(const u32x4*)(Y + (size_t)(rw - yoff) * DM + c); } }
; #pragma unroll
;         for (int k = 0; k < RP; ++k) { const int row = row0 + k * NGW; if (row < row_hi) {
;             const float rs = __builtin_amdgcn_rsqf(ssv[k] * (1.0f / DM) + RMS_EPS); float s = 0.f;
; #pragma unroll
;             for (int j = 0; j < 2; ++j) { const int c = 8 * lane + 512 * j; const u32x4 r = rr[k][j], o = oo[k][j]; const f32x4 ga = gv[j][0], gb = gv[j][1];
;                 f32x4 ya, yb; ya[0] = bflo(r.x) + bflo(o.x) * rs * ga[0]; ya[1] = bfhi(r.x) + bfhi(o.x) * rs * ga[1]; ya[2] = bflo(r.y) + bflo(o.y) * rs * ga[2]; ya[3] = bfhi(r.y) + bfhi(o.y) * rs * ga[3];
;                 yb[0] = bflo(r.z) + bflo(o.z) * rs * gb[0]; yb[1] = bfhi(r.z) + bfhi(o.z) * rs * gb[1]; yb[2] = bflo(r.w) + bflo(o.w) * rs * gb[2]; yb[3] = bfhi(r.w) + bfhi(o.w) * rs * gb[3];
;                 if (wf32) { *(f32x4*)(outf + (size_t)row * DM + c) = ya; *(f32x4*)(outf + (size_t)row * DM + c + 4) = yb; }
;                 s += (ya[0] * ya[0] + ya[1] * ya[1]) + (ya[2] * ya[2] + ya[3] * ya[3]) + (yb[0] * yb[0] + yb[1] * yb[1]) + (yb[2] * yb[2] + yb[3] * yb[3]);
;                 u32x4 w; w.x = pk2(ya[0], ya[1]); w.y = pk2(ya[2], ya[3]); w.z = pk2(yb[0], yb[1]); w.w = pk2(yb[2], yb[3]); *(u32x4*)(R + (size_t)row * DM + c) = w; }
;             s = wave_sum(s); if (lane == 0) rstd_out[row] = __builtin_amdgcn_rsqf(s * (1.0f / DM) + RMS_EPS); } }
	v_fmamk_f32 v96, v40, 0x3a800000, v244
	v_rsq_f32_e32 v96, v96
	v_add_u32_e32 v19, 0x400000, v19
	v_add_u32_e32 v23, 0x800000, v23
	v_lshlrev_b32_e32 v106, 16, v32
	v_and_b32_e32 v107, 0xffff0000, v32
	v_lshlrev_b32_e32 v108, 16, v24
	v_and_b32_e32 v109, 0xffff0000, v24
	v_pk_mul_f32 v[106:107], v[96:97], v[106:107] op_sel_hi:[0,1]
	v_pk_fma_f32 v[98:99], v[10:11], v[106:107], v[108:109]
	v_lshlrev_b32_e32 v106, 16, v33
	v_and_b32_e32 v107, 0xffff0000, v33
	v_lshlrev_b32_e32 v108, 16, v25
	v_and_b32_e32 v109, 0xffff0000, v25
	v_pk_mul_f32 v[106:107], v[96:97], v[106:107] op_sel_hi:[0,1]
	v_pk_fma_f32 v[100:101], v[12:13], v[106:107], v[108:109]
	v_lshlrev_b32_e32 v106, 16, v34
	v_and_b32_e32 v107, 0xffff0000, v34
	v_lshlrev_b32_e32 v108, 16, v26
	v_and_b32_e32 v109, 0xffff0000, v26
	v_pk_mul_f32 v[106:107], v[96:97], v[106:107] op_sel_hi:[0,1]
	v_pk_fma_f32 v[102:103], v[14:15], v[106:107], v[108:109]
	v_lshlrev_b32_e32 v106, 16, v35
	v_and_b32_e32 v107, 0xffff0000, v35
	v_lshlrev_b32_e32 v108, 16, v27
	v_and_b32_e32 v109, 0xffff0000, v27
	v_pk_mul_f32 v[106:107], v[96:97], v[106:107] op_sel_hi:[0,1]
	v_pk_fma_f32 v[104:105], v[16:17], v[106:107], v[108:109]
	v_pk_mul_f32 v[110:111], v[98:99], v[98:99]
	v_pk_fma_f32 v[110:111], v[100:101], v[100:101], v[110:111]
	v_pk_fma_f32 v[110:111], v[102:103], v[102:103], v[110:111]
	v_pk_fma_f32 v[110:111], v[104:105], v[104:105], v[110:111]
	v_cvt_pk_bf16_f32 v24, v98, v99
	v_cvt_pk_bf16_f32 v25, v100, v101
	v_cvt_pk_bf16_f32 v26, v102, v103
	v_cvt_pk_bf16_f32 v27, v104, v105
	global_store_dwordx4 v19, v[24:27], s[4:5]
	global_store_dwordx4 v23, v[98:101], s[6:7]
	global_store_dwordx4 v23, v[102:105], s[6:7] offset:16
	v_lshlrev_b32_e32 v106, 16, v36
	v_and_b32_e32 v107, 0xffff0000, v36
	v_lshlrev_b32_e32 v108, 16, v28
	v_and_b32_e32 v109, 0xffff0000, v28
	v_pk_mul_f32 v[106:107], v[96:97], v[106:107] op_sel_hi:[0,1]
	v_pk_fma_f32 v[98:99], v[2:3], v[106:107], v[108:109]
	v_lshlrev_b32_e32 v106, 16, v37
	v_and_b32_e32 v107, 0xffff0000, v37
	v_lshlrev_b32_e32 v108, 16, v29
	v_and_b32_e32 v109, 0xffff0000, v29
	v_pk_mul_f32 v[106:107], v[96:97], v[106:107] op_sel_hi:[0,1]
	v_pk_fma_f32 v[100:101], v[4:5], v[106:107], v[108:109]
	v_lshlrev_b32_e32 v106, 16, v38
	v_and_b32_e32 v107, 0xffff0000, v38
	v_lshlrev_b32_e32 v108, 16, v30
	v_and_b32_e32 v109, 0xffff0000, v30
	v_pk_mul_f32 v[106:107], v[96:97], v[106:107] op_sel_hi:[0,1]
	v_pk_fma_f32 v[102:103], v[6:7], v[106:107], v[108:109]
	v_lshlrev_b32_e32 v106, 16, v39
	v_and_b32_e32 v107, 0xffff0000, v39
	v_lshlrev_b32_e32 v108, 16, v31
	v_and_b32_e32 v109, 0xffff0000, v31
	v_pk_mul_f32 v[106:107], v[96:97], v[106:107] op_sel_hi:[0,1]
	v_pk_fma_f32 v[104:105], v[8:9], v[106:107], v[108:109]
	v_pk_fma_f32 v[110:111], v[98:99], v[98:99], v[110:111]
	v_pk_fma_f32 v[110:111], v[100:101], v[100:101], v[110:111]
	v_pk_fma_f32 v[110:111], v[102:103], v[102:103], v[110:111]
	v_pk_fma_f32 v[110:111], v[104:105], v[104:105], v[110:111]
	v_cvt_pk_bf16_f32 v28, v98, v99
	v_cvt_pk_bf16_f32 v29, v100, v101
	v_cvt_pk_bf16_f32 v30, v102, v103
	v_cvt_pk_bf16_f32 v31, v104, v105
	global_store_dwordx4 v19, v[28:31], s[4:5] offset:1024
	global_store_dwordx4 v23, v[98:101], s[6:7] offset:2048
	global_store_dwordx4 v23, v[102:105], s[6:7] offset:2064
	v_add_f32_e32 v112, v110, v111
	v_add_u32_e32 v22, 0x2000, v22
	s_nop 1
	v_add_f32_dpp v112, v112, v112 quad_perm:[1,0,3,2] row_mask:0xf bank_mask:0xf
	s_nop 1
	v_add_f32_dpp v112, v112, v112 quad_perm:[2,3,0,1] row_mask:0xf bank_mask:0xf
	s_nop 1
	v_add_f32_dpp v112, v112, v112 row_half_mirror row_mask:0xf bank_mask:0xf
	s_nop 1
	v_add_f32_dpp v112, v112, v112 row_mirror row_mask:0xf bank_mask:0xf
	s_nop 1
	v_add_f32_dpp v112, v112, v112 row_bcast:15 row_mask:0xa bank_mask:0xf
	s_nop 1
	v_add_f32_dpp v112, v112, v112 row_bcast:31 row_mask:0xc bank_mask:0xf
	v_fmamk_f32 v113, v112, 0x3a800000, v244
	v_rsq_f32_e32 v113, v113
	s_mov_b64 exec, s[8:9]
	global_store_dword v22, v113, s[4:5]
	s_mov_b64 exec, -1
	s_waitcnt vmcnt(31)
	v_fmamk_f32 v96, v58, 0x3a800000, v244
	v_rsq_f32_e32 v96, v96
	v_add_u32_e32 v19, 0x400000, v19
	v_add_u32_e32 v23, 0x800000, v23
	v_lshlrev_b32_e32 v106, 16, v50
	v_and_b32_e32 v107, 0xffff0000, v50
	v_lshlrev_b32_e32 v108, 16, v42
	v_and_b32_e32 v109, 0xffff0000, v42
	v_pk_mul_f32 v[106:107], v[96:97], v[106:107] op_sel_hi:[0,1]
	v_pk_fma_f32 v[98:99], v[10:11], v[106:107], v[108:109]
	v_lshlrev_b32_e32 v106, 16, v51
	v_and_b32_e32 v107, 0xffff0000, v51
	v_lshlrev_b32_e32 v108, 16, v43
	v_and_b32_e32 v109, 0xffff0000, v43
	v_pk_mul_f32 v[106:107], v[96:97], v[106:107] op_sel_hi:[0,1]
	v_pk_fma_f32 v[100:101], v[12:13], v[106:107], v[108:109]
	v_lshlrev_b32_e32 v106, 16, v52
	v_and_b32_e32 v107, 0xffff0000, v52
	v_lshlrev_b32_e32 v108, 16, v44
	v_and_b32_e32 v109, 0xffff0000, v44
	v_pk_mul_f32 v[106:107], v[96:97], v[106:107] op_sel_hi:[0,1]
	v_pk_fma_f32 v[102:103], v[14:15], v[106:107], v[108:109]
	v_lshlrev_b32_e32 v106, 16, v53
	v_and_b32_e32 v107, 0xffff0000, v53
	v_lshlrev_b32_e32 v108, 16, v45
	v_and_b32_e32 v109, 0xffff0000, v45
	v_pk_mul_f32 v[106:107], v[96:97], v[106:107] op_sel_hi:[0,1]
	v_pk_fma_f32 v[104:105], v[16:17], v[106:107], v[108:109]
	v_pk_mul_f32 v[110:111], v[98:99], v[98:99]
	v_pk_fma_f32 v[110:111], v[100:101], v[100:101], v[110:111]
	v_pk_fma_f32 v[110:111], v[102:103], v[102:103], v[110:111]
	v_pk_fma_f32 v[110:111], v[104:105], v[104:105], v[110:111]
	v_cvt_pk_bf16_f32 v42, v98, v99
	v_cvt_pk_bf16_f32 v43, v100, v101
	v_cvt_pk_bf16_f32 v44, v102, v103
	v_cvt_pk_bf16_f32 v45, v104, v105
	global_store_dwordx4 v19, v[42:45], s[4:5]
	global_store_dwordx4 v23, v[98:101], s[6:7]
; __device__ __forceinline__ float bflo(unsigned w) { return __uint_as_float(w << 16); }
; __device__ __forceinline__ float bfhi(unsigned w) { return __uint_as_float(w & 0xffff0000u); }
; __device__ __forceinline__ void resid_rows(bf16_t* R, const bf16_t* Y, const float* ssqY, const float* g, float* rstd_out, float* outf, bool wf32, int row_lo, int row_hi, int yoff, int gw, int NGW, int lane) {
;     ...
;     for (int row0 = row_lo + gw; row0 < row_hi; row0 += RP * NGW) {
;         u32x4 rr[RP][2], oo[RP][2]; float ssv[RP];
; #pragma unroll
;         for (int k = 0; k < RP; ++k) { const int row = row0 + k * NGW; const bool ok = row < row_hi; const int rw = ok ? row : row0;
;             ssv[k] = ssqY[rw];
; #pragma unroll
;             for (int j = 0; j < 2; ++j) { const int c = 8 * lane + 512 * j; rr[k][j] = *(const u32x4*)(R + (size_t)rw * DM + c); oo[k][j] = *(const u32x4*)(Y + (size_t)(rw - yoff) * DM + c); } }
; #pragma unroll
;         for (int k = 0; k < RP; ++k) { const int row = row0 + k * NGW; if (row < row_hi) {
;             const float rs = __builtin_amdgcn_rsqf(ssv[k] * (1.0f / DM) + RMS_EPS); float s = 0.f;
; #pragma unroll
;             for (int j = 0; j < 2; ++j) { const int c = 8 * lane + 512 * j; const u32x4 r = rr[k][j], o = oo[k][j]; const f32x4 ga = gv[j][0], gb = gv[j][1];
;                 f32x4 ya, yb; ya[0] = bflo(r.x) + bflo(o.x) * rs * ga[0]; ya[1] = bfhi(r.x) + bfhi(o.x) * rs * ga[1]; ya[2] = bflo(r.y) + bflo(o.y) * rs * ga[2]; ya[3] = bfhi(r.y) + bfhi(o.y) * rs * ga[3];
;                 yb[0] = bflo(r.z) + bflo(o.z) * rs * gb[0]; yb[1] = bfhi(r.z) + bfhi(o.z) * rs * gb[1]; yb[2] = bflo(r.w) + bflo(o.w) * rs * gb[2]; yb[3] = bfhi(r.w) + bfhi(o.w) * rs * gb[3];
;                 if (wf32) { *(f32x4*)(outf + (size_t)row * DM + c) = ya; *(f32x4*)(outf + (size_t)row * DM + c + 4) = yb; }
;                 s += (ya[0] * ya[0] + ya[1] * ya[1]) + (ya[2] * ya[2] + ya[3] * ya[3]) + (yb[0] * yb[0] + yb[1] * yb[1]) + (yb[2] * yb[2] + yb[3] * yb[3]);
;                 u32x4 w; w.x = pk2(ya[0], ya[1]); w.y = pk2(ya[2], ya[3]); w.z = pk2(yb[0], yb[1]); w.w = pk2(yb[2], yb[3]); *(u32x4*)(R + (size_t)row * DM + c) = w; }
;             s = wave_sum(s); if (lane == 0) rstd_out[row] = __builtin_amdgcn_rsqf(s * (1.0f / DM) + RMS_EPS); } }
	global_store_dwordx4 v23, v[102:105], s[6:7] offset:16
	v_lshlrev_b32_e32 v106, 16, v54
	v_and_b32_e32 v107, 0xffff0000, v54
	v_lshlrev_b32_e32 v108, 16, v46
	v_and_b32_e32 v109, 0xffff0000, v46
	v_pk_mul_f32 v[106:107], v[96:97], v[106:107] op_sel_hi:[0,1]
	v_pk_fma_f32 v[98:99], v[2:3], v[106:107], v[108:109]
	v_lshlrev_b32_e32 v106, 16, v55
	v_and_b32_e32 v107, 0xffff0000, v55
	v_lshlrev_b32_e32 v108, 16, v47
	v_and_b32_e32 v109, 0xffff0000, v47
	v_pk_mul_f32 v[106:107], v[96:97], v[106:107] op_sel_hi:[0,1]
	v_pk_fma_f32 v[100:101], v[4:5], v[106:107], v[108:109]
	v_lshlrev_b32_e32 v106, 16, v56
	v_and_b32_e32 v107, 0xffff0000, v56
	v_lshlrev_b32_e32 v108, 16, v48
	v_and_b32_e32 v109, 0xffff0000, v48
	v_pk_mul_f32 v[106:107], v[96:97], v[106:107] op_sel_hi:[0,1]
	v_pk_fma_f32 v[102:103], v[6:7], v[106:107], v[108:109]
	v_lshlrev_b32_e32 v106, 16, v57
	v_and_b32_e32 v107, 0xffff0000, v57
	v_lshlrev_b32_e32 v108, 16, v49
	v_and_b32_e32 v109, 0xffff0000, v49
	v_pk_mul_f32 v[106:107], v[96:97], v[106:107] op_sel_hi:[0,1]
	v_pk_fma_f32 v[104:105], v[8:9], v[106:107], v[108:109]
	v_pk_fma_f32 v[110:111], v[98:99], v[98:99], v[110:111]
	v_pk_fma_f32 v[110:111], v[100:101], v[100:101], v[110:111]
	v_pk_fma_f32 v[110:111], v[102:103], v[102:103], v[110:111]
	v_pk_fma_f32 v[110:111], v[104:105], v[104:105], v[110:111]
	v_cvt_pk_bf16_f32 v46, v98, v99
	v_cvt_pk_bf16_f32 v47, v100, v101
	v_cvt_pk_bf16_f32 v48, v102, v103
	v_cvt_pk_bf16_f32 v49, v104, v105
	global_store_dwordx4 v19, v[46:49], s[4:5] offset:1024
	global_store_dwordx4 v23, v[98:101], s[6:7] offset:2048
	global_store_dwordx4 v23, v[102:105], s[6:7] offset:2064
	v_add_f32_e32 v112, v110, v111
	v_add_u32_e32 v22, 0x2000, v22
	s_nop 1
	v_add_f32_dpp v112, v112, v112 quad_perm:[1,0,3,2] row_mask:0xf bank_mask:0xf
	s_nop 1
	v_add_f32_dpp v112, v112, v112 quad_perm:[2,3,0,1] row_mask:0xf bank_mask:0xf
	s_nop 1
	v_add_f32_dpp v112, v112, v112 row_half_mirror row_mask:0xf bank_mask:0xf
	s_nop 1
	v_add_f32_dpp v112, v112, v112 row_mirror row_mask:0xf bank_mask:0xf
	s_nop 1
	v_add_f32_dpp v112, v112, v112 row_bcast:15 row_mask:0xa bank_mask:0xf
	s_nop 1
	v_add_f32_dpp v112, v112, v112 row_bcast:31 row_mask:0xc bank_mask:0xf
	v_fmamk_f32 v113, v112, 0x3a800000, v244
	v_rsq_f32_e32 v113, v113
	s_mov_b64 exec, s[8:9]
	global_store_dword v22, v113, s[4:5]
	s_mov_b64 exec, -1
	s_waitcnt vmcnt(26)
	v_fmamk_f32 v96, v76, 0x3a800000, v244
	v_rsq_f32_e32 v96, v96
	v_add_u32_e32 v19, 0x400000, v19
	v_add_u32_e32 v23, 0x800000, v23
	v_lshlrev_b32_e32 v106, 16, v68
	v_and_b32_e32 v107, 0xffff0000, v68
	v_lshlrev_b32_e32 v108, 16, v60
	v_and_b32_e32 v109, 0xffff0000, v60
	v_pk_mul_f32 v[106:107], v[96:97], v[106:107] op_sel_hi:[0,1]
	v_pk_fma_f32 v[98:99], v[10:11], v[106:107], v[108:109]
	v_lshlrev_b32_e32 v106, 16, v69
	v_and_b32_e32 v107, 0xffff0000, v69
	v_lshlrev_b32_e32 v108, 16, v61
	v_and_b32_e32 v109, 0xffff0000, v61
	v_pk_mul_f32 v[106:107], v[96:97], v[106:107] op_sel_hi:[0,1]
	v_pk_fma_f32 v[100:101], v[12:13], v[106:107], v[108:109]
	v_lshlrev_b32_e32 v106, 16, v70
	v_and_b32_e32 v107, 0xffff0000, v70
	v_lshlrev_b32_e32 v108, 16, v62
	v_and_b32_e32 v109, 0xffff0000, v62
	v_pk_mul_f32 v[106:107], v[96:97], v[106:107] op_sel_hi:[0,1]
	v_pk_fma_f32 v[102:103], v[14:15], v[106:107], v[108:109]
	v_lshlrev_b32_e32 v106, 16, v71
	v_and_b32_e32 v107, 0xffff0000, v71
	v_lshlrev_b32_e32 v108, 16, v63
	v_and_b32_e32 v109, 0xffff0000, v63
	v_pk_mul_f32 v[106:107], v[96:97], v[106:107] op_sel_hi:[0,1]
	v_pk_fma_f32 v[104:105], v[16:17], v[106:107], v[108:109]
	v_pk_mul_f32 v[110:111], v[98:99], v[98:99]
	v_pk_fma_f32 v[110:111], v[100:101], v[100:101], v[110:111]
	v_pk_fma_f32 v[110:111], v[102:103], v[102:103], v[110:111]
	v_pk_fma_f32 v[110:111], v[104:105], v[104:105], v[110:111]
	v_cvt_pk_bf16_f32 v60, v98, v99
	v_cvt_pk_bf16_f32 v61, v100, v101
	v_cvt_pk_bf16_f32 v62, v102, v103
	v_cvt_pk_bf16_f32 v63, v104, v105
	global_store_dwordx4 v19, v[60:63], s[4:5]
	global_store_dwordx4 v23, v[98:101], s[6:7]
	global_store_dwordx4 v23, v[102:105], s[6:7] offset:16
	v_lshlrev_b32_e32 v106, 16, v72
	v_and_b32_e32 v107, 0xffff0000, v72
	v_lshlrev_b32_e32 v108, 16, v64
	v_and_b32_e32 v109, 0xffff0000, v64
	v_pk_mul_f32 v[106:107], v[96:97], v[106:107] op_sel_hi:[0,1]
	v_pk_fma_f32 v[98:99], v[2:3], v[106:107], v[108:109]
	v_lshlrev_b32_e32 v106, 16, v73
	v_and_b32_e32 v107, 0xffff0000, v73
	v_lshlrev_b32_e32 v108, 16, v65
	v_and_b32_e32 v109, 0xffff0000, v65
	v_pk_mul_f32 v[106:107], v[96:97], v[106:107] op_sel_hi:[0,1]
	v_pk_fma_f32 v[100:101], v[4:5], v[106:107], v[108:109]
	v_lshlrev_b32_e32 v106, 16, v74
	v_and_b32_e32 v107, 0xffff0000, v74
	v_lshlrev_b32_e32 v108, 16, v66
	v_and_b32_e32 v109, 0xffff0000, v66
	v_pk_mul_f32 v[106:107], v[96:97], v[106:107] op_sel_hi:[0,1]
	v_pk_fma_f32 v[102:103], v[6:7], v[106:107], v[108:109]
	v_lshlrev_b32_e32 v106, 16, v75
	v_and_b32_e32 v107, 0xffff0000, v75
	v_lshlrev_b32_e32 v108, 16, v67
	v_and_b32_e32 v109, 0xffff0000, v67
	v_pk_mul_f32 v[106:107], v[96:97], v[106:107] op_sel_hi:[0,1]
	v_pk_fma_f32 v[104:105], v[8:9], v[106:107], v[108:109]
	v_pk_fma_f32 v[110:111], v[98:99], v[98:99], v[110:111]
	v_pk_fma_f32 v[110:111], v[100:101], v[100:101], v[110:111]
	v_pk_fma_f32 v[110:111], v[102:103], v[102:103], v[110:111]
	v_pk_fma_f32 v[110:111], v[104:105], v[104:105], v[110:111]
	v_cvt_pk_bf16_f32 v64, v98, v99
	v_cvt_pk_bf16_f32 v65, v100, v101
	v_cvt_pk_bf16_f32 v66, v102, v103
	v_cvt_pk_bf16_f32 v67, v104, v105
	global_store_dwordx4 v19, v[64:67], s[4:5] offset:1024
	global_store_dwordx4 v23, v[98:101], s[6:7] offset:2048
	global_store_dwordx4 v23, v[102:105], s[6:7] offset:2064
	v_add_f32_e32 v112, v110, v111
	v_add_u32_e32 v22, 0x2000, v22
	s_nop 1
	v_add_f32_dpp v112, v112, v112 quad_perm:[1,0,3,2] row_mask:0xf bank_mask:0xf
	s_nop 1
	v_add_f32_dpp v112, v112, v112 quad_perm:[2,3,0,1] row_mask:0xf bank_mask:0xf
	s_nop 1
	v_add_f32_dpp v112, v112, v112 row_half_mirror row_mask:0xf bank_mask:0xf
	s_nop 1
	v_add_f32_dpp v112, v112, v112 row_mirror row_mask:0xf bank_mask:0xf
	s_nop 1
	v_add_f32_dpp v112, v112, v112 row_bcast:15 row_mask:0xa bank_mask:0xf
	s_nop 1
	v_add_f32_dpp v112, v112, v112 row_bcast:31 row_mask:0xc bank_mask:0xf
	v_fmamk_f32 v113, v112, 0x3a800000, v244
	v_rsq_f32_e32 v113, v113
	s_mov_b64 exec, s[8:9]
	global_store_dword v22, v113, s[4:5]
	s_mov_b64 exec, -1
	s_waitcnt vmcnt(21)
; __device__ __forceinline__ float bflo(unsigned w) { return __uint_as_float(w << 16); }
; __device__ __forceinline__ float bfhi(unsigned w) { return __uint_as_float(w & 0xffff0000u); }
; __device__ __forceinline__ void resid_rows(bf16_t* R, const bf16_t* Y, const float* ssqY, const float* g, float* rstd_out, float* outf, bool wf32, int row_lo, int row_hi, int yoff, int gw, int NGW, int lane) {
;     ...
;     for (int row0 = row_lo + gw; row0 < row_hi; row0 += RP * NGW) {
;         u32x4 rr[RP][2], oo[RP][2]; float ssv[RP];
; #pragma unroll
;         for (int k = 0; k < RP; ++k) { const int row = row0 + k * NGW; const bool ok = row < row_hi; const int rw = ok ? row : row0;
;             ssv[k] = ssqY[rw];
; #pragma unroll
;             for (int j = 0; j < 2; ++j) { const int c = 8 * lane + 512 * j; rr[k][j] = *(const u32x4*)(R + (size_t)rw * DM + c); oo[k][j] = *(const u32x4*)(Y + (size_t)(rw - yoff) * DM + c); } }
; #pragma unroll
;         for (int k = 0; k < RP; ++k) { const int row = row0 + k * NGW; if (row < row_hi) {
;             const float rs = __builtin_amdgcn_rsqf(ssv[k] * (1.0f / DM) + RMS_EPS); float s = 0.f;
; #pragma unroll
;             for (int j = 0; j < 2; ++j) { const int c = 8 * lane + 512 * j; const u32x4 r = rr[k][j], o = oo[k][j]; const f32x4 ga = gv[j][0], gb = gv[j][1];
;                 f32x4 ya, yb; ya[0] = bflo(r.x) + bflo(o.x) * rs * ga[0]; ya[1] = bfhi(r.x) + bfhi(o.x) * rs * ga[1]; ya[2] = bflo(r.y) + bflo(o.y) * rs * ga[2]; ya[3] = bfhi(r.y) + bfhi(o.y) * rs * ga[3];
;                 yb[0] = bflo(r.z) + bflo(o.z) * rs * gb[0]; yb[1] = bfhi(r.z) + bfhi(o.z) * rs * gb[1]; yb[2] = bflo(r.w) + bflo(o.w) * rs * gb[2]; yb[3] = bfhi(r.w) + bfhi(o.w) * rs * gb[3];
;                 if (wf32) { *(f32x4*)(outf + (size_t)row * DM + c) = ya; *(f32x4*)(outf + (size_t)row * DM + c + 4) = yb; }
;                 s += (ya[0] * ya[0] + ya[1] * ya[1]) + (ya[2] * ya[2] + ya[3] * ya[3]) + (yb[0] * yb[0] + yb[1] * yb[1]) + (yb[2] * yb[2] + yb[3] * yb[3]);
;                 u32x4 w; w.x = pk2(ya[0], ya[1]); w.y = pk2(ya[2], ya[3]); w.z = pk2(yb[0], yb[1]); w.w = pk2(yb[2], yb[3]); *(u32x4*)(R + (size_t)row * DM + c) = w; }
;             s = wave_sum(s); if (lane == 0) rstd_out[row] = __builtin_amdgcn_rsqf(s * (1.0f / DM) + RMS_EPS); } }
	v_fmamk_f32 v96, v94, 0x3a800000, v244
	v_rsq_f32_e32 v96, v96
	v_add_u32_e32 v19, 0x400000, v19
	v_add_u32_e32 v23, 0x800000, v23
	v_lshlrev_b32_e32 v106, 16, v86
	v_and_b32_e32 v107, 0xffff0000, v86
	v_lshlrev_b32_e32 v108, 16, v78
	v_and_b32_e32 v109, 0xffff0000, v78
	v_pk_mul_f32 v[106:107], v[96:97], v[106:107] op_sel_hi:[0,1]
	v_pk_fma_f32 v[98:99], v[10:11], v[106:107], v[108:109]
	v_lshlrev_b32_e32 v106, 16, v87
	v_and_b32_e32 v107, 0xffff0000, v87
	v_lshlrev_b32_e32 v108, 16, v79
	v_and_b32_e32 v109, 0xffff0000, v79
	v_pk_mul_f32 v[106:107], v[96:97], v[106:107] op_sel_hi:[0,1]
	v_pk_fma_f32 v[100:101], v[12:13], v[106:107], v[108:109]
	v_lshlrev_b32_e32 v106, 16, v88
	v_and_b32_e32 v107, 0xffff0000, v88
	v_lshlrev_b32_e32 v108, 16, v80
	v_and_b32_e32 v109, 0xffff0000, v80
	v_pk_mul_f32 v[106:107], v[96:97], v[106:107] op_sel_hi:[0,1]
	v_pk_fma_f32 v[102:103], v[14:15], v[106:107], v[108:109]
	v_lshlrev_b32_e32 v106, 16, v89
	v_and_b32_e32 v107, 0xffff0000, v89
	v_lshlrev_b32_e32 v108, 16, v81
	v_and_b32_e32 v109, 0xffff0000, v81
	v_pk_mul_f32 v[106:107], v[96:97], v[106:107] op_sel_hi:[0,1]
	v_pk_fma_f32 v[104:105], v[16:17], v[106:107], v[108:109]
	v_pk_mul_f32 v[110:111], v[98:99], v[98:99]
	v_pk_fma_f32 v[110:111], v[100:101], v[100:101], v[110:111]
	v_pk_fma_f32 v[110:111], v[102:103], v[102:103], v[110:111]
	v_pk_fma_f32 v[110:111], v[104:105], v[104:105], v[110:111]
	v_cvt_pk_bf16_f32 v78, v98, v99
	v_cvt_pk_bf16_f32 v79, v100, v101
	v_cvt_pk_bf16_f32 v80, v102, v103
	v_cvt_pk_bf16_f32 v81, v104, v105
	global_store_dwordx4 v19, v[78:81], s[4:5]
	global_store_dwordx4 v23, v[98:101], s[6:7]
	global_store_dwordx4 v23, v[102:105], s[6:7] offset:16
	v_lshlrev_b32_e32 v106, 16, v90
	v_and_b32_e32 v107, 0xffff0000, v90
	v_lshlrev_b32_e32 v108, 16, v82
	v_and_b32_e32 v109, 0xffff0000, v82
	v_pk_mul_f32 v[106:107], v[96:97], v[106:107] op_sel_hi:[0,1]
	v_pk_fma_f32 v[98:99], v[2:3], v[106:107], v[108:109]
	v_lshlrev_b32_e32 v106, 16, v91
	v_and_b32_e32 v107, 0xffff0000, v91
	v_lshlrev_b32_e32 v108, 16, v83
	v_and_b32_e32 v109, 0xffff0000, v83
	v_pk_mul_f32 v[106:107], v[96:97], v[106:107] op_sel_hi:[0,1]
	v_pk_fma_f32 v[100:101], v[4:5], v[106:107], v[108:109]
	v_lshlrev_b32_e32 v106, 16, v92
	v_and_b32_e32 v107, 0xffff0000, v92
	v_lshlrev_b32_e32 v108, 16, v84
	v_and_b32_e32 v109, 0xffff0000, v84
	v_pk_mul_f32 v[106:107], v[96:97], v[106:107] op_sel_hi:[0,1]
	v_pk_fma_f32 v[102:103], v[6:7], v[106:107], v[108:109]
	v_lshlrev_b32_e32 v106, 16, v93
	v_and_b32_e32 v107, 0xffff0000, v93
	v_lshlrev_b32_e32 v108, 16, v85
	v_and_b32_e32 v109, 0xffff0000, v85
	v_pk_mul_f32 v[106:107], v[96:97], v[106:107] op_sel_hi:[0,1]
	v_pk_fma_f32 v[104:105], v[8:9], v[106:107], v[108:109]
	v_pk_fma_f32 v[110:111], v[98:99], v[98:99], v[110:111]
	v_pk_fma_f32 v[110:111], v[100:101], v[100:101], v[110:111]
	v_pk_fma_f32 v[110:111], v[102:103], v[102:103], v[110:111]
	v_pk_fma_f32 v[110:111], v[104:105], v[104:105], v[110:111]
	v_cvt_pk_bf16_f32 v82, v98, v99
	v_cvt_pk_bf16_f32 v83, v100, v101
	v_cvt_pk_bf16_f32 v84, v102, v103
	v_cvt_pk_bf16_f32 v85, v104, v105
	global_store_dwordx4 v19, v[82:85], s[4:5] offset:1024
	global_store_dwordx4 v23, v[98:101], s[6:7] offset:2048
	global_store_dwordx4 v23, v[102:105], s[6:7] offset:2064
	v_add_f32_e32 v112, v110, v111
	v_add_u32_e32 v22, 0x2000, v22
	s_nop 1
	v_add_f32_dpp v112, v112, v112 quad_perm:[1,0,3,2] row_mask:0xf bank_mask:0xf
	s_nop 1
	v_add_f32_dpp v112, v112, v112 quad_perm:[2,3,0,1] row_mask:0xf bank_mask:0xf
	s_nop 1
	v_add_f32_dpp v112, v112, v112 row_half_mirror row_mask:0xf bank_mask:0xf
	s_nop 1
	v_add_f32_dpp v112, v112, v112 row_mirror row_mask:0xf bank_mask:0xf
	s_nop 1
	v_add_f32_dpp v112, v112, v112 row_bcast:15 row_mask:0xa bank_mask:0xf
	s_nop 1
	v_add_f32_dpp v112, v112, v112 row_bcast:31 row_mask:0xc bank_mask:0xf
	v_fmamk_f32 v113, v112, 0x3a800000, v244
	v_rsq_f32_e32 v113, v113
	s_mov_b64 exec, s[8:9]
	global_store_dword v22, v113, s[4:5]
	s_mov_b64 exec, -1
